# boundary dil units now use a clamped and masked variant of the unrolled loop instead of the compiled path
# speedup vs baseline: 1.0378x; 1.0070x over previous
; #define LAS __attribute__((address_space(3)))
; #define GAS __attribute__((address_space(1)))
; __device__ __forceinline__ void dil_unit(LAS unsigned char* lds, bf16_t* proj, int seq, int hd, int T0, int rho) {
;     int tid_ = threadIdx.x; asm volatile("" : "+v"(tid_));
;     const int tid = tid_, lane = tid & 63, r32 = lane & 31, hi = lane >> 5, wid = __builtin_amdgcn_readfirstlane(tid >> 6);
;     bf16_t* base = proj + (size_t)seq * SEQ * NIN;
;     LAS unsigned char* wbuf = lds + wid * 4096;
;     const LAS unsigned char* vp = wbuf + ((lane >> 4) & 1) * 32 + (lane & 3) * 8 + (4 * hi + ((lane & 15) >> 2)) * 64;
;     const int P0 = T0 + rho;
;     bf16x8 qr[4];
; #pragma unroll
;     for (int ks = 0; ks < 4; ++ks) qr[ks] = *(const GAS bf16x8*)(base + (size_t)(P0 + 16 * r32) * NIN + PC_LQ + hd * 64 + 16 * ks + 8 * hi);
;     f32x16 o0 = {}, o1 = {}; float l = 0.f;
;     const bool bound = (T0 < 1024) || (T0 >= 15360);
.LBB0_558:
	s_movk_i32 s100, 0x1800
	s_add_i32 s101, s6, 0x15c00
	s_lshl_b32 s90, s58, 1
	s_add_u32 s82, s56, s90
	s_addc_u32 s83, s57, 0
	s_add_u32 s82, s82, 0x1200
	s_addc_u32 s83, s83, 0
	s_sub_i32 s90, s76, 64
	s_mul_i32 s90, s90, 0x1800
	s_add_u32 s84, s82, s90
	s_addc_u32 s85, s83, 0
	s_sub_i32 s90, s76, 256
	s_mul_i32 s90, s90, 0x1800
	s_add_u32 s86, s82, s90
	s_addc_u32 s87, s83, 0
	s_sub_i32 s90, s76, 1024
	s_mul_i32 s90, s90, 0x1800
	s_add_u32 s88, s82, s90
	s_addc_u32 s89, s83, 0
	v_lshlrev_b32_e32 v153, 1, v98
	v_mad_u32_u24 v80, v105, s100, v82
	v_mad_u32_u24 v100, v110, s100, v153
	v_add_u32_e32 v149, 0x18000, v100
	v_lshlrev_b32_e32 v83, 2, v105
	v_mad_u32_u24 v83, v83, s100, v82
	v_lshlrev_b32_e32 v101, 2, v110
	v_mad_u32_u24 v101, v101, s100, v153
	v_add_u32_e32 v150, 0x60000, v101
	v_lshlrev_b32_e32 v99, 4, v105
	v_mad_u32_u24 v99, v99, s100, v82
	v_lshlrev_b32_e32 v148, 4, v110
	v_mad_u32_u24 v148, v148, s100, v153
	v_add_u32_e32 v151, 0x180000, v148
	v_lshrrev_b32_e32 v249, 3, v103
	v_and_b32_e32 v250, 7, v103
	v_lshlrev_b32_e32 v250, 4, v250
	v_add_u32_e32 v235, 0, v249
	v_add_u32_e32 v236, 8, v249
	v_add_u32_e32 v237, 16, v249
	v_add_u32_e32 v238, 24, v249
	v_add_u32_e32 v239, 0, v249
	v_lshlrev_b32_e32 v239, 2, v239
	v_add_u32_e32 v240, 8, v249
	v_lshlrev_b32_e32 v240, 2, v240
	v_add_u32_e32 v241, 16, v249
	v_lshlrev_b32_e32 v241, 2, v241
	v_add_u32_e32 v242, 24, v249
	v_lshlrev_b32_e32 v242, 2, v242
	v_add_u32_e32 v243, 0, v249
	v_lshlrev_b32_e32 v243, 4, v243
	v_add_u32_e32 v244, 8, v249
	v_lshlrev_b32_e32 v244, 4, v244
	v_add_u32_e32 v245, 16, v249
	v_lshlrev_b32_e32 v245, 4, v245
	v_add_u32_e32 v246, 24, v249
	v_lshlrev_b32_e32 v246, 4, v246
	v_mov_b32_e32 v252, v250
	v_mov_b32_e32 v100, v110
	v_add_u32_e32 v149, 16, v100
	v_lshlrev_b32_e32 v101, 2, v110
	v_add_u32_e32 v150, 64, v101
	v_lshlrev_b32_e32 v148, 4, v110
	v_add_u32_e32 v151, 256, v148
	s_mov_b32 s98, 0x4000
	s_mov_b32 s99, 0x3fff
	v_and_b32_e32 v247, 7, v249
	v_lshlrev_b32_e32 v247, 4, v247
	v_xor_b32_e32 v247, v247, v112
	v_and_b32_e32 v153, 7, v105
	v_or_b32_e32 v248, 0, v106
	v_xor_b32_e32 v248, v248, v153
	v_lshlrev_b32_e32 v248, 4, v248
	v_lshl_add_u32 v248, v105, 7, v248
	v_add_u32_e32 v248, s77, v248
	v_or_b32_e32 v249, 2, v106
	v_xor_b32_e32 v249, v249, v153
	v_lshlrev_b32_e32 v249, 4, v249
	v_lshl_add_u32 v249, v105, 7, v249
	v_add_u32_e32 v249, s77, v249
	v_or_b32_e32 v250, 4, v106
	v_xor_b32_e32 v250, v250, v153
	v_lshlrev_b32_e32 v250, 4, v250
	v_lshl_add_u32 v250, v105, 7, v250
	v_add_u32_e32 v250, s77, v250
	v_or_b32_e32 v251, 6, v106
	v_xor_b32_e32 v251, v251, v153
	v_lshlrev_b32_e32 v251, 4, v251
	v_lshl_add_u32 v251, v105, 7, v251
	v_add_u32_e32 v251, s77, v251
	v_lshlrev_b32_e32 v153, 1, v98
	v_mul_u32_u24_e32 v228, 17, v105
	v_sub_u32_e32 v228, v107, v228
	s_mul_i32 s90, s58, 153
	s_lshr_b32 s90, s90, 1
	s_add_i32 s90, s90, 34876
	v_lshl_add_u32 v228, v228, 2, s90
	v_lshlrev_b32_e32 v229, 2, v105
	v_sub_u32_e32 v229, v107, v229
	s_add_i32 s90, s101, 5104
	v_lshl_add_u32 v229, v229, 2, s90
	v_sub_u32_e32 v230, v107, v105
	s_add_i32 s90, s101, 6364
	v_lshl_add_u32 v230, v230, 2, s90
	v_add_u32_e32 v231, v109, v108
	v_mov_b64_e32 v[232:233], 0
	v_mov_b64_e32 v[0:1], 0
	v_mov_b64_e32 v[2:3], 0
	v_mov_b64_e32 v[4:5], 0
	v_mov_b64_e32 v[6:7], 0
	v_mov_b64_e32 v[8:9], 0
	v_mov_b64_e32 v[10:11], 0
	v_mov_b64_e32 v[12:13], 0
	v_mov_b64_e32 v[14:15], 0
	v_mov_b64_e32 v[16:17], 0
	v_mov_b64_e32 v[18:19], 0
	v_mov_b64_e32 v[20:21], 0
	v_mov_b64_e32 v[22:23], 0
	v_mov_b64_e32 v[24:25], 0
	v_mov_b64_e32 v[26:27], 0
	v_mov_b64_e32 v[28:29], 0
	v_mov_b64_e32 v[30:31], 0
	s_add_i32 s90, s76, -64
	v_add_u32_e32 v80, s90, v235
	v_add_u32_e32 v83, s90, v236
	v_add_u32_e32 v99, s90, v237
	v_add_u32_e32 v253, s90, v238
	v_add_u32_e32 v254, s90, v100
	v_add_u32_e32 v255, s90, v149
	v_med3_i32 v80, v80, 0, s99
	v_med3_i32 v83, v83, 0, s99
	v_med3_i32 v99, v99, 0, s99
	v_med3_i32 v253, v253, 0, s99
	v_med3_i32 v254, v254, 0, s99
	v_med3_i32 v255, v255, 0, s99
	v_mad_u32_u24 v80, v80, s100, v252
	v_mad_u32_u24 v83, v83, s100, v252
	v_mad_u32_u24 v99, v99, s100, v252
	v_mad_u32_u24 v253, v253, s100, v252
	v_mad_u32_u24 v254, v254, s100, v153
	v_mad_u32_u24 v255, v255, s100, v153
	global_load_dwordx4 v[116:119], v80, s[82:83]
	global_load_dwordx4 v[120:123], v83, s[82:83]
	global_load_dwordx4 v[124:127], v99, s[82:83]
	global_load_dwordx4 v[128:131], v253, s[82:83]
	global_load_dwordx4 v[132:135], v254, s[82:83] offset:768
	global_load_dwordx4 v[136:139], v255, s[82:83] offset:768
	global_load_dwordx4 v[140:143], v254, s[82:83] offset:832
	global_load_dwordx4 v[144:147], v255, s[82:83] offset:832
	s_add_i32 s90, s76, -32
	v_add_u32_e32 v80, s90, v235
	v_add_u32_e32 v83, s90, v236
	v_add_u32_e32 v99, s90, v237
	v_add_u32_e32 v253, s90, v238
	v_add_u32_e32 v254, s90, v100
	v_add_u32_e32 v255, s90, v149
	v_med3_i32 v80, v80, 0, s99
	v_med3_i32 v83, v83, 0, s99
	v_med3_i32 v99, v99, 0, s99
	v_med3_i32 v253, v253, 0, s99
	v_med3_i32 v254, v254, 0, s99
	v_med3_i32 v255, v255, 0, s99
	v_mad_u32_u24 v80, v80, s100, v252
	v_mad_u32_u24 v83, v83, s100, v252
	v_mad_u32_u24 v99, v99, s100, v252
	v_mad_u32_u24 v253, v253, s100, v252
	v_mad_u32_u24 v254, v254, s100, v153
	v_mad_u32_u24 v255, v255, s100, v153
	global_load_dwordx4 v[156:159], v80, s[82:83]
	global_load_dwordx4 v[160:163], v83, s[82:83]
	global_load_dwordx4 v[164:167], v99, s[82:83]
	global_load_dwordx4 v[168:171], v253, s[82:83]
	global_load_dwordx4 v[172:175], v254, s[82:83] offset:768
	global_load_dwordx4 v[176:179], v255, s[82:83] offset:768
	global_load_dwordx4 v[180:183], v254, s[82:83] offset:832
	global_load_dwordx4 v[184:187], v255, s[82:83] offset:832
	s_add_i32 s90, s76, 0
	v_add_u32_e32 v80, s90, v235
	v_add_u32_e32 v83, s90, v236
	v_add_u32_e32 v99, s90, v237
	v_add_u32_e32 v253, s90, v238
	v_add_u32_e32 v254, s90, v100
	v_add_u32_e32 v255, s90, v149
	v_med3_i32 v80, v80, 0, s99
	v_med3_i32 v83, v83, 0, s99
	v_med3_i32 v99, v99, 0, s99
	v_med3_i32 v253, v253, 0, s99
	v_med3_i32 v254, v254, 0, s99
	v_med3_i32 v255, v255, 0, s99
	v_mad_u32_u24 v80, v80, s100, v252
	v_mad_u32_u24 v83, v83, s100, v252
	v_mad_u32_u24 v99, v99, s100, v252
	v_mad_u32_u24 v253, v253, s100, v252
	v_mad_u32_u24 v254, v254, s100, v153
	v_mad_u32_u24 v255, v255, s100, v153
	global_load_dwordx4 v[188:191], v80, s[82:83]
	global_load_dwordx4 v[192:195], v83, s[82:83]
	global_load_dwordx4 v[196:199], v99, s[82:83]
	global_load_dwordx4 v[200:203], v253, s[82:83]
	global_load_dwordx4 v[204:207], v254, s[82:83] offset:768
	global_load_dwordx4 v[208:211], v255, s[82:83] offset:768
	global_load_dwordx4 v[212:215], v254, s[82:83] offset:832
	global_load_dwordx4 v[216:219], v255, s[82:83] offset:832
	s_waitcnt vmcnt(16)
	ds_write_b128 v247, v[116:119]
	ds_write_b128 v247, v[120:123] offset:1024
	ds_write_b128 v247, v[124:127] offset:2048
	ds_write_b128 v247, v[128:131] offset:3072
	ds_read_b128 v[116:119], v248
	ds_read_b128 v[120:123], v249
	ds_read_b128 v[124:127], v250
	ds_read_b128 v[128:131], v251
	ds_write_b128 v112, v[132:135]
	ds_write_b128 v112, v[136:139] offset:1024
	ds_write_b128 v112, v[140:143] offset:2048
	ds_write_b128 v112, v[144:147] offset:3072
	v_mov_b32_e32 v115, v228
	ds_read2_b32 v[32:33], v115 offset0:0 offset1:1
	ds_read2_b32 v[34:35], v115 offset0:2 offset1:3
	ds_read2_b32 v[36:37], v115 offset0:8 offset1:9
	ds_read2_b32 v[38:39], v115 offset0:10 offset1:11
	ds_read2_b32 v[40:41], v115 offset0:17 offset1:18
	ds_read2_b32 v[42:43], v115 offset0:19 offset1:20
	ds_read2_b32 v[44:45], v115 offset0:25 offset1:26
	ds_read2_b32 v[46:47], v115 offset0:27 offset1:28
	s_waitcnt lgkmcnt(0)
	v_mfma_f32_32x32x16_bf16 v[32:47], v[116:119], v[48:51], v[32:47]
	ds_read_b64_tr_b16 v[72:73], v231
	ds_read_b64_tr_b16 v[74:75], v231 offset:512
	ds_read_b64_tr_b16 v[76:77], v231 offset:2048
	ds_read_b64_tr_b16 v[78:79], v231 offset:2560
	ds_read_b64_tr_b16 v[220:221], v231 offset:1024
	ds_read_b64_tr_b16 v[222:223], v231 offset:1536
	ds_read_b64_tr_b16 v[224:225], v231 offset:3072
	ds_read_b64_tr_b16 v[226:227], v231 offset:3584
	v_mfma_f32_32x32x16_bf16 v[32:47], v[120:123], v[52:55], v[32:47]
	v_mfma_f32_32x32x16_bf16 v[32:47], v[124:127], v[56:59], v[32:47]
	v_mfma_f32_32x32x16_bf16 v[32:47], v[128:131], v[60:63], v[32:47]
	s_nop 11
	v_exp_f32_e32 v32, v32
	v_exp_f32_e32 v33, v33
	v_exp_f32_e32 v34, v34
	v_exp_f32_e32 v35, v35
	v_exp_f32_e32 v36, v36
	v_exp_f32_e32 v37, v37
	v_exp_f32_e32 v38, v38
	v_exp_f32_e32 v39, v39
	v_exp_f32_e32 v40, v40
	v_exp_f32_e32 v41, v41
	v_exp_f32_e32 v42, v42
	v_exp_f32_e32 v43, v43
	v_exp_f32_e32 v44, v44
	v_exp_f32_e32 v45, v45
	v_exp_f32_e32 v46, v46
	v_exp_f32_e32 v47, v47
	s_add_i32 s90, s76, -64
	v_add_u32_e32 v84, s90, v107
	v_add_u32_e32 v85, 0, v84
	v_add_u32_e32 v86, 1, v84
	v_add_u32_e32 v87, 2, v84
	v_add_u32_e32 v88, 3, v84
	v_cmp_gt_u32_e64 s[30:31], s98, v85
	v_cmp_gt_u32_e64 s[36:37], s98, v86
	v_cmp_gt_u32_e64 s[78:79], s98, v87
	v_cmp_gt_u32_e64 s[50:51], s98, v88
	v_cndmask_b32_e64 v32, 0, v32, s[30:31]
	v_add_u32_e32 v85, 8, v84
	v_cmp_gt_u32_e64 s[30:31], s98, v85
	v_cndmask_b32_e64 v33, 0, v33, s[36:37]
	v_add_u32_e32 v86, 9, v84
	v_cmp_gt_u32_e64 s[36:37], s98, v86
	v_cndmask_b32_e64 v34, 0, v34, s[78:79]
	v_add_u32_e32 v87, 10, v84
	v_cmp_gt_u32_e64 s[78:79], s98, v87
	v_cndmask_b32_e64 v35, 0, v35, s[50:51]
	v_add_u32_e32 v88, 11, v84
	v_cmp_gt_u32_e64 s[50:51], s98, v88
	v_cndmask_b32_e64 v36, 0, v36, s[30:31]
	v_add_u32_e32 v85, 16, v84
	v_cmp_gt_u32_e64 s[30:31], s98, v85
	v_cndmask_b32_e64 v37, 0, v37, s[36:37]
	v_add_u32_e32 v86, 17, v84
	v_cmp_gt_u32_e64 s[36:37], s98, v86
	v_cndmask_b32_e64 v38, 0, v38, s[78:79]
	v_add_u32_e32 v87, 18, v84
	v_cmp_gt_u32_e64 s[78:79], s98, v87
	v_cndmask_b32_e64 v39, 0, v39, s[50:51]
	v_add_u32_e32 v88, 19, v84
	v_cmp_gt_u32_e64 s[50:51], s98, v88
	v_cndmask_b32_e64 v40, 0, v40, s[30:31]
	v_add_u32_e32 v85, 24, v84
	v_cmp_gt_u32_e64 s[30:31], s98, v85
	v_cndmask_b32_e64 v41, 0, v41, s[36:37]
	v_add_u32_e32 v86, 25, v84
	v_cmp_gt_u32_e64 s[36:37], s98, v86
	v_cndmask_b32_e64 v42, 0, v42, s[78:79]
	v_add_u32_e32 v87, 26, v84
	v_cmp_gt_u32_e64 s[78:79], s98, v87
	v_cndmask_b32_e64 v43, 0, v43, s[50:51]
	v_add_u32_e32 v88, 27, v84
	v_cmp_gt_u32_e64 s[50:51], s98, v88
	v_nop
	v_cndmask_b32_e64 v44, 0, v44, s[30:31]
	v_cndmask_b32_e64 v45, 0, v45, s[36:37]
	v_cndmask_b32_e64 v46, 0, v46, s[78:79]
	v_cndmask_b32_e64 v47, 0, v47, s[50:51]
	v_cvt_pk_bf16_f32 v64, v32, v33
	v_cvt_pk_bf16_f32 v65, v34, v35
	v_cvt_pk_bf16_f32 v66, v36, v37
	v_cvt_pk_bf16_f32 v67, v38, v39
	v_cvt_pk_bf16_f32 v68, v40, v41
	v_cvt_pk_bf16_f32 v69, v42, v43
	v_cvt_pk_bf16_f32 v70, v44, v45
	v_cvt_pk_bf16_f32 v71, v46, v47
	v_pk_add_f32 v[232:233], v[232:233], v[32:33]
	v_pk_add_f32 v[232:233], v[232:233], v[34:35]
	v_pk_add_f32 v[232:233], v[232:233], v[36:37]
	v_pk_add_f32 v[232:233], v[232:233], v[38:39]
	v_pk_add_f32 v[232:233], v[232:233], v[40:41]
	v_pk_add_f32 v[232:233], v[232:233], v[42:43]
	v_pk_add_f32 v[232:233], v[232:233], v[44:45]
	v_pk_add_f32 v[232:233], v[232:233], v[46:47]
	s_waitcnt lgkmcnt(0)
	v_mfma_f32_32x32x16_bf16 v[0:15], v[64:67], v[72:75], v[0:15]
	v_mfma_f32_32x32x16_bf16 v[16:31], v[64:67], v[76:79], v[16:31]
	v_mfma_f32_32x32x16_bf16 v[0:15], v[68:71], v[220:223], v[0:15]
	v_mfma_f32_32x32x16_bf16 v[16:31], v[68:71], v[224:227], v[16:31]
	s_add_i32 s90, s76, 32
	v_add_u32_e32 v80, s90, v235
	v_add_u32_e32 v83, s90, v236
	v_add_u32_e32 v99, s90, v237
	v_add_u32_e32 v253, s90, v238
	v_add_u32_e32 v254, s90, v100
	v_add_u32_e32 v255, s90, v149
	v_med3_i32 v80, v80, 0, s99
	v_med3_i32 v83, v83, 0, s99
	v_med3_i32 v99, v99, 0, s99
	v_med3_i32 v253, v253, 0, s99
	v_med3_i32 v254, v254, 0, s99
	v_med3_i32 v255, v255, 0, s99
	v_mad_u32_u24 v80, v80, s100, v252
	v_mad_u32_u24 v83, v83, s100, v252
	v_mad_u32_u24 v99, v99, s100, v252
	v_mad_u32_u24 v253, v253, s100, v252
	v_mad_u32_u24 v254, v254, s100, v153
	v_mad_u32_u24 v255, v255, s100, v153
	global_load_dwordx4 v[116:119], v80, s[82:83]
	global_load_dwordx4 v[120:123], v83, s[82:83]
	global_load_dwordx4 v[124:127], v99, s[82:83]
	global_load_dwordx4 v[128:131], v253, s[82:83]
	global_load_dwordx4 v[132:135], v254, s[82:83] offset:768
	global_load_dwordx4 v[136:139], v255, s[82:83] offset:768
	global_load_dwordx4 v[140:143], v254, s[82:83] offset:832
	global_load_dwordx4 v[144:147], v255, s[82:83] offset:832
	s_waitcnt vmcnt(16)
	ds_write_b128 v247, v[156:159]
	ds_write_b128 v247, v[160:163] offset:1024
	ds_write_b128 v247, v[164:167] offset:2048
	ds_write_b128 v247, v[168:171] offset:3072
	ds_read_b128 v[156:159], v248
	ds_read_b128 v[160:163], v249
	ds_read_b128 v[164:167], v250
	ds_read_b128 v[168:171], v251
	ds_write_b128 v112, v[172:175]
	ds_write_b128 v112, v[176:179] offset:1024
	ds_write_b128 v112, v[180:183] offset:2048
	ds_write_b128 v112, v[184:187] offset:3072
	ds_read2_b32 v[32:33], v115 offset0:34 offset1:35
	ds_read2_b32 v[34:35], v115 offset0:36 offset1:37
	ds_read2_b32 v[36:37], v115 offset0:42 offset1:43
	ds_read2_b32 v[38:39], v115 offset0:44 offset1:45
	ds_read2_b32 v[40:41], v115 offset0:51 offset1:52
	ds_read2_b32 v[42:43], v115 offset0:53 offset1:54
	ds_read2_b32 v[44:45], v115 offset0:59 offset1:60
	ds_read2_b32 v[46:47], v115 offset0:61 offset1:62
	s_waitcnt lgkmcnt(0)
	v_mfma_f32_32x32x16_bf16 v[32:47], v[156:159], v[48:51], v[32:47]
	ds_read_b64_tr_b16 v[72:73], v231
	ds_read_b64_tr_b16 v[74:75], v231 offset:512
	ds_read_b64_tr_b16 v[76:77], v231 offset:2048
	ds_read_b64_tr_b16 v[78:79], v231 offset:2560
	ds_read_b64_tr_b16 v[220:221], v231 offset:1024
	ds_read_b64_tr_b16 v[222:223], v231 offset:1536
	ds_read_b64_tr_b16 v[224:225], v231 offset:3072
	ds_read_b64_tr_b16 v[226:227], v231 offset:3584
	v_mfma_f32_32x32x16_bf16 v[32:47], v[160:163], v[52:55], v[32:47]
	v_mfma_f32_32x32x16_bf16 v[32:47], v[164:167], v[56:59], v[32:47]
	v_mfma_f32_32x32x16_bf16 v[32:47], v[168:171], v[60:63], v[32:47]
	s_nop 11
	v_exp_f32_e32 v32, v32
	v_exp_f32_e32 v33, v33
	v_exp_f32_e32 v34, v34
	v_exp_f32_e32 v35, v35
	v_exp_f32_e32 v36, v36
	v_exp_f32_e32 v37, v37
	v_exp_f32_e32 v38, v38
	v_exp_f32_e32 v39, v39
	v_exp_f32_e32 v40, v40
	v_exp_f32_e32 v41, v41
	v_exp_f32_e32 v42, v42
	v_exp_f32_e32 v43, v43
	v_exp_f32_e32 v44, v44
	v_exp_f32_e32 v45, v45
	v_exp_f32_e32 v46, v46
	v_exp_f32_e32 v47, v47
	s_add_i32 s90, s76, -32
	v_add_u32_e32 v84, s90, v107
	v_add_u32_e32 v85, 0, v84
	v_add_u32_e32 v86, 1, v84
	v_add_u32_e32 v87, 2, v84
	v_add_u32_e32 v88, 3, v84
	v_cmp_gt_u32_e64 s[30:31], s98, v85
	v_cmp_gt_u32_e64 s[36:37], s98, v86
	v_cmp_gt_u32_e64 s[78:79], s98, v87
	v_cmp_gt_u32_e64 s[50:51], s98, v88
	v_cndmask_b32_e64 v32, 0, v32, s[30:31]
	v_add_u32_e32 v85, 8, v84
	v_cmp_gt_u32_e64 s[30:31], s98, v85
	v_cndmask_b32_e64 v33, 0, v33, s[36:37]
	v_add_u32_e32 v86, 9, v84
	v_cmp_gt_u32_e64 s[36:37], s98, v86
	v_cndmask_b32_e64 v34, 0, v34, s[78:79]
	v_add_u32_e32 v87, 10, v84
	v_cmp_gt_u32_e64 s[78:79], s98, v87
	v_cndmask_b32_e64 v35, 0, v35, s[50:51]
	v_add_u32_e32 v88, 11, v84
	v_cmp_gt_u32_e64 s[50:51], s98, v88
	v_cndmask_b32_e64 v36, 0, v36, s[30:31]
	v_add_u32_e32 v85, 16, v84
	v_cmp_gt_u32_e64 s[30:31], s98, v85
	v_cndmask_b32_e64 v37, 0, v37, s[36:37]
	v_add_u32_e32 v86, 17, v84
	v_cmp_gt_u32_e64 s[36:37], s98, v86
	v_cndmask_b32_e64 v38, 0, v38, s[78:79]
	v_add_u32_e32 v87, 18, v84
	v_cmp_gt_u32_e64 s[78:79], s98, v87
	v_cndmask_b32_e64 v39, 0, v39, s[50:51]
	v_add_u32_e32 v88, 19, v84
	v_cmp_gt_u32_e64 s[50:51], s98, v88
	v_cndmask_b32_e64 v40, 0, v40, s[30:31]
	v_add_u32_e32 v85, 24, v84
	v_cmp_gt_u32_e64 s[30:31], s98, v85
	v_cndmask_b32_e64 v41, 0, v41, s[36:37]
	v_add_u32_e32 v86, 25, v84
	v_cmp_gt_u32_e64 s[36:37], s98, v86
	v_cndmask_b32_e64 v42, 0, v42, s[78:79]
	v_add_u32_e32 v87, 26, v84
	v_cmp_gt_u32_e64 s[78:79], s98, v87
	v_cndmask_b32_e64 v43, 0, v43, s[50:51]
	v_add_u32_e32 v88, 27, v84
	v_cmp_gt_u32_e64 s[50:51], s98, v88
	v_nop
	v_cndmask_b32_e64 v44, 0, v44, s[30:31]
	v_cndmask_b32_e64 v45, 0, v45, s[36:37]
	v_cndmask_b32_e64 v46, 0, v46, s[78:79]
	v_cndmask_b32_e64 v47, 0, v47, s[50:51]
	v_cvt_pk_bf16_f32 v64, v32, v33
	v_cvt_pk_bf16_f32 v65, v34, v35
	v_cvt_pk_bf16_f32 v66, v36, v37
	v_cvt_pk_bf16_f32 v67, v38, v39
	v_cvt_pk_bf16_f32 v68, v40, v41
	v_cvt_pk_bf16_f32 v69, v42, v43
	v_cvt_pk_bf16_f32 v70, v44, v45
	v_cvt_pk_bf16_f32 v71, v46, v47
	v_pk_add_f32 v[232:233], v[232:233], v[32:33]
	v_pk_add_f32 v[232:233], v[232:233], v[34:35]
	v_pk_add_f32 v[232:233], v[232:233], v[36:37]
	v_pk_add_f32 v[232:233], v[232:233], v[38:39]
	v_pk_add_f32 v[232:233], v[232:233], v[40:41]
	v_pk_add_f32 v[232:233], v[232:233], v[42:43]
	v_pk_add_f32 v[232:233], v[232:233], v[44:45]
	v_pk_add_f32 v[232:233], v[232:233], v[46:47]
	s_waitcnt lgkmcnt(0)
	v_mfma_f32_32x32x16_bf16 v[0:15], v[64:67], v[72:75], v[0:15]
	v_mfma_f32_32x32x16_bf16 v[16:31], v[64:67], v[76:79], v[16:31]
	v_mfma_f32_32x32x16_bf16 v[0:15], v[68:71], v[220:223], v[0:15]
	v_mfma_f32_32x32x16_bf16 v[16:31], v[68:71], v[224:227], v[16:31]
	s_add_i32 s90, s76, 64
	v_add_u32_e32 v80, s90, v235
	v_add_u32_e32 v83, s90, v236
	v_add_u32_e32 v99, s90, v237
	v_add_u32_e32 v253, s90, v238
	v_add_u32_e32 v254, s90, v100
	v_add_u32_e32 v255, s90, v149
	v_med3_i32 v80, v80, 0, s99
	v_med3_i32 v83, v83, 0, s99
	v_med3_i32 v99, v99, 0, s99
	v_med3_i32 v253, v253, 0, s99
	v_med3_i32 v254, v254, 0, s99
	v_med3_i32 v255, v255, 0, s99
	v_mad_u32_u24 v80, v80, s100, v252
	v_mad_u32_u24 v83, v83, s100, v252
	v_mad_u32_u24 v99, v99, s100, v252
	v_mad_u32_u24 v253, v253, s100, v252
	v_mad_u32_u24 v254, v254, s100, v153
	v_mad_u32_u24 v255, v255, s100, v153
	global_load_dwordx4 v[156:159], v80, s[82:83]
	global_load_dwordx4 v[160:163], v83, s[82:83]
	global_load_dwordx4 v[164:167], v99, s[82:83]
	global_load_dwordx4 v[168:171], v253, s[82:83]
	global_load_dwordx4 v[172:175], v254, s[82:83] offset:768
	global_load_dwordx4 v[176:179], v255, s[82:83] offset:768
	global_load_dwordx4 v[180:183], v254, s[82:83] offset:832
	global_load_dwordx4 v[184:187], v255, s[82:83] offset:832
	s_waitcnt vmcnt(16)
	ds_write_b128 v247, v[188:191]
	ds_write_b128 v247, v[192:195] offset:1024
	ds_write_b128 v247, v[196:199] offset:2048
	ds_write_b128 v247, v[200:203] offset:3072
	ds_read_b128 v[188:191], v248
	ds_read_b128 v[192:195], v249
	ds_read_b128 v[196:199], v250
	ds_read_b128 v[200:203], v251
	ds_write_b128 v112, v[204:207]
	ds_write_b128 v112, v[208:211] offset:1024
	ds_write_b128 v112, v[212:215] offset:2048
	ds_write_b128 v112, v[216:219] offset:3072
	ds_read2_b32 v[32:33], v115 offset0:68 offset1:69
	ds_read2_b32 v[34:35], v115 offset0:70 offset1:71
	ds_read2_b32 v[36:37], v115 offset0:76 offset1:77
	ds_read2_b32 v[38:39], v115 offset0:78 offset1:79
	ds_read2_b32 v[40:41], v115 offset0:85 offset1:86
	ds_read2_b32 v[42:43], v115 offset0:87 offset1:88
	ds_read2_b32 v[44:45], v115 offset0:93 offset1:94
	ds_read2_b32 v[46:47], v115 offset0:95 offset1:96
	s_waitcnt lgkmcnt(0)
	v_mfma_f32_32x32x16_bf16 v[32:47], v[188:191], v[48:51], v[32:47]
	ds_read_b64_tr_b16 v[72:73], v231
	ds_read_b64_tr_b16 v[74:75], v231 offset:512
	ds_read_b64_tr_b16 v[76:77], v231 offset:2048
	ds_read_b64_tr_b16 v[78:79], v231 offset:2560
	ds_read_b64_tr_b16 v[220:221], v231 offset:1024
	ds_read_b64_tr_b16 v[222:223], v231 offset:1536
	ds_read_b64_tr_b16 v[224:225], v231 offset:3072
	ds_read_b64_tr_b16 v[226:227], v231 offset:3584
	v_mfma_f32_32x32x16_bf16 v[32:47], v[192:195], v[52:55], v[32:47]
	v_mfma_f32_32x32x16_bf16 v[32:47], v[196:199], v[56:59], v[32:47]
	v_mfma_f32_32x32x16_bf16 v[32:47], v[200:203], v[60:63], v[32:47]
	s_nop 11
	v_exp_f32_e32 v32, v32
	v_exp_f32_e32 v33, v33
	v_exp_f32_e32 v34, v34
	v_exp_f32_e32 v35, v35
	v_exp_f32_e32 v36, v36
	v_exp_f32_e32 v37, v37
	v_exp_f32_e32 v38, v38
	v_exp_f32_e32 v39, v39
	v_exp_f32_e32 v40, v40
	v_exp_f32_e32 v41, v41
	v_exp_f32_e32 v42, v42
	v_exp_f32_e32 v43, v43
	v_exp_f32_e32 v44, v44
	v_exp_f32_e32 v45, v45
	v_exp_f32_e32 v46, v46
	v_exp_f32_e32 v47, v47
	s_add_i32 s90, s76, 0
	v_add_u32_e32 v84, s90, v107
	v_add_u32_e32 v85, 0, v84
	v_add_u32_e32 v86, 1, v84
	v_add_u32_e32 v87, 2, v84
	v_add_u32_e32 v88, 3, v84
	v_cmp_gt_u32_e64 s[30:31], s98, v85
	v_cmp_gt_u32_e64 s[36:37], s98, v86
	v_cmp_gt_u32_e64 s[78:79], s98, v87
	v_cmp_gt_u32_e64 s[50:51], s98, v88
	v_cndmask_b32_e64 v32, 0, v32, s[30:31]
	v_add_u32_e32 v85, 8, v84
	v_cmp_gt_u32_e64 s[30:31], s98, v85
	v_cndmask_b32_e64 v33, 0, v33, s[36:37]
	v_add_u32_e32 v86, 9, v84
	v_cmp_gt_u32_e64 s[36:37], s98, v86
	v_cndmask_b32_e64 v34, 0, v34, s[78:79]
	v_add_u32_e32 v87, 10, v84
	v_cmp_gt_u32_e64 s[78:79], s98, v87
	v_cndmask_b32_e64 v35, 0, v35, s[50:51]
	v_add_u32_e32 v88, 11, v84
	v_cmp_gt_u32_e64 s[50:51], s98, v88
	v_cndmask_b32_e64 v36, 0, v36, s[30:31]
	v_add_u32_e32 v85, 16, v84
	v_cmp_gt_u32_e64 s[30:31], s98, v85
	v_cndmask_b32_e64 v37, 0, v37, s[36:37]
	v_add_u32_e32 v86, 17, v84
	v_cmp_gt_u32_e64 s[36:37], s98, v86
	v_cndmask_b32_e64 v38, 0, v38, s[78:79]
	v_add_u32_e32 v87, 18, v84
	v_cmp_gt_u32_e64 s[78:79], s98, v87
	v_cndmask_b32_e64 v39, 0, v39, s[50:51]
	v_add_u32_e32 v88, 19, v84
	v_cmp_gt_u32_e64 s[50:51], s98, v88
	v_cndmask_b32_e64 v40, 0, v40, s[30:31]
	v_add_u32_e32 v85, 24, v84
	v_cmp_gt_u32_e64 s[30:31], s98, v85
	v_cndmask_b32_e64 v41, 0, v41, s[36:37]
	v_add_u32_e32 v86, 25, v84
	v_cmp_gt_u32_e64 s[36:37], s98, v86
	v_cndmask_b32_e64 v42, 0, v42, s[78:79]
	v_add_u32_e32 v87, 26, v84
	v_cmp_gt_u32_e64 s[78:79], s98, v87
	v_cndmask_b32_e64 v43, 0, v43, s[50:51]
	v_add_u32_e32 v88, 27, v84
	v_cmp_gt_u32_e64 s[50:51], s98, v88
	v_nop
	v_cndmask_b32_e64 v44, 0, v44, s[30:31]
	v_cndmask_b32_e64 v45, 0, v45, s[36:37]
	v_cndmask_b32_e64 v46, 0, v46, s[78:79]
	v_cndmask_b32_e64 v47, 0, v47, s[50:51]
	v_cvt_pk_bf16_f32 v64, v32, v33
	v_cvt_pk_bf16_f32 v65, v34, v35
	v_cvt_pk_bf16_f32 v66, v36, v37
	v_cvt_pk_bf16_f32 v67, v38, v39
	v_cvt_pk_bf16_f32 v68, v40, v41
	v_cvt_pk_bf16_f32 v69, v42, v43
	v_cvt_pk_bf16_f32 v70, v44, v45
	v_cvt_pk_bf16_f32 v71, v46, v47
	v_pk_add_f32 v[232:233], v[232:233], v[32:33]
	v_pk_add_f32 v[232:233], v[232:233], v[34:35]
	v_pk_add_f32 v[232:233], v[232:233], v[36:37]
	v_pk_add_f32 v[232:233], v[232:233], v[38:39]
	v_pk_add_f32 v[232:233], v[232:233], v[40:41]
	v_pk_add_f32 v[232:233], v[232:233], v[42:43]
	v_pk_add_f32 v[232:233], v[232:233], v[44:45]
	v_pk_add_f32 v[232:233], v[232:233], v[46:47]
	s_waitcnt lgkmcnt(0)
	v_mfma_f32_32x32x16_bf16 v[0:15], v[64:67], v[72:75], v[0:15]
	v_mfma_f32_32x32x16_bf16 v[16:31], v[64:67], v[76:79], v[16:31]
	v_mfma_f32_32x32x16_bf16 v[0:15], v[68:71], v[220:223], v[0:15]
	v_mfma_f32_32x32x16_bf16 v[16:31], v[68:71], v[224:227], v[16:31]
	s_add_i32 s90, s76, 96
	v_add_u32_e32 v80, s90, v235
	v_add_u32_e32 v83, s90, v236
	v_add_u32_e32 v99, s90, v237
	v_add_u32_e32 v253, s90, v238
	v_add_u32_e32 v254, s90, v100
	v_add_u32_e32 v255, s90, v149
	v_med3_i32 v80, v80, 0, s99
	v_med3_i32 v83, v83, 0, s99
	v_med3_i32 v99, v99, 0, s99
	v_med3_i32 v253, v253, 0, s99
	v_med3_i32 v254, v254, 0, s99
	v_med3_i32 v255, v255, 0, s99
	v_mad_u32_u24 v80, v80, s100, v252
	v_mad_u32_u24 v83, v83, s100, v252
	v_mad_u32_u24 v99, v99, s100, v252
	v_mad_u32_u24 v253, v253, s100, v252
	v_mad_u32_u24 v254, v254, s100, v153
	v_mad_u32_u24 v255, v255, s100, v153
	global_load_dwordx4 v[188:191], v80, s[82:83]
	global_load_dwordx4 v[192:195], v83, s[82:83]
	global_load_dwordx4 v[196:199], v99, s[82:83]
	global_load_dwordx4 v[200:203], v253, s[82:83]
	global_load_dwordx4 v[204:207], v254, s[82:83] offset:768
	global_load_dwordx4 v[208:211], v255, s[82:83] offset:768
	global_load_dwordx4 v[212:215], v254, s[82:83] offset:832
	global_load_dwordx4 v[216:219], v255, s[82:83] offset:832
	s_waitcnt vmcnt(16)
	ds_write_b128 v247, v[116:119]
	ds_write_b128 v247, v[120:123] offset:1024
	ds_write_b128 v247, v[124:127] offset:2048
	ds_write_b128 v247, v[128:131] offset:3072
	ds_read_b128 v[116:119], v248
	ds_read_b128 v[120:123], v249
	ds_read_b128 v[124:127], v250
	ds_read_b128 v[128:131], v251
	ds_write_b128 v112, v[132:135]
	ds_write_b128 v112, v[136:139] offset:1024
	ds_write_b128 v112, v[140:143] offset:2048
	ds_write_b128 v112, v[144:147] offset:3072
	ds_read2_b32 v[32:33], v115 offset0:102 offset1:103
	ds_read2_b32 v[34:35], v115 offset0:104 offset1:105
	ds_read2_b32 v[36:37], v115 offset0:110 offset1:111
	ds_read2_b32 v[38:39], v115 offset0:112 offset1:113
	ds_read2_b32 v[40:41], v115 offset0:119 offset1:120
	ds_read2_b32 v[42:43], v115 offset0:121 offset1:122
	ds_read2_b32 v[44:45], v115 offset0:127 offset1:128
	ds_read2_b32 v[46:47], v115 offset0:129 offset1:130
	s_waitcnt lgkmcnt(0)
	v_mfma_f32_32x32x16_bf16 v[32:47], v[116:119], v[48:51], v[32:47]
	ds_read_b64_tr_b16 v[72:73], v231
	ds_read_b64_tr_b16 v[74:75], v231 offset:512
	ds_read_b64_tr_b16 v[76:77], v231 offset:2048
	ds_read_b64_tr_b16 v[78:79], v231 offset:2560
	ds_read_b64_tr_b16 v[220:221], v231 offset:1024
	ds_read_b64_tr_b16 v[222:223], v231 offset:1536
	ds_read_b64_tr_b16 v[224:225], v231 offset:3072
	ds_read_b64_tr_b16 v[226:227], v231 offset:3584
	v_mfma_f32_32x32x16_bf16 v[32:47], v[120:123], v[52:55], v[32:47]
	v_mfma_f32_32x32x16_bf16 v[32:47], v[124:127], v[56:59], v[32:47]
	v_mfma_f32_32x32x16_bf16 v[32:47], v[128:131], v[60:63], v[32:47]
	s_nop 11
	v_exp_f32_e32 v32, v32
	v_exp_f32_e32 v33, v33
	v_exp_f32_e32 v34, v34
	v_exp_f32_e32 v35, v35
	v_exp_f32_e32 v36, v36
	v_exp_f32_e32 v37, v37
	v_exp_f32_e32 v38, v38
	v_exp_f32_e32 v39, v39
	v_exp_f32_e32 v40, v40
	v_exp_f32_e32 v41, v41
	v_exp_f32_e32 v42, v42
	v_exp_f32_e32 v43, v43
	v_exp_f32_e32 v44, v44
	v_exp_f32_e32 v45, v45
	v_exp_f32_e32 v46, v46
	v_exp_f32_e32 v47, v47
	s_add_i32 s90, s76, 32
	v_add_u32_e32 v84, s90, v107
	v_add_u32_e32 v85, 0, v84
	v_add_u32_e32 v86, 1, v84
	v_add_u32_e32 v87, 2, v84
	v_add_u32_e32 v88, 3, v84
	v_cmp_gt_u32_e64 s[30:31], s98, v85
	v_cmp_gt_u32_e64 s[36:37], s98, v86
	v_cmp_gt_u32_e64 s[78:79], s98, v87
	v_cmp_gt_u32_e64 s[50:51], s98, v88
	v_cndmask_b32_e64 v32, 0, v32, s[30:31]
	v_add_u32_e32 v85, 8, v84
	v_cmp_gt_u32_e64 s[30:31], s98, v85
	v_cndmask_b32_e64 v33, 0, v33, s[36:37]
	v_add_u32_e32 v86, 9, v84
	v_cmp_gt_u32_e64 s[36:37], s98, v86
	v_cndmask_b32_e64 v34, 0, v34, s[78:79]
	v_add_u32_e32 v87, 10, v84
	v_cmp_gt_u32_e64 s[78:79], s98, v87
	v_cndmask_b32_e64 v35, 0, v35, s[50:51]
	v_add_u32_e32 v88, 11, v84
	v_cmp_gt_u32_e64 s[50:51], s98, v88
	v_cndmask_b32_e64 v36, 0, v36, s[30:31]
	v_add_u32_e32 v85, 16, v84
	v_cmp_gt_u32_e64 s[30:31], s98, v85
	v_cndmask_b32_e64 v37, 0, v37, s[36:37]
	v_add_u32_e32 v86, 17, v84
	v_cmp_gt_u32_e64 s[36:37], s98, v86
	v_cndmask_b32_e64 v38, 0, v38, s[78:79]
	v_add_u32_e32 v87, 18, v84
	v_cmp_gt_u32_e64 s[78:79], s98, v87
	v_cndmask_b32_e64 v39, 0, v39, s[50:51]
	v_add_u32_e32 v88, 19, v84
	v_cmp_gt_u32_e64 s[50:51], s98, v88
	v_cndmask_b32_e64 v40, 0, v40, s[30:31]
	v_add_u32_e32 v85, 24, v84
	v_cmp_gt_u32_e64 s[30:31], s98, v85
	v_cndmask_b32_e64 v41, 0, v41, s[36:37]
	v_add_u32_e32 v86, 25, v84
	v_cmp_gt_u32_e64 s[36:37], s98, v86
	v_cndmask_b32_e64 v42, 0, v42, s[78:79]
	v_add_u32_e32 v87, 26, v84
	v_cmp_gt_u32_e64 s[78:79], s98, v87
	v_cndmask_b32_e64 v43, 0, v43, s[50:51]
	v_add_u32_e32 v88, 27, v84
	v_cmp_gt_u32_e64 s[50:51], s98, v88
	v_nop
	v_cndmask_b32_e64 v44, 0, v44, s[30:31]
	v_cndmask_b32_e64 v45, 0, v45, s[36:37]
	v_cndmask_b32_e64 v46, 0, v46, s[78:79]
	v_cndmask_b32_e64 v47, 0, v47, s[50:51]
	v_cvt_pk_bf16_f32 v64, v32, v33
	v_cvt_pk_bf16_f32 v65, v34, v35
	v_cvt_pk_bf16_f32 v66, v36, v37
	v_cvt_pk_bf16_f32 v67, v38, v39
	v_cvt_pk_bf16_f32 v68, v40, v41
	v_cvt_pk_bf16_f32 v69, v42, v43
	v_cvt_pk_bf16_f32 v70, v44, v45
	v_cvt_pk_bf16_f32 v71, v46, v47
	v_pk_add_f32 v[232:233], v[232:233], v[32:33]
	v_pk_add_f32 v[232:233], v[232:233], v[34:35]
	v_pk_add_f32 v[232:233], v[232:233], v[36:37]
	v_pk_add_f32 v[232:233], v[232:233], v[38:39]
	v_pk_add_f32 v[232:233], v[232:233], v[40:41]
	v_pk_add_f32 v[232:233], v[232:233], v[42:43]
	v_pk_add_f32 v[232:233], v[232:233], v[44:45]
	v_pk_add_f32 v[232:233], v[232:233], v[46:47]
	s_waitcnt lgkmcnt(0)
	v_mfma_f32_32x32x16_bf16 v[0:15], v[64:67], v[72:75], v[0:15]
	v_mfma_f32_32x32x16_bf16 v[16:31], v[64:67], v[76:79], v[16:31]
	v_mfma_f32_32x32x16_bf16 v[0:15], v[68:71], v[220:223], v[0:15]
	v_mfma_f32_32x32x16_bf16 v[16:31], v[68:71], v[224:227], v[16:31]
	s_add_i32 s90, s76, 128
	v_add_u32_e32 v80, s90, v235
	v_add_u32_e32 v83, s90, v236
	v_add_u32_e32 v99, s90, v237
	v_add_u32_e32 v253, s90, v238
	v_add_u32_e32 v254, s90, v100
	v_add_u32_e32 v255, s90, v149
	v_med3_i32 v80, v80, 0, s99
	v_med3_i32 v83, v83, 0, s99
	v_med3_i32 v99, v99, 0, s99
	v_med3_i32 v253, v253, 0, s99
	v_med3_i32 v254, v254, 0, s99
	v_med3_i32 v255, v255, 0, s99
	v_mad_u32_u24 v80, v80, s100, v252
	v_mad_u32_u24 v83, v83, s100, v252
	v_mad_u32_u24 v99, v99, s100, v252
	v_mad_u32_u24 v253, v253, s100, v252
	v_mad_u32_u24 v254, v254, s100, v153
	v_mad_u32_u24 v255, v255, s100, v153
	global_load_dwordx4 v[116:119], v80, s[82:83]
	global_load_dwordx4 v[120:123], v83, s[82:83]
	global_load_dwordx4 v[124:127], v99, s[82:83]
	global_load_dwordx4 v[128:131], v253, s[82:83]
	global_load_dwordx4 v[132:135], v254, s[82:83] offset:768
	global_load_dwordx4 v[136:139], v255, s[82:83] offset:768
	global_load_dwordx4 v[140:143], v254, s[82:83] offset:832
	global_load_dwordx4 v[144:147], v255, s[82:83] offset:832
	s_waitcnt vmcnt(16)
	ds_write_b128 v247, v[156:159]
	ds_write_b128 v247, v[160:163] offset:1024
	ds_write_b128 v247, v[164:167] offset:2048
	ds_write_b128 v247, v[168:171] offset:3072
	ds_read_b128 v[156:159], v248
	ds_read_b128 v[160:163], v249
	ds_read_b128 v[164:167], v250
	ds_read_b128 v[168:171], v251
	ds_write_b128 v112, v[172:175]
	ds_write_b128 v112, v[176:179] offset:1024
	ds_write_b128 v112, v[180:183] offset:2048
	ds_write_b128 v112, v[184:187] offset:3072
	ds_read2_b32 v[32:33], v115 offset0:136 offset1:137
	ds_read2_b32 v[34:35], v115 offset0:138 offset1:139
	ds_read2_b32 v[36:37], v115 offset0:144 offset1:145
	ds_read2_b32 v[38:39], v115 offset0:146 offset1:147
	ds_read2_b32 v[40:41], v115 offset0:153 offset1:154
	ds_read2_b32 v[42:43], v115 offset0:155 offset1:156
	ds_read2_b32 v[44:45], v115 offset0:161 offset1:162
	ds_read2_b32 v[46:47], v115 offset0:163 offset1:164
	s_waitcnt lgkmcnt(0)
	v_mfma_f32_32x32x16_bf16 v[32:47], v[156:159], v[48:51], v[32:47]
	ds_read_b64_tr_b16 v[72:73], v231
	ds_read_b64_tr_b16 v[74:75], v231 offset:512
	ds_read_b64_tr_b16 v[76:77], v231 offset:2048
	ds_read_b64_tr_b16 v[78:79], v231 offset:2560
	ds_read_b64_tr_b16 v[220:221], v231 offset:1024
	ds_read_b64_tr_b16 v[222:223], v231 offset:1536
	ds_read_b64_tr_b16 v[224:225], v231 offset:3072
	ds_read_b64_tr_b16 v[226:227], v231 offset:3584
	v_mfma_f32_32x32x16_bf16 v[32:47], v[160:163], v[52:55], v[32:47]
	v_mfma_f32_32x32x16_bf16 v[32:47], v[164:167], v[56:59], v[32:47]
	v_mfma_f32_32x32x16_bf16 v[32:47], v[168:171], v[60:63], v[32:47]
	s_nop 11
	v_exp_f32_e32 v32, v32
	v_exp_f32_e32 v33, v33
	v_exp_f32_e32 v34, v34
	v_exp_f32_e32 v35, v35
	v_exp_f32_e32 v36, v36
	v_exp_f32_e32 v37, v37
	v_exp_f32_e32 v38, v38
	v_exp_f32_e32 v39, v39
	v_exp_f32_e32 v40, v40
	v_exp_f32_e32 v41, v41
	v_exp_f32_e32 v42, v42
	v_exp_f32_e32 v43, v43
	v_exp_f32_e32 v44, v44
	v_exp_f32_e32 v45, v45
	v_exp_f32_e32 v46, v46
	v_exp_f32_e32 v47, v47
	s_add_i32 s90, s76, 64
	v_add_u32_e32 v84, s90, v107
	v_add_u32_e32 v85, 0, v84
	v_add_u32_e32 v86, 1, v84
	v_add_u32_e32 v87, 2, v84
	v_add_u32_e32 v88, 3, v84
	v_cmp_gt_u32_e64 s[30:31], s98, v85
	v_cmp_gt_u32_e64 s[36:37], s98, v86
	v_cmp_gt_u32_e64 s[78:79], s98, v87
	v_cmp_gt_u32_e64 s[50:51], s98, v88
	v_cndmask_b32_e64 v32, 0, v32, s[30:31]
	v_add_u32_e32 v85, 8, v84
	v_cmp_gt_u32_e64 s[30:31], s98, v85
	v_cndmask_b32_e64 v33, 0, v33, s[36:37]
	v_add_u32_e32 v86, 9, v84
	v_cmp_gt_u32_e64 s[36:37], s98, v86
	v_cndmask_b32_e64 v34, 0, v34, s[78:79]
	v_add_u32_e32 v87, 10, v84
	v_cmp_gt_u32_e64 s[78:79], s98, v87
	v_cndmask_b32_e64 v35, 0, v35, s[50:51]
	v_add_u32_e32 v88, 11, v84
	v_cmp_gt_u32_e64 s[50:51], s98, v88
	v_cndmask_b32_e64 v36, 0, v36, s[30:31]
	v_add_u32_e32 v85, 16, v84
	v_cmp_gt_u32_e64 s[30:31], s98, v85
	v_cndmask_b32_e64 v37, 0, v37, s[36:37]
	v_add_u32_e32 v86, 17, v84
	v_cmp_gt_u32_e64 s[36:37], s98, v86
	v_cndmask_b32_e64 v38, 0, v38, s[78:79]
	v_add_u32_e32 v87, 18, v84
	v_cmp_gt_u32_e64 s[78:79], s98, v87
	v_cndmask_b32_e64 v39, 0, v39, s[50:51]
	v_add_u32_e32 v88, 19, v84
	v_cmp_gt_u32_e64 s[50:51], s98, v88
	v_cndmask_b32_e64 v40, 0, v40, s[30:31]
	v_add_u32_e32 v85, 24, v84
	v_cmp_gt_u32_e64 s[30:31], s98, v85
	v_cndmask_b32_e64 v41, 0, v41, s[36:37]
	v_add_u32_e32 v86, 25, v84
	v_cmp_gt_u32_e64 s[36:37], s98, v86
	v_cndmask_b32_e64 v42, 0, v42, s[78:79]
	v_add_u32_e32 v87, 26, v84
	v_cmp_gt_u32_e64 s[78:79], s98, v87
	v_cndmask_b32_e64 v43, 0, v43, s[50:51]
	v_add_u32_e32 v88, 27, v84
	v_cmp_gt_u32_e64 s[50:51], s98, v88
	v_nop
	v_cndmask_b32_e64 v44, 0, v44, s[30:31]
	v_cndmask_b32_e64 v45, 0, v45, s[36:37]
	v_cndmask_b32_e64 v46, 0, v46, s[78:79]
	v_cndmask_b32_e64 v47, 0, v47, s[50:51]
	v_cvt_pk_bf16_f32 v64, v32, v33
	v_cvt_pk_bf16_f32 v65, v34, v35
	v_cvt_pk_bf16_f32 v66, v36, v37
	v_cvt_pk_bf16_f32 v67, v38, v39
	v_cvt_pk_bf16_f32 v68, v40, v41
	v_cvt_pk_bf16_f32 v69, v42, v43
	v_cvt_pk_bf16_f32 v70, v44, v45
	v_cvt_pk_bf16_f32 v71, v46, v47
	v_pk_add_f32 v[232:233], v[232:233], v[32:33]
	v_pk_add_f32 v[232:233], v[232:233], v[34:35]
	v_pk_add_f32 v[232:233], v[232:233], v[36:37]
	v_pk_add_f32 v[232:233], v[232:233], v[38:39]
	v_pk_add_f32 v[232:233], v[232:233], v[40:41]
	v_pk_add_f32 v[232:233], v[232:233], v[42:43]
	v_pk_add_f32 v[232:233], v[232:233], v[44:45]
	v_pk_add_f32 v[232:233], v[232:233], v[46:47]
	s_waitcnt lgkmcnt(0)
	v_mfma_f32_32x32x16_bf16 v[0:15], v[64:67], v[72:75], v[0:15]
	v_mfma_f32_32x32x16_bf16 v[16:31], v[64:67], v[76:79], v[16:31]
	v_mfma_f32_32x32x16_bf16 v[0:15], v[68:71], v[220:223], v[0:15]
	v_mfma_f32_32x32x16_bf16 v[16:31], v[68:71], v[224:227], v[16:31]
	s_add_i32 s90, s76, 160
	v_add_u32_e32 v80, s90, v235
	v_add_u32_e32 v83, s90, v236
	v_add_u32_e32 v99, s90, v237
	v_add_u32_e32 v253, s90, v238
	v_add_u32_e32 v254, s90, v100
	v_add_u32_e32 v255, s90, v149
	v_med3_i32 v80, v80, 0, s99
	v_med3_i32 v83, v83, 0, s99
	v_med3_i32 v99, v99, 0, s99
	v_med3_i32 v253, v253, 0, s99
	v_med3_i32 v254, v254, 0, s99
	v_med3_i32 v255, v255, 0, s99
	v_mad_u32_u24 v80, v80, s100, v252
	v_mad_u32_u24 v83, v83, s100, v252
	v_mad_u32_u24 v99, v99, s100, v252
	v_mad_u32_u24 v253, v253, s100, v252
	v_mad_u32_u24 v254, v254, s100, v153
	v_mad_u32_u24 v255, v255, s100, v153
	global_load_dwordx4 v[156:159], v80, s[82:83]
	global_load_dwordx4 v[160:163], v83, s[82:83]
	global_load_dwordx4 v[164:167], v99, s[82:83]
	global_load_dwordx4 v[168:171], v253, s[82:83]
	global_load_dwordx4 v[172:175], v254, s[82:83] offset:768
	global_load_dwordx4 v[176:179], v255, s[82:83] offset:768
	global_load_dwordx4 v[180:183], v254, s[82:83] offset:832
	global_load_dwordx4 v[184:187], v255, s[82:83] offset:832
	s_waitcnt vmcnt(16)
	ds_write_b128 v247, v[188:191]
	ds_write_b128 v247, v[192:195] offset:1024
	ds_write_b128 v247, v[196:199] offset:2048
	ds_write_b128 v247, v[200:203] offset:3072
	ds_read_b128 v[188:191], v248
	ds_read_b128 v[192:195], v249
	ds_read_b128 v[196:199], v250
	ds_read_b128 v[200:203], v251
	ds_write_b128 v112, v[204:207]
	ds_write_b128 v112, v[208:211] offset:1024
	ds_write_b128 v112, v[212:215] offset:2048
	ds_write_b128 v112, v[216:219] offset:3072
	ds_read2_b32 v[32:33], v115 offset0:170 offset1:171
	ds_read2_b32 v[34:35], v115 offset0:172 offset1:173
	ds_read2_b32 v[36:37], v115 offset0:178 offset1:179
	ds_read2_b32 v[38:39], v115 offset0:180 offset1:181
	ds_read2_b32 v[40:41], v115 offset0:187 offset1:188
	ds_read2_b32 v[42:43], v115 offset0:189 offset1:190
	ds_read2_b32 v[44:45], v115 offset0:195 offset1:196
	ds_read2_b32 v[46:47], v115 offset0:197 offset1:198
	s_waitcnt lgkmcnt(0)
	v_mfma_f32_32x32x16_bf16 v[32:47], v[188:191], v[48:51], v[32:47]
	ds_read_b64_tr_b16 v[72:73], v231
	ds_read_b64_tr_b16 v[74:75], v231 offset:512
	ds_read_b64_tr_b16 v[76:77], v231 offset:2048
	ds_read_b64_tr_b16 v[78:79], v231 offset:2560
	ds_read_b64_tr_b16 v[220:221], v231 offset:1024
	ds_read_b64_tr_b16 v[222:223], v231 offset:1536
	ds_read_b64_tr_b16 v[224:225], v231 offset:3072
	ds_read_b64_tr_b16 v[226:227], v231 offset:3584
	v_mfma_f32_32x32x16_bf16 v[32:47], v[192:195], v[52:55], v[32:47]
	v_mfma_f32_32x32x16_bf16 v[32:47], v[196:199], v[56:59], v[32:47]
	v_mfma_f32_32x32x16_bf16 v[32:47], v[200:203], v[60:63], v[32:47]
	s_nop 11
	v_exp_f32_e32 v32, v32
	v_exp_f32_e32 v33, v33
	v_exp_f32_e32 v34, v34
	v_exp_f32_e32 v35, v35
	v_exp_f32_e32 v36, v36
	v_exp_f32_e32 v37, v37
	v_exp_f32_e32 v38, v38
	v_exp_f32_e32 v39, v39
	v_exp_f32_e32 v40, v40
	v_exp_f32_e32 v41, v41
	v_exp_f32_e32 v42, v42
	v_exp_f32_e32 v43, v43
	v_exp_f32_e32 v44, v44
	v_exp_f32_e32 v45, v45
	v_exp_f32_e32 v46, v46
	v_exp_f32_e32 v47, v47
	s_add_i32 s90, s76, 96
	v_add_u32_e32 v84, s90, v107
	v_add_u32_e32 v85, 0, v84
	v_add_u32_e32 v86, 1, v84
	v_add_u32_e32 v87, 2, v84
	v_add_u32_e32 v88, 3, v84
	v_cmp_gt_u32_e64 s[30:31], s98, v85
	v_cmp_gt_u32_e64 s[36:37], s98, v86
	v_cmp_gt_u32_e64 s[78:79], s98, v87
	v_cmp_gt_u32_e64 s[50:51], s98, v88
	v_cndmask_b32_e64 v32, 0, v32, s[30:31]
	v_add_u32_e32 v85, 8, v84
	v_cmp_gt_u32_e64 s[30:31], s98, v85
	v_cndmask_b32_e64 v33, 0, v33, s[36:37]
	v_add_u32_e32 v86, 9, v84
	v_cmp_gt_u32_e64 s[36:37], s98, v86
	v_cndmask_b32_e64 v34, 0, v34, s[78:79]
	v_add_u32_e32 v87, 10, v84
	v_cmp_gt_u32_e64 s[78:79], s98, v87
	v_cndmask_b32_e64 v35, 0, v35, s[50:51]
	v_add_u32_e32 v88, 11, v84
	v_cmp_gt_u32_e64 s[50:51], s98, v88
	v_cndmask_b32_e64 v36, 0, v36, s[30:31]
	v_add_u32_e32 v85, 16, v84
	v_cmp_gt_u32_e64 s[30:31], s98, v85
	v_cndmask_b32_e64 v37, 0, v37, s[36:37]
	v_add_u32_e32 v86, 17, v84
	v_cmp_gt_u32_e64 s[36:37], s98, v86
	v_cndmask_b32_e64 v38, 0, v38, s[78:79]
	v_add_u32_e32 v87, 18, v84
	v_cmp_gt_u32_e64 s[78:79], s98, v87
	v_cndmask_b32_e64 v39, 0, v39, s[50:51]
	v_add_u32_e32 v88, 19, v84
	v_cmp_gt_u32_e64 s[50:51], s98, v88
	v_cndmask_b32_e64 v40, 0, v40, s[30:31]
	v_add_u32_e32 v85, 24, v84
	v_cmp_gt_u32_e64 s[30:31], s98, v85
	v_cndmask_b32_e64 v41, 0, v41, s[36:37]
	v_add_u32_e32 v86, 25, v84
	v_cmp_gt_u32_e64 s[36:37], s98, v86
	v_cndmask_b32_e64 v42, 0, v42, s[78:79]
	v_add_u32_e32 v87, 26, v84
	v_cmp_gt_u32_e64 s[78:79], s98, v87
	v_cndmask_b32_e64 v43, 0, v43, s[50:51]
	v_add_u32_e32 v88, 27, v84
	v_cmp_gt_u32_e64 s[50:51], s98, v88
	v_nop
	v_cndmask_b32_e64 v44, 0, v44, s[30:31]
	v_cndmask_b32_e64 v45, 0, v45, s[36:37]
	v_cndmask_b32_e64 v46, 0, v46, s[78:79]
	v_cndmask_b32_e64 v47, 0, v47, s[50:51]
	v_cvt_pk_bf16_f32 v64, v32, v33
	v_cvt_pk_bf16_f32 v65, v34, v35
	v_cvt_pk_bf16_f32 v66, v36, v37
	v_cvt_pk_bf16_f32 v67, v38, v39
	v_cvt_pk_bf16_f32 v68, v40, v41
	v_cvt_pk_bf16_f32 v69, v42, v43
	v_cvt_pk_bf16_f32 v70, v44, v45
	v_cvt_pk_bf16_f32 v71, v46, v47
	v_pk_add_f32 v[232:233], v[232:233], v[32:33]
	v_pk_add_f32 v[232:233], v[232:233], v[34:35]
	v_pk_add_f32 v[232:233], v[232:233], v[36:37]
	v_pk_add_f32 v[232:233], v[232:233], v[38:39]
	v_pk_add_f32 v[232:233], v[232:233], v[40:41]
	v_pk_add_f32 v[232:233], v[232:233], v[42:43]
	v_pk_add_f32 v[232:233], v[232:233], v[44:45]
	v_pk_add_f32 v[232:233], v[232:233], v[46:47]
	s_waitcnt lgkmcnt(0)
	v_mfma_f32_32x32x16_bf16 v[0:15], v[64:67], v[72:75], v[0:15]
	v_mfma_f32_32x32x16_bf16 v[16:31], v[64:67], v[76:79], v[16:31]
	v_mfma_f32_32x32x16_bf16 v[0:15], v[68:71], v[220:223], v[0:15]
	v_mfma_f32_32x32x16_bf16 v[16:31], v[68:71], v[224:227], v[16:31]
	s_add_i32 s90, s76, 192
	v_add_u32_e32 v80, s90, v235
	v_add_u32_e32 v83, s90, v236
	v_add_u32_e32 v99, s90, v237
	v_add_u32_e32 v253, s90, v238
	v_add_u32_e32 v254, s90, v100
	v_add_u32_e32 v255, s90, v149
	v_med3_i32 v80, v80, 0, s99
	v_med3_i32 v83, v83, 0, s99
	v_med3_i32 v99, v99, 0, s99
	v_med3_i32 v253, v253, 0, s99
	v_med3_i32 v254, v254, 0, s99
	v_med3_i32 v255, v255, 0, s99
	v_mad_u32_u24 v80, v80, s100, v252
	v_mad_u32_u24 v83, v83, s100, v252
	v_mad_u32_u24 v99, v99, s100, v252
	v_mad_u32_u24 v253, v253, s100, v252
	v_mad_u32_u24 v254, v254, s100, v153
	v_mad_u32_u24 v255, v255, s100, v153
	global_load_dwordx4 v[188:191], v80, s[82:83]
	global_load_dwordx4 v[192:195], v83, s[82:83]
	global_load_dwordx4 v[196:199], v99, s[82:83]
	global_load_dwordx4 v[200:203], v253, s[82:83]
	global_load_dwordx4 v[204:207], v254, s[82:83] offset:768
	global_load_dwordx4 v[208:211], v255, s[82:83] offset:768
	global_load_dwordx4 v[212:215], v254, s[82:83] offset:832
	global_load_dwordx4 v[216:219], v255, s[82:83] offset:832
	s_waitcnt vmcnt(16)
	ds_write_b128 v247, v[116:119]
	ds_write_b128 v247, v[120:123] offset:1024
	ds_write_b128 v247, v[124:127] offset:2048
	ds_write_b128 v247, v[128:131] offset:3072
	ds_read_b128 v[116:119], v248
	ds_read_b128 v[120:123], v249
	ds_read_b128 v[124:127], v250
	ds_read_b128 v[128:131], v251
	ds_write_b128 v112, v[132:135]
	ds_write_b128 v112, v[136:139] offset:1024
	ds_write_b128 v112, v[140:143] offset:2048
	ds_write_b128 v112, v[144:147] offset:3072
	ds_read2_b32 v[32:33], v115 offset0:204 offset1:205
	ds_read2_b32 v[34:35], v115 offset0:206 offset1:207
	ds_read2_b32 v[36:37], v115 offset0:212 offset1:213
	ds_read2_b32 v[38:39], v115 offset0:214 offset1:215
	ds_read2_b32 v[40:41], v115 offset0:221 offset1:222
	ds_read2_b32 v[42:43], v115 offset0:223 offset1:224
	ds_read2_b32 v[44:45], v115 offset0:229 offset1:230
	ds_read2_b32 v[46:47], v115 offset0:231 offset1:232
	s_waitcnt lgkmcnt(0)
	v_mfma_f32_32x32x16_bf16 v[32:47], v[116:119], v[48:51], v[32:47]
	ds_read_b64_tr_b16 v[72:73], v231
	ds_read_b64_tr_b16 v[74:75], v231 offset:512
	ds_read_b64_tr_b16 v[76:77], v231 offset:2048
	ds_read_b64_tr_b16 v[78:79], v231 offset:2560
	ds_read_b64_tr_b16 v[220:221], v231 offset:1024
	ds_read_b64_tr_b16 v[222:223], v231 offset:1536
	ds_read_b64_tr_b16 v[224:225], v231 offset:3072
	ds_read_b64_tr_b16 v[226:227], v231 offset:3584
	v_mfma_f32_32x32x16_bf16 v[32:47], v[120:123], v[52:55], v[32:47]
	v_mfma_f32_32x32x16_bf16 v[32:47], v[124:127], v[56:59], v[32:47]
	v_mfma_f32_32x32x16_bf16 v[32:47], v[128:131], v[60:63], v[32:47]
	s_nop 11
	v_exp_f32_e32 v32, v32
	v_exp_f32_e32 v33, v33
	v_exp_f32_e32 v34, v34
	v_exp_f32_e32 v35, v35
	v_exp_f32_e32 v36, v36
	v_exp_f32_e32 v37, v37
	v_exp_f32_e32 v38, v38
	v_exp_f32_e32 v39, v39
	v_exp_f32_e32 v40, v40
	v_exp_f32_e32 v41, v41
	v_exp_f32_e32 v42, v42
	v_exp_f32_e32 v43, v43
	v_exp_f32_e32 v44, v44
	v_exp_f32_e32 v45, v45
	v_exp_f32_e32 v46, v46
	v_exp_f32_e32 v47, v47
	s_add_i32 s90, s76, 128
	v_add_u32_e32 v84, s90, v107
	v_add_u32_e32 v85, 0, v84
	v_add_u32_e32 v86, 1, v84
	v_add_u32_e32 v87, 2, v84
	v_add_u32_e32 v88, 3, v84
	v_cmp_gt_u32_e64 s[30:31], s98, v85
	v_cmp_gt_u32_e64 s[36:37], s98, v86
	v_cmp_gt_u32_e64 s[78:79], s98, v87
	v_cmp_gt_u32_e64 s[50:51], s98, v88
	v_cndmask_b32_e64 v32, 0, v32, s[30:31]
	v_add_u32_e32 v85, 8, v84
	v_cmp_gt_u32_e64 s[30:31], s98, v85
	v_cndmask_b32_e64 v33, 0, v33, s[36:37]
	v_add_u32_e32 v86, 9, v84
	v_cmp_gt_u32_e64 s[36:37], s98, v86
	v_cndmask_b32_e64 v34, 0, v34, s[78:79]
	v_add_u32_e32 v87, 10, v84
	v_cmp_gt_u32_e64 s[78:79], s98, v87
	v_cndmask_b32_e64 v35, 0, v35, s[50:51]
	v_add_u32_e32 v88, 11, v84
	v_cmp_gt_u32_e64 s[50:51], s98, v88
	v_cndmask_b32_e64 v36, 0, v36, s[30:31]
	v_add_u32_e32 v85, 16, v84
	v_cmp_gt_u32_e64 s[30:31], s98, v85
	v_cndmask_b32_e64 v37, 0, v37, s[36:37]
	v_add_u32_e32 v86, 17, v84
	v_cmp_gt_u32_e64 s[36:37], s98, v86
	v_cndmask_b32_e64 v38, 0, v38, s[78:79]
	v_add_u32_e32 v87, 18, v84
	v_cmp_gt_u32_e64 s[78:79], s98, v87
	v_cndmask_b32_e64 v39, 0, v39, s[50:51]
	v_add_u32_e32 v88, 19, v84
	v_cmp_gt_u32_e64 s[50:51], s98, v88
	v_cndmask_b32_e64 v40, 0, v40, s[30:31]
	v_add_u32_e32 v85, 24, v84
	v_cmp_gt_u32_e64 s[30:31], s98, v85
	v_cndmask_b32_e64 v41, 0, v41, s[36:37]
	v_add_u32_e32 v86, 25, v84
	v_cmp_gt_u32_e64 s[36:37], s98, v86
	v_cndmask_b32_e64 v42, 0, v42, s[78:79]
	v_add_u32_e32 v87, 26, v84
	v_cmp_gt_u32_e64 s[78:79], s98, v87
	v_cndmask_b32_e64 v43, 0, v43, s[50:51]
	v_add_u32_e32 v88, 27, v84
	v_cmp_gt_u32_e64 s[50:51], s98, v88
	v_nop
	v_cndmask_b32_e64 v44, 0, v44, s[30:31]
	v_cndmask_b32_e64 v45, 0, v45, s[36:37]
	v_cndmask_b32_e64 v46, 0, v46, s[78:79]
	v_cndmask_b32_e64 v47, 0, v47, s[50:51]
	v_cvt_pk_bf16_f32 v64, v32, v33
	v_cvt_pk_bf16_f32 v65, v34, v35
	v_cvt_pk_bf16_f32 v66, v36, v37
	v_cvt_pk_bf16_f32 v67, v38, v39
	v_cvt_pk_bf16_f32 v68, v40, v41
	v_cvt_pk_bf16_f32 v69, v42, v43
	v_cvt_pk_bf16_f32 v70, v44, v45
	v_cvt_pk_bf16_f32 v71, v46, v47
	v_pk_add_f32 v[232:233], v[232:233], v[32:33]
	v_pk_add_f32 v[232:233], v[232:233], v[34:35]
	v_pk_add_f32 v[232:233], v[232:233], v[36:37]
	v_pk_add_f32 v[232:233], v[232:233], v[38:39]
	v_pk_add_f32 v[232:233], v[232:233], v[40:41]
	v_pk_add_f32 v[232:233], v[232:233], v[42:43]
	v_pk_add_f32 v[232:233], v[232:233], v[44:45]
	v_pk_add_f32 v[232:233], v[232:233], v[46:47]
	s_waitcnt lgkmcnt(0)
	v_mfma_f32_32x32x16_bf16 v[0:15], v[64:67], v[72:75], v[0:15]
	v_mfma_f32_32x32x16_bf16 v[16:31], v[64:67], v[76:79], v[16:31]
	v_mfma_f32_32x32x16_bf16 v[0:15], v[68:71], v[220:223], v[0:15]
	v_mfma_f32_32x32x16_bf16 v[16:31], v[68:71], v[224:227], v[16:31]
	s_add_i32 s90, s76, 224
	v_add_u32_e32 v80, s90, v235
	v_add_u32_e32 v83, s90, v236
	v_add_u32_e32 v99, s90, v237
	v_add_u32_e32 v253, s90, v238
	v_add_u32_e32 v254, s90, v100
	v_add_u32_e32 v255, s90, v149
	v_med3_i32 v80, v80, 0, s99
	v_med3_i32 v83, v83, 0, s99
	v_med3_i32 v99, v99, 0, s99
	v_med3_i32 v253, v253, 0, s99
	v_med3_i32 v254, v254, 0, s99
	v_med3_i32 v255, v255, 0, s99
	v_mad_u32_u24 v80, v80, s100, v252
	v_mad_u32_u24 v83, v83, s100, v252
	v_mad_u32_u24 v99, v99, s100, v252
	v_mad_u32_u24 v253, v253, s100, v252
	v_mad_u32_u24 v254, v254, s100, v153
	v_mad_u32_u24 v255, v255, s100, v153
	global_load_dwordx4 v[116:119], v80, s[82:83]
	global_load_dwordx4 v[120:123], v83, s[82:83]
	global_load_dwordx4 v[124:127], v99, s[82:83]
	global_load_dwordx4 v[128:131], v253, s[82:83]
	global_load_dwordx4 v[132:135], v254, s[82:83] offset:768
	global_load_dwordx4 v[136:139], v255, s[82:83] offset:768
	global_load_dwordx4 v[140:143], v254, s[82:83] offset:832
	global_load_dwordx4 v[144:147], v255, s[82:83] offset:832
	s_waitcnt vmcnt(16)
	ds_write_b128 v247, v[156:159]
	ds_write_b128 v247, v[160:163] offset:1024
	ds_write_b128 v247, v[164:167] offset:2048
	ds_write_b128 v247, v[168:171] offset:3072
	ds_read_b128 v[156:159], v248
	ds_read_b128 v[160:163], v249
	ds_read_b128 v[164:167], v250
	ds_read_b128 v[168:171], v251
	ds_write_b128 v112, v[172:175]
	ds_write_b128 v112, v[176:179] offset:1024
	ds_write_b128 v112, v[180:183] offset:2048
	ds_write_b128 v112, v[184:187] offset:3072
	v_add_u32_e32 v115, 952, v115
	ds_read2_b32 v[32:33], v115 offset0:0 offset1:1
	ds_read2_b32 v[34:35], v115 offset0:2 offset1:3
	ds_read2_b32 v[36:37], v115 offset0:8 offset1:9
	ds_read2_b32 v[38:39], v115 offset0:10 offset1:11
	ds_read2_b32 v[40:41], v115 offset0:17 offset1:18
	ds_read2_b32 v[42:43], v115 offset0:19 offset1:20
	ds_read2_b32 v[44:45], v115 offset0:25 offset1:26
	ds_read2_b32 v[46:47], v115 offset0:27 offset1:28
	s_waitcnt lgkmcnt(0)
	v_mfma_f32_32x32x16_bf16 v[32:47], v[156:159], v[48:51], v[32:47]
	ds_read_b64_tr_b16 v[72:73], v231
	ds_read_b64_tr_b16 v[74:75], v231 offset:512
	ds_read_b64_tr_b16 v[76:77], v231 offset:2048
	ds_read_b64_tr_b16 v[78:79], v231 offset:2560
	ds_read_b64_tr_b16 v[220:221], v231 offset:1024
	ds_read_b64_tr_b16 v[222:223], v231 offset:1536
	ds_read_b64_tr_b16 v[224:225], v231 offset:3072
	ds_read_b64_tr_b16 v[226:227], v231 offset:3584
	v_mfma_f32_32x32x16_bf16 v[32:47], v[160:163], v[52:55], v[32:47]
	v_mfma_f32_32x32x16_bf16 v[32:47], v[164:167], v[56:59], v[32:47]
	v_mfma_f32_32x32x16_bf16 v[32:47], v[168:171], v[60:63], v[32:47]
	s_nop 11
	v_exp_f32_e32 v32, v32
	v_exp_f32_e32 v33, v33
	v_exp_f32_e32 v34, v34
	v_exp_f32_e32 v35, v35
	v_exp_f32_e32 v36, v36
	v_exp_f32_e32 v37, v37
	v_exp_f32_e32 v38, v38
	v_exp_f32_e32 v39, v39
	v_exp_f32_e32 v40, v40
	v_exp_f32_e32 v41, v41
	v_exp_f32_e32 v42, v42
	v_exp_f32_e32 v43, v43
	v_exp_f32_e32 v44, v44
	v_exp_f32_e32 v45, v45
	v_exp_f32_e32 v46, v46
	v_exp_f32_e32 v47, v47
	s_add_i32 s90, s76, 160
	v_add_u32_e32 v84, s90, v107
	v_add_u32_e32 v85, 0, v84
	v_add_u32_e32 v86, 1, v84
	v_add_u32_e32 v87, 2, v84
	v_add_u32_e32 v88, 3, v84
	v_cmp_gt_u32_e64 s[30:31], s98, v85
	v_cmp_gt_u32_e64 s[36:37], s98, v86
	v_cmp_gt_u32_e64 s[78:79], s98, v87
	v_cmp_gt_u32_e64 s[50:51], s98, v88
	v_cndmask_b32_e64 v32, 0, v32, s[30:31]
	v_add_u32_e32 v85, 8, v84
	v_cmp_gt_u32_e64 s[30:31], s98, v85
	v_cndmask_b32_e64 v33, 0, v33, s[36:37]
	v_add_u32_e32 v86, 9, v84
	v_cmp_gt_u32_e64 s[36:37], s98, v86
	v_cndmask_b32_e64 v34, 0, v34, s[78:79]
	v_add_u32_e32 v87, 10, v84
	v_cmp_gt_u32_e64 s[78:79], s98, v87
	v_cndmask_b32_e64 v35, 0, v35, s[50:51]
	v_add_u32_e32 v88, 11, v84
	v_cmp_gt_u32_e64 s[50:51], s98, v88
	v_cndmask_b32_e64 v36, 0, v36, s[30:31]
	v_add_u32_e32 v85, 16, v84
	v_cmp_gt_u32_e64 s[30:31], s98, v85
	v_cndmask_b32_e64 v37, 0, v37, s[36:37]
	v_add_u32_e32 v86, 17, v84
	v_cmp_gt_u32_e64 s[36:37], s98, v86
	v_cndmask_b32_e64 v38, 0, v38, s[78:79]
	v_add_u32_e32 v87, 18, v84
	v_cmp_gt_u32_e64 s[78:79], s98, v87
	v_cndmask_b32_e64 v39, 0, v39, s[50:51]
	v_add_u32_e32 v88, 19, v84
	v_cmp_gt_u32_e64 s[50:51], s98, v88
	v_cndmask_b32_e64 v40, 0, v40, s[30:31]
	v_add_u32_e32 v85, 24, v84
	v_cmp_gt_u32_e64 s[30:31], s98, v85
	v_cndmask_b32_e64 v41, 0, v41, s[36:37]
	v_add_u32_e32 v86, 25, v84
	v_cmp_gt_u32_e64 s[36:37], s98, v86
	v_cndmask_b32_e64 v42, 0, v42, s[78:79]
	v_add_u32_e32 v87, 26, v84
	v_cmp_gt_u32_e64 s[78:79], s98, v87
	v_cndmask_b32_e64 v43, 0, v43, s[50:51]
	v_add_u32_e32 v88, 27, v84
	v_cmp_gt_u32_e64 s[50:51], s98, v88
	v_nop
	v_cndmask_b32_e64 v44, 0, v44, s[30:31]
	v_cndmask_b32_e64 v45, 0, v45, s[36:37]
	v_cndmask_b32_e64 v46, 0, v46, s[78:79]
	v_cndmask_b32_e64 v47, 0, v47, s[50:51]
	v_cvt_pk_bf16_f32 v64, v32, v33
	v_cvt_pk_bf16_f32 v65, v34, v35
	v_cvt_pk_bf16_f32 v66, v36, v37
	v_cvt_pk_bf16_f32 v67, v38, v39
	v_cvt_pk_bf16_f32 v68, v40, v41
	v_cvt_pk_bf16_f32 v69, v42, v43
	v_cvt_pk_bf16_f32 v70, v44, v45
	v_cvt_pk_bf16_f32 v71, v46, v47
	v_pk_add_f32 v[232:233], v[232:233], v[32:33]
	v_pk_add_f32 v[232:233], v[232:233], v[34:35]
	v_pk_add_f32 v[232:233], v[232:233], v[36:37]
	v_pk_add_f32 v[232:233], v[232:233], v[38:39]
	v_pk_add_f32 v[232:233], v[232:233], v[40:41]
	v_pk_add_f32 v[232:233], v[232:233], v[42:43]
	v_pk_add_f32 v[232:233], v[232:233], v[44:45]
	v_pk_add_f32 v[232:233], v[232:233], v[46:47]
	s_waitcnt lgkmcnt(0)
	v_mfma_f32_32x32x16_bf16 v[0:15], v[64:67], v[72:75], v[0:15]
	v_mfma_f32_32x32x16_bf16 v[16:31], v[64:67], v[76:79], v[16:31]
	v_mfma_f32_32x32x16_bf16 v[0:15], v[68:71], v[220:223], v[0:15]
	v_mfma_f32_32x32x16_bf16 v[16:31], v[68:71], v[224:227], v[16:31]
	s_add_i32 s90, s76, 256
	v_add_u32_e32 v80, s90, v235
	v_add_u32_e32 v83, s90, v236
	v_add_u32_e32 v99, s90, v237
	v_add_u32_e32 v253, s90, v238
	v_add_u32_e32 v254, s90, v100
	v_add_u32_e32 v255, s90, v149
	v_med3_i32 v80, v80, 0, s99
	v_med3_i32 v83, v83, 0, s99
	v_med3_i32 v99, v99, 0, s99
	v_med3_i32 v253, v253, 0, s99
	v_med3_i32 v254, v254, 0, s99
	v_med3_i32 v255, v255, 0, s99
	v_mad_u32_u24 v80, v80, s100, v252
	v_mad_u32_u24 v83, v83, s100, v252
	v_mad_u32_u24 v99, v99, s100, v252
	v_mad_u32_u24 v253, v253, s100, v252
	v_mad_u32_u24 v254, v254, s100, v153
	v_mad_u32_u24 v255, v255, s100, v153
	global_load_dwordx4 v[156:159], v80, s[82:83]
	global_load_dwordx4 v[160:163], v83, s[82:83]
	global_load_dwordx4 v[164:167], v99, s[82:83]
	global_load_dwordx4 v[168:171], v253, s[82:83]
	global_load_dwordx4 v[172:175], v254, s[82:83] offset:768
	global_load_dwordx4 v[176:179], v255, s[82:83] offset:768
	global_load_dwordx4 v[180:183], v254, s[82:83] offset:832
	global_load_dwordx4 v[184:187], v255, s[82:83] offset:832
	s_waitcnt vmcnt(16)
	ds_write_b128 v247, v[188:191]
	ds_write_b128 v247, v[192:195] offset:1024
	ds_write_b128 v247, v[196:199] offset:2048
	ds_write_b128 v247, v[200:203] offset:3072
	ds_read_b128 v[188:191], v248
	ds_read_b128 v[192:195], v249
	ds_read_b128 v[196:199], v250
	ds_read_b128 v[200:203], v251
	ds_write_b128 v112, v[204:207]
	ds_write_b128 v112, v[208:211] offset:1024
	ds_write_b128 v112, v[212:215] offset:2048
	ds_write_b128 v112, v[216:219] offset:3072
	ds_read2_b32 v[32:33], v115 offset0:34 offset1:35
	ds_read2_b32 v[34:35], v115 offset0:36 offset1:37
	ds_read2_b32 v[36:37], v115 offset0:42 offset1:43
	ds_read2_b32 v[38:39], v115 offset0:44 offset1:45
	ds_read2_b32 v[40:41], v115 offset0:51 offset1:52
	ds_read2_b32 v[42:43], v115 offset0:53 offset1:54
	ds_read2_b32 v[44:45], v115 offset0:59 offset1:60
	ds_read2_b32 v[46:47], v115 offset0:61 offset1:62
	s_waitcnt lgkmcnt(0)
	v_mfma_f32_32x32x16_bf16 v[32:47], v[188:191], v[48:51], v[32:47]
	ds_read_b64_tr_b16 v[72:73], v231
	ds_read_b64_tr_b16 v[74:75], v231 offset:512
	ds_read_b64_tr_b16 v[76:77], v231 offset:2048
	ds_read_b64_tr_b16 v[78:79], v231 offset:2560
	ds_read_b64_tr_b16 v[220:221], v231 offset:1024
	ds_read_b64_tr_b16 v[222:223], v231 offset:1536
	ds_read_b64_tr_b16 v[224:225], v231 offset:3072
	ds_read_b64_tr_b16 v[226:227], v231 offset:3584
	v_mfma_f32_32x32x16_bf16 v[32:47], v[192:195], v[52:55], v[32:47]
	v_mfma_f32_32x32x16_bf16 v[32:47], v[196:199], v[56:59], v[32:47]
	v_mfma_f32_32x32x16_bf16 v[32:47], v[200:203], v[60:63], v[32:47]
	s_nop 11
	v_exp_f32_e32 v32, v32
	v_exp_f32_e32 v33, v33
	v_exp_f32_e32 v34, v34
	v_exp_f32_e32 v35, v35
	v_exp_f32_e32 v36, v36
	v_exp_f32_e32 v37, v37
	v_exp_f32_e32 v38, v38
	v_exp_f32_e32 v39, v39
	v_exp_f32_e32 v40, v40
	v_exp_f32_e32 v41, v41
	v_exp_f32_e32 v42, v42
	v_exp_f32_e32 v43, v43
	v_exp_f32_e32 v44, v44
	v_exp_f32_e32 v45, v45
	v_exp_f32_e32 v46, v46
	v_exp_f32_e32 v47, v47
	s_add_i32 s90, s76, 192
	v_add_u32_e32 v84, s90, v107
	v_add_u32_e32 v85, 0, v84
	v_add_u32_e32 v86, 1, v84
	v_add_u32_e32 v87, 2, v84
	v_add_u32_e32 v88, 3, v84
	v_cmp_gt_u32_e64 s[30:31], s98, v85
	v_cmp_gt_u32_e64 s[36:37], s98, v86
	v_cmp_gt_u32_e64 s[78:79], s98, v87
	v_cmp_gt_u32_e64 s[50:51], s98, v88
	v_cndmask_b32_e64 v32, 0, v32, s[30:31]
	v_add_u32_e32 v85, 8, v84
	v_cmp_gt_u32_e64 s[30:31], s98, v85
	v_cndmask_b32_e64 v33, 0, v33, s[36:37]
	v_add_u32_e32 v86, 9, v84
	v_cmp_gt_u32_e64 s[36:37], s98, v86
	v_cndmask_b32_e64 v34, 0, v34, s[78:79]
	v_add_u32_e32 v87, 10, v84
	v_cmp_gt_u32_e64 s[78:79], s98, v87
	v_cndmask_b32_e64 v35, 0, v35, s[50:51]
	v_add_u32_e32 v88, 11, v84
	v_cmp_gt_u32_e64 s[50:51], s98, v88
	v_cndmask_b32_e64 v36, 0, v36, s[30:31]
	v_add_u32_e32 v85, 16, v84
	v_cmp_gt_u32_e64 s[30:31], s98, v85
	v_cndmask_b32_e64 v37, 0, v37, s[36:37]
	v_add_u32_e32 v86, 17, v84
	v_cmp_gt_u32_e64 s[36:37], s98, v86
	v_cndmask_b32_e64 v38, 0, v38, s[78:79]
	v_add_u32_e32 v87, 18, v84
	v_cmp_gt_u32_e64 s[78:79], s98, v87
	v_cndmask_b32_e64 v39, 0, v39, s[50:51]
	v_add_u32_e32 v88, 19, v84
	v_cmp_gt_u32_e64 s[50:51], s98, v88
	v_cndmask_b32_e64 v40, 0, v40, s[30:31]
	v_add_u32_e32 v85, 24, v84
	v_cmp_gt_u32_e64 s[30:31], s98, v85
	v_cndmask_b32_e64 v41, 0, v41, s[36:37]
	v_add_u32_e32 v86, 25, v84
	v_cmp_gt_u32_e64 s[36:37], s98, v86
	v_cndmask_b32_e64 v42, 0, v42, s[78:79]
	v_add_u32_e32 v87, 26, v84
	v_cmp_gt_u32_e64 s[78:79], s98, v87
	v_cndmask_b32_e64 v43, 0, v43, s[50:51]
	v_add_u32_e32 v88, 27, v84
	v_cmp_gt_u32_e64 s[50:51], s98, v88
	v_nop
	v_cndmask_b32_e64 v44, 0, v44, s[30:31]
	v_cndmask_b32_e64 v45, 0, v45, s[36:37]
	v_cndmask_b32_e64 v46, 0, v46, s[78:79]
	v_cndmask_b32_e64 v47, 0, v47, s[50:51]
	v_cvt_pk_bf16_f32 v64, v32, v33
	v_cvt_pk_bf16_f32 v65, v34, v35
	v_cvt_pk_bf16_f32 v66, v36, v37
	v_cvt_pk_bf16_f32 v67, v38, v39
	v_cvt_pk_bf16_f32 v68, v40, v41
	v_cvt_pk_bf16_f32 v69, v42, v43
	v_cvt_pk_bf16_f32 v70, v44, v45
	v_cvt_pk_bf16_f32 v71, v46, v47
	v_pk_add_f32 v[232:233], v[232:233], v[32:33]
	v_pk_add_f32 v[232:233], v[232:233], v[34:35]
	v_pk_add_f32 v[232:233], v[232:233], v[36:37]
	v_pk_add_f32 v[232:233], v[232:233], v[38:39]
	v_pk_add_f32 v[232:233], v[232:233], v[40:41]
	v_pk_add_f32 v[232:233], v[232:233], v[42:43]
	v_pk_add_f32 v[232:233], v[232:233], v[44:45]
	v_pk_add_f32 v[232:233], v[232:233], v[46:47]
	s_waitcnt lgkmcnt(0)
	v_mfma_f32_32x32x16_bf16 v[0:15], v[64:67], v[72:75], v[0:15]
	v_mfma_f32_32x32x16_bf16 v[16:31], v[64:67], v[76:79], v[16:31]
	v_mfma_f32_32x32x16_bf16 v[0:15], v[68:71], v[220:223], v[0:15]
	v_mfma_f32_32x32x16_bf16 v[16:31], v[68:71], v[224:227], v[16:31]
	s_add_i32 s90, s76, 288
	v_add_u32_e32 v80, s90, v235
	v_add_u32_e32 v83, s90, v236
	v_add_u32_e32 v99, s90, v237
	v_add_u32_e32 v253, s90, v238
	v_add_u32_e32 v254, s90, v100
	v_add_u32_e32 v255, s90, v149
	v_med3_i32 v80, v80, 0, s99
	v_med3_i32 v83, v83, 0, s99
	v_med3_i32 v99, v99, 0, s99
	v_med3_i32 v253, v253, 0, s99
	v_med3_i32 v254, v254, 0, s99
	v_med3_i32 v255, v255, 0, s99
	v_mad_u32_u24 v80, v80, s100, v252
	v_mad_u32_u24 v83, v83, s100, v252
	v_mad_u32_u24 v99, v99, s100, v252
	v_mad_u32_u24 v253, v253, s100, v252
	v_mad_u32_u24 v254, v254, s100, v153
	v_mad_u32_u24 v255, v255, s100, v153
	global_load_dwordx4 v[188:191], v80, s[82:83]
	global_load_dwordx4 v[192:195], v83, s[82:83]
	global_load_dwordx4 v[196:199], v99, s[82:83]
	global_load_dwordx4 v[200:203], v253, s[82:83]
	global_load_dwordx4 v[204:207], v254, s[82:83] offset:768
	global_load_dwordx4 v[208:211], v255, s[82:83] offset:768
	global_load_dwordx4 v[212:215], v254, s[82:83] offset:832
	global_load_dwordx4 v[216:219], v255, s[82:83] offset:832
	s_waitcnt vmcnt(16)
	ds_write_b128 v247, v[116:119]
	ds_write_b128 v247, v[120:123] offset:1024
	ds_write_b128 v247, v[124:127] offset:2048
	ds_write_b128 v247, v[128:131] offset:3072
	ds_read_b128 v[116:119], v248
	ds_read_b128 v[120:123], v249
	ds_read_b128 v[124:127], v250
	ds_read_b128 v[128:131], v251
	ds_write_b128 v112, v[132:135]
	ds_write_b128 v112, v[136:139] offset:1024
	ds_write_b128 v112, v[140:143] offset:2048
	ds_write_b128 v112, v[144:147] offset:3072
	ds_read2_b32 v[32:33], v115 offset0:68 offset1:69
	ds_read2_b32 v[34:35], v115 offset0:70 offset1:71
	ds_read2_b32 v[36:37], v115 offset0:76 offset1:77
	ds_read2_b32 v[38:39], v115 offset0:78 offset1:79
	ds_read2_b32 v[40:41], v115 offset0:85 offset1:86
	ds_read2_b32 v[42:43], v115 offset0:87 offset1:88
	ds_read2_b32 v[44:45], v115 offset0:93 offset1:94
	ds_read2_b32 v[46:47], v115 offset0:95 offset1:96
	s_waitcnt lgkmcnt(0)
	v_mfma_f32_32x32x16_bf16 v[32:47], v[116:119], v[48:51], v[32:47]
	ds_read_b64_tr_b16 v[72:73], v231
	ds_read_b64_tr_b16 v[74:75], v231 offset:512
	ds_read_b64_tr_b16 v[76:77], v231 offset:2048
	ds_read_b64_tr_b16 v[78:79], v231 offset:2560
	ds_read_b64_tr_b16 v[220:221], v231 offset:1024
	ds_read_b64_tr_b16 v[222:223], v231 offset:1536
	ds_read_b64_tr_b16 v[224:225], v231 offset:3072
	ds_read_b64_tr_b16 v[226:227], v231 offset:3584
	v_mfma_f32_32x32x16_bf16 v[32:47], v[120:123], v[52:55], v[32:47]
	v_mfma_f32_32x32x16_bf16 v[32:47], v[124:127], v[56:59], v[32:47]
	v_mfma_f32_32x32x16_bf16 v[32:47], v[128:131], v[60:63], v[32:47]
	s_nop 11
	v_exp_f32_e32 v32, v32
	v_exp_f32_e32 v33, v33
	v_exp_f32_e32 v34, v34
	v_exp_f32_e32 v35, v35
	v_exp_f32_e32 v36, v36
	v_exp_f32_e32 v37, v37
	v_exp_f32_e32 v38, v38
	v_exp_f32_e32 v39, v39
	v_exp_f32_e32 v40, v40
	v_exp_f32_e32 v41, v41
	v_exp_f32_e32 v42, v42
	v_exp_f32_e32 v43, v43
	v_exp_f32_e32 v44, v44
	v_exp_f32_e32 v45, v45
	v_exp_f32_e32 v46, v46
	v_exp_f32_e32 v47, v47
	s_add_i32 s90, s76, 224
	v_add_u32_e32 v84, s90, v107
	v_add_u32_e32 v85, 0, v84
	v_add_u32_e32 v86, 1, v84
	v_add_u32_e32 v87, 2, v84
	v_add_u32_e32 v88, 3, v84
	v_cmp_gt_u32_e64 s[30:31], s98, v85
	v_cmp_gt_u32_e64 s[36:37], s98, v86
	v_cmp_gt_u32_e64 s[78:79], s98, v87
	v_cmp_gt_u32_e64 s[50:51], s98, v88
	v_cndmask_b32_e64 v32, 0, v32, s[30:31]
	v_add_u32_e32 v85, 8, v84
	v_cmp_gt_u32_e64 s[30:31], s98, v85
	v_cndmask_b32_e64 v33, 0, v33, s[36:37]
	v_add_u32_e32 v86, 9, v84
	v_cmp_gt_u32_e64 s[36:37], s98, v86
	v_cndmask_b32_e64 v34, 0, v34, s[78:79]
	v_add_u32_e32 v87, 10, v84
	v_cmp_gt_u32_e64 s[78:79], s98, v87
	v_cndmask_b32_e64 v35, 0, v35, s[50:51]
	v_add_u32_e32 v88, 11, v84
	v_cmp_gt_u32_e64 s[50:51], s98, v88
	v_cndmask_b32_e64 v36, 0, v36, s[30:31]
	v_add_u32_e32 v85, 16, v84
	v_cmp_gt_u32_e64 s[30:31], s98, v85
	v_cndmask_b32_e64 v37, 0, v37, s[36:37]
	v_add_u32_e32 v86, 17, v84
	v_cmp_gt_u32_e64 s[36:37], s98, v86
	v_cndmask_b32_e64 v38, 0, v38, s[78:79]
	v_add_u32_e32 v87, 18, v84
	v_cmp_gt_u32_e64 s[78:79], s98, v87
	v_cndmask_b32_e64 v39, 0, v39, s[50:51]
	v_add_u32_e32 v88, 19, v84
	v_cmp_gt_u32_e64 s[50:51], s98, v88
	v_cndmask_b32_e64 v40, 0, v40, s[30:31]
	v_add_u32_e32 v85, 24, v84
	v_cmp_gt_u32_e64 s[30:31], s98, v85
	v_cndmask_b32_e64 v41, 0, v41, s[36:37]
	v_add_u32_e32 v86, 25, v84
	v_cmp_gt_u32_e64 s[36:37], s98, v86
	v_cndmask_b32_e64 v42, 0, v42, s[78:79]
	v_add_u32_e32 v87, 26, v84
	v_cmp_gt_u32_e64 s[78:79], s98, v87
	v_cndmask_b32_e64 v43, 0, v43, s[50:51]
	v_add_u32_e32 v88, 27, v84
	v_cmp_gt_u32_e64 s[50:51], s98, v88
	v_nop
	v_cndmask_b32_e64 v44, 0, v44, s[30:31]
	v_cndmask_b32_e64 v45, 0, v45, s[36:37]
	v_cndmask_b32_e64 v46, 0, v46, s[78:79]
	v_cndmask_b32_e64 v47, 0, v47, s[50:51]
	v_cvt_pk_bf16_f32 v64, v32, v33
	v_cvt_pk_bf16_f32 v65, v34, v35
	v_cvt_pk_bf16_f32 v66, v36, v37
	v_cvt_pk_bf16_f32 v67, v38, v39
	v_cvt_pk_bf16_f32 v68, v40, v41
	v_cvt_pk_bf16_f32 v69, v42, v43
	v_cvt_pk_bf16_f32 v70, v44, v45
	v_cvt_pk_bf16_f32 v71, v46, v47
	v_pk_add_f32 v[232:233], v[232:233], v[32:33]
	v_pk_add_f32 v[232:233], v[232:233], v[34:35]
	v_pk_add_f32 v[232:233], v[232:233], v[36:37]
	v_pk_add_f32 v[232:233], v[232:233], v[38:39]
	v_pk_add_f32 v[232:233], v[232:233], v[40:41]
	v_pk_add_f32 v[232:233], v[232:233], v[42:43]
	v_pk_add_f32 v[232:233], v[232:233], v[44:45]
	v_pk_add_f32 v[232:233], v[232:233], v[46:47]
	s_waitcnt lgkmcnt(0)
	v_mfma_f32_32x32x16_bf16 v[0:15], v[64:67], v[72:75], v[0:15]
	v_mfma_f32_32x32x16_bf16 v[16:31], v[64:67], v[76:79], v[16:31]
	v_mfma_f32_32x32x16_bf16 v[0:15], v[68:71], v[220:223], v[0:15]
	v_mfma_f32_32x32x16_bf16 v[16:31], v[68:71], v[224:227], v[16:31]
	s_add_i32 s90, s76, 320
	v_add_u32_e32 v80, s90, v235
	v_add_u32_e32 v83, s90, v236
	v_add_u32_e32 v99, s90, v237
	v_add_u32_e32 v253, s90, v238
	v_add_u32_e32 v254, s90, v100
	v_add_u32_e32 v255, s90, v149
	v_med3_i32 v80, v80, 0, s99
	v_med3_i32 v83, v83, 0, s99
	v_med3_i32 v99, v99, 0, s99
	v_med3_i32 v253, v253, 0, s99
	v_med3_i32 v254, v254, 0, s99
	v_med3_i32 v255, v255, 0, s99
	v_mad_u32_u24 v80, v80, s100, v252
	v_mad_u32_u24 v83, v83, s100, v252
	v_mad_u32_u24 v99, v99, s100, v252
	v_mad_u32_u24 v253, v253, s100, v252
	v_mad_u32_u24 v254, v254, s100, v153
	v_mad_u32_u24 v255, v255, s100, v153
	global_load_dwordx4 v[116:119], v80, s[82:83]
	global_load_dwordx4 v[120:123], v83, s[82:83]
	global_load_dwordx4 v[124:127], v99, s[82:83]
	global_load_dwordx4 v[128:131], v253, s[82:83]
	global_load_dwordx4 v[132:135], v254, s[82:83] offset:768
	global_load_dwordx4 v[136:139], v255, s[82:83] offset:768
	global_load_dwordx4 v[140:143], v254, s[82:83] offset:832
	global_load_dwordx4 v[144:147], v255, s[82:83] offset:832
	s_waitcnt vmcnt(16)
	ds_write_b128 v247, v[156:159]
	ds_write_b128 v247, v[160:163] offset:1024
	ds_write_b128 v247, v[164:167] offset:2048
	ds_write_b128 v247, v[168:171] offset:3072
	ds_read_b128 v[156:159], v248
	ds_read_b128 v[160:163], v249
	ds_read_b128 v[164:167], v250
	ds_read_b128 v[168:171], v251
	ds_write_b128 v112, v[172:175]
	ds_write_b128 v112, v[176:179] offset:1024
	ds_write_b128 v112, v[180:183] offset:2048
	ds_write_b128 v112, v[184:187] offset:3072
	ds_read2_b32 v[32:33], v115 offset0:102 offset1:103
	ds_read2_b32 v[34:35], v115 offset0:104 offset1:105
	ds_read2_b32 v[36:37], v115 offset0:110 offset1:111
	ds_read2_b32 v[38:39], v115 offset0:112 offset1:113
	ds_read2_b32 v[40:41], v115 offset0:119 offset1:120
	ds_read2_b32 v[42:43], v115 offset0:121 offset1:122
	ds_read2_b32 v[44:45], v115 offset0:127 offset1:128
	ds_read2_b32 v[46:47], v115 offset0:129 offset1:130
	s_waitcnt lgkmcnt(0)
	v_mfma_f32_32x32x16_bf16 v[32:47], v[156:159], v[48:51], v[32:47]
	ds_read_b64_tr_b16 v[72:73], v231
	ds_read_b64_tr_b16 v[74:75], v231 offset:512
	ds_read_b64_tr_b16 v[76:77], v231 offset:2048
	ds_read_b64_tr_b16 v[78:79], v231 offset:2560
	ds_read_b64_tr_b16 v[220:221], v231 offset:1024
	ds_read_b64_tr_b16 v[222:223], v231 offset:1536
	ds_read_b64_tr_b16 v[224:225], v231 offset:3072
	ds_read_b64_tr_b16 v[226:227], v231 offset:3584
	v_mfma_f32_32x32x16_bf16 v[32:47], v[160:163], v[52:55], v[32:47]
	v_mfma_f32_32x32x16_bf16 v[32:47], v[164:167], v[56:59], v[32:47]
	v_mfma_f32_32x32x16_bf16 v[32:47], v[168:171], v[60:63], v[32:47]
	s_nop 11
	v_exp_f32_e32 v32, v32
	v_exp_f32_e32 v33, v33
	v_exp_f32_e32 v34, v34
	v_exp_f32_e32 v35, v35
	v_exp_f32_e32 v36, v36
	v_exp_f32_e32 v37, v37
	v_exp_f32_e32 v38, v38
	v_exp_f32_e32 v39, v39
	v_exp_f32_e32 v40, v40
	v_exp_f32_e32 v41, v41
	v_exp_f32_e32 v42, v42
	v_exp_f32_e32 v43, v43
	v_exp_f32_e32 v44, v44
	v_exp_f32_e32 v45, v45
	v_exp_f32_e32 v46, v46
	v_exp_f32_e32 v47, v47
	s_add_i32 s90, s76, 256
	v_add_u32_e32 v84, s90, v107
	v_add_u32_e32 v85, 0, v84
	v_add_u32_e32 v86, 1, v84
	v_add_u32_e32 v87, 2, v84
	v_add_u32_e32 v88, 3, v84
	v_cmp_gt_u32_e64 s[30:31], s98, v85
	v_cmp_gt_u32_e64 s[36:37], s98, v86
	v_cmp_gt_u32_e64 s[78:79], s98, v87
	v_cmp_gt_u32_e64 s[50:51], s98, v88
	v_cndmask_b32_e64 v32, 0, v32, s[30:31]
	v_add_u32_e32 v85, 8, v84
	v_cmp_gt_u32_e64 s[30:31], s98, v85
	v_cndmask_b32_e64 v33, 0, v33, s[36:37]
	v_add_u32_e32 v86, 9, v84
	v_cmp_gt_u32_e64 s[36:37], s98, v86
	v_cndmask_b32_e64 v34, 0, v34, s[78:79]
	v_add_u32_e32 v87, 10, v84
	v_cmp_gt_u32_e64 s[78:79], s98, v87
	v_cndmask_b32_e64 v35, 0, v35, s[50:51]
	v_add_u32_e32 v88, 11, v84
	v_cmp_gt_u32_e64 s[50:51], s98, v88
	v_cndmask_b32_e64 v36, 0, v36, s[30:31]
	v_add_u32_e32 v85, 16, v84
	v_cmp_gt_u32_e64 s[30:31], s98, v85
	v_cndmask_b32_e64 v37, 0, v37, s[36:37]
	v_add_u32_e32 v86, 17, v84
	v_cmp_gt_u32_e64 s[36:37], s98, v86
	v_cndmask_b32_e64 v38, 0, v38, s[78:79]
	v_add_u32_e32 v87, 18, v84
	v_cmp_gt_u32_e64 s[78:79], s98, v87
	v_cndmask_b32_e64 v39, 0, v39, s[50:51]
	v_add_u32_e32 v88, 19, v84
	v_cmp_gt_u32_e64 s[50:51], s98, v88
	v_cndmask_b32_e64 v40, 0, v40, s[30:31]
	v_add_u32_e32 v85, 24, v84
	v_cmp_gt_u32_e64 s[30:31], s98, v85
	v_cndmask_b32_e64 v41, 0, v41, s[36:37]
	v_add_u32_e32 v86, 25, v84
	v_cmp_gt_u32_e64 s[36:37], s98, v86
	v_cndmask_b32_e64 v42, 0, v42, s[78:79]
	v_add_u32_e32 v87, 26, v84
	v_cmp_gt_u32_e64 s[78:79], s98, v87
	v_cndmask_b32_e64 v43, 0, v43, s[50:51]
	v_add_u32_e32 v88, 27, v84
	v_cmp_gt_u32_e64 s[50:51], s98, v88
	v_nop
	v_cndmask_b32_e64 v44, 0, v44, s[30:31]
	v_cndmask_b32_e64 v45, 0, v45, s[36:37]
	v_cndmask_b32_e64 v46, 0, v46, s[78:79]
	v_cndmask_b32_e64 v47, 0, v47, s[50:51]
	v_cvt_pk_bf16_f32 v64, v32, v33
	v_cvt_pk_bf16_f32 v65, v34, v35
	v_cvt_pk_bf16_f32 v66, v36, v37
	v_cvt_pk_bf16_f32 v67, v38, v39
	v_cvt_pk_bf16_f32 v68, v40, v41
	v_cvt_pk_bf16_f32 v69, v42, v43
	v_cvt_pk_bf16_f32 v70, v44, v45
	v_cvt_pk_bf16_f32 v71, v46, v47
	v_pk_add_f32 v[232:233], v[232:233], v[32:33]
	v_pk_add_f32 v[232:233], v[232:233], v[34:35]
	v_pk_add_f32 v[232:233], v[232:233], v[36:37]
	v_pk_add_f32 v[232:233], v[232:233], v[38:39]
	v_pk_add_f32 v[232:233], v[232:233], v[40:41]
	v_pk_add_f32 v[232:233], v[232:233], v[42:43]
	v_pk_add_f32 v[232:233], v[232:233], v[44:45]
	v_pk_add_f32 v[232:233], v[232:233], v[46:47]
	s_waitcnt lgkmcnt(0)
	v_mfma_f32_32x32x16_bf16 v[0:15], v[64:67], v[72:75], v[0:15]
	v_mfma_f32_32x32x16_bf16 v[16:31], v[64:67], v[76:79], v[16:31]
	v_mfma_f32_32x32x16_bf16 v[0:15], v[68:71], v[220:223], v[0:15]
	v_mfma_f32_32x32x16_bf16 v[16:31], v[68:71], v[224:227], v[16:31]
	s_add_i32 s90, s76, 352
	v_add_u32_e32 v80, s90, v235
	v_add_u32_e32 v83, s90, v236
	v_add_u32_e32 v99, s90, v237
	v_add_u32_e32 v253, s90, v238
	v_add_u32_e32 v254, s90, v100
	v_add_u32_e32 v255, s90, v149
	v_med3_i32 v80, v80, 0, s99
	v_med3_i32 v83, v83, 0, s99
	v_med3_i32 v99, v99, 0, s99
	v_med3_i32 v253, v253, 0, s99
	v_med3_i32 v254, v254, 0, s99
	v_med3_i32 v255, v255, 0, s99
	v_mad_u32_u24 v80, v80, s100, v252
	v_mad_u32_u24 v83, v83, s100, v252
	v_mad_u32_u24 v99, v99, s100, v252
	v_mad_u32_u24 v253, v253, s100, v252
	v_mad_u32_u24 v254, v254, s100, v153
	v_mad_u32_u24 v255, v255, s100, v153
	global_load_dwordx4 v[156:159], v80, s[82:83]
	global_load_dwordx4 v[160:163], v83, s[82:83]
	global_load_dwordx4 v[164:167], v99, s[82:83]
	global_load_dwordx4 v[168:171], v253, s[82:83]
	global_load_dwordx4 v[172:175], v254, s[82:83] offset:768
	global_load_dwordx4 v[176:179], v255, s[82:83] offset:768
	global_load_dwordx4 v[180:183], v254, s[82:83] offset:832
	global_load_dwordx4 v[184:187], v255, s[82:83] offset:832
	s_waitcnt vmcnt(16)
	ds_write_b128 v247, v[188:191]
	ds_write_b128 v247, v[192:195] offset:1024
	ds_write_b128 v247, v[196:199] offset:2048
	ds_write_b128 v247, v[200:203] offset:3072
	ds_read_b128 v[188:191], v248
	ds_read_b128 v[192:195], v249
	ds_read_b128 v[196:199], v250
	ds_read_b128 v[200:203], v251
	ds_write_b128 v112, v[204:207]
	ds_write_b128 v112, v[208:211] offset:1024
	ds_write_b128 v112, v[212:215] offset:2048
	ds_write_b128 v112, v[216:219] offset:3072
	ds_read2_b32 v[32:33], v115 offset0:136 offset1:137
	ds_read2_b32 v[34:35], v115 offset0:138 offset1:139
	ds_read2_b32 v[36:37], v115 offset0:144 offset1:145
	ds_read2_b32 v[38:39], v115 offset0:146 offset1:147
	ds_read2_b32 v[40:41], v115 offset0:153 offset1:154
	ds_read2_b32 v[42:43], v115 offset0:155 offset1:156
	ds_read2_b32 v[44:45], v115 offset0:161 offset1:162
	ds_read2_b32 v[46:47], v115 offset0:163 offset1:164
	s_waitcnt lgkmcnt(0)
	v_mfma_f32_32x32x16_bf16 v[32:47], v[188:191], v[48:51], v[32:47]
	ds_read_b64_tr_b16 v[72:73], v231
	ds_read_b64_tr_b16 v[74:75], v231 offset:512
	ds_read_b64_tr_b16 v[76:77], v231 offset:2048
	ds_read_b64_tr_b16 v[78:79], v231 offset:2560
	ds_read_b64_tr_b16 v[220:221], v231 offset:1024
	ds_read_b64_tr_b16 v[222:223], v231 offset:1536
	ds_read_b64_tr_b16 v[224:225], v231 offset:3072
	ds_read_b64_tr_b16 v[226:227], v231 offset:3584
	v_mfma_f32_32x32x16_bf16 v[32:47], v[192:195], v[52:55], v[32:47]
	v_mfma_f32_32x32x16_bf16 v[32:47], v[196:199], v[56:59], v[32:47]
	v_mfma_f32_32x32x16_bf16 v[32:47], v[200:203], v[60:63], v[32:47]
	s_nop 11
	v_exp_f32_e32 v32, v32
	v_exp_f32_e32 v33, v33
	v_exp_f32_e32 v34, v34
	v_exp_f32_e32 v35, v35
	v_exp_f32_e32 v36, v36
	v_exp_f32_e32 v37, v37
	v_exp_f32_e32 v38, v38
	v_exp_f32_e32 v39, v39
	v_exp_f32_e32 v40, v40
	v_exp_f32_e32 v41, v41
	v_exp_f32_e32 v42, v42
	v_exp_f32_e32 v43, v43
	v_exp_f32_e32 v44, v44
	v_exp_f32_e32 v45, v45
	v_exp_f32_e32 v46, v46
	v_exp_f32_e32 v47, v47
	s_add_i32 s90, s76, 288
	v_add_u32_e32 v84, s90, v107
	v_add_u32_e32 v85, 0, v84
	v_add_u32_e32 v86, 1, v84
	v_add_u32_e32 v87, 2, v84
	v_add_u32_e32 v88, 3, v84
	v_cmp_gt_u32_e64 s[30:31], s98, v85
	v_cmp_gt_u32_e64 s[36:37], s98, v86
	v_cmp_gt_u32_e64 s[78:79], s98, v87
	v_cmp_gt_u32_e64 s[50:51], s98, v88
	v_cndmask_b32_e64 v32, 0, v32, s[30:31]
	v_add_u32_e32 v85, 8, v84
	v_cmp_gt_u32_e64 s[30:31], s98, v85
	v_cndmask_b32_e64 v33, 0, v33, s[36:37]
	v_add_u32_e32 v86, 9, v84
	v_cmp_gt_u32_e64 s[36:37], s98, v86
	v_cndmask_b32_e64 v34, 0, v34, s[78:79]
	v_add_u32_e32 v87, 10, v84
	v_cmp_gt_u32_e64 s[78:79], s98, v87
	v_cndmask_b32_e64 v35, 0, v35, s[50:51]
	v_add_u32_e32 v88, 11, v84
	v_cmp_gt_u32_e64 s[50:51], s98, v88
	v_cndmask_b32_e64 v36, 0, v36, s[30:31]
	v_add_u32_e32 v85, 16, v84
	v_cmp_gt_u32_e64 s[30:31], s98, v85
	v_cndmask_b32_e64 v37, 0, v37, s[36:37]
	v_add_u32_e32 v86, 17, v84
	v_cmp_gt_u32_e64 s[36:37], s98, v86
	v_cndmask_b32_e64 v38, 0, v38, s[78:79]
	v_add_u32_e32 v87, 18, v84
	v_cmp_gt_u32_e64 s[78:79], s98, v87
	v_cndmask_b32_e64 v39, 0, v39, s[50:51]
	v_add_u32_e32 v88, 19, v84
	v_cmp_gt_u32_e64 s[50:51], s98, v88
	v_cndmask_b32_e64 v40, 0, v40, s[30:31]
	v_add_u32_e32 v85, 24, v84
	v_cmp_gt_u32_e64 s[30:31], s98, v85
	v_cndmask_b32_e64 v41, 0, v41, s[36:37]
	v_add_u32_e32 v86, 25, v84
	v_cmp_gt_u32_e64 s[36:37], s98, v86
	v_cndmask_b32_e64 v42, 0, v42, s[78:79]
	v_add_u32_e32 v87, 26, v84
	v_cmp_gt_u32_e64 s[78:79], s98, v87
	v_cndmask_b32_e64 v43, 0, v43, s[50:51]
	v_add_u32_e32 v88, 27, v84
	v_cmp_gt_u32_e64 s[50:51], s98, v88
	v_nop
	v_cndmask_b32_e64 v44, 0, v44, s[30:31]
	v_cndmask_b32_e64 v45, 0, v45, s[36:37]
	v_cndmask_b32_e64 v46, 0, v46, s[78:79]
	v_cndmask_b32_e64 v47, 0, v47, s[50:51]
	v_cvt_pk_bf16_f32 v64, v32, v33
	v_cvt_pk_bf16_f32 v65, v34, v35
	v_cvt_pk_bf16_f32 v66, v36, v37
	v_cvt_pk_bf16_f32 v67, v38, v39
	v_cvt_pk_bf16_f32 v68, v40, v41
	v_cvt_pk_bf16_f32 v69, v42, v43
	v_cvt_pk_bf16_f32 v70, v44, v45
	v_cvt_pk_bf16_f32 v71, v46, v47
	v_pk_add_f32 v[232:233], v[232:233], v[32:33]
	v_pk_add_f32 v[232:233], v[232:233], v[34:35]
	v_pk_add_f32 v[232:233], v[232:233], v[36:37]
	v_pk_add_f32 v[232:233], v[232:233], v[38:39]
	v_pk_add_f32 v[232:233], v[232:233], v[40:41]
	v_pk_add_f32 v[232:233], v[232:233], v[42:43]
	v_pk_add_f32 v[232:233], v[232:233], v[44:45]
	v_pk_add_f32 v[232:233], v[232:233], v[46:47]
	s_waitcnt lgkmcnt(0)
	v_mfma_f32_32x32x16_bf16 v[0:15], v[64:67], v[72:75], v[0:15]
	v_mfma_f32_32x32x16_bf16 v[16:31], v[64:67], v[76:79], v[16:31]
	v_mfma_f32_32x32x16_bf16 v[0:15], v[68:71], v[220:223], v[0:15]
	v_mfma_f32_32x32x16_bf16 v[16:31], v[68:71], v[224:227], v[16:31]
	s_add_i32 s90, s76, 384
	v_add_u32_e32 v80, s90, v235
	v_add_u32_e32 v83, s90, v236
	v_add_u32_e32 v99, s90, v237
	v_add_u32_e32 v253, s90, v238
	v_add_u32_e32 v254, s90, v100
	v_add_u32_e32 v255, s90, v149
	v_med3_i32 v80, v80, 0, s99
	v_med3_i32 v83, v83, 0, s99
	v_med3_i32 v99, v99, 0, s99
	v_med3_i32 v253, v253, 0, s99
	v_med3_i32 v254, v254, 0, s99
	v_med3_i32 v255, v255, 0, s99
	v_mad_u32_u24 v80, v80, s100, v252
	v_mad_u32_u24 v83, v83, s100, v252
	v_mad_u32_u24 v99, v99, s100, v252
	v_mad_u32_u24 v253, v253, s100, v252
	v_mad_u32_u24 v254, v254, s100, v153
	v_mad_u32_u24 v255, v255, s100, v153
	global_load_dwordx4 v[188:191], v80, s[82:83]
	global_load_dwordx4 v[192:195], v83, s[82:83]
	global_load_dwordx4 v[196:199], v99, s[82:83]
	global_load_dwordx4 v[200:203], v253, s[82:83]
	global_load_dwordx4 v[204:207], v254, s[82:83] offset:768
	global_load_dwordx4 v[208:211], v255, s[82:83] offset:768
	global_load_dwordx4 v[212:215], v254, s[82:83] offset:832
	global_load_dwordx4 v[216:219], v255, s[82:83] offset:832
	s_waitcnt vmcnt(16)
	ds_write_b128 v247, v[116:119]
	ds_write_b128 v247, v[120:123] offset:1024
	ds_write_b128 v247, v[124:127] offset:2048
	ds_write_b128 v247, v[128:131] offset:3072
	ds_read_b128 v[116:119], v248
	ds_read_b128 v[120:123], v249
	ds_read_b128 v[124:127], v250
	ds_read_b128 v[128:131], v251
	ds_write_b128 v112, v[132:135]
	ds_write_b128 v112, v[136:139] offset:1024
	ds_write_b128 v112, v[140:143] offset:2048
	ds_write_b128 v112, v[144:147] offset:3072
	ds_read2_b32 v[32:33], v115 offset0:170 offset1:171
	ds_read2_b32 v[34:35], v115 offset0:172 offset1:173
	ds_read2_b32 v[36:37], v115 offset0:178 offset1:179
	ds_read2_b32 v[38:39], v115 offset0:180 offset1:181
	ds_read2_b32 v[40:41], v115 offset0:187 offset1:188
	ds_read2_b32 v[42:43], v115 offset0:189 offset1:190
	ds_read2_b32 v[44:45], v115 offset0:195 offset1:196
	ds_read2_b32 v[46:47], v115 offset0:197 offset1:198
	s_waitcnt lgkmcnt(0)
	v_mfma_f32_32x32x16_bf16 v[32:47], v[116:119], v[48:51], v[32:47]
	ds_read_b64_tr_b16 v[72:73], v231
	ds_read_b64_tr_b16 v[74:75], v231 offset:512
	ds_read_b64_tr_b16 v[76:77], v231 offset:2048
	ds_read_b64_tr_b16 v[78:79], v231 offset:2560
	ds_read_b64_tr_b16 v[220:221], v231 offset:1024
	ds_read_b64_tr_b16 v[222:223], v231 offset:1536
	ds_read_b64_tr_b16 v[224:225], v231 offset:3072
	ds_read_b64_tr_b16 v[226:227], v231 offset:3584
	v_mfma_f32_32x32x16_bf16 v[32:47], v[120:123], v[52:55], v[32:47]
	v_mfma_f32_32x32x16_bf16 v[32:47], v[124:127], v[56:59], v[32:47]
	v_mfma_f32_32x32x16_bf16 v[32:47], v[128:131], v[60:63], v[32:47]
	s_nop 11
	v_exp_f32_e32 v32, v32
	v_exp_f32_e32 v33, v33
	v_exp_f32_e32 v34, v34
	v_exp_f32_e32 v35, v35
	v_exp_f32_e32 v36, v36
	v_exp_f32_e32 v37, v37
	v_exp_f32_e32 v38, v38
	v_exp_f32_e32 v39, v39
	v_exp_f32_e32 v40, v40
	v_exp_f32_e32 v41, v41
	v_exp_f32_e32 v42, v42
	v_exp_f32_e32 v43, v43
	v_exp_f32_e32 v44, v44
	v_exp_f32_e32 v45, v45
	v_exp_f32_e32 v46, v46
	v_exp_f32_e32 v47, v47
	s_add_i32 s90, s76, 320
	v_add_u32_e32 v84, s90, v107
	v_add_u32_e32 v85, 0, v84
	v_add_u32_e32 v86, 1, v84
	v_add_u32_e32 v87, 2, v84
	v_add_u32_e32 v88, 3, v84
	v_cmp_gt_u32_e64 s[30:31], s98, v85
	v_cmp_gt_u32_e64 s[36:37], s98, v86
	v_cmp_gt_u32_e64 s[78:79], s98, v87
	v_cmp_gt_u32_e64 s[50:51], s98, v88
	v_cndmask_b32_e64 v32, 0, v32, s[30:31]
	v_add_u32_e32 v85, 8, v84
	v_cmp_gt_u32_e64 s[30:31], s98, v85
	v_cndmask_b32_e64 v33, 0, v33, s[36:37]
	v_add_u32_e32 v86, 9, v84
	v_cmp_gt_u32_e64 s[36:37], s98, v86
	v_cndmask_b32_e64 v34, 0, v34, s[78:79]
	v_add_u32_e32 v87, 10, v84
	v_cmp_gt_u32_e64 s[78:79], s98, v87
	v_cndmask_b32_e64 v35, 0, v35, s[50:51]
	v_add_u32_e32 v88, 11, v84
	v_cmp_gt_u32_e64 s[50:51], s98, v88
	v_cndmask_b32_e64 v36, 0, v36, s[30:31]
	v_add_u32_e32 v85, 16, v84
	v_cmp_gt_u32_e64 s[30:31], s98, v85
	v_cndmask_b32_e64 v37, 0, v37, s[36:37]
	v_add_u32_e32 v86, 17, v84
	v_cmp_gt_u32_e64 s[36:37], s98, v86
	v_cndmask_b32_e64 v38, 0, v38, s[78:79]
	v_add_u32_e32 v87, 18, v84
	v_cmp_gt_u32_e64 s[78:79], s98, v87
	v_cndmask_b32_e64 v39, 0, v39, s[50:51]
	v_add_u32_e32 v88, 19, v84
	v_cmp_gt_u32_e64 s[50:51], s98, v88
	v_cndmask_b32_e64 v40, 0, v40, s[30:31]
	v_add_u32_e32 v85, 24, v84
	v_cmp_gt_u32_e64 s[30:31], s98, v85
	v_cndmask_b32_e64 v41, 0, v41, s[36:37]
	v_add_u32_e32 v86, 25, v84
	v_cmp_gt_u32_e64 s[36:37], s98, v86
	v_cndmask_b32_e64 v42, 0, v42, s[78:79]
	v_add_u32_e32 v87, 26, v84
	v_cmp_gt_u32_e64 s[78:79], s98, v87
	v_cndmask_b32_e64 v43, 0, v43, s[50:51]
	v_add_u32_e32 v88, 27, v84
	v_cmp_gt_u32_e64 s[50:51], s98, v88
	v_nop
	v_cndmask_b32_e64 v44, 0, v44, s[30:31]
	v_cndmask_b32_e64 v45, 0, v45, s[36:37]
	v_cndmask_b32_e64 v46, 0, v46, s[78:79]
	v_cndmask_b32_e64 v47, 0, v47, s[50:51]
	v_cvt_pk_bf16_f32 v64, v32, v33
	v_cvt_pk_bf16_f32 v65, v34, v35
	v_cvt_pk_bf16_f32 v66, v36, v37
	v_cvt_pk_bf16_f32 v67, v38, v39
	v_cvt_pk_bf16_f32 v68, v40, v41
	v_cvt_pk_bf16_f32 v69, v42, v43
	v_cvt_pk_bf16_f32 v70, v44, v45
	v_cvt_pk_bf16_f32 v71, v46, v47
	v_pk_add_f32 v[232:233], v[232:233], v[32:33]
	v_pk_add_f32 v[232:233], v[232:233], v[34:35]
	v_pk_add_f32 v[232:233], v[232:233], v[36:37]
	v_pk_add_f32 v[232:233], v[232:233], v[38:39]
	v_pk_add_f32 v[232:233], v[232:233], v[40:41]
	v_pk_add_f32 v[232:233], v[232:233], v[42:43]
	v_pk_add_f32 v[232:233], v[232:233], v[44:45]
	v_pk_add_f32 v[232:233], v[232:233], v[46:47]
	s_waitcnt lgkmcnt(0)
	v_mfma_f32_32x32x16_bf16 v[0:15], v[64:67], v[72:75], v[0:15]
	v_mfma_f32_32x32x16_bf16 v[16:31], v[64:67], v[76:79], v[16:31]
	v_mfma_f32_32x32x16_bf16 v[0:15], v[68:71], v[220:223], v[0:15]
	v_mfma_f32_32x32x16_bf16 v[16:31], v[68:71], v[224:227], v[16:31]
	s_add_i32 s90, s76, 416
	v_add_u32_e32 v80, s90, v235
	v_add_u32_e32 v83, s90, v236
	v_add_u32_e32 v99, s90, v237
	v_add_u32_e32 v253, s90, v238
	v_add_u32_e32 v254, s90, v100
	v_add_u32_e32 v255, s90, v149
	v_med3_i32 v80, v80, 0, s99
	v_med3_i32 v83, v83, 0, s99
	v_med3_i32 v99, v99, 0, s99
	v_med3_i32 v253, v253, 0, s99
	v_med3_i32 v254, v254, 0, s99
	v_med3_i32 v255, v255, 0, s99
	v_mad_u32_u24 v80, v80, s100, v252
	v_mad_u32_u24 v83, v83, s100, v252
	v_mad_u32_u24 v99, v99, s100, v252
	v_mad_u32_u24 v253, v253, s100, v252
	v_mad_u32_u24 v254, v254, s100, v153
	v_mad_u32_u24 v255, v255, s100, v153
	global_load_dwordx4 v[116:119], v80, s[82:83]
	global_load_dwordx4 v[120:123], v83, s[82:83]
	global_load_dwordx4 v[124:127], v99, s[82:83]
	global_load_dwordx4 v[128:131], v253, s[82:83]
	global_load_dwordx4 v[132:135], v254, s[82:83] offset:768
	global_load_dwordx4 v[136:139], v255, s[82:83] offset:768
	global_load_dwordx4 v[140:143], v254, s[82:83] offset:832
	global_load_dwordx4 v[144:147], v255, s[82:83] offset:832
	s_waitcnt vmcnt(16)
	ds_write_b128 v247, v[156:159]
	ds_write_b128 v247, v[160:163] offset:1024
	ds_write_b128 v247, v[164:167] offset:2048
	ds_write_b128 v247, v[168:171] offset:3072
	ds_read_b128 v[156:159], v248
	ds_read_b128 v[160:163], v249
	ds_read_b128 v[164:167], v250
	ds_read_b128 v[168:171], v251
	ds_write_b128 v112, v[172:175]
	ds_write_b128 v112, v[176:179] offset:1024
	ds_write_b128 v112, v[180:183] offset:2048
	ds_write_b128 v112, v[184:187] offset:3072
	ds_read2_b32 v[32:33], v115 offset0:204 offset1:205
	ds_read2_b32 v[34:35], v115 offset0:206 offset1:207
	ds_read2_b32 v[36:37], v115 offset0:212 offset1:213
	ds_read2_b32 v[38:39], v115 offset0:214 offset1:215
	ds_read2_b32 v[40:41], v115 offset0:221 offset1:222
	ds_read2_b32 v[42:43], v115 offset0:223 offset1:224
	ds_read2_b32 v[44:45], v115 offset0:229 offset1:230
	ds_read2_b32 v[46:47], v115 offset0:231 offset1:232
	s_waitcnt lgkmcnt(0)
	v_mfma_f32_32x32x16_bf16 v[32:47], v[156:159], v[48:51], v[32:47]
	ds_read_b64_tr_b16 v[72:73], v231
	ds_read_b64_tr_b16 v[74:75], v231 offset:512
	ds_read_b64_tr_b16 v[76:77], v231 offset:2048
	ds_read_b64_tr_b16 v[78:79], v231 offset:2560
	ds_read_b64_tr_b16 v[220:221], v231 offset:1024
	ds_read_b64_tr_b16 v[222:223], v231 offset:1536
	ds_read_b64_tr_b16 v[224:225], v231 offset:3072
	ds_read_b64_tr_b16 v[226:227], v231 offset:3584
	v_mfma_f32_32x32x16_bf16 v[32:47], v[160:163], v[52:55], v[32:47]
	v_mfma_f32_32x32x16_bf16 v[32:47], v[164:167], v[56:59], v[32:47]
	v_mfma_f32_32x32x16_bf16 v[32:47], v[168:171], v[60:63], v[32:47]
	s_nop 11
	v_exp_f32_e32 v32, v32
	v_exp_f32_e32 v33, v33
	v_exp_f32_e32 v34, v34
	v_exp_f32_e32 v35, v35
	v_exp_f32_e32 v36, v36
	v_exp_f32_e32 v37, v37
	v_exp_f32_e32 v38, v38
	v_exp_f32_e32 v39, v39
	v_exp_f32_e32 v40, v40
	v_exp_f32_e32 v41, v41
	v_exp_f32_e32 v42, v42
	v_exp_f32_e32 v43, v43
	v_exp_f32_e32 v44, v44
	v_exp_f32_e32 v45, v45
	v_exp_f32_e32 v46, v46
	v_exp_f32_e32 v47, v47
	s_add_i32 s90, s76, 352
	v_add_u32_e32 v84, s90, v107
	v_add_u32_e32 v85, 0, v84
	v_add_u32_e32 v86, 1, v84
	v_add_u32_e32 v87, 2, v84
	v_add_u32_e32 v88, 3, v84
	v_cmp_gt_u32_e64 s[30:31], s98, v85
	v_cmp_gt_u32_e64 s[36:37], s98, v86
	v_cmp_gt_u32_e64 s[78:79], s98, v87
	v_cmp_gt_u32_e64 s[50:51], s98, v88
	v_cndmask_b32_e64 v32, 0, v32, s[30:31]
	v_add_u32_e32 v85, 8, v84
	v_cmp_gt_u32_e64 s[30:31], s98, v85
	v_cndmask_b32_e64 v33, 0, v33, s[36:37]
	v_add_u32_e32 v86, 9, v84
	v_cmp_gt_u32_e64 s[36:37], s98, v86
	v_cndmask_b32_e64 v34, 0, v34, s[78:79]
	v_add_u32_e32 v87, 10, v84
	v_cmp_gt_u32_e64 s[78:79], s98, v87
	v_cndmask_b32_e64 v35, 0, v35, s[50:51]
	v_add_u32_e32 v88, 11, v84
	v_cmp_gt_u32_e64 s[50:51], s98, v88
	v_cndmask_b32_e64 v36, 0, v36, s[30:31]
	v_add_u32_e32 v85, 16, v84
	v_cmp_gt_u32_e64 s[30:31], s98, v85
	v_cndmask_b32_e64 v37, 0, v37, s[36:37]
	v_add_u32_e32 v86, 17, v84
	v_cmp_gt_u32_e64 s[36:37], s98, v86
	v_cndmask_b32_e64 v38, 0, v38, s[78:79]
	v_add_u32_e32 v87, 18, v84
	v_cmp_gt_u32_e64 s[78:79], s98, v87
	v_cndmask_b32_e64 v39, 0, v39, s[50:51]
	v_add_u32_e32 v88, 19, v84
	v_cmp_gt_u32_e64 s[50:51], s98, v88
	v_cndmask_b32_e64 v40, 0, v40, s[30:31]
	v_add_u32_e32 v85, 24, v84
	v_cmp_gt_u32_e64 s[30:31], s98, v85
	v_cndmask_b32_e64 v41, 0, v41, s[36:37]
	v_add_u32_e32 v86, 25, v84
	v_cmp_gt_u32_e64 s[36:37], s98, v86
	v_cndmask_b32_e64 v42, 0, v42, s[78:79]
	v_add_u32_e32 v87, 26, v84
	v_cmp_gt_u32_e64 s[78:79], s98, v87
	v_cndmask_b32_e64 v43, 0, v43, s[50:51]
	v_add_u32_e32 v88, 27, v84
	v_cmp_gt_u32_e64 s[50:51], s98, v88
	v_nop
	v_cndmask_b32_e64 v44, 0, v44, s[30:31]
	v_cndmask_b32_e64 v45, 0, v45, s[36:37]
	v_cndmask_b32_e64 v46, 0, v46, s[78:79]
	v_cndmask_b32_e64 v47, 0, v47, s[50:51]
	v_cvt_pk_bf16_f32 v64, v32, v33
	v_cvt_pk_bf16_f32 v65, v34, v35
	v_cvt_pk_bf16_f32 v66, v36, v37
	v_cvt_pk_bf16_f32 v67, v38, v39
	v_cvt_pk_bf16_f32 v68, v40, v41
	v_cvt_pk_bf16_f32 v69, v42, v43
	v_cvt_pk_bf16_f32 v70, v44, v45
	v_cvt_pk_bf16_f32 v71, v46, v47
	v_pk_add_f32 v[232:233], v[232:233], v[32:33]
	v_pk_add_f32 v[232:233], v[232:233], v[34:35]
	v_pk_add_f32 v[232:233], v[232:233], v[36:37]
	v_pk_add_f32 v[232:233], v[232:233], v[38:39]
	v_pk_add_f32 v[232:233], v[232:233], v[40:41]
	v_pk_add_f32 v[232:233], v[232:233], v[42:43]
	v_pk_add_f32 v[232:233], v[232:233], v[44:45]
	v_pk_add_f32 v[232:233], v[232:233], v[46:47]
	s_waitcnt lgkmcnt(0)
	v_mfma_f32_32x32x16_bf16 v[0:15], v[64:67], v[72:75], v[0:15]
	v_mfma_f32_32x32x16_bf16 v[16:31], v[64:67], v[76:79], v[16:31]
	v_mfma_f32_32x32x16_bf16 v[0:15], v[68:71], v[220:223], v[0:15]
	v_mfma_f32_32x32x16_bf16 v[16:31], v[68:71], v[224:227], v[16:31]
	s_add_i32 s90, s76, 448
	v_add_u32_e32 v80, s90, v235
	v_add_u32_e32 v83, s90, v236
	v_add_u32_e32 v99, s90, v237
	v_add_u32_e32 v253, s90, v238
	v_add_u32_e32 v254, s90, v100
	v_add_u32_e32 v255, s90, v149
	v_med3_i32 v80, v80, 0, s99
	v_med3_i32 v83, v83, 0, s99
	v_med3_i32 v99, v99, 0, s99
	v_med3_i32 v253, v253, 0, s99
	v_med3_i32 v254, v254, 0, s99
	v_med3_i32 v255, v255, 0, s99
	v_mad_u32_u24 v80, v80, s100, v252
	v_mad_u32_u24 v83, v83, s100, v252
	v_mad_u32_u24 v99, v99, s100, v252
	v_mad_u32_u24 v253, v253, s100, v252
	v_mad_u32_u24 v254, v254, s100, v153
	v_mad_u32_u24 v255, v255, s100, v153
	global_load_dwordx4 v[156:159], v80, s[82:83]
	global_load_dwordx4 v[160:163], v83, s[82:83]
	global_load_dwordx4 v[164:167], v99, s[82:83]
	global_load_dwordx4 v[168:171], v253, s[82:83]
	global_load_dwordx4 v[172:175], v254, s[82:83] offset:768
	global_load_dwordx4 v[176:179], v255, s[82:83] offset:768
	global_load_dwordx4 v[180:183], v254, s[82:83] offset:832
	global_load_dwordx4 v[184:187], v255, s[82:83] offset:832
	s_waitcnt vmcnt(16)
	ds_write_b128 v247, v[188:191]
	ds_write_b128 v247, v[192:195] offset:1024
	ds_write_b128 v247, v[196:199] offset:2048
	ds_write_b128 v247, v[200:203] offset:3072
	ds_read_b128 v[188:191], v248
	ds_read_b128 v[192:195], v249
	ds_read_b128 v[196:199], v250
	ds_read_b128 v[200:203], v251
	ds_write_b128 v112, v[204:207]
	ds_write_b128 v112, v[208:211] offset:1024
	ds_write_b128 v112, v[212:215] offset:2048
	ds_write_b128 v112, v[216:219] offset:3072
	v_add_u32_e32 v115, 952, v115
	ds_read2_b32 v[32:33], v115 offset0:0 offset1:1
	ds_read2_b32 v[34:35], v115 offset0:2 offset1:3
	ds_read2_b32 v[36:37], v115 offset0:8 offset1:9
	ds_read2_b32 v[38:39], v115 offset0:10 offset1:11
	ds_read2_b32 v[40:41], v115 offset0:17 offset1:18
	ds_read2_b32 v[42:43], v115 offset0:19 offset1:20
	ds_read2_b32 v[44:45], v115 offset0:25 offset1:26
	ds_read2_b32 v[46:47], v115 offset0:27 offset1:28
	s_waitcnt lgkmcnt(0)
	v_mfma_f32_32x32x16_bf16 v[32:47], v[188:191], v[48:51], v[32:47]
	ds_read_b64_tr_b16 v[72:73], v231
	ds_read_b64_tr_b16 v[74:75], v231 offset:512
	ds_read_b64_tr_b16 v[76:77], v231 offset:2048
	ds_read_b64_tr_b16 v[78:79], v231 offset:2560
	ds_read_b64_tr_b16 v[220:221], v231 offset:1024
	ds_read_b64_tr_b16 v[222:223], v231 offset:1536
	ds_read_b64_tr_b16 v[224:225], v231 offset:3072
	ds_read_b64_tr_b16 v[226:227], v231 offset:3584
	v_mfma_f32_32x32x16_bf16 v[32:47], v[192:195], v[52:55], v[32:47]
	v_mfma_f32_32x32x16_bf16 v[32:47], v[196:199], v[56:59], v[32:47]
	v_mfma_f32_32x32x16_bf16 v[32:47], v[200:203], v[60:63], v[32:47]
	s_nop 11
	v_exp_f32_e32 v32, v32
	v_exp_f32_e32 v33, v33
	v_exp_f32_e32 v34, v34
	v_exp_f32_e32 v35, v35
	v_exp_f32_e32 v36, v36
	v_exp_f32_e32 v37, v37
	v_exp_f32_e32 v38, v38
	v_exp_f32_e32 v39, v39
	v_exp_f32_e32 v40, v40
	v_exp_f32_e32 v41, v41
	v_exp_f32_e32 v42, v42
	v_exp_f32_e32 v43, v43
	v_exp_f32_e32 v44, v44
	v_exp_f32_e32 v45, v45
	v_exp_f32_e32 v46, v46
	v_exp_f32_e32 v47, v47
	s_add_i32 s90, s76, 384
	v_add_u32_e32 v84, s90, v107
	v_add_u32_e32 v85, 0, v84
	v_add_u32_e32 v86, 1, v84
	v_add_u32_e32 v87, 2, v84
	v_add_u32_e32 v88, 3, v84
	v_cmp_gt_u32_e64 s[30:31], s98, v85
	v_cmp_gt_u32_e64 s[36:37], s98, v86
	v_cmp_gt_u32_e64 s[78:79], s98, v87
	v_cmp_gt_u32_e64 s[50:51], s98, v88
	v_cndmask_b32_e64 v32, 0, v32, s[30:31]
	v_add_u32_e32 v85, 8, v84
	v_cmp_gt_u32_e64 s[30:31], s98, v85
	v_cndmask_b32_e64 v33, 0, v33, s[36:37]
	v_add_u32_e32 v86, 9, v84
	v_cmp_gt_u32_e64 s[36:37], s98, v86
	v_cndmask_b32_e64 v34, 0, v34, s[78:79]
	v_add_u32_e32 v87, 10, v84
	v_cmp_gt_u32_e64 s[78:79], s98, v87
	v_cndmask_b32_e64 v35, 0, v35, s[50:51]
	v_add_u32_e32 v88, 11, v84
	v_cmp_gt_u32_e64 s[50:51], s98, v88
	v_cndmask_b32_e64 v36, 0, v36, s[30:31]
	v_add_u32_e32 v85, 16, v84
	v_cmp_gt_u32_e64 s[30:31], s98, v85
	v_cndmask_b32_e64 v37, 0, v37, s[36:37]
	v_add_u32_e32 v86, 17, v84
	v_cmp_gt_u32_e64 s[36:37], s98, v86
	v_cndmask_b32_e64 v38, 0, v38, s[78:79]
	v_add_u32_e32 v87, 18, v84
	v_cmp_gt_u32_e64 s[78:79], s98, v87
	v_cndmask_b32_e64 v39, 0, v39, s[50:51]
	v_add_u32_e32 v88, 19, v84
	v_cmp_gt_u32_e64 s[50:51], s98, v88
	v_cndmask_b32_e64 v40, 0, v40, s[30:31]
	v_add_u32_e32 v85, 24, v84
	v_cmp_gt_u32_e64 s[30:31], s98, v85
	v_cndmask_b32_e64 v41, 0, v41, s[36:37]
	v_add_u32_e32 v86, 25, v84
	v_cmp_gt_u32_e64 s[36:37], s98, v86
	v_cndmask_b32_e64 v42, 0, v42, s[78:79]
	v_add_u32_e32 v87, 26, v84
	v_cmp_gt_u32_e64 s[78:79], s98, v87
	v_cndmask_b32_e64 v43, 0, v43, s[50:51]
	v_add_u32_e32 v88, 27, v84
	v_cmp_gt_u32_e64 s[50:51], s98, v88
	v_nop
	v_cndmask_b32_e64 v44, 0, v44, s[30:31]
	v_cndmask_b32_e64 v45, 0, v45, s[36:37]
	v_cndmask_b32_e64 v46, 0, v46, s[78:79]
	v_cndmask_b32_e64 v47, 0, v47, s[50:51]
	v_cvt_pk_bf16_f32 v64, v32, v33
	v_cvt_pk_bf16_f32 v65, v34, v35
	v_cvt_pk_bf16_f32 v66, v36, v37
	v_cvt_pk_bf16_f32 v67, v38, v39
	v_cvt_pk_bf16_f32 v68, v40, v41
	v_cvt_pk_bf16_f32 v69, v42, v43
	v_cvt_pk_bf16_f32 v70, v44, v45
	v_cvt_pk_bf16_f32 v71, v46, v47
	v_pk_add_f32 v[232:233], v[232:233], v[32:33]
	v_pk_add_f32 v[232:233], v[232:233], v[34:35]
	v_pk_add_f32 v[232:233], v[232:233], v[36:37]
	v_pk_add_f32 v[232:233], v[232:233], v[38:39]
	v_pk_add_f32 v[232:233], v[232:233], v[40:41]
	v_pk_add_f32 v[232:233], v[232:233], v[42:43]
	v_pk_add_f32 v[232:233], v[232:233], v[44:45]
	v_pk_add_f32 v[232:233], v[232:233], v[46:47]
	s_waitcnt lgkmcnt(0)
	v_mfma_f32_32x32x16_bf16 v[0:15], v[64:67], v[72:75], v[0:15]
	v_mfma_f32_32x32x16_bf16 v[16:31], v[64:67], v[76:79], v[16:31]
	v_mfma_f32_32x32x16_bf16 v[0:15], v[68:71], v[220:223], v[0:15]
	v_mfma_f32_32x32x16_bf16 v[16:31], v[68:71], v[224:227], v[16:31]
	s_add_i32 s90, s76, 480
	v_add_u32_e32 v80, s90, v235
	v_add_u32_e32 v83, s90, v236
	v_add_u32_e32 v99, s90, v237
	v_add_u32_e32 v253, s90, v238
	v_add_u32_e32 v254, s90, v100
	v_add_u32_e32 v255, s90, v149
	v_med3_i32 v80, v80, 0, s99
	v_med3_i32 v83, v83, 0, s99
	v_med3_i32 v99, v99, 0, s99
	v_med3_i32 v253, v253, 0, s99
	v_med3_i32 v254, v254, 0, s99
	v_med3_i32 v255, v255, 0, s99
	v_mad_u32_u24 v80, v80, s100, v252
	v_mad_u32_u24 v83, v83, s100, v252
	v_mad_u32_u24 v99, v99, s100, v252
	v_mad_u32_u24 v253, v253, s100, v252
	v_mad_u32_u24 v254, v254, s100, v153
	v_mad_u32_u24 v255, v255, s100, v153
	global_load_dwordx4 v[188:191], v80, s[82:83]
	global_load_dwordx4 v[192:195], v83, s[82:83]
	global_load_dwordx4 v[196:199], v99, s[82:83]
	global_load_dwordx4 v[200:203], v253, s[82:83]
	global_load_dwordx4 v[204:207], v254, s[82:83] offset:768
	global_load_dwordx4 v[208:211], v255, s[82:83] offset:768
	global_load_dwordx4 v[212:215], v254, s[82:83] offset:832
	global_load_dwordx4 v[216:219], v255, s[82:83] offset:832
	s_waitcnt vmcnt(16)
	ds_write_b128 v247, v[116:119]
	ds_write_b128 v247, v[120:123] offset:1024
	ds_write_b128 v247, v[124:127] offset:2048
	ds_write_b128 v247, v[128:131] offset:3072
	ds_read_b128 v[116:119], v248
	ds_read_b128 v[120:123], v249
	ds_read_b128 v[124:127], v250
	ds_read_b128 v[128:131], v251
	ds_write_b128 v112, v[132:135]
	ds_write_b128 v112, v[136:139] offset:1024
	ds_write_b128 v112, v[140:143] offset:2048
	ds_write_b128 v112, v[144:147] offset:3072
	ds_read2_b32 v[32:33], v115 offset0:34 offset1:35
	ds_read2_b32 v[34:35], v115 offset0:36 offset1:37
	ds_read2_b32 v[36:37], v115 offset0:42 offset1:43
	ds_read2_b32 v[38:39], v115 offset0:44 offset1:45
	ds_read2_b32 v[40:41], v115 offset0:51 offset1:52
	ds_read2_b32 v[42:43], v115 offset0:53 offset1:54
	ds_read2_b32 v[44:45], v115 offset0:59 offset1:60
	ds_read2_b32 v[46:47], v115 offset0:61 offset1:62
	s_waitcnt lgkmcnt(0)
	v_mfma_f32_32x32x16_bf16 v[32:47], v[116:119], v[48:51], v[32:47]
	ds_read_b64_tr_b16 v[72:73], v231
	ds_read_b64_tr_b16 v[74:75], v231 offset:512
	ds_read_b64_tr_b16 v[76:77], v231 offset:2048
	ds_read_b64_tr_b16 v[78:79], v231 offset:2560
	ds_read_b64_tr_b16 v[220:221], v231 offset:1024
	ds_read_b64_tr_b16 v[222:223], v231 offset:1536
	ds_read_b64_tr_b16 v[224:225], v231 offset:3072
	ds_read_b64_tr_b16 v[226:227], v231 offset:3584
	v_mfma_f32_32x32x16_bf16 v[32:47], v[120:123], v[52:55], v[32:47]
	v_mfma_f32_32x32x16_bf16 v[32:47], v[124:127], v[56:59], v[32:47]
	v_mfma_f32_32x32x16_bf16 v[32:47], v[128:131], v[60:63], v[32:47]
	s_nop 11
	v_exp_f32_e32 v32, v32
	v_exp_f32_e32 v33, v33
	v_exp_f32_e32 v34, v34
	v_exp_f32_e32 v35, v35
	v_exp_f32_e32 v36, v36
	v_exp_f32_e32 v37, v37
	v_exp_f32_e32 v38, v38
	v_exp_f32_e32 v39, v39
	v_exp_f32_e32 v40, v40
	v_exp_f32_e32 v41, v41
	v_exp_f32_e32 v42, v42
	v_exp_f32_e32 v43, v43
	v_exp_f32_e32 v44, v44
	v_exp_f32_e32 v45, v45
	v_exp_f32_e32 v46, v46
	v_exp_f32_e32 v47, v47
	s_add_i32 s90, s76, 416
	v_add_u32_e32 v84, s90, v107
	v_add_u32_e32 v85, 0, v84
	v_add_u32_e32 v86, 1, v84
	v_add_u32_e32 v87, 2, v84
	v_add_u32_e32 v88, 3, v84
	v_cmp_gt_u32_e64 s[30:31], s98, v85
	v_cmp_gt_u32_e64 s[36:37], s98, v86
	v_cmp_gt_u32_e64 s[78:79], s98, v87
	v_cmp_gt_u32_e64 s[50:51], s98, v88
	v_cndmask_b32_e64 v32, 0, v32, s[30:31]
	v_add_u32_e32 v85, 8, v84
	v_cmp_gt_u32_e64 s[30:31], s98, v85
	v_cndmask_b32_e64 v33, 0, v33, s[36:37]
	v_add_u32_e32 v86, 9, v84
	v_cmp_gt_u32_e64 s[36:37], s98, v86
	v_cndmask_b32_e64 v34, 0, v34, s[78:79]
	v_add_u32_e32 v87, 10, v84
	v_cmp_gt_u32_e64 s[78:79], s98, v87
	v_cndmask_b32_e64 v35, 0, v35, s[50:51]
	v_add_u32_e32 v88, 11, v84
	v_cmp_gt_u32_e64 s[50:51], s98, v88
	v_cndmask_b32_e64 v36, 0, v36, s[30:31]
	v_add_u32_e32 v85, 16, v84
	v_cmp_gt_u32_e64 s[30:31], s98, v85
	v_cndmask_b32_e64 v37, 0, v37, s[36:37]
	v_add_u32_e32 v86, 17, v84
	v_cmp_gt_u32_e64 s[36:37], s98, v86
	v_cndmask_b32_e64 v38, 0, v38, s[78:79]
	v_add_u32_e32 v87, 18, v84
	v_cmp_gt_u32_e64 s[78:79], s98, v87
	v_cndmask_b32_e64 v39, 0, v39, s[50:51]
	v_add_u32_e32 v88, 19, v84
	v_cmp_gt_u32_e64 s[50:51], s98, v88
	v_cndmask_b32_e64 v40, 0, v40, s[30:31]
	v_add_u32_e32 v85, 24, v84
	v_cmp_gt_u32_e64 s[30:31], s98, v85
	v_cndmask_b32_e64 v41, 0, v41, s[36:37]
	v_add_u32_e32 v86, 25, v84
	v_cmp_gt_u32_e64 s[36:37], s98, v86
	v_cndmask_b32_e64 v42, 0, v42, s[78:79]
	v_add_u32_e32 v87, 26, v84
	v_cmp_gt_u32_e64 s[78:79], s98, v87
	v_cndmask_b32_e64 v43, 0, v43, s[50:51]
	v_add_u32_e32 v88, 27, v84
	v_cmp_gt_u32_e64 s[50:51], s98, v88
	v_nop
	v_cndmask_b32_e64 v44, 0, v44, s[30:31]
	v_cndmask_b32_e64 v45, 0, v45, s[36:37]
	v_cndmask_b32_e64 v46, 0, v46, s[78:79]
	v_cndmask_b32_e64 v47, 0, v47, s[50:51]
	v_cvt_pk_bf16_f32 v64, v32, v33
	v_cvt_pk_bf16_f32 v65, v34, v35
	v_cvt_pk_bf16_f32 v66, v36, v37
	v_cvt_pk_bf16_f32 v67, v38, v39
	v_cvt_pk_bf16_f32 v68, v40, v41
	v_cvt_pk_bf16_f32 v69, v42, v43
	v_cvt_pk_bf16_f32 v70, v44, v45
	v_cvt_pk_bf16_f32 v71, v46, v47
	v_pk_add_f32 v[232:233], v[232:233], v[32:33]
	v_pk_add_f32 v[232:233], v[232:233], v[34:35]
	v_pk_add_f32 v[232:233], v[232:233], v[36:37]
	v_pk_add_f32 v[232:233], v[232:233], v[38:39]
	v_pk_add_f32 v[232:233], v[232:233], v[40:41]
	v_pk_add_f32 v[232:233], v[232:233], v[42:43]
	v_pk_add_f32 v[232:233], v[232:233], v[44:45]
	v_pk_add_f32 v[232:233], v[232:233], v[46:47]
	s_waitcnt lgkmcnt(0)
	v_mfma_f32_32x32x16_bf16 v[0:15], v[64:67], v[72:75], v[0:15]
	v_mfma_f32_32x32x16_bf16 v[16:31], v[64:67], v[76:79], v[16:31]
	v_mfma_f32_32x32x16_bf16 v[0:15], v[68:71], v[220:223], v[0:15]
	v_mfma_f32_32x32x16_bf16 v[16:31], v[68:71], v[224:227], v[16:31]
	s_add_i32 s90, s76, 512
	v_add_u32_e32 v80, s90, v235
	v_add_u32_e32 v83, s90, v236
	v_add_u32_e32 v99, s90, v237
	v_add_u32_e32 v253, s90, v238
	v_add_u32_e32 v254, s90, v100
	v_add_u32_e32 v255, s90, v149
	v_med3_i32 v80, v80, 0, s99
	v_med3_i32 v83, v83, 0, s99
	v_med3_i32 v99, v99, 0, s99
	v_med3_i32 v253, v253, 0, s99
	v_med3_i32 v254, v254, 0, s99
	v_med3_i32 v255, v255, 0, s99
	v_mad_u32_u24 v80, v80, s100, v252
	v_mad_u32_u24 v83, v83, s100, v252
	v_mad_u32_u24 v99, v99, s100, v252
	v_mad_u32_u24 v253, v253, s100, v252
	v_mad_u32_u24 v254, v254, s100, v153
	v_mad_u32_u24 v255, v255, s100, v153
	global_load_dwordx4 v[116:119], v80, s[82:83]
	global_load_dwordx4 v[120:123], v83, s[82:83]
	global_load_dwordx4 v[124:127], v99, s[82:83]
	global_load_dwordx4 v[128:131], v253, s[82:83]
	global_load_dwordx4 v[132:135], v254, s[82:83] offset:768
	global_load_dwordx4 v[136:139], v255, s[82:83] offset:768
	global_load_dwordx4 v[140:143], v254, s[82:83] offset:832
	global_load_dwordx4 v[144:147], v255, s[82:83] offset:832
	s_waitcnt vmcnt(16)
	ds_write_b128 v247, v[156:159]
	ds_write_b128 v247, v[160:163] offset:1024
	ds_write_b128 v247, v[164:167] offset:2048
	ds_write_b128 v247, v[168:171] offset:3072
	ds_read_b128 v[156:159], v248
	ds_read_b128 v[160:163], v249
	ds_read_b128 v[164:167], v250
	ds_read_b128 v[168:171], v251
	ds_write_b128 v112, v[172:175]
	ds_write_b128 v112, v[176:179] offset:1024
	ds_write_b128 v112, v[180:183] offset:2048
	ds_write_b128 v112, v[184:187] offset:3072
	ds_read2_b32 v[32:33], v115 offset0:68 offset1:69
	ds_read2_b32 v[34:35], v115 offset0:70 offset1:71
	ds_read2_b32 v[36:37], v115 offset0:76 offset1:77
	ds_read2_b32 v[38:39], v115 offset0:78 offset1:79
	ds_read2_b32 v[40:41], v115 offset0:85 offset1:86
	ds_read2_b32 v[42:43], v115 offset0:87 offset1:88
	ds_read2_b32 v[44:45], v115 offset0:93 offset1:94
	ds_read2_b32 v[46:47], v115 offset0:95 offset1:96
	s_waitcnt lgkmcnt(0)
	v_mfma_f32_32x32x16_bf16 v[32:47], v[156:159], v[48:51], v[32:47]
	ds_read_b64_tr_b16 v[72:73], v231
	ds_read_b64_tr_b16 v[74:75], v231 offset:512
	ds_read_b64_tr_b16 v[76:77], v231 offset:2048
	ds_read_b64_tr_b16 v[78:79], v231 offset:2560
	ds_read_b64_tr_b16 v[220:221], v231 offset:1024
	ds_read_b64_tr_b16 v[222:223], v231 offset:1536
	ds_read_b64_tr_b16 v[224:225], v231 offset:3072
	ds_read_b64_tr_b16 v[226:227], v231 offset:3584
	v_mfma_f32_32x32x16_bf16 v[32:47], v[160:163], v[52:55], v[32:47]
	v_mfma_f32_32x32x16_bf16 v[32:47], v[164:167], v[56:59], v[32:47]
	v_mfma_f32_32x32x16_bf16 v[32:47], v[168:171], v[60:63], v[32:47]
	s_nop 11
	v_exp_f32_e32 v32, v32
	v_exp_f32_e32 v33, v33
	v_exp_f32_e32 v34, v34
	v_exp_f32_e32 v35, v35
	v_exp_f32_e32 v36, v36
	v_exp_f32_e32 v37, v37
	v_exp_f32_e32 v38, v38
	v_exp_f32_e32 v39, v39
	v_exp_f32_e32 v40, v40
	v_exp_f32_e32 v41, v41
	v_exp_f32_e32 v42, v42
	v_exp_f32_e32 v43, v43
	v_exp_f32_e32 v44, v44
	v_exp_f32_e32 v45, v45
	v_exp_f32_e32 v46, v46
	v_exp_f32_e32 v47, v47
	s_add_i32 s90, s76, 448
	v_add_u32_e32 v84, s90, v107
	v_add_u32_e32 v85, 0, v84
	v_add_u32_e32 v86, 1, v84
	v_add_u32_e32 v87, 2, v84
	v_add_u32_e32 v88, 3, v84
	v_cmp_gt_u32_e64 s[30:31], s98, v85
	v_cmp_gt_u32_e64 s[36:37], s98, v86
	v_cmp_gt_u32_e64 s[78:79], s98, v87
	v_cmp_gt_u32_e64 s[50:51], s98, v88
	v_cndmask_b32_e64 v32, 0, v32, s[30:31]
	v_add_u32_e32 v85, 8, v84
	v_cmp_gt_u32_e64 s[30:31], s98, v85
	v_cndmask_b32_e64 v33, 0, v33, s[36:37]
	v_add_u32_e32 v86, 9, v84
	v_cmp_gt_u32_e64 s[36:37], s98, v86
	v_cndmask_b32_e64 v34, 0, v34, s[78:79]
	v_add_u32_e32 v87, 10, v84
	v_cmp_gt_u32_e64 s[78:79], s98, v87
	v_cndmask_b32_e64 v35, 0, v35, s[50:51]
	v_add_u32_e32 v88, 11, v84
	v_cmp_gt_u32_e64 s[50:51], s98, v88
	v_cndmask_b32_e64 v36, 0, v36, s[30:31]
	v_add_u32_e32 v85, 16, v84
	v_cmp_gt_u32_e64 s[30:31], s98, v85
	v_cndmask_b32_e64 v37, 0, v37, s[36:37]
	v_add_u32_e32 v86, 17, v84
	v_cmp_gt_u32_e64 s[36:37], s98, v86
	v_cndmask_b32_e64 v38, 0, v38, s[78:79]
	v_add_u32_e32 v87, 18, v84
	v_cmp_gt_u32_e64 s[78:79], s98, v87
	v_cndmask_b32_e64 v39, 0, v39, s[50:51]
	v_add_u32_e32 v88, 19, v84
	v_cmp_gt_u32_e64 s[50:51], s98, v88
	v_cndmask_b32_e64 v40, 0, v40, s[30:31]
	v_add_u32_e32 v85, 24, v84
	v_cmp_gt_u32_e64 s[30:31], s98, v85
	v_cndmask_b32_e64 v41, 0, v41, s[36:37]
	v_add_u32_e32 v86, 25, v84
	v_cmp_gt_u32_e64 s[36:37], s98, v86
	v_cndmask_b32_e64 v42, 0, v42, s[78:79]
	v_add_u32_e32 v87, 26, v84
	v_cmp_gt_u32_e64 s[78:79], s98, v87
	v_cndmask_b32_e64 v43, 0, v43, s[50:51]
	v_add_u32_e32 v88, 27, v84
	v_cmp_gt_u32_e64 s[50:51], s98, v88
	v_nop
	v_cndmask_b32_e64 v44, 0, v44, s[30:31]
	v_cndmask_b32_e64 v45, 0, v45, s[36:37]
	v_cndmask_b32_e64 v46, 0, v46, s[78:79]
	v_cndmask_b32_e64 v47, 0, v47, s[50:51]
	v_cvt_pk_bf16_f32 v64, v32, v33
	v_cvt_pk_bf16_f32 v65, v34, v35
	v_cvt_pk_bf16_f32 v66, v36, v37
	v_cvt_pk_bf16_f32 v67, v38, v39
	v_cvt_pk_bf16_f32 v68, v40, v41
	v_cvt_pk_bf16_f32 v69, v42, v43
	v_cvt_pk_bf16_f32 v70, v44, v45
	v_cvt_pk_bf16_f32 v71, v46, v47
	v_pk_add_f32 v[232:233], v[232:233], v[32:33]
	v_pk_add_f32 v[232:233], v[232:233], v[34:35]
	v_pk_add_f32 v[232:233], v[232:233], v[36:37]
	v_pk_add_f32 v[232:233], v[232:233], v[38:39]
	v_pk_add_f32 v[232:233], v[232:233], v[40:41]
	v_pk_add_f32 v[232:233], v[232:233], v[42:43]
	v_pk_add_f32 v[232:233], v[232:233], v[44:45]
	v_pk_add_f32 v[232:233], v[232:233], v[46:47]
	s_waitcnt lgkmcnt(0)
	v_mfma_f32_32x32x16_bf16 v[0:15], v[64:67], v[72:75], v[0:15]
	v_mfma_f32_32x32x16_bf16 v[16:31], v[64:67], v[76:79], v[16:31]
	v_mfma_f32_32x32x16_bf16 v[0:15], v[68:71], v[220:223], v[0:15]
	v_mfma_f32_32x32x16_bf16 v[16:31], v[68:71], v[224:227], v[16:31]
	s_add_i32 s90, s76, 544
	v_add_u32_e32 v80, s90, v235
	v_add_u32_e32 v83, s90, v236
	v_add_u32_e32 v99, s90, v237
	v_add_u32_e32 v253, s90, v238
	v_add_u32_e32 v254, s90, v100
	v_add_u32_e32 v255, s90, v149
	v_med3_i32 v80, v80, 0, s99
	v_med3_i32 v83, v83, 0, s99
	v_med3_i32 v99, v99, 0, s99
	v_med3_i32 v253, v253, 0, s99
	v_med3_i32 v254, v254, 0, s99
	v_med3_i32 v255, v255, 0, s99
	v_mad_u32_u24 v80, v80, s100, v252
	v_mad_u32_u24 v83, v83, s100, v252
	v_mad_u32_u24 v99, v99, s100, v252
	v_mad_u32_u24 v253, v253, s100, v252
	v_mad_u32_u24 v254, v254, s100, v153
	v_mad_u32_u24 v255, v255, s100, v153
	global_load_dwordx4 v[156:159], v80, s[82:83]
	global_load_dwordx4 v[160:163], v83, s[82:83]
	global_load_dwordx4 v[164:167], v99, s[82:83]
	global_load_dwordx4 v[168:171], v253, s[82:83]
	global_load_dwordx4 v[172:175], v254, s[82:83] offset:768
	global_load_dwordx4 v[176:179], v255, s[82:83] offset:768
	global_load_dwordx4 v[180:183], v254, s[82:83] offset:832
	global_load_dwordx4 v[184:187], v255, s[82:83] offset:832
	s_waitcnt vmcnt(16)
	ds_write_b128 v247, v[188:191]
	ds_write_b128 v247, v[192:195] offset:1024
	ds_write_b128 v247, v[196:199] offset:2048
	ds_write_b128 v247, v[200:203] offset:3072
	ds_read_b128 v[188:191], v248
	ds_read_b128 v[192:195], v249
	ds_read_b128 v[196:199], v250
	ds_read_b128 v[200:203], v251
	ds_write_b128 v112, v[204:207]
	ds_write_b128 v112, v[208:211] offset:1024
	ds_write_b128 v112, v[212:215] offset:2048
	ds_write_b128 v112, v[216:219] offset:3072
	ds_read2_b32 v[32:33], v115 offset0:102 offset1:103
	ds_read2_b32 v[34:35], v115 offset0:104 offset1:105
	ds_read2_b32 v[36:37], v115 offset0:110 offset1:111
	ds_read2_b32 v[38:39], v115 offset0:112 offset1:113
	ds_read2_b32 v[40:41], v115 offset0:119 offset1:120
	ds_read2_b32 v[42:43], v115 offset0:121 offset1:122
	ds_read2_b32 v[44:45], v115 offset0:127 offset1:128
	ds_read2_b32 v[46:47], v115 offset0:129 offset1:130
	s_waitcnt lgkmcnt(0)
	v_mfma_f32_32x32x16_bf16 v[32:47], v[188:191], v[48:51], v[32:47]
	ds_read_b64_tr_b16 v[72:73], v231
	ds_read_b64_tr_b16 v[74:75], v231 offset:512
	ds_read_b64_tr_b16 v[76:77], v231 offset:2048
	ds_read_b64_tr_b16 v[78:79], v231 offset:2560
	ds_read_b64_tr_b16 v[220:221], v231 offset:1024
	ds_read_b64_tr_b16 v[222:223], v231 offset:1536
	ds_read_b64_tr_b16 v[224:225], v231 offset:3072
	ds_read_b64_tr_b16 v[226:227], v231 offset:3584
	v_mfma_f32_32x32x16_bf16 v[32:47], v[192:195], v[52:55], v[32:47]
	v_mfma_f32_32x32x16_bf16 v[32:47], v[196:199], v[56:59], v[32:47]
	v_mfma_f32_32x32x16_bf16 v[32:47], v[200:203], v[60:63], v[32:47]
	s_nop 11
	v_exp_f32_e32 v32, v32
	v_exp_f32_e32 v33, v33
	v_exp_f32_e32 v34, v34
	v_exp_f32_e32 v35, v35
	v_exp_f32_e32 v36, v36
	v_exp_f32_e32 v37, v37
	v_exp_f32_e32 v38, v38
	v_exp_f32_e32 v39, v39
	v_exp_f32_e32 v40, v40
	v_exp_f32_e32 v41, v41
	v_exp_f32_e32 v42, v42
	v_exp_f32_e32 v43, v43
	v_exp_f32_e32 v44, v44
	v_exp_f32_e32 v45, v45
	v_exp_f32_e32 v46, v46
	v_exp_f32_e32 v47, v47
	s_add_i32 s90, s76, 480
	v_add_u32_e32 v84, s90, v107
	v_add_u32_e32 v85, 0, v84
	v_add_u32_e32 v86, 1, v84
	v_add_u32_e32 v87, 2, v84
	v_add_u32_e32 v88, 3, v84
	v_cmp_gt_u32_e64 s[30:31], s98, v85
	v_cmp_gt_u32_e64 s[36:37], s98, v86
	v_cmp_gt_u32_e64 s[78:79], s98, v87
	v_cmp_gt_u32_e64 s[50:51], s98, v88
	v_cndmask_b32_e64 v32, 0, v32, s[30:31]
	v_add_u32_e32 v85, 8, v84
	v_cmp_gt_u32_e64 s[30:31], s98, v85
	v_cndmask_b32_e64 v33, 0, v33, s[36:37]
	v_add_u32_e32 v86, 9, v84
	v_cmp_gt_u32_e64 s[36:37], s98, v86
	v_cndmask_b32_e64 v34, 0, v34, s[78:79]
	v_add_u32_e32 v87, 10, v84
	v_cmp_gt_u32_e64 s[78:79], s98, v87
	v_cndmask_b32_e64 v35, 0, v35, s[50:51]
	v_add_u32_e32 v88, 11, v84
	v_cmp_gt_u32_e64 s[50:51], s98, v88
	v_cndmask_b32_e64 v36, 0, v36, s[30:31]
	v_add_u32_e32 v85, 16, v84
	v_cmp_gt_u32_e64 s[30:31], s98, v85
	v_cndmask_b32_e64 v37, 0, v37, s[36:37]
	v_add_u32_e32 v86, 17, v84
	v_cmp_gt_u32_e64 s[36:37], s98, v86
	v_cndmask_b32_e64 v38, 0, v38, s[78:79]
	v_add_u32_e32 v87, 18, v84
	v_cmp_gt_u32_e64 s[78:79], s98, v87
	v_cndmask_b32_e64 v39, 0, v39, s[50:51]
	v_add_u32_e32 v88, 19, v84
	v_cmp_gt_u32_e64 s[50:51], s98, v88
	v_cndmask_b32_e64 v40, 0, v40, s[30:31]
	v_add_u32_e32 v85, 24, v84
	v_cmp_gt_u32_e64 s[30:31], s98, v85
	v_cndmask_b32_e64 v41, 0, v41, s[36:37]
	v_add_u32_e32 v86, 25, v84
	v_cmp_gt_u32_e64 s[36:37], s98, v86
	v_cndmask_b32_e64 v42, 0, v42, s[78:79]
	v_add_u32_e32 v87, 26, v84
	v_cmp_gt_u32_e64 s[78:79], s98, v87
	v_cndmask_b32_e64 v43, 0, v43, s[50:51]
	v_add_u32_e32 v88, 27, v84
	v_cmp_gt_u32_e64 s[50:51], s98, v88
	v_nop
	v_cndmask_b32_e64 v44, 0, v44, s[30:31]
	v_cndmask_b32_e64 v45, 0, v45, s[36:37]
	v_cndmask_b32_e64 v46, 0, v46, s[78:79]
	v_cndmask_b32_e64 v47, 0, v47, s[50:51]
	v_cvt_pk_bf16_f32 v64, v32, v33
	v_cvt_pk_bf16_f32 v65, v34, v35
	v_cvt_pk_bf16_f32 v66, v36, v37
	v_cvt_pk_bf16_f32 v67, v38, v39
	v_cvt_pk_bf16_f32 v68, v40, v41
	v_cvt_pk_bf16_f32 v69, v42, v43
	v_cvt_pk_bf16_f32 v70, v44, v45
	v_cvt_pk_bf16_f32 v71, v46, v47
	v_pk_add_f32 v[232:233], v[232:233], v[32:33]
	v_pk_add_f32 v[232:233], v[232:233], v[34:35]
	v_pk_add_f32 v[232:233], v[232:233], v[36:37]
	v_pk_add_f32 v[232:233], v[232:233], v[38:39]
	v_pk_add_f32 v[232:233], v[232:233], v[40:41]
	v_pk_add_f32 v[232:233], v[232:233], v[42:43]
	v_pk_add_f32 v[232:233], v[232:233], v[44:45]
	v_pk_add_f32 v[232:233], v[232:233], v[46:47]
	s_waitcnt lgkmcnt(0)
	v_mfma_f32_32x32x16_bf16 v[0:15], v[64:67], v[72:75], v[0:15]
	v_mfma_f32_32x32x16_bf16 v[16:31], v[64:67], v[76:79], v[16:31]
	v_mfma_f32_32x32x16_bf16 v[0:15], v[68:71], v[220:223], v[0:15]
	v_mfma_f32_32x32x16_bf16 v[16:31], v[68:71], v[224:227], v[16:31]
	s_add_i32 s90, s76, -256
	v_add_u32_e32 v80, s90, v239
	v_add_u32_e32 v83, s90, v240
	v_add_u32_e32 v99, s90, v241
	v_add_u32_e32 v253, s90, v242
	v_add_u32_e32 v254, s90, v101
	v_add_u32_e32 v255, s90, v150
	v_med3_i32 v80, v80, 0, s99
	v_med3_i32 v83, v83, 0, s99
	v_med3_i32 v99, v99, 0, s99
	v_med3_i32 v253, v253, 0, s99
	v_med3_i32 v254, v254, 0, s99
	v_med3_i32 v255, v255, 0, s99
	v_mad_u32_u24 v80, v80, s100, v252
	v_mad_u32_u24 v83, v83, s100, v252
	v_mad_u32_u24 v99, v99, s100, v252
	v_mad_u32_u24 v253, v253, s100, v252
	v_mad_u32_u24 v254, v254, s100, v153
	v_mad_u32_u24 v255, v255, s100, v153
	global_load_dwordx4 v[188:191], v80, s[82:83]
	global_load_dwordx4 v[192:195], v83, s[82:83]
	global_load_dwordx4 v[196:199], v99, s[82:83]
	global_load_dwordx4 v[200:203], v253, s[82:83]
	global_load_dwordx4 v[204:207], v254, s[82:83] offset:768
	global_load_dwordx4 v[208:211], v255, s[82:83] offset:768
	global_load_dwordx4 v[212:215], v254, s[82:83] offset:832
	global_load_dwordx4 v[216:219], v255, s[82:83] offset:832
	s_waitcnt vmcnt(16)
	ds_write_b128 v247, v[116:119]
	ds_write_b128 v247, v[120:123] offset:1024
	ds_write_b128 v247, v[124:127] offset:2048
	ds_write_b128 v247, v[128:131] offset:3072
	ds_read_b128 v[116:119], v248
	ds_read_b128 v[120:123], v249
	ds_read_b128 v[124:127], v250
	ds_read_b128 v[128:131], v251
	ds_write_b128 v112, v[132:135]
	ds_write_b128 v112, v[136:139] offset:1024
	ds_write_b128 v112, v[140:143] offset:2048
	ds_write_b128 v112, v[144:147] offset:3072
	ds_read2_b32 v[32:33], v115 offset0:136 offset1:137
	ds_read2_b32 v[34:35], v115 offset0:138 offset1:139
	ds_read2_b32 v[36:37], v115 offset0:144 offset1:145
	ds_read2_b32 v[38:39], v115 offset0:146 offset1:147
	ds_read2_b32 v[40:41], v115 offset0:153 offset1:154
	ds_read2_b32 v[42:43], v115 offset0:155 offset1:156
	ds_read2_b32 v[44:45], v115 offset0:161 offset1:162
	ds_read2_b32 v[46:47], v115 offset0:163 offset1:164
	s_waitcnt lgkmcnt(0)
	v_mfma_f32_32x32x16_bf16 v[32:47], v[116:119], v[48:51], v[32:47]
	ds_read_b64_tr_b16 v[72:73], v231
	ds_read_b64_tr_b16 v[74:75], v231 offset:512
	ds_read_b64_tr_b16 v[76:77], v231 offset:2048
	ds_read_b64_tr_b16 v[78:79], v231 offset:2560
	ds_read_b64_tr_b16 v[220:221], v231 offset:1024
	ds_read_b64_tr_b16 v[222:223], v231 offset:1536
	ds_read_b64_tr_b16 v[224:225], v231 offset:3072
	ds_read_b64_tr_b16 v[226:227], v231 offset:3584
	v_mfma_f32_32x32x16_bf16 v[32:47], v[120:123], v[52:55], v[32:47]
	v_mfma_f32_32x32x16_bf16 v[32:47], v[124:127], v[56:59], v[32:47]
	v_mfma_f32_32x32x16_bf16 v[32:47], v[128:131], v[60:63], v[32:47]
	s_nop 11
	v_exp_f32_e32 v32, v32
	v_exp_f32_e32 v33, v33
	v_exp_f32_e32 v34, v34
	v_exp_f32_e32 v35, v35
	v_exp_f32_e32 v36, v36
	v_exp_f32_e32 v37, v37
	v_exp_f32_e32 v38, v38
	v_exp_f32_e32 v39, v39
	v_exp_f32_e32 v40, v40
	v_exp_f32_e32 v41, v41
	v_exp_f32_e32 v42, v42
	v_exp_f32_e32 v43, v43
	v_exp_f32_e32 v44, v44
	v_exp_f32_e32 v45, v45
	v_exp_f32_e32 v46, v46
	v_exp_f32_e32 v47, v47
	s_add_i32 s90, s76, 512
	v_add_u32_e32 v84, s90, v107
	v_add_u32_e32 v85, 0, v84
	v_add_u32_e32 v86, 1, v84
	v_add_u32_e32 v87, 2, v84
	v_add_u32_e32 v88, 3, v84
	v_cmp_gt_u32_e64 s[30:31], s98, v85
	v_cmp_gt_u32_e64 s[36:37], s98, v86
	v_cmp_gt_u32_e64 s[78:79], s98, v87
	v_cmp_gt_u32_e64 s[50:51], s98, v88
	v_cndmask_b32_e64 v32, 0, v32, s[30:31]
	v_add_u32_e32 v85, 8, v84
	v_cmp_gt_u32_e64 s[30:31], s98, v85
	v_cndmask_b32_e64 v33, 0, v33, s[36:37]
	v_add_u32_e32 v86, 9, v84
	v_cmp_gt_u32_e64 s[36:37], s98, v86
	v_cndmask_b32_e64 v34, 0, v34, s[78:79]
	v_add_u32_e32 v87, 10, v84
	v_cmp_gt_u32_e64 s[78:79], s98, v87
	v_cndmask_b32_e64 v35, 0, v35, s[50:51]
	v_add_u32_e32 v88, 11, v84
	v_cmp_gt_u32_e64 s[50:51], s98, v88
	v_cndmask_b32_e64 v36, 0, v36, s[30:31]
	v_add_u32_e32 v85, 16, v84
	v_cmp_gt_u32_e64 s[30:31], s98, v85
	v_cndmask_b32_e64 v37, 0, v37, s[36:37]
	v_add_u32_e32 v86, 17, v84
	v_cmp_gt_u32_e64 s[36:37], s98, v86
	v_cndmask_b32_e64 v38, 0, v38, s[78:79]
	v_add_u32_e32 v87, 18, v84
	v_cmp_gt_u32_e64 s[78:79], s98, v87
	v_cndmask_b32_e64 v39, 0, v39, s[50:51]
	v_add_u32_e32 v88, 19, v84
	v_cmp_gt_u32_e64 s[50:51], s98, v88
	v_cndmask_b32_e64 v40, 0, v40, s[30:31]
	v_add_u32_e32 v85, 24, v84
	v_cmp_gt_u32_e64 s[30:31], s98, v85
	v_cndmask_b32_e64 v41, 0, v41, s[36:37]
	v_add_u32_e32 v86, 25, v84
	v_cmp_gt_u32_e64 s[36:37], s98, v86
	v_cndmask_b32_e64 v42, 0, v42, s[78:79]
	v_add_u32_e32 v87, 26, v84
	v_cmp_gt_u32_e64 s[78:79], s98, v87
	v_cndmask_b32_e64 v43, 0, v43, s[50:51]
	v_add_u32_e32 v88, 27, v84
	v_cmp_gt_u32_e64 s[50:51], s98, v88
	v_nop
	v_cndmask_b32_e64 v44, 0, v44, s[30:31]
	v_cndmask_b32_e64 v45, 0, v45, s[36:37]
	v_cndmask_b32_e64 v46, 0, v46, s[78:79]
	v_cndmask_b32_e64 v47, 0, v47, s[50:51]
	v_cvt_pk_bf16_f32 v64, v32, v33
	v_cvt_pk_bf16_f32 v65, v34, v35
	v_cvt_pk_bf16_f32 v66, v36, v37
	v_cvt_pk_bf16_f32 v67, v38, v39
	v_cvt_pk_bf16_f32 v68, v40, v41
	v_cvt_pk_bf16_f32 v69, v42, v43
	v_cvt_pk_bf16_f32 v70, v44, v45
	v_cvt_pk_bf16_f32 v71, v46, v47
	v_pk_add_f32 v[232:233], v[232:233], v[32:33]
	v_pk_add_f32 v[232:233], v[232:233], v[34:35]
	v_pk_add_f32 v[232:233], v[232:233], v[36:37]
	v_pk_add_f32 v[232:233], v[232:233], v[38:39]
	v_pk_add_f32 v[232:233], v[232:233], v[40:41]
	v_pk_add_f32 v[232:233], v[232:233], v[42:43]
	v_pk_add_f32 v[232:233], v[232:233], v[44:45]
	v_pk_add_f32 v[232:233], v[232:233], v[46:47]
	s_waitcnt lgkmcnt(0)
	v_mfma_f32_32x32x16_bf16 v[0:15], v[64:67], v[72:75], v[0:15]
	v_mfma_f32_32x32x16_bf16 v[16:31], v[64:67], v[76:79], v[16:31]
	v_mfma_f32_32x32x16_bf16 v[0:15], v[68:71], v[220:223], v[0:15]
	v_mfma_f32_32x32x16_bf16 v[16:31], v[68:71], v[224:227], v[16:31]
	s_add_i32 s90, s76, -128
	v_add_u32_e32 v80, s90, v239
	v_add_u32_e32 v83, s90, v240
	v_add_u32_e32 v99, s90, v241
	v_add_u32_e32 v253, s90, v242
	v_add_u32_e32 v254, s90, v101
	v_add_u32_e32 v255, s90, v150
	v_med3_i32 v80, v80, 0, s99
	v_med3_i32 v83, v83, 0, s99
	v_med3_i32 v99, v99, 0, s99
	v_med3_i32 v253, v253, 0, s99
	v_med3_i32 v254, v254, 0, s99
	v_med3_i32 v255, v255, 0, s99
	v_mad_u32_u24 v80, v80, s100, v252
	v_mad_u32_u24 v83, v83, s100, v252
	v_mad_u32_u24 v99, v99, s100, v252
	v_mad_u32_u24 v253, v253, s100, v252
	v_mad_u32_u24 v254, v254, s100, v153
	v_mad_u32_u24 v255, v255, s100, v153
	global_load_dwordx4 v[116:119], v80, s[82:83]
	global_load_dwordx4 v[120:123], v83, s[82:83]
	global_load_dwordx4 v[124:127], v99, s[82:83]
	global_load_dwordx4 v[128:131], v253, s[82:83]
	global_load_dwordx4 v[132:135], v254, s[82:83] offset:768
	global_load_dwordx4 v[136:139], v255, s[82:83] offset:768
	global_load_dwordx4 v[140:143], v254, s[82:83] offset:832
	global_load_dwordx4 v[144:147], v255, s[82:83] offset:832
	s_waitcnt vmcnt(16)
	ds_write_b128 v247, v[156:159]
	ds_write_b128 v247, v[160:163] offset:1024
	ds_write_b128 v247, v[164:167] offset:2048
	ds_write_b128 v247, v[168:171] offset:3072
	ds_read_b128 v[156:159], v248
	ds_read_b128 v[160:163], v249
	ds_read_b128 v[164:167], v250
	ds_read_b128 v[168:171], v251
	ds_write_b128 v112, v[172:175]
	ds_write_b128 v112, v[176:179] offset:1024
	ds_write_b128 v112, v[180:183] offset:2048
	ds_write_b128 v112, v[184:187] offset:3072
	ds_read2_b32 v[32:33], v115 offset0:170 offset1:171
	ds_read2_b32 v[34:35], v115 offset0:172 offset1:173
	ds_read2_b32 v[36:37], v115 offset0:178 offset1:179
	ds_read2_b32 v[38:39], v115 offset0:180 offset1:181
	ds_read2_b32 v[40:41], v115 offset0:187 offset1:188
	ds_read2_b32 v[42:43], v115 offset0:189 offset1:190
	ds_read2_b32 v[44:45], v115 offset0:195 offset1:196
	ds_read2_b32 v[46:47], v115 offset0:197 offset1:198
	s_waitcnt lgkmcnt(0)
	v_mfma_f32_32x32x16_bf16 v[32:47], v[156:159], v[48:51], v[32:47]
	ds_read_b64_tr_b16 v[72:73], v231
	ds_read_b64_tr_b16 v[74:75], v231 offset:512
	ds_read_b64_tr_b16 v[76:77], v231 offset:2048
	ds_read_b64_tr_b16 v[78:79], v231 offset:2560
	ds_read_b64_tr_b16 v[220:221], v231 offset:1024
	ds_read_b64_tr_b16 v[222:223], v231 offset:1536
	ds_read_b64_tr_b16 v[224:225], v231 offset:3072
	ds_read_b64_tr_b16 v[226:227], v231 offset:3584
	v_mfma_f32_32x32x16_bf16 v[32:47], v[160:163], v[52:55], v[32:47]
	v_mfma_f32_32x32x16_bf16 v[32:47], v[164:167], v[56:59], v[32:47]
	v_mfma_f32_32x32x16_bf16 v[32:47], v[168:171], v[60:63], v[32:47]
	s_nop 11
	v_exp_f32_e32 v32, v32
	v_exp_f32_e32 v33, v33
	v_exp_f32_e32 v34, v34
	v_exp_f32_e32 v35, v35
	v_exp_f32_e32 v36, v36
	v_exp_f32_e32 v37, v37
	v_exp_f32_e32 v38, v38
	v_exp_f32_e32 v39, v39
	v_exp_f32_e32 v40, v40
	v_exp_f32_e32 v41, v41
	v_exp_f32_e32 v42, v42
	v_exp_f32_e32 v43, v43
	v_exp_f32_e32 v44, v44
	v_exp_f32_e32 v45, v45
	v_exp_f32_e32 v46, v46
	v_exp_f32_e32 v47, v47
	s_add_i32 s90, s76, 544
	v_add_u32_e32 v84, s90, v107
	v_add_u32_e32 v85, 0, v84
	v_add_u32_e32 v86, 1, v84
	v_add_u32_e32 v87, 2, v84
	v_add_u32_e32 v88, 3, v84
	v_cmp_gt_u32_e64 s[30:31], s98, v85
	v_cmp_gt_u32_e64 s[36:37], s98, v86
	v_cmp_gt_u32_e64 s[78:79], s98, v87
	v_cmp_gt_u32_e64 s[50:51], s98, v88
	v_cndmask_b32_e64 v32, 0, v32, s[30:31]
	v_add_u32_e32 v85, 8, v84
	v_cmp_gt_u32_e64 s[30:31], s98, v85
	v_cndmask_b32_e64 v33, 0, v33, s[36:37]
	v_add_u32_e32 v86, 9, v84
	v_cmp_gt_u32_e64 s[36:37], s98, v86
	v_cndmask_b32_e64 v34, 0, v34, s[78:79]
	v_add_u32_e32 v87, 10, v84
	v_cmp_gt_u32_e64 s[78:79], s98, v87
	v_cndmask_b32_e64 v35, 0, v35, s[50:51]
	v_add_u32_e32 v88, 11, v84
	v_cmp_gt_u32_e64 s[50:51], s98, v88
	v_cndmask_b32_e64 v36, 0, v36, s[30:31]
	v_add_u32_e32 v85, 16, v84
	v_cmp_gt_u32_e64 s[30:31], s98, v85
	v_cndmask_b32_e64 v37, 0, v37, s[36:37]
	v_add_u32_e32 v86, 17, v84
	v_cmp_gt_u32_e64 s[36:37], s98, v86
	v_cndmask_b32_e64 v38, 0, v38, s[78:79]
	v_add_u32_e32 v87, 18, v84
	v_cmp_gt_u32_e64 s[78:79], s98, v87
	v_cndmask_b32_e64 v39, 0, v39, s[50:51]
	v_add_u32_e32 v88, 19, v84
	v_cmp_gt_u32_e64 s[50:51], s98, v88
	v_cndmask_b32_e64 v40, 0, v40, s[30:31]
	v_add_u32_e32 v85, 24, v84
	v_cmp_gt_u32_e64 s[30:31], s98, v85
	v_cndmask_b32_e64 v41, 0, v41, s[36:37]
	v_add_u32_e32 v86, 25, v84
	v_cmp_gt_u32_e64 s[36:37], s98, v86
	v_cndmask_b32_e64 v42, 0, v42, s[78:79]
	v_add_u32_e32 v87, 26, v84
	v_cmp_gt_u32_e64 s[78:79], s98, v87
	v_cndmask_b32_e64 v43, 0, v43, s[50:51]
	v_add_u32_e32 v88, 27, v84
	v_cmp_gt_u32_e64 s[50:51], s98, v88
	v_nop
	v_cndmask_b32_e64 v44, 0, v44, s[30:31]
	v_cndmask_b32_e64 v45, 0, v45, s[36:37]
	v_cndmask_b32_e64 v46, 0, v46, s[78:79]
	v_cndmask_b32_e64 v47, 0, v47, s[50:51]
	v_cvt_pk_bf16_f32 v64, v32, v33
	v_cvt_pk_bf16_f32 v65, v34, v35
	v_cvt_pk_bf16_f32 v66, v36, v37
	v_cvt_pk_bf16_f32 v67, v38, v39
	v_cvt_pk_bf16_f32 v68, v40, v41
	v_cvt_pk_bf16_f32 v69, v42, v43
	v_cvt_pk_bf16_f32 v70, v44, v45
	v_cvt_pk_bf16_f32 v71, v46, v47
	v_pk_add_f32 v[232:233], v[232:233], v[32:33]
	v_pk_add_f32 v[232:233], v[232:233], v[34:35]
	v_pk_add_f32 v[232:233], v[232:233], v[36:37]
	v_pk_add_f32 v[232:233], v[232:233], v[38:39]
	v_pk_add_f32 v[232:233], v[232:233], v[40:41]
	v_pk_add_f32 v[232:233], v[232:233], v[42:43]
	v_pk_add_f32 v[232:233], v[232:233], v[44:45]
	v_pk_add_f32 v[232:233], v[232:233], v[46:47]
	s_waitcnt lgkmcnt(0)
	v_mfma_f32_32x32x16_bf16 v[0:15], v[64:67], v[72:75], v[0:15]
	v_mfma_f32_32x32x16_bf16 v[16:31], v[64:67], v[76:79], v[16:31]
	v_mfma_f32_32x32x16_bf16 v[0:15], v[68:71], v[220:223], v[0:15]
	v_mfma_f32_32x32x16_bf16 v[16:31], v[68:71], v[224:227], v[16:31]
	s_add_i32 s90, s76, 0
	v_add_u32_e32 v80, s90, v239
	v_add_u32_e32 v83, s90, v240
	v_add_u32_e32 v99, s90, v241
	v_add_u32_e32 v253, s90, v242
	v_add_u32_e32 v254, s90, v101
	v_add_u32_e32 v255, s90, v150
	v_med3_i32 v80, v80, 0, s99
	v_med3_i32 v83, v83, 0, s99
	v_med3_i32 v99, v99, 0, s99
	v_med3_i32 v253, v253, 0, s99
	v_med3_i32 v254, v254, 0, s99
	v_med3_i32 v255, v255, 0, s99
	v_mad_u32_u24 v80, v80, s100, v252
	v_mad_u32_u24 v83, v83, s100, v252
	v_mad_u32_u24 v99, v99, s100, v252
	v_mad_u32_u24 v253, v253, s100, v252
	v_mad_u32_u24 v254, v254, s100, v153
	v_mad_u32_u24 v255, v255, s100, v153
	global_load_dwordx4 v[156:159], v80, s[82:83]
	global_load_dwordx4 v[160:163], v83, s[82:83]
	global_load_dwordx4 v[164:167], v99, s[82:83]
	global_load_dwordx4 v[168:171], v253, s[82:83]
	global_load_dwordx4 v[172:175], v254, s[82:83] offset:768
	global_load_dwordx4 v[176:179], v255, s[82:83] offset:768
	global_load_dwordx4 v[180:183], v254, s[82:83] offset:832
	global_load_dwordx4 v[184:187], v255, s[82:83] offset:832
	s_waitcnt vmcnt(16)
	ds_write_b128 v247, v[188:191]
	ds_write_b128 v247, v[192:195] offset:1024
	ds_write_b128 v247, v[196:199] offset:2048
	ds_write_b128 v247, v[200:203] offset:3072
	ds_read_b128 v[188:191], v248
	ds_read_b128 v[192:195], v249
	ds_read_b128 v[196:199], v250
	ds_read_b128 v[200:203], v251
	ds_write_b128 v112, v[204:207]
	ds_write_b128 v112, v[208:211] offset:1024
	ds_write_b128 v112, v[212:215] offset:2048
	ds_write_b128 v112, v[216:219] offset:3072
	v_mov_b32_e32 v115, v229
	ds_read2_b32 v[32:33], v115 offset0:0 offset1:1
	ds_read2_b32 v[34:35], v115 offset0:2 offset1:3
	ds_read2_b32 v[36:37], v115 offset0:8 offset1:9
	ds_read2_b32 v[38:39], v115 offset0:10 offset1:11
	ds_read2_b32 v[40:41], v115 offset0:16 offset1:17
	ds_read2_b32 v[42:43], v115 offset0:18 offset1:19
	ds_read2_b32 v[44:45], v115 offset0:24 offset1:25
	ds_read2_b32 v[46:47], v115 offset0:26 offset1:27
	s_waitcnt lgkmcnt(0)
	v_mfma_f32_32x32x16_bf16 v[32:47], v[188:191], v[48:51], v[32:47]
	ds_read_b64_tr_b16 v[72:73], v231
	ds_read_b64_tr_b16 v[74:75], v231 offset:512
	ds_read_b64_tr_b16 v[76:77], v231 offset:2048
	ds_read_b64_tr_b16 v[78:79], v231 offset:2560
	ds_read_b64_tr_b16 v[220:221], v231 offset:1024
	ds_read_b64_tr_b16 v[222:223], v231 offset:1536
	ds_read_b64_tr_b16 v[224:225], v231 offset:3072
	ds_read_b64_tr_b16 v[226:227], v231 offset:3584
	v_mfma_f32_32x32x16_bf16 v[32:47], v[192:195], v[52:55], v[32:47]
	v_mfma_f32_32x32x16_bf16 v[32:47], v[196:199], v[56:59], v[32:47]
	v_mfma_f32_32x32x16_bf16 v[32:47], v[200:203], v[60:63], v[32:47]
	s_nop 11
	v_exp_f32_e32 v32, v32
	v_exp_f32_e32 v33, v33
	v_exp_f32_e32 v34, v34
	v_exp_f32_e32 v35, v35
	v_exp_f32_e32 v36, v36
	v_exp_f32_e32 v37, v37
	v_exp_f32_e32 v38, v38
	v_exp_f32_e32 v39, v39
	v_exp_f32_e32 v40, v40
	v_exp_f32_e32 v41, v41
	v_exp_f32_e32 v42, v42
	v_exp_f32_e32 v43, v43
	v_exp_f32_e32 v44, v44
	v_exp_f32_e32 v45, v45
	v_exp_f32_e32 v46, v46
	v_exp_f32_e32 v47, v47
	s_add_i32 s90, s76, -256
	v_lshlrev_b32_e32 v84, 2, v107
	v_add_u32_e32 v84, s90, v84
	v_add_u32_e32 v85, 0, v84
	v_add_u32_e32 v86, 4, v84
	v_add_u32_e32 v87, 8, v84
	v_add_u32_e32 v88, 12, v84
	v_cmp_gt_u32_e64 s[30:31], s98, v85
	v_cmp_gt_u32_e64 s[36:37], s98, v86
	v_cmp_gt_u32_e64 s[78:79], s98, v87
	v_cmp_gt_u32_e64 s[50:51], s98, v88
	v_cndmask_b32_e64 v32, 0, v32, s[30:31]
	v_add_u32_e32 v85, 32, v84
	v_cmp_gt_u32_e64 s[30:31], s98, v85
	v_cndmask_b32_e64 v33, 0, v33, s[36:37]
	v_add_u32_e32 v86, 36, v84
	v_cmp_gt_u32_e64 s[36:37], s98, v86
	v_cndmask_b32_e64 v34, 0, v34, s[78:79]
	v_add_u32_e32 v87, 40, v84
	v_cmp_gt_u32_e64 s[78:79], s98, v87
	v_cndmask_b32_e64 v35, 0, v35, s[50:51]
	v_add_u32_e32 v88, 44, v84
	v_cmp_gt_u32_e64 s[50:51], s98, v88
	v_cndmask_b32_e64 v36, 0, v36, s[30:31]
	v_add_u32_e32 v85, 64, v84
	v_cmp_gt_u32_e64 s[30:31], s98, v85
	v_cndmask_b32_e64 v37, 0, v37, s[36:37]
	v_add_u32_e32 v86, 68, v84
	v_cmp_gt_u32_e64 s[36:37], s98, v86
	v_cndmask_b32_e64 v38, 0, v38, s[78:79]
	v_add_u32_e32 v87, 72, v84
	v_cmp_gt_u32_e64 s[78:79], s98, v87
	v_cndmask_b32_e64 v39, 0, v39, s[50:51]
	v_add_u32_e32 v88, 76, v84
	v_cmp_gt_u32_e64 s[50:51], s98, v88
	v_cndmask_b32_e64 v40, 0, v40, s[30:31]
	v_add_u32_e32 v85, 96, v84
	v_cmp_gt_u32_e64 s[30:31], s98, v85
	v_cndmask_b32_e64 v41, 0, v41, s[36:37]
	v_add_u32_e32 v86, 100, v84
	v_cmp_gt_u32_e64 s[36:37], s98, v86
	v_cndmask_b32_e64 v42, 0, v42, s[78:79]
	v_add_u32_e32 v87, 104, v84
	v_cmp_gt_u32_e64 s[78:79], s98, v87
	v_cndmask_b32_e64 v43, 0, v43, s[50:51]
	v_add_u32_e32 v88, 108, v84
	v_cmp_gt_u32_e64 s[50:51], s98, v88
	v_nop
	v_cndmask_b32_e64 v44, 0, v44, s[30:31]
	v_cndmask_b32_e64 v45, 0, v45, s[36:37]
	v_cndmask_b32_e64 v46, 0, v46, s[78:79]
	v_cndmask_b32_e64 v47, 0, v47, s[50:51]
	v_cvt_pk_bf16_f32 v64, v32, v33
	v_cvt_pk_bf16_f32 v65, v34, v35
	v_cvt_pk_bf16_f32 v66, v36, v37
	v_cvt_pk_bf16_f32 v67, v38, v39
	v_cvt_pk_bf16_f32 v68, v40, v41
	v_cvt_pk_bf16_f32 v69, v42, v43
	v_cvt_pk_bf16_f32 v70, v44, v45
	v_cvt_pk_bf16_f32 v71, v46, v47
	v_pk_add_f32 v[232:233], v[232:233], v[32:33]
	v_pk_add_f32 v[232:233], v[232:233], v[34:35]
	v_pk_add_f32 v[232:233], v[232:233], v[36:37]
	v_pk_add_f32 v[232:233], v[232:233], v[38:39]
	v_pk_add_f32 v[232:233], v[232:233], v[40:41]
	v_pk_add_f32 v[232:233], v[232:233], v[42:43]
	v_pk_add_f32 v[232:233], v[232:233], v[44:45]
	v_pk_add_f32 v[232:233], v[232:233], v[46:47]
	s_waitcnt lgkmcnt(0)
	v_mfma_f32_32x32x16_bf16 v[0:15], v[64:67], v[72:75], v[0:15]
	v_mfma_f32_32x32x16_bf16 v[16:31], v[64:67], v[76:79], v[16:31]
	v_mfma_f32_32x32x16_bf16 v[0:15], v[68:71], v[220:223], v[0:15]
	v_mfma_f32_32x32x16_bf16 v[16:31], v[68:71], v[224:227], v[16:31]
	s_add_i32 s90, s76, 128
	v_add_u32_e32 v80, s90, v239
	v_add_u32_e32 v83, s90, v240
	v_add_u32_e32 v99, s90, v241
	v_add_u32_e32 v253, s90, v242
	v_add_u32_e32 v254, s90, v101
	v_add_u32_e32 v255, s90, v150
	v_med3_i32 v80, v80, 0, s99
	v_med3_i32 v83, v83, 0, s99
	v_med3_i32 v99, v99, 0, s99
	v_med3_i32 v253, v253, 0, s99
	v_med3_i32 v254, v254, 0, s99
	v_med3_i32 v255, v255, 0, s99
	v_mad_u32_u24 v80, v80, s100, v252
	v_mad_u32_u24 v83, v83, s100, v252
	v_mad_u32_u24 v99, v99, s100, v252
	v_mad_u32_u24 v253, v253, s100, v252
	v_mad_u32_u24 v254, v254, s100, v153
	v_mad_u32_u24 v255, v255, s100, v153
	global_load_dwordx4 v[188:191], v80, s[82:83]
	global_load_dwordx4 v[192:195], v83, s[82:83]
	global_load_dwordx4 v[196:199], v99, s[82:83]
	global_load_dwordx4 v[200:203], v253, s[82:83]
	global_load_dwordx4 v[204:207], v254, s[82:83] offset:768
	global_load_dwordx4 v[208:211], v255, s[82:83] offset:768
	global_load_dwordx4 v[212:215], v254, s[82:83] offset:832
	global_load_dwordx4 v[216:219], v255, s[82:83] offset:832
	s_waitcnt vmcnt(16)
	ds_write_b128 v247, v[116:119]
	ds_write_b128 v247, v[120:123] offset:1024
	ds_write_b128 v247, v[124:127] offset:2048
	ds_write_b128 v247, v[128:131] offset:3072
	ds_read_b128 v[116:119], v248
	ds_read_b128 v[120:123], v249
	ds_read_b128 v[124:127], v250
	ds_read_b128 v[128:131], v251
	ds_write_b128 v112, v[132:135]
	ds_write_b128 v112, v[136:139] offset:1024
	ds_write_b128 v112, v[140:143] offset:2048
	ds_write_b128 v112, v[144:147] offset:3072
	ds_read2_b32 v[32:33], v115 offset0:32 offset1:33
	ds_read2_b32 v[34:35], v115 offset0:34 offset1:35
	ds_read2_b32 v[36:37], v115 offset0:40 offset1:41
	ds_read2_b32 v[38:39], v115 offset0:42 offset1:43
	ds_read2_b32 v[40:41], v115 offset0:48 offset1:49
	ds_read2_b32 v[42:43], v115 offset0:50 offset1:51
	ds_read2_b32 v[44:45], v115 offset0:56 offset1:57
	ds_read2_b32 v[46:47], v115 offset0:58 offset1:59
	s_waitcnt lgkmcnt(0)
	v_mfma_f32_32x32x16_bf16 v[32:47], v[116:119], v[48:51], v[32:47]
	ds_read_b64_tr_b16 v[72:73], v231
	ds_read_b64_tr_b16 v[74:75], v231 offset:512
	ds_read_b64_tr_b16 v[76:77], v231 offset:2048
	ds_read_b64_tr_b16 v[78:79], v231 offset:2560
	ds_read_b64_tr_b16 v[220:221], v231 offset:1024
	ds_read_b64_tr_b16 v[222:223], v231 offset:1536
	ds_read_b64_tr_b16 v[224:225], v231 offset:3072
	ds_read_b64_tr_b16 v[226:227], v231 offset:3584
	v_mfma_f32_32x32x16_bf16 v[32:47], v[120:123], v[52:55], v[32:47]
	v_mfma_f32_32x32x16_bf16 v[32:47], v[124:127], v[56:59], v[32:47]
	v_mfma_f32_32x32x16_bf16 v[32:47], v[128:131], v[60:63], v[32:47]
	s_nop 11
	v_exp_f32_e32 v32, v32
	v_exp_f32_e32 v33, v33
	v_exp_f32_e32 v34, v34
	v_exp_f32_e32 v35, v35
	v_exp_f32_e32 v36, v36
	v_exp_f32_e32 v37, v37
	v_exp_f32_e32 v38, v38
	v_exp_f32_e32 v39, v39
	v_exp_f32_e32 v40, v40
	v_exp_f32_e32 v41, v41
	v_exp_f32_e32 v42, v42
	v_exp_f32_e32 v43, v43
	v_exp_f32_e32 v44, v44
	v_exp_f32_e32 v45, v45
	v_exp_f32_e32 v46, v46
	v_exp_f32_e32 v47, v47
	s_add_i32 s90, s76, -128
	v_lshlrev_b32_e32 v84, 2, v107
	v_add_u32_e32 v84, s90, v84
	v_add_u32_e32 v85, 0, v84
	v_add_u32_e32 v86, 4, v84
	v_add_u32_e32 v87, 8, v84
	v_add_u32_e32 v88, 12, v84
	v_cmp_gt_u32_e64 s[30:31], s98, v85
	v_cmp_gt_u32_e64 s[36:37], s98, v86
	v_cmp_gt_u32_e64 s[78:79], s98, v87
	v_cmp_gt_u32_e64 s[50:51], s98, v88
	v_cndmask_b32_e64 v32, 0, v32, s[30:31]
	v_add_u32_e32 v85, 32, v84
	v_cmp_gt_u32_e64 s[30:31], s98, v85
	v_cndmask_b32_e64 v33, 0, v33, s[36:37]
	v_add_u32_e32 v86, 36, v84
	v_cmp_gt_u32_e64 s[36:37], s98, v86
	v_cndmask_b32_e64 v34, 0, v34, s[78:79]
	v_add_u32_e32 v87, 40, v84
	v_cmp_gt_u32_e64 s[78:79], s98, v87
	v_cndmask_b32_e64 v35, 0, v35, s[50:51]
	v_add_u32_e32 v88, 44, v84
	v_cmp_gt_u32_e64 s[50:51], s98, v88
	v_cndmask_b32_e64 v36, 0, v36, s[30:31]
	v_add_u32_e32 v85, 64, v84
	v_cmp_gt_u32_e64 s[30:31], s98, v85
	v_cndmask_b32_e64 v37, 0, v37, s[36:37]
	v_add_u32_e32 v86, 68, v84
	v_cmp_gt_u32_e64 s[36:37], s98, v86
	v_cndmask_b32_e64 v38, 0, v38, s[78:79]
	v_add_u32_e32 v87, 72, v84
	v_cmp_gt_u32_e64 s[78:79], s98, v87
	v_cndmask_b32_e64 v39, 0, v39, s[50:51]
	v_add_u32_e32 v88, 76, v84
	v_cmp_gt_u32_e64 s[50:51], s98, v88
	v_cndmask_b32_e64 v40, 0, v40, s[30:31]
	v_add_u32_e32 v85, 96, v84
	v_cmp_gt_u32_e64 s[30:31], s98, v85
	v_cndmask_b32_e64 v41, 0, v41, s[36:37]
	v_add_u32_e32 v86, 100, v84
	v_cmp_gt_u32_e64 s[36:37], s98, v86
	v_cndmask_b32_e64 v42, 0, v42, s[78:79]
	v_add_u32_e32 v87, 104, v84
	v_cmp_gt_u32_e64 s[78:79], s98, v87
	v_cndmask_b32_e64 v43, 0, v43, s[50:51]
	v_add_u32_e32 v88, 108, v84
	v_cmp_gt_u32_e64 s[50:51], s98, v88
	v_nop
	v_cndmask_b32_e64 v44, 0, v44, s[30:31]
	v_cndmask_b32_e64 v45, 0, v45, s[36:37]
	v_cndmask_b32_e64 v46, 0, v46, s[78:79]
	v_cndmask_b32_e64 v47, 0, v47, s[50:51]
	v_cvt_pk_bf16_f32 v64, v32, v33
	v_cvt_pk_bf16_f32 v65, v34, v35
	v_cvt_pk_bf16_f32 v66, v36, v37
	v_cvt_pk_bf16_f32 v67, v38, v39
	v_cvt_pk_bf16_f32 v68, v40, v41
	v_cvt_pk_bf16_f32 v69, v42, v43
	v_cvt_pk_bf16_f32 v70, v44, v45
	v_cvt_pk_bf16_f32 v71, v46, v47
	v_pk_add_f32 v[232:233], v[232:233], v[32:33]
	v_pk_add_f32 v[232:233], v[232:233], v[34:35]
	v_pk_add_f32 v[232:233], v[232:233], v[36:37]
	v_pk_add_f32 v[232:233], v[232:233], v[38:39]
	v_pk_add_f32 v[232:233], v[232:233], v[40:41]
	v_pk_add_f32 v[232:233], v[232:233], v[42:43]
	v_pk_add_f32 v[232:233], v[232:233], v[44:45]
	v_pk_add_f32 v[232:233], v[232:233], v[46:47]
	s_waitcnt lgkmcnt(0)
	v_mfma_f32_32x32x16_bf16 v[0:15], v[64:67], v[72:75], v[0:15]
	v_mfma_f32_32x32x16_bf16 v[16:31], v[64:67], v[76:79], v[16:31]
	v_mfma_f32_32x32x16_bf16 v[0:15], v[68:71], v[220:223], v[0:15]
	v_mfma_f32_32x32x16_bf16 v[16:31], v[68:71], v[224:227], v[16:31]
	s_add_i32 s90, s76, 256
	v_add_u32_e32 v80, s90, v239
	v_add_u32_e32 v83, s90, v240
	v_add_u32_e32 v99, s90, v241
	v_add_u32_e32 v253, s90, v242
	v_add_u32_e32 v254, s90, v101
	v_add_u32_e32 v255, s90, v150
	v_med3_i32 v80, v80, 0, s99
	v_med3_i32 v83, v83, 0, s99
	v_med3_i32 v99, v99, 0, s99
	v_med3_i32 v253, v253, 0, s99
	v_med3_i32 v254, v254, 0, s99
	v_med3_i32 v255, v255, 0, s99
	v_mad_u32_u24 v80, v80, s100, v252
	v_mad_u32_u24 v83, v83, s100, v252
	v_mad_u32_u24 v99, v99, s100, v252
	v_mad_u32_u24 v253, v253, s100, v252
	v_mad_u32_u24 v254, v254, s100, v153
	v_mad_u32_u24 v255, v255, s100, v153
	global_load_dwordx4 v[116:119], v80, s[82:83]
	global_load_dwordx4 v[120:123], v83, s[82:83]
	global_load_dwordx4 v[124:127], v99, s[82:83]
	global_load_dwordx4 v[128:131], v253, s[82:83]
	global_load_dwordx4 v[132:135], v254, s[82:83] offset:768
	global_load_dwordx4 v[136:139], v255, s[82:83] offset:768
	global_load_dwordx4 v[140:143], v254, s[82:83] offset:832
	global_load_dwordx4 v[144:147], v255, s[82:83] offset:832
	s_waitcnt vmcnt(16)
	ds_write_b128 v247, v[156:159]
	ds_write_b128 v247, v[160:163] offset:1024
	ds_write_b128 v247, v[164:167] offset:2048
	ds_write_b128 v247, v[168:171] offset:3072
	ds_read_b128 v[156:159], v248
	ds_read_b128 v[160:163], v249
	ds_read_b128 v[164:167], v250
	ds_read_b128 v[168:171], v251
	ds_write_b128 v112, v[172:175]
	ds_write_b128 v112, v[176:179] offset:1024
	ds_write_b128 v112, v[180:183] offset:2048
	ds_write_b128 v112, v[184:187] offset:3072
	ds_read2_b32 v[32:33], v115 offset0:64 offset1:65
	ds_read2_b32 v[34:35], v115 offset0:66 offset1:67
	ds_read2_b32 v[36:37], v115 offset0:72 offset1:73
	ds_read2_b32 v[38:39], v115 offset0:74 offset1:75
	ds_read2_b32 v[40:41], v115 offset0:80 offset1:81
	ds_read2_b32 v[42:43], v115 offset0:82 offset1:83
	ds_read2_b32 v[44:45], v115 offset0:88 offset1:89
	ds_read2_b32 v[46:47], v115 offset0:90 offset1:91
	s_waitcnt lgkmcnt(0)
	v_mfma_f32_32x32x16_bf16 v[32:47], v[156:159], v[48:51], v[32:47]
	ds_read_b64_tr_b16 v[72:73], v231
	ds_read_b64_tr_b16 v[74:75], v231 offset:512
	ds_read_b64_tr_b16 v[76:77], v231 offset:2048
	ds_read_b64_tr_b16 v[78:79], v231 offset:2560
	ds_read_b64_tr_b16 v[220:221], v231 offset:1024
	ds_read_b64_tr_b16 v[222:223], v231 offset:1536
	ds_read_b64_tr_b16 v[224:225], v231 offset:3072
	ds_read_b64_tr_b16 v[226:227], v231 offset:3584
	v_mfma_f32_32x32x16_bf16 v[32:47], v[160:163], v[52:55], v[32:47]
	v_mfma_f32_32x32x16_bf16 v[32:47], v[164:167], v[56:59], v[32:47]
	v_mfma_f32_32x32x16_bf16 v[32:47], v[168:171], v[60:63], v[32:47]
	s_nop 11
	v_exp_f32_e32 v32, v32
	v_exp_f32_e32 v33, v33
	v_exp_f32_e32 v34, v34
	v_exp_f32_e32 v35, v35
	v_exp_f32_e32 v36, v36
	v_exp_f32_e32 v37, v37
	v_exp_f32_e32 v38, v38
	v_exp_f32_e32 v39, v39
	v_exp_f32_e32 v40, v40
	v_exp_f32_e32 v41, v41
	v_exp_f32_e32 v42, v42
	v_exp_f32_e32 v43, v43
	v_exp_f32_e32 v44, v44
	v_exp_f32_e32 v45, v45
	v_exp_f32_e32 v46, v46
	v_exp_f32_e32 v47, v47
	s_add_i32 s90, s76, 0
	v_lshlrev_b32_e32 v84, 2, v107
	v_add_u32_e32 v84, s90, v84
	v_add_u32_e32 v85, 0, v84
	v_add_u32_e32 v86, 4, v84
	v_add_u32_e32 v87, 8, v84
	v_add_u32_e32 v88, 12, v84
	v_cmp_gt_u32_e64 s[30:31], s98, v85
	v_cmp_gt_u32_e64 s[36:37], s98, v86
	v_cmp_gt_u32_e64 s[78:79], s98, v87
	v_cmp_gt_u32_e64 s[50:51], s98, v88
	v_cndmask_b32_e64 v32, 0, v32, s[30:31]
	v_add_u32_e32 v85, 32, v84
	v_cmp_gt_u32_e64 s[30:31], s98, v85
	v_cndmask_b32_e64 v33, 0, v33, s[36:37]
	v_add_u32_e32 v86, 36, v84
	v_cmp_gt_u32_e64 s[36:37], s98, v86
	v_cndmask_b32_e64 v34, 0, v34, s[78:79]
	v_add_u32_e32 v87, 40, v84
	v_cmp_gt_u32_e64 s[78:79], s98, v87
	v_cndmask_b32_e64 v35, 0, v35, s[50:51]
	v_add_u32_e32 v88, 44, v84
	v_cmp_gt_u32_e64 s[50:51], s98, v88
	v_cndmask_b32_e64 v36, 0, v36, s[30:31]
	v_add_u32_e32 v85, 64, v84
	v_cmp_gt_u32_e64 s[30:31], s98, v85
	v_cndmask_b32_e64 v37, 0, v37, s[36:37]
	v_add_u32_e32 v86, 68, v84
	v_cmp_gt_u32_e64 s[36:37], s98, v86
	v_cndmask_b32_e64 v38, 0, v38, s[78:79]
	v_add_u32_e32 v87, 72, v84
	v_cmp_gt_u32_e64 s[78:79], s98, v87
	v_cndmask_b32_e64 v39, 0, v39, s[50:51]
	v_add_u32_e32 v88, 76, v84
	v_cmp_gt_u32_e64 s[50:51], s98, v88
	v_cndmask_b32_e64 v40, 0, v40, s[30:31]
	v_add_u32_e32 v85, 96, v84
	v_cmp_gt_u32_e64 s[30:31], s98, v85
	v_cndmask_b32_e64 v41, 0, v41, s[36:37]
	v_add_u32_e32 v86, 100, v84
	v_cmp_gt_u32_e64 s[36:37], s98, v86
	v_cndmask_b32_e64 v42, 0, v42, s[78:79]
	v_add_u32_e32 v87, 104, v84
	v_cmp_gt_u32_e64 s[78:79], s98, v87
	v_cndmask_b32_e64 v43, 0, v43, s[50:51]
	v_add_u32_e32 v88, 108, v84
	v_cmp_gt_u32_e64 s[50:51], s98, v88
	v_nop
	v_cndmask_b32_e64 v44, 0, v44, s[30:31]
	v_cndmask_b32_e64 v45, 0, v45, s[36:37]
	v_cndmask_b32_e64 v46, 0, v46, s[78:79]
	v_cndmask_b32_e64 v47, 0, v47, s[50:51]
	v_cvt_pk_bf16_f32 v64, v32, v33
	v_cvt_pk_bf16_f32 v65, v34, v35
	v_cvt_pk_bf16_f32 v66, v36, v37
	v_cvt_pk_bf16_f32 v67, v38, v39
	v_cvt_pk_bf16_f32 v68, v40, v41
	v_cvt_pk_bf16_f32 v69, v42, v43
	v_cvt_pk_bf16_f32 v70, v44, v45
	v_cvt_pk_bf16_f32 v71, v46, v47
	v_pk_add_f32 v[232:233], v[232:233], v[32:33]
	v_pk_add_f32 v[232:233], v[232:233], v[34:35]
	v_pk_add_f32 v[232:233], v[232:233], v[36:37]
	v_pk_add_f32 v[232:233], v[232:233], v[38:39]
	v_pk_add_f32 v[232:233], v[232:233], v[40:41]
	v_pk_add_f32 v[232:233], v[232:233], v[42:43]
	v_pk_add_f32 v[232:233], v[232:233], v[44:45]
	v_pk_add_f32 v[232:233], v[232:233], v[46:47]
	s_waitcnt lgkmcnt(0)
	v_mfma_f32_32x32x16_bf16 v[0:15], v[64:67], v[72:75], v[0:15]
	v_mfma_f32_32x32x16_bf16 v[16:31], v[64:67], v[76:79], v[16:31]
	v_mfma_f32_32x32x16_bf16 v[0:15], v[68:71], v[220:223], v[0:15]
	v_mfma_f32_32x32x16_bf16 v[16:31], v[68:71], v[224:227], v[16:31]
	s_add_i32 s90, s76, 384
	v_add_u32_e32 v80, s90, v239
	v_add_u32_e32 v83, s90, v240
	v_add_u32_e32 v99, s90, v241
	v_add_u32_e32 v253, s90, v242
	v_add_u32_e32 v254, s90, v101
	v_add_u32_e32 v255, s90, v150
	v_med3_i32 v80, v80, 0, s99
	v_med3_i32 v83, v83, 0, s99
	v_med3_i32 v99, v99, 0, s99
	v_med3_i32 v253, v253, 0, s99
	v_med3_i32 v254, v254, 0, s99
	v_med3_i32 v255, v255, 0, s99
	v_mad_u32_u24 v80, v80, s100, v252
	v_mad_u32_u24 v83, v83, s100, v252
	v_mad_u32_u24 v99, v99, s100, v252
	v_mad_u32_u24 v253, v253, s100, v252
	v_mad_u32_u24 v254, v254, s100, v153
	v_mad_u32_u24 v255, v255, s100, v153
	global_load_dwordx4 v[156:159], v80, s[82:83]
	global_load_dwordx4 v[160:163], v83, s[82:83]
	global_load_dwordx4 v[164:167], v99, s[82:83]
	global_load_dwordx4 v[168:171], v253, s[82:83]
	global_load_dwordx4 v[172:175], v254, s[82:83] offset:768
	global_load_dwordx4 v[176:179], v255, s[82:83] offset:768
	global_load_dwordx4 v[180:183], v254, s[82:83] offset:832
	global_load_dwordx4 v[184:187], v255, s[82:83] offset:832
	s_waitcnt vmcnt(16)
	ds_write_b128 v247, v[188:191]
	ds_write_b128 v247, v[192:195] offset:1024
	ds_write_b128 v247, v[196:199] offset:2048
	ds_write_b128 v247, v[200:203] offset:3072
	ds_read_b128 v[188:191], v248
	ds_read_b128 v[192:195], v249
	ds_read_b128 v[196:199], v250
	ds_read_b128 v[200:203], v251
	ds_write_b128 v112, v[204:207]
	ds_write_b128 v112, v[208:211] offset:1024
	ds_write_b128 v112, v[212:215] offset:2048
	ds_write_b128 v112, v[216:219] offset:3072
	ds_read2_b32 v[32:33], v115 offset0:96 offset1:97
	ds_read2_b32 v[34:35], v115 offset0:98 offset1:99
	ds_read2_b32 v[36:37], v115 offset0:104 offset1:105
	ds_read2_b32 v[38:39], v115 offset0:106 offset1:107
	ds_read2_b32 v[40:41], v115 offset0:112 offset1:113
	ds_read2_b32 v[42:43], v115 offset0:114 offset1:115
	ds_read2_b32 v[44:45], v115 offset0:120 offset1:121
	ds_read2_b32 v[46:47], v115 offset0:122 offset1:123
	s_waitcnt lgkmcnt(0)
	v_mfma_f32_32x32x16_bf16 v[32:47], v[188:191], v[48:51], v[32:47]
	ds_read_b64_tr_b16 v[72:73], v231
	ds_read_b64_tr_b16 v[74:75], v231 offset:512
	ds_read_b64_tr_b16 v[76:77], v231 offset:2048
	ds_read_b64_tr_b16 v[78:79], v231 offset:2560
	ds_read_b64_tr_b16 v[220:221], v231 offset:1024
	ds_read_b64_tr_b16 v[222:223], v231 offset:1536
	ds_read_b64_tr_b16 v[224:225], v231 offset:3072
	ds_read_b64_tr_b16 v[226:227], v231 offset:3584
	v_mfma_f32_32x32x16_bf16 v[32:47], v[192:195], v[52:55], v[32:47]
	v_mfma_f32_32x32x16_bf16 v[32:47], v[196:199], v[56:59], v[32:47]
	v_mfma_f32_32x32x16_bf16 v[32:47], v[200:203], v[60:63], v[32:47]
	s_nop 11
	v_exp_f32_e32 v32, v32
	v_exp_f32_e32 v33, v33
	v_exp_f32_e32 v34, v34
	v_exp_f32_e32 v35, v35
	v_exp_f32_e32 v36, v36
	v_exp_f32_e32 v37, v37
	v_exp_f32_e32 v38, v38
	v_exp_f32_e32 v39, v39
	v_exp_f32_e32 v40, v40
	v_exp_f32_e32 v41, v41
	v_exp_f32_e32 v42, v42
	v_exp_f32_e32 v43, v43
	v_exp_f32_e32 v44, v44
	v_exp_f32_e32 v45, v45
	v_exp_f32_e32 v46, v46
	v_exp_f32_e32 v47, v47
	s_add_i32 s90, s76, 128
	v_lshlrev_b32_e32 v84, 2, v107
	v_add_u32_e32 v84, s90, v84
	v_add_u32_e32 v85, 0, v84
	v_add_u32_e32 v86, 4, v84
	v_add_u32_e32 v87, 8, v84
	v_add_u32_e32 v88, 12, v84
	v_cmp_gt_u32_e64 s[30:31], s98, v85
	v_cmp_gt_u32_e64 s[36:37], s98, v86
	v_cmp_gt_u32_e64 s[78:79], s98, v87
	v_cmp_gt_u32_e64 s[50:51], s98, v88
	v_cndmask_b32_e64 v32, 0, v32, s[30:31]
	v_add_u32_e32 v85, 32, v84
	v_cmp_gt_u32_e64 s[30:31], s98, v85
	v_cndmask_b32_e64 v33, 0, v33, s[36:37]
	v_add_u32_e32 v86, 36, v84
	v_cmp_gt_u32_e64 s[36:37], s98, v86
	v_cndmask_b32_e64 v34, 0, v34, s[78:79]
	v_add_u32_e32 v87, 40, v84
	v_cmp_gt_u32_e64 s[78:79], s98, v87
	v_cndmask_b32_e64 v35, 0, v35, s[50:51]
	v_add_u32_e32 v88, 44, v84
	v_cmp_gt_u32_e64 s[50:51], s98, v88
	v_cndmask_b32_e64 v36, 0, v36, s[30:31]
	v_add_u32_e32 v85, 64, v84
	v_cmp_gt_u32_e64 s[30:31], s98, v85
	v_cndmask_b32_e64 v37, 0, v37, s[36:37]
	v_add_u32_e32 v86, 68, v84
	v_cmp_gt_u32_e64 s[36:37], s98, v86
	v_cndmask_b32_e64 v38, 0, v38, s[78:79]
	v_add_u32_e32 v87, 72, v84
	v_cmp_gt_u32_e64 s[78:79], s98, v87
	v_cndmask_b32_e64 v39, 0, v39, s[50:51]
	v_add_u32_e32 v88, 76, v84
	v_cmp_gt_u32_e64 s[50:51], s98, v88
	v_cndmask_b32_e64 v40, 0, v40, s[30:31]
	v_add_u32_e32 v85, 96, v84
	v_cmp_gt_u32_e64 s[30:31], s98, v85
	v_cndmask_b32_e64 v41, 0, v41, s[36:37]
	v_add_u32_e32 v86, 100, v84
	v_cmp_gt_u32_e64 s[36:37], s98, v86
	v_cndmask_b32_e64 v42, 0, v42, s[78:79]
	v_add_u32_e32 v87, 104, v84
	v_cmp_gt_u32_e64 s[78:79], s98, v87
	v_cndmask_b32_e64 v43, 0, v43, s[50:51]
	v_add_u32_e32 v88, 108, v84
	v_cmp_gt_u32_e64 s[50:51], s98, v88
	v_nop
	v_cndmask_b32_e64 v44, 0, v44, s[30:31]
	v_cndmask_b32_e64 v45, 0, v45, s[36:37]
	v_cndmask_b32_e64 v46, 0, v46, s[78:79]
	v_cndmask_b32_e64 v47, 0, v47, s[50:51]
	v_cvt_pk_bf16_f32 v64, v32, v33
	v_cvt_pk_bf16_f32 v65, v34, v35
	v_cvt_pk_bf16_f32 v66, v36, v37
	v_cvt_pk_bf16_f32 v67, v38, v39
	v_cvt_pk_bf16_f32 v68, v40, v41
	v_cvt_pk_bf16_f32 v69, v42, v43
	v_cvt_pk_bf16_f32 v70, v44, v45
	v_cvt_pk_bf16_f32 v71, v46, v47
	v_pk_add_f32 v[232:233], v[232:233], v[32:33]
	v_pk_add_f32 v[232:233], v[232:233], v[34:35]
	v_pk_add_f32 v[232:233], v[232:233], v[36:37]
	v_pk_add_f32 v[232:233], v[232:233], v[38:39]
	v_pk_add_f32 v[232:233], v[232:233], v[40:41]
	v_pk_add_f32 v[232:233], v[232:233], v[42:43]
	v_pk_add_f32 v[232:233], v[232:233], v[44:45]
	v_pk_add_f32 v[232:233], v[232:233], v[46:47]
	s_waitcnt lgkmcnt(0)
	v_mfma_f32_32x32x16_bf16 v[0:15], v[64:67], v[72:75], v[0:15]
	v_mfma_f32_32x32x16_bf16 v[16:31], v[64:67], v[76:79], v[16:31]
	v_mfma_f32_32x32x16_bf16 v[0:15], v[68:71], v[220:223], v[0:15]
	v_mfma_f32_32x32x16_bf16 v[16:31], v[68:71], v[224:227], v[16:31]
	s_add_i32 s90, s76, 512
	v_add_u32_e32 v80, s90, v239
	v_add_u32_e32 v83, s90, v240
	v_add_u32_e32 v99, s90, v241
	v_add_u32_e32 v253, s90, v242
	v_add_u32_e32 v254, s90, v101
	v_add_u32_e32 v255, s90, v150
	v_med3_i32 v80, v80, 0, s99
	v_med3_i32 v83, v83, 0, s99
	v_med3_i32 v99, v99, 0, s99
	v_med3_i32 v253, v253, 0, s99
	v_med3_i32 v254, v254, 0, s99
	v_med3_i32 v255, v255, 0, s99
	v_mad_u32_u24 v80, v80, s100, v252
	v_mad_u32_u24 v83, v83, s100, v252
	v_mad_u32_u24 v99, v99, s100, v252
	v_mad_u32_u24 v253, v253, s100, v252
	v_mad_u32_u24 v254, v254, s100, v153
	v_mad_u32_u24 v255, v255, s100, v153
	global_load_dwordx4 v[188:191], v80, s[82:83]
	global_load_dwordx4 v[192:195], v83, s[82:83]
	global_load_dwordx4 v[196:199], v99, s[82:83]
	global_load_dwordx4 v[200:203], v253, s[82:83]
	global_load_dwordx4 v[204:207], v254, s[82:83] offset:768
	global_load_dwordx4 v[208:211], v255, s[82:83] offset:768
	global_load_dwordx4 v[212:215], v254, s[82:83] offset:832
	global_load_dwordx4 v[216:219], v255, s[82:83] offset:832
	s_waitcnt vmcnt(16)
	ds_write_b128 v247, v[116:119]
	ds_write_b128 v247, v[120:123] offset:1024
	ds_write_b128 v247, v[124:127] offset:2048
	ds_write_b128 v247, v[128:131] offset:3072
	ds_read_b128 v[116:119], v248
	ds_read_b128 v[120:123], v249
	ds_read_b128 v[124:127], v250
	ds_read_b128 v[128:131], v251
	ds_write_b128 v112, v[132:135]
	ds_write_b128 v112, v[136:139] offset:1024
	ds_write_b128 v112, v[140:143] offset:2048
	ds_write_b128 v112, v[144:147] offset:3072
	ds_read2_b32 v[32:33], v115 offset0:128 offset1:129
	ds_read2_b32 v[34:35], v115 offset0:130 offset1:131
	ds_read2_b32 v[36:37], v115 offset0:136 offset1:137
	ds_read2_b32 v[38:39], v115 offset0:138 offset1:139
	ds_read2_b32 v[40:41], v115 offset0:144 offset1:145
	ds_read2_b32 v[42:43], v115 offset0:146 offset1:147
	ds_read2_b32 v[44:45], v115 offset0:152 offset1:153
	ds_read2_b32 v[46:47], v115 offset0:154 offset1:155
	s_waitcnt lgkmcnt(0)
	v_mfma_f32_32x32x16_bf16 v[32:47], v[116:119], v[48:51], v[32:47]
	ds_read_b64_tr_b16 v[72:73], v231
	ds_read_b64_tr_b16 v[74:75], v231 offset:512
	ds_read_b64_tr_b16 v[76:77], v231 offset:2048
	ds_read_b64_tr_b16 v[78:79], v231 offset:2560
	ds_read_b64_tr_b16 v[220:221], v231 offset:1024
	ds_read_b64_tr_b16 v[222:223], v231 offset:1536
	ds_read_b64_tr_b16 v[224:225], v231 offset:3072
	ds_read_b64_tr_b16 v[226:227], v231 offset:3584
	v_mfma_f32_32x32x16_bf16 v[32:47], v[120:123], v[52:55], v[32:47]
	v_mfma_f32_32x32x16_bf16 v[32:47], v[124:127], v[56:59], v[32:47]
	v_mfma_f32_32x32x16_bf16 v[32:47], v[128:131], v[60:63], v[32:47]
	s_nop 11
	v_exp_f32_e32 v32, v32
	v_exp_f32_e32 v33, v33
	v_exp_f32_e32 v34, v34
	v_exp_f32_e32 v35, v35
	v_exp_f32_e32 v36, v36
	v_exp_f32_e32 v37, v37
	v_exp_f32_e32 v38, v38
	v_exp_f32_e32 v39, v39
	v_exp_f32_e32 v40, v40
	v_exp_f32_e32 v41, v41
	v_exp_f32_e32 v42, v42
	v_exp_f32_e32 v43, v43
	v_exp_f32_e32 v44, v44
	v_exp_f32_e32 v45, v45
	v_exp_f32_e32 v46, v46
	v_exp_f32_e32 v47, v47
	s_add_i32 s90, s76, 256
	v_lshlrev_b32_e32 v84, 2, v107
	v_add_u32_e32 v84, s90, v84
	v_add_u32_e32 v85, 0, v84
	v_add_u32_e32 v86, 4, v84
	v_add_u32_e32 v87, 8, v84
	v_add_u32_e32 v88, 12, v84
	v_cmp_gt_u32_e64 s[30:31], s98, v85
	v_cmp_gt_u32_e64 s[36:37], s98, v86
	v_cmp_gt_u32_e64 s[78:79], s98, v87
	v_cmp_gt_u32_e64 s[50:51], s98, v88
	v_cndmask_b32_e64 v32, 0, v32, s[30:31]
	v_add_u32_e32 v85, 32, v84
	v_cmp_gt_u32_e64 s[30:31], s98, v85
	v_cndmask_b32_e64 v33, 0, v33, s[36:37]
	v_add_u32_e32 v86, 36, v84
	v_cmp_gt_u32_e64 s[36:37], s98, v86
	v_cndmask_b32_e64 v34, 0, v34, s[78:79]
	v_add_u32_e32 v87, 40, v84
	v_cmp_gt_u32_e64 s[78:79], s98, v87
	v_cndmask_b32_e64 v35, 0, v35, s[50:51]
	v_add_u32_e32 v88, 44, v84
	v_cmp_gt_u32_e64 s[50:51], s98, v88
	v_cndmask_b32_e64 v36, 0, v36, s[30:31]
	v_add_u32_e32 v85, 64, v84
	v_cmp_gt_u32_e64 s[30:31], s98, v85
	v_cndmask_b32_e64 v37, 0, v37, s[36:37]
	v_add_u32_e32 v86, 68, v84
	v_cmp_gt_u32_e64 s[36:37], s98, v86
	v_cndmask_b32_e64 v38, 0, v38, s[78:79]
	v_add_u32_e32 v87, 72, v84
	v_cmp_gt_u32_e64 s[78:79], s98, v87
	v_cndmask_b32_e64 v39, 0, v39, s[50:51]
	v_add_u32_e32 v88, 76, v84
	v_cmp_gt_u32_e64 s[50:51], s98, v88
	v_cndmask_b32_e64 v40, 0, v40, s[30:31]
	v_add_u32_e32 v85, 96, v84
	v_cmp_gt_u32_e64 s[30:31], s98, v85
	v_cndmask_b32_e64 v41, 0, v41, s[36:37]
	v_add_u32_e32 v86, 100, v84
	v_cmp_gt_u32_e64 s[36:37], s98, v86
	v_cndmask_b32_e64 v42, 0, v42, s[78:79]
	v_add_u32_e32 v87, 104, v84
	v_cmp_gt_u32_e64 s[78:79], s98, v87
	v_cndmask_b32_e64 v43, 0, v43, s[50:51]
	v_add_u32_e32 v88, 108, v84
	v_cmp_gt_u32_e64 s[50:51], s98, v88
	v_nop
	v_cndmask_b32_e64 v44, 0, v44, s[30:31]
	v_cndmask_b32_e64 v45, 0, v45, s[36:37]
	v_cndmask_b32_e64 v46, 0, v46, s[78:79]
	v_cndmask_b32_e64 v47, 0, v47, s[50:51]
	v_cvt_pk_bf16_f32 v64, v32, v33
	v_cvt_pk_bf16_f32 v65, v34, v35
	v_cvt_pk_bf16_f32 v66, v36, v37
	v_cvt_pk_bf16_f32 v67, v38, v39
	v_cvt_pk_bf16_f32 v68, v40, v41
	v_cvt_pk_bf16_f32 v69, v42, v43
	v_cvt_pk_bf16_f32 v70, v44, v45
	v_cvt_pk_bf16_f32 v71, v46, v47
	v_pk_add_f32 v[232:233], v[232:233], v[32:33]
	v_pk_add_f32 v[232:233], v[232:233], v[34:35]
	v_pk_add_f32 v[232:233], v[232:233], v[36:37]
	v_pk_add_f32 v[232:233], v[232:233], v[38:39]
	v_pk_add_f32 v[232:233], v[232:233], v[40:41]
	v_pk_add_f32 v[232:233], v[232:233], v[42:43]
	v_pk_add_f32 v[232:233], v[232:233], v[44:45]
	v_pk_add_f32 v[232:233], v[232:233], v[46:47]
	s_waitcnt lgkmcnt(0)
	v_mfma_f32_32x32x16_bf16 v[0:15], v[64:67], v[72:75], v[0:15]
	v_mfma_f32_32x32x16_bf16 v[16:31], v[64:67], v[76:79], v[16:31]
	v_mfma_f32_32x32x16_bf16 v[0:15], v[68:71], v[220:223], v[0:15]
	v_mfma_f32_32x32x16_bf16 v[16:31], v[68:71], v[224:227], v[16:31]
	s_add_i32 s90, s76, 640
	v_add_u32_e32 v80, s90, v239
	v_add_u32_e32 v83, s90, v240
	v_add_u32_e32 v99, s90, v241
	v_add_u32_e32 v253, s90, v242
	v_add_u32_e32 v254, s90, v101
	v_add_u32_e32 v255, s90, v150
	v_med3_i32 v80, v80, 0, s99
	v_med3_i32 v83, v83, 0, s99
	v_med3_i32 v99, v99, 0, s99
	v_med3_i32 v253, v253, 0, s99
	v_med3_i32 v254, v254, 0, s99
	v_med3_i32 v255, v255, 0, s99
	v_mad_u32_u24 v80, v80, s100, v252
	v_mad_u32_u24 v83, v83, s100, v252
	v_mad_u32_u24 v99, v99, s100, v252
	v_mad_u32_u24 v253, v253, s100, v252
	v_mad_u32_u24 v254, v254, s100, v153
	v_mad_u32_u24 v255, v255, s100, v153
	global_load_dwordx4 v[116:119], v80, s[82:83]
	global_load_dwordx4 v[120:123], v83, s[82:83]
	global_load_dwordx4 v[124:127], v99, s[82:83]
	global_load_dwordx4 v[128:131], v253, s[82:83]
	global_load_dwordx4 v[132:135], v254, s[82:83] offset:768
	global_load_dwordx4 v[136:139], v255, s[82:83] offset:768
	global_load_dwordx4 v[140:143], v254, s[82:83] offset:832
	global_load_dwordx4 v[144:147], v255, s[82:83] offset:832
	s_waitcnt vmcnt(16)
	ds_write_b128 v247, v[156:159]
	ds_write_b128 v247, v[160:163] offset:1024
	ds_write_b128 v247, v[164:167] offset:2048
	ds_write_b128 v247, v[168:171] offset:3072
	ds_read_b128 v[156:159], v248
	ds_read_b128 v[160:163], v249
	ds_read_b128 v[164:167], v250
	ds_read_b128 v[168:171], v251
	ds_write_b128 v112, v[172:175]
	ds_write_b128 v112, v[176:179] offset:1024
	ds_write_b128 v112, v[180:183] offset:2048
	ds_write_b128 v112, v[184:187] offset:3072
	ds_read2_b32 v[32:33], v115 offset0:160 offset1:161
	ds_read2_b32 v[34:35], v115 offset0:162 offset1:163
	ds_read2_b32 v[36:37], v115 offset0:168 offset1:169
	ds_read2_b32 v[38:39], v115 offset0:170 offset1:171
	ds_read2_b32 v[40:41], v115 offset0:176 offset1:177
	ds_read2_b32 v[42:43], v115 offset0:178 offset1:179
	ds_read2_b32 v[44:45], v115 offset0:184 offset1:185
	ds_read2_b32 v[46:47], v115 offset0:186 offset1:187
	s_waitcnt lgkmcnt(0)
	v_mfma_f32_32x32x16_bf16 v[32:47], v[156:159], v[48:51], v[32:47]
	ds_read_b64_tr_b16 v[72:73], v231
	ds_read_b64_tr_b16 v[74:75], v231 offset:512
	ds_read_b64_tr_b16 v[76:77], v231 offset:2048
	ds_read_b64_tr_b16 v[78:79], v231 offset:2560
	ds_read_b64_tr_b16 v[220:221], v231 offset:1024
	ds_read_b64_tr_b16 v[222:223], v231 offset:1536
	ds_read_b64_tr_b16 v[224:225], v231 offset:3072
	ds_read_b64_tr_b16 v[226:227], v231 offset:3584
	v_mfma_f32_32x32x16_bf16 v[32:47], v[160:163], v[52:55], v[32:47]
	v_mfma_f32_32x32x16_bf16 v[32:47], v[164:167], v[56:59], v[32:47]
	v_mfma_f32_32x32x16_bf16 v[32:47], v[168:171], v[60:63], v[32:47]
	s_nop 11
	v_exp_f32_e32 v32, v32
	v_exp_f32_e32 v33, v33
	v_exp_f32_e32 v34, v34
	v_exp_f32_e32 v35, v35
	v_exp_f32_e32 v36, v36
	v_exp_f32_e32 v37, v37
	v_exp_f32_e32 v38, v38
	v_exp_f32_e32 v39, v39
	v_exp_f32_e32 v40, v40
	v_exp_f32_e32 v41, v41
	v_exp_f32_e32 v42, v42
	v_exp_f32_e32 v43, v43
	v_exp_f32_e32 v44, v44
	v_exp_f32_e32 v45, v45
	v_exp_f32_e32 v46, v46
	v_exp_f32_e32 v47, v47
	s_add_i32 s90, s76, 384
	v_lshlrev_b32_e32 v84, 2, v107
	v_add_u32_e32 v84, s90, v84
	v_add_u32_e32 v85, 0, v84
	v_add_u32_e32 v86, 4, v84
	v_add_u32_e32 v87, 8, v84
	v_add_u32_e32 v88, 12, v84
	v_cmp_gt_u32_e64 s[30:31], s98, v85
	v_cmp_gt_u32_e64 s[36:37], s98, v86
	v_cmp_gt_u32_e64 s[78:79], s98, v87
	v_cmp_gt_u32_e64 s[50:51], s98, v88
	v_cndmask_b32_e64 v32, 0, v32, s[30:31]
	v_add_u32_e32 v85, 32, v84
	v_cmp_gt_u32_e64 s[30:31], s98, v85
	v_cndmask_b32_e64 v33, 0, v33, s[36:37]
	v_add_u32_e32 v86, 36, v84
	v_cmp_gt_u32_e64 s[36:37], s98, v86
	v_cndmask_b32_e64 v34, 0, v34, s[78:79]
	v_add_u32_e32 v87, 40, v84
	v_cmp_gt_u32_e64 s[78:79], s98, v87
	v_cndmask_b32_e64 v35, 0, v35, s[50:51]
	v_add_u32_e32 v88, 44, v84
	v_cmp_gt_u32_e64 s[50:51], s98, v88
	v_cndmask_b32_e64 v36, 0, v36, s[30:31]
	v_add_u32_e32 v85, 64, v84
	v_cmp_gt_u32_e64 s[30:31], s98, v85
	v_cndmask_b32_e64 v37, 0, v37, s[36:37]
	v_add_u32_e32 v86, 68, v84
	v_cmp_gt_u32_e64 s[36:37], s98, v86
	v_cndmask_b32_e64 v38, 0, v38, s[78:79]
	v_add_u32_e32 v87, 72, v84
	v_cmp_gt_u32_e64 s[78:79], s98, v87
	v_cndmask_b32_e64 v39, 0, v39, s[50:51]
	v_add_u32_e32 v88, 76, v84
	v_cmp_gt_u32_e64 s[50:51], s98, v88
	v_cndmask_b32_e64 v40, 0, v40, s[30:31]
	v_add_u32_e32 v85, 96, v84
	v_cmp_gt_u32_e64 s[30:31], s98, v85
	v_cndmask_b32_e64 v41, 0, v41, s[36:37]
	v_add_u32_e32 v86, 100, v84
	v_cmp_gt_u32_e64 s[36:37], s98, v86
	v_cndmask_b32_e64 v42, 0, v42, s[78:79]
	v_add_u32_e32 v87, 104, v84
	v_cmp_gt_u32_e64 s[78:79], s98, v87
	v_cndmask_b32_e64 v43, 0, v43, s[50:51]
	v_add_u32_e32 v88, 108, v84
	v_cmp_gt_u32_e64 s[50:51], s98, v88
	v_nop
	v_cndmask_b32_e64 v44, 0, v44, s[30:31]
	v_cndmask_b32_e64 v45, 0, v45, s[36:37]
	v_cndmask_b32_e64 v46, 0, v46, s[78:79]
	v_cndmask_b32_e64 v47, 0, v47, s[50:51]
	v_cvt_pk_bf16_f32 v64, v32, v33
	v_cvt_pk_bf16_f32 v65, v34, v35
	v_cvt_pk_bf16_f32 v66, v36, v37
	v_cvt_pk_bf16_f32 v67, v38, v39
	v_cvt_pk_bf16_f32 v68, v40, v41
	v_cvt_pk_bf16_f32 v69, v42, v43
	v_cvt_pk_bf16_f32 v70, v44, v45
	v_cvt_pk_bf16_f32 v71, v46, v47
	v_pk_add_f32 v[232:233], v[232:233], v[32:33]
	v_pk_add_f32 v[232:233], v[232:233], v[34:35]
	v_pk_add_f32 v[232:233], v[232:233], v[36:37]
	v_pk_add_f32 v[232:233], v[232:233], v[38:39]
	v_pk_add_f32 v[232:233], v[232:233], v[40:41]
	v_pk_add_f32 v[232:233], v[232:233], v[42:43]
	v_pk_add_f32 v[232:233], v[232:233], v[44:45]
	v_pk_add_f32 v[232:233], v[232:233], v[46:47]
	s_waitcnt lgkmcnt(0)
	v_mfma_f32_32x32x16_bf16 v[0:15], v[64:67], v[72:75], v[0:15]
	v_mfma_f32_32x32x16_bf16 v[16:31], v[64:67], v[76:79], v[16:31]
	v_mfma_f32_32x32x16_bf16 v[0:15], v[68:71], v[220:223], v[0:15]
	v_mfma_f32_32x32x16_bf16 v[16:31], v[68:71], v[224:227], v[16:31]
	s_add_i32 s90, s76, -1024
	v_add_u32_e32 v80, s90, v243
	v_add_u32_e32 v83, s90, v244
	v_add_u32_e32 v99, s90, v245
	v_add_u32_e32 v253, s90, v246
	v_add_u32_e32 v254, s90, v148
	v_add_u32_e32 v255, s90, v151
	v_med3_i32 v80, v80, 0, s99
	v_med3_i32 v83, v83, 0, s99
	v_med3_i32 v99, v99, 0, s99
	v_med3_i32 v253, v253, 0, s99
	v_med3_i32 v254, v254, 0, s99
	v_med3_i32 v255, v255, 0, s99
	v_mad_u32_u24 v80, v80, s100, v252
	v_mad_u32_u24 v83, v83, s100, v252
	v_mad_u32_u24 v99, v99, s100, v252
	v_mad_u32_u24 v253, v253, s100, v252
	v_mad_u32_u24 v254, v254, s100, v153
	v_mad_u32_u24 v255, v255, s100, v153
	global_load_dwordx4 v[156:159], v80, s[82:83]
	global_load_dwordx4 v[160:163], v83, s[82:83]
	global_load_dwordx4 v[164:167], v99, s[82:83]
	global_load_dwordx4 v[168:171], v253, s[82:83]
	global_load_dwordx4 v[172:175], v254, s[82:83] offset:768
	global_load_dwordx4 v[176:179], v255, s[82:83] offset:768
	global_load_dwordx4 v[180:183], v254, s[82:83] offset:832
	global_load_dwordx4 v[184:187], v255, s[82:83] offset:832
	s_waitcnt vmcnt(16)
	ds_write_b128 v247, v[188:191]
	ds_write_b128 v247, v[192:195] offset:1024
	ds_write_b128 v247, v[196:199] offset:2048
	ds_write_b128 v247, v[200:203] offset:3072
	ds_read_b128 v[188:191], v248
	ds_read_b128 v[192:195], v249
	ds_read_b128 v[196:199], v250
	ds_read_b128 v[200:203], v251
	ds_write_b128 v112, v[204:207]
	ds_write_b128 v112, v[208:211] offset:1024
	ds_write_b128 v112, v[212:215] offset:2048
	ds_write_b128 v112, v[216:219] offset:3072
	ds_read2_b32 v[32:33], v115 offset0:192 offset1:193
	ds_read2_b32 v[34:35], v115 offset0:194 offset1:195
	ds_read2_b32 v[36:37], v115 offset0:200 offset1:201
	ds_read2_b32 v[38:39], v115 offset0:202 offset1:203
	ds_read2_b32 v[40:41], v115 offset0:208 offset1:209
	ds_read2_b32 v[42:43], v115 offset0:210 offset1:211
	ds_read2_b32 v[44:45], v115 offset0:216 offset1:217
	ds_read2_b32 v[46:47], v115 offset0:218 offset1:219
	s_waitcnt lgkmcnt(0)
	v_mfma_f32_32x32x16_bf16 v[32:47], v[188:191], v[48:51], v[32:47]
	ds_read_b64_tr_b16 v[72:73], v231
	ds_read_b64_tr_b16 v[74:75], v231 offset:512
	ds_read_b64_tr_b16 v[76:77], v231 offset:2048
	ds_read_b64_tr_b16 v[78:79], v231 offset:2560
	ds_read_b64_tr_b16 v[220:221], v231 offset:1024
	ds_read_b64_tr_b16 v[222:223], v231 offset:1536
	ds_read_b64_tr_b16 v[224:225], v231 offset:3072
	ds_read_b64_tr_b16 v[226:227], v231 offset:3584
	v_mfma_f32_32x32x16_bf16 v[32:47], v[192:195], v[52:55], v[32:47]
	v_mfma_f32_32x32x16_bf16 v[32:47], v[196:199], v[56:59], v[32:47]
	v_mfma_f32_32x32x16_bf16 v[32:47], v[200:203], v[60:63], v[32:47]
	s_nop 11
	v_exp_f32_e32 v32, v32
	v_exp_f32_e32 v33, v33
	v_exp_f32_e32 v34, v34
	v_exp_f32_e32 v35, v35
	v_exp_f32_e32 v36, v36
	v_exp_f32_e32 v37, v37
	v_exp_f32_e32 v38, v38
	v_exp_f32_e32 v39, v39
	v_exp_f32_e32 v40, v40
	v_exp_f32_e32 v41, v41
	v_exp_f32_e32 v42, v42
	v_exp_f32_e32 v43, v43
	v_exp_f32_e32 v44, v44
	v_exp_f32_e32 v45, v45
	v_exp_f32_e32 v46, v46
	v_exp_f32_e32 v47, v47
	s_add_i32 s90, s76, 512
	v_lshlrev_b32_e32 v84, 2, v107
	v_add_u32_e32 v84, s90, v84
	v_add_u32_e32 v85, 0, v84
	v_add_u32_e32 v86, 4, v84
	v_add_u32_e32 v87, 8, v84
	v_add_u32_e32 v88, 12, v84
	v_cmp_gt_u32_e64 s[30:31], s98, v85
	v_cmp_gt_u32_e64 s[36:37], s98, v86
	v_cmp_gt_u32_e64 s[78:79], s98, v87
	v_cmp_gt_u32_e64 s[50:51], s98, v88
	v_cndmask_b32_e64 v32, 0, v32, s[30:31]
	v_add_u32_e32 v85, 32, v84
	v_cmp_gt_u32_e64 s[30:31], s98, v85
	v_cndmask_b32_e64 v33, 0, v33, s[36:37]
	v_add_u32_e32 v86, 36, v84
	v_cmp_gt_u32_e64 s[36:37], s98, v86
	v_cndmask_b32_e64 v34, 0, v34, s[78:79]
	v_add_u32_e32 v87, 40, v84
	v_cmp_gt_u32_e64 s[78:79], s98, v87
	v_cndmask_b32_e64 v35, 0, v35, s[50:51]
	v_add_u32_e32 v88, 44, v84
	v_cmp_gt_u32_e64 s[50:51], s98, v88
	v_cndmask_b32_e64 v36, 0, v36, s[30:31]
	v_add_u32_e32 v85, 64, v84
	v_cmp_gt_u32_e64 s[30:31], s98, v85
	v_cndmask_b32_e64 v37, 0, v37, s[36:37]
	v_add_u32_e32 v86, 68, v84
	v_cmp_gt_u32_e64 s[36:37], s98, v86
	v_cndmask_b32_e64 v38, 0, v38, s[78:79]
	v_add_u32_e32 v87, 72, v84
	v_cmp_gt_u32_e64 s[78:79], s98, v87
	v_cndmask_b32_e64 v39, 0, v39, s[50:51]
	v_add_u32_e32 v88, 76, v84
	v_cmp_gt_u32_e64 s[50:51], s98, v88
	v_cndmask_b32_e64 v40, 0, v40, s[30:31]
	v_add_u32_e32 v85, 96, v84
	v_cmp_gt_u32_e64 s[30:31], s98, v85
	v_cndmask_b32_e64 v41, 0, v41, s[36:37]
	v_add_u32_e32 v86, 100, v84
	v_cmp_gt_u32_e64 s[36:37], s98, v86
	v_cndmask_b32_e64 v42, 0, v42, s[78:79]
	v_add_u32_e32 v87, 104, v84
	v_cmp_gt_u32_e64 s[78:79], s98, v87
	v_cndmask_b32_e64 v43, 0, v43, s[50:51]
	v_add_u32_e32 v88, 108, v84
	v_cmp_gt_u32_e64 s[50:51], s98, v88
	v_nop
	v_cndmask_b32_e64 v44, 0, v44, s[30:31]
	v_cndmask_b32_e64 v45, 0, v45, s[36:37]
	v_cndmask_b32_e64 v46, 0, v46, s[78:79]
	v_cndmask_b32_e64 v47, 0, v47, s[50:51]
	v_cvt_pk_bf16_f32 v64, v32, v33
	v_cvt_pk_bf16_f32 v65, v34, v35
	v_cvt_pk_bf16_f32 v66, v36, v37
	v_cvt_pk_bf16_f32 v67, v38, v39
	v_cvt_pk_bf16_f32 v68, v40, v41
	v_cvt_pk_bf16_f32 v69, v42, v43
	v_cvt_pk_bf16_f32 v70, v44, v45
	v_cvt_pk_bf16_f32 v71, v46, v47
	v_pk_add_f32 v[232:233], v[232:233], v[32:33]
	v_pk_add_f32 v[232:233], v[232:233], v[34:35]
	v_pk_add_f32 v[232:233], v[232:233], v[36:37]
	v_pk_add_f32 v[232:233], v[232:233], v[38:39]
	v_pk_add_f32 v[232:233], v[232:233], v[40:41]
	v_pk_add_f32 v[232:233], v[232:233], v[42:43]
	v_pk_add_f32 v[232:233], v[232:233], v[44:45]
	v_pk_add_f32 v[232:233], v[232:233], v[46:47]
	s_waitcnt lgkmcnt(0)
	v_mfma_f32_32x32x16_bf16 v[0:15], v[64:67], v[72:75], v[0:15]
	v_mfma_f32_32x32x16_bf16 v[16:31], v[64:67], v[76:79], v[16:31]
	v_mfma_f32_32x32x16_bf16 v[0:15], v[68:71], v[220:223], v[0:15]
	v_mfma_f32_32x32x16_bf16 v[16:31], v[68:71], v[224:227], v[16:31]
	s_add_i32 s90, s76, -512
	v_add_u32_e32 v80, s90, v243
	v_add_u32_e32 v83, s90, v244
	v_add_u32_e32 v99, s90, v245
	v_add_u32_e32 v253, s90, v246
	v_add_u32_e32 v254, s90, v148
	v_add_u32_e32 v255, s90, v151
	v_med3_i32 v80, v80, 0, s99
	v_med3_i32 v83, v83, 0, s99
	v_med3_i32 v99, v99, 0, s99
	v_med3_i32 v253, v253, 0, s99
	v_med3_i32 v254, v254, 0, s99
	v_med3_i32 v255, v255, 0, s99
	v_mad_u32_u24 v80, v80, s100, v252
	v_mad_u32_u24 v83, v83, s100, v252
	v_mad_u32_u24 v99, v99, s100, v252
	v_mad_u32_u24 v253, v253, s100, v252
	v_mad_u32_u24 v254, v254, s100, v153
	v_mad_u32_u24 v255, v255, s100, v153
	global_load_dwordx4 v[188:191], v80, s[82:83]
	global_load_dwordx4 v[192:195], v83, s[82:83]
	global_load_dwordx4 v[196:199], v99, s[82:83]
	global_load_dwordx4 v[200:203], v253, s[82:83]
	global_load_dwordx4 v[204:207], v254, s[82:83] offset:768
	global_load_dwordx4 v[208:211], v255, s[82:83] offset:768
	global_load_dwordx4 v[212:215], v254, s[82:83] offset:832
	global_load_dwordx4 v[216:219], v255, s[82:83] offset:832
	s_waitcnt vmcnt(16)
	ds_write_b128 v247, v[116:119]
	ds_write_b128 v247, v[120:123] offset:1024
	ds_write_b128 v247, v[124:127] offset:2048
	ds_write_b128 v247, v[128:131] offset:3072
	ds_read_b128 v[116:119], v248
	ds_read_b128 v[120:123], v249
	ds_read_b128 v[124:127], v250
	ds_read_b128 v[128:131], v251
	ds_write_b128 v112, v[132:135]
	ds_write_b128 v112, v[136:139] offset:1024
	ds_write_b128 v112, v[140:143] offset:2048
	ds_write_b128 v112, v[144:147] offset:3072
	ds_read2_b32 v[32:33], v115 offset0:224 offset1:225
	ds_read2_b32 v[34:35], v115 offset0:226 offset1:227
	ds_read2_b32 v[36:37], v115 offset0:232 offset1:233
	ds_read2_b32 v[38:39], v115 offset0:234 offset1:235
	ds_read2_b32 v[40:41], v115 offset0:240 offset1:241
	ds_read2_b32 v[42:43], v115 offset0:242 offset1:243
	ds_read2_b32 v[44:45], v115 offset0:248 offset1:249
	ds_read2_b32 v[46:47], v115 offset0:250 offset1:251
	s_waitcnt lgkmcnt(0)
	v_mfma_f32_32x32x16_bf16 v[32:47], v[116:119], v[48:51], v[32:47]
	ds_read_b64_tr_b16 v[72:73], v231
	ds_read_b64_tr_b16 v[74:75], v231 offset:512
	ds_read_b64_tr_b16 v[76:77], v231 offset:2048
	ds_read_b64_tr_b16 v[78:79], v231 offset:2560
	ds_read_b64_tr_b16 v[220:221], v231 offset:1024
	ds_read_b64_tr_b16 v[222:223], v231 offset:1536
	ds_read_b64_tr_b16 v[224:225], v231 offset:3072
	ds_read_b64_tr_b16 v[226:227], v231 offset:3584
	v_mfma_f32_32x32x16_bf16 v[32:47], v[120:123], v[52:55], v[32:47]
	v_mfma_f32_32x32x16_bf16 v[32:47], v[124:127], v[56:59], v[32:47]
	v_mfma_f32_32x32x16_bf16 v[32:47], v[128:131], v[60:63], v[32:47]
	s_nop 11
	v_exp_f32_e32 v32, v32
	v_exp_f32_e32 v33, v33
	v_exp_f32_e32 v34, v34
	v_exp_f32_e32 v35, v35
	v_exp_f32_e32 v36, v36
	v_exp_f32_e32 v37, v37
	v_exp_f32_e32 v38, v38
	v_exp_f32_e32 v39, v39
	v_exp_f32_e32 v40, v40
	v_exp_f32_e32 v41, v41
	v_exp_f32_e32 v42, v42
	v_exp_f32_e32 v43, v43
	v_exp_f32_e32 v44, v44
	v_exp_f32_e32 v45, v45
	v_exp_f32_e32 v46, v46
	v_exp_f32_e32 v47, v47
	s_add_i32 s90, s76, 640
	v_lshlrev_b32_e32 v84, 2, v107
	v_add_u32_e32 v84, s90, v84
	v_add_u32_e32 v85, 0, v84
	v_add_u32_e32 v86, 4, v84
	v_add_u32_e32 v87, 8, v84
	v_add_u32_e32 v88, 12, v84
	v_cmp_gt_u32_e64 s[30:31], s98, v85
	v_cmp_gt_u32_e64 s[36:37], s98, v86
	v_cmp_gt_u32_e64 s[78:79], s98, v87
	v_cmp_gt_u32_e64 s[50:51], s98, v88
	v_cndmask_b32_e64 v32, 0, v32, s[30:31]
	v_add_u32_e32 v85, 32, v84
	v_cmp_gt_u32_e64 s[30:31], s98, v85
	v_cndmask_b32_e64 v33, 0, v33, s[36:37]
	v_add_u32_e32 v86, 36, v84
	v_cmp_gt_u32_e64 s[36:37], s98, v86
	v_cndmask_b32_e64 v34, 0, v34, s[78:79]
	v_add_u32_e32 v87, 40, v84
	v_cmp_gt_u32_e64 s[78:79], s98, v87
	v_cndmask_b32_e64 v35, 0, v35, s[50:51]
	v_add_u32_e32 v88, 44, v84
	v_cmp_gt_u32_e64 s[50:51], s98, v88
	v_cndmask_b32_e64 v36, 0, v36, s[30:31]
	v_add_u32_e32 v85, 64, v84
	v_cmp_gt_u32_e64 s[30:31], s98, v85
	v_cndmask_b32_e64 v37, 0, v37, s[36:37]
	v_add_u32_e32 v86, 68, v84
	v_cmp_gt_u32_e64 s[36:37], s98, v86
	v_cndmask_b32_e64 v38, 0, v38, s[78:79]
	v_add_u32_e32 v87, 72, v84
	v_cmp_gt_u32_e64 s[78:79], s98, v87
	v_cndmask_b32_e64 v39, 0, v39, s[50:51]
	v_add_u32_e32 v88, 76, v84
	v_cmp_gt_u32_e64 s[50:51], s98, v88
	v_cndmask_b32_e64 v40, 0, v40, s[30:31]
	v_add_u32_e32 v85, 96, v84
	v_cmp_gt_u32_e64 s[30:31], s98, v85
	v_cndmask_b32_e64 v41, 0, v41, s[36:37]
	v_add_u32_e32 v86, 100, v84
	v_cmp_gt_u32_e64 s[36:37], s98, v86
	v_cndmask_b32_e64 v42, 0, v42, s[78:79]
	v_add_u32_e32 v87, 104, v84
	v_cmp_gt_u32_e64 s[78:79], s98, v87
	v_cndmask_b32_e64 v43, 0, v43, s[50:51]
	v_add_u32_e32 v88, 108, v84
	v_cmp_gt_u32_e64 s[50:51], s98, v88
	v_nop
	v_cndmask_b32_e64 v44, 0, v44, s[30:31]
	v_cndmask_b32_e64 v45, 0, v45, s[36:37]
	v_cndmask_b32_e64 v46, 0, v46, s[78:79]
	v_cndmask_b32_e64 v47, 0, v47, s[50:51]
	v_cvt_pk_bf16_f32 v64, v32, v33
	v_cvt_pk_bf16_f32 v65, v34, v35
	v_cvt_pk_bf16_f32 v66, v36, v37
	v_cvt_pk_bf16_f32 v67, v38, v39
	v_cvt_pk_bf16_f32 v68, v40, v41
	v_cvt_pk_bf16_f32 v69, v42, v43
	v_cvt_pk_bf16_f32 v70, v44, v45
	v_cvt_pk_bf16_f32 v71, v46, v47
	v_pk_add_f32 v[232:233], v[232:233], v[32:33]
	v_pk_add_f32 v[232:233], v[232:233], v[34:35]
	v_pk_add_f32 v[232:233], v[232:233], v[36:37]
	v_pk_add_f32 v[232:233], v[232:233], v[38:39]
	v_pk_add_f32 v[232:233], v[232:233], v[40:41]
	v_pk_add_f32 v[232:233], v[232:233], v[42:43]
	v_pk_add_f32 v[232:233], v[232:233], v[44:45]
	v_pk_add_f32 v[232:233], v[232:233], v[46:47]
	s_waitcnt lgkmcnt(0)
	v_mfma_f32_32x32x16_bf16 v[0:15], v[64:67], v[72:75], v[0:15]
	v_mfma_f32_32x32x16_bf16 v[16:31], v[64:67], v[76:79], v[16:31]
	v_mfma_f32_32x32x16_bf16 v[0:15], v[68:71], v[220:223], v[0:15]
	v_mfma_f32_32x32x16_bf16 v[16:31], v[68:71], v[224:227], v[16:31]
	s_add_i32 s90, s76, 0
	v_add_u32_e32 v80, s90, v243
	v_add_u32_e32 v83, s90, v244
	v_add_u32_e32 v99, s90, v245
	v_add_u32_e32 v253, s90, v246
	v_add_u32_e32 v254, s90, v148
	v_add_u32_e32 v255, s90, v151
	v_med3_i32 v80, v80, 0, s99
	v_med3_i32 v83, v83, 0, s99
	v_med3_i32 v99, v99, 0, s99
	v_med3_i32 v253, v253, 0, s99
	v_med3_i32 v254, v254, 0, s99
	v_med3_i32 v255, v255, 0, s99
	v_mad_u32_u24 v80, v80, s100, v252
	v_mad_u32_u24 v83, v83, s100, v252
	v_mad_u32_u24 v99, v99, s100, v252
	v_mad_u32_u24 v253, v253, s100, v252
	v_mad_u32_u24 v254, v254, s100, v153
	v_mad_u32_u24 v255, v255, s100, v153
	global_load_dwordx4 v[116:119], v80, s[82:83]
	global_load_dwordx4 v[120:123], v83, s[82:83]
	global_load_dwordx4 v[124:127], v99, s[82:83]
	global_load_dwordx4 v[128:131], v253, s[82:83]
	global_load_dwordx4 v[132:135], v254, s[82:83] offset:768
	global_load_dwordx4 v[136:139], v255, s[82:83] offset:768
	global_load_dwordx4 v[140:143], v254, s[82:83] offset:832
	global_load_dwordx4 v[144:147], v255, s[82:83] offset:832
	s_waitcnt vmcnt(16)
	ds_write_b128 v247, v[156:159]
	ds_write_b128 v247, v[160:163] offset:1024
	ds_write_b128 v247, v[164:167] offset:2048
	ds_write_b128 v247, v[168:171] offset:3072
	ds_read_b128 v[156:159], v248
	ds_read_b128 v[160:163], v249
	ds_read_b128 v[164:167], v250
	ds_read_b128 v[168:171], v251
	ds_write_b128 v112, v[172:175]
	ds_write_b128 v112, v[176:179] offset:1024
	ds_write_b128 v112, v[180:183] offset:2048
	ds_write_b128 v112, v[184:187] offset:3072
	v_mov_b32_e32 v115, v230
	ds_read2_b32 v[32:33], v115 offset0:0 offset1:1
	ds_read2_b32 v[34:35], v115 offset0:2 offset1:3
	ds_read2_b32 v[36:37], v115 offset0:8 offset1:9
	ds_read2_b32 v[38:39], v115 offset0:10 offset1:11
	ds_read2_b32 v[40:41], v115 offset0:16 offset1:17
	ds_read2_b32 v[42:43], v115 offset0:18 offset1:19
	ds_read2_b32 v[44:45], v115 offset0:24 offset1:25
	ds_read2_b32 v[46:47], v115 offset0:26 offset1:27
	s_waitcnt lgkmcnt(0)
	v_mfma_f32_32x32x16_bf16 v[32:47], v[156:159], v[48:51], v[32:47]
	ds_read_b64_tr_b16 v[72:73], v231
	ds_read_b64_tr_b16 v[74:75], v231 offset:512
	ds_read_b64_tr_b16 v[76:77], v231 offset:2048
	ds_read_b64_tr_b16 v[78:79], v231 offset:2560
	ds_read_b64_tr_b16 v[220:221], v231 offset:1024
	ds_read_b64_tr_b16 v[222:223], v231 offset:1536
	ds_read_b64_tr_b16 v[224:225], v231 offset:3072
	ds_read_b64_tr_b16 v[226:227], v231 offset:3584
	v_mfma_f32_32x32x16_bf16 v[32:47], v[160:163], v[52:55], v[32:47]
	v_mfma_f32_32x32x16_bf16 v[32:47], v[164:167], v[56:59], v[32:47]
	v_mfma_f32_32x32x16_bf16 v[32:47], v[168:171], v[60:63], v[32:47]
	s_nop 11
	v_exp_f32_e32 v32, v32
	v_exp_f32_e32 v33, v33
	v_exp_f32_e32 v34, v34
	v_exp_f32_e32 v35, v35
	v_exp_f32_e32 v36, v36
	v_exp_f32_e32 v37, v37
	v_exp_f32_e32 v38, v38
	v_exp_f32_e32 v39, v39
	v_exp_f32_e32 v40, v40
	v_exp_f32_e32 v41, v41
	v_exp_f32_e32 v42, v42
	v_exp_f32_e32 v43, v43
	v_exp_f32_e32 v44, v44
	v_exp_f32_e32 v45, v45
	v_exp_f32_e32 v46, v46
	v_exp_f32_e32 v47, v47
	s_add_i32 s90, s76, -1024
	v_lshlrev_b32_e32 v84, 4, v107
	v_add_u32_e32 v84, s90, v84
	v_add_u32_e32 v85, 0, v84
	v_add_u32_e32 v86, 16, v84
	v_add_u32_e32 v87, 32, v84
	v_add_u32_e32 v88, 48, v84
	v_cmp_gt_u32_e64 s[30:31], s98, v85
	v_cmp_gt_u32_e64 s[36:37], s98, v86
	v_cmp_gt_u32_e64 s[78:79], s98, v87
	v_cmp_gt_u32_e64 s[50:51], s98, v88
	v_cndmask_b32_e64 v32, 0, v32, s[30:31]
	v_add_u32_e32 v85, 128, v84
	v_cmp_gt_u32_e64 s[30:31], s98, v85
	v_cndmask_b32_e64 v33, 0, v33, s[36:37]
	v_add_u32_e32 v86, 144, v84
	v_cmp_gt_u32_e64 s[36:37], s98, v86
	v_cndmask_b32_e64 v34, 0, v34, s[78:79]
	v_add_u32_e32 v87, 160, v84
	v_cmp_gt_u32_e64 s[78:79], s98, v87
	v_cndmask_b32_e64 v35, 0, v35, s[50:51]
	v_add_u32_e32 v88, 176, v84
	v_cmp_gt_u32_e64 s[50:51], s98, v88
	v_cndmask_b32_e64 v36, 0, v36, s[30:31]
	v_add_u32_e32 v85, 256, v84
	v_cmp_gt_u32_e64 s[30:31], s98, v85
	v_cndmask_b32_e64 v37, 0, v37, s[36:37]
	v_add_u32_e32 v86, 272, v84
	v_cmp_gt_u32_e64 s[36:37], s98, v86
	v_cndmask_b32_e64 v38, 0, v38, s[78:79]
	v_add_u32_e32 v87, 288, v84
	v_cmp_gt_u32_e64 s[78:79], s98, v87
	v_cndmask_b32_e64 v39, 0, v39, s[50:51]
	v_add_u32_e32 v88, 304, v84
	v_cmp_gt_u32_e64 s[50:51], s98, v88
	v_cndmask_b32_e64 v40, 0, v40, s[30:31]
	v_add_u32_e32 v85, 384, v84
	v_cmp_gt_u32_e64 s[30:31], s98, v85
	v_cndmask_b32_e64 v41, 0, v41, s[36:37]
	v_add_u32_e32 v86, 400, v84
	v_cmp_gt_u32_e64 s[36:37], s98, v86
	v_cndmask_b32_e64 v42, 0, v42, s[78:79]
	v_add_u32_e32 v87, 416, v84
	v_cmp_gt_u32_e64 s[78:79], s98, v87
	v_cndmask_b32_e64 v43, 0, v43, s[50:51]
	v_add_u32_e32 v88, 432, v84
	v_cmp_gt_u32_e64 s[50:51], s98, v88
	v_nop
	v_cndmask_b32_e64 v44, 0, v44, s[30:31]
	v_cndmask_b32_e64 v45, 0, v45, s[36:37]
	v_cndmask_b32_e64 v46, 0, v46, s[78:79]
	v_cndmask_b32_e64 v47, 0, v47, s[50:51]
	v_cvt_pk_bf16_f32 v64, v32, v33
	v_cvt_pk_bf16_f32 v65, v34, v35
	v_cvt_pk_bf16_f32 v66, v36, v37
	v_cvt_pk_bf16_f32 v67, v38, v39
	v_cvt_pk_bf16_f32 v68, v40, v41
	v_cvt_pk_bf16_f32 v69, v42, v43
	v_cvt_pk_bf16_f32 v70, v44, v45
	v_cvt_pk_bf16_f32 v71, v46, v47
	v_pk_add_f32 v[232:233], v[232:233], v[32:33]
	v_pk_add_f32 v[232:233], v[232:233], v[34:35]
	v_pk_add_f32 v[232:233], v[232:233], v[36:37]
	v_pk_add_f32 v[232:233], v[232:233], v[38:39]
	v_pk_add_f32 v[232:233], v[232:233], v[40:41]
	v_pk_add_f32 v[232:233], v[232:233], v[42:43]
	v_pk_add_f32 v[232:233], v[232:233], v[44:45]
	v_pk_add_f32 v[232:233], v[232:233], v[46:47]
	s_waitcnt lgkmcnt(0)
	v_mfma_f32_32x32x16_bf16 v[0:15], v[64:67], v[72:75], v[0:15]
	v_mfma_f32_32x32x16_bf16 v[16:31], v[64:67], v[76:79], v[16:31]
	v_mfma_f32_32x32x16_bf16 v[0:15], v[68:71], v[220:223], v[0:15]
	v_mfma_f32_32x32x16_bf16 v[16:31], v[68:71], v[224:227], v[16:31]
	s_add_i32 s90, s76, 512
	v_add_u32_e32 v80, s90, v243
	v_add_u32_e32 v83, s90, v244
	v_add_u32_e32 v99, s90, v245
	v_add_u32_e32 v253, s90, v246
	v_add_u32_e32 v254, s90, v148
	v_add_u32_e32 v255, s90, v151
	v_med3_i32 v80, v80, 0, s99
	v_med3_i32 v83, v83, 0, s99
	v_med3_i32 v99, v99, 0, s99
	v_med3_i32 v253, v253, 0, s99
	v_med3_i32 v254, v254, 0, s99
	v_med3_i32 v255, v255, 0, s99
	v_mad_u32_u24 v80, v80, s100, v252
	v_mad_u32_u24 v83, v83, s100, v252
	v_mad_u32_u24 v99, v99, s100, v252
	v_mad_u32_u24 v253, v253, s100, v252
	v_mad_u32_u24 v254, v254, s100, v153
	v_mad_u32_u24 v255, v255, s100, v153
	global_load_dwordx4 v[156:159], v80, s[82:83]
	global_load_dwordx4 v[160:163], v83, s[82:83]
	global_load_dwordx4 v[164:167], v99, s[82:83]
	global_load_dwordx4 v[168:171], v253, s[82:83]
	global_load_dwordx4 v[172:175], v254, s[82:83] offset:768
	global_load_dwordx4 v[176:179], v255, s[82:83] offset:768
	global_load_dwordx4 v[180:183], v254, s[82:83] offset:832
	global_load_dwordx4 v[184:187], v255, s[82:83] offset:832
	s_waitcnt vmcnt(16)
	ds_write_b128 v247, v[188:191]
	ds_write_b128 v247, v[192:195] offset:1024
	ds_write_b128 v247, v[196:199] offset:2048
	ds_write_b128 v247, v[200:203] offset:3072
	ds_read_b128 v[188:191], v248
	ds_read_b128 v[192:195], v249
	ds_read_b128 v[196:199], v250
	ds_read_b128 v[200:203], v251
	ds_write_b128 v112, v[204:207]
	ds_write_b128 v112, v[208:211] offset:1024
	ds_write_b128 v112, v[212:215] offset:2048
	ds_write_b128 v112, v[216:219] offset:3072
	ds_read2_b32 v[32:33], v115 offset0:32 offset1:33
	ds_read2_b32 v[34:35], v115 offset0:34 offset1:35
	ds_read2_b32 v[36:37], v115 offset0:40 offset1:41
	ds_read2_b32 v[38:39], v115 offset0:42 offset1:43
	ds_read2_b32 v[40:41], v115 offset0:48 offset1:49
	ds_read2_b32 v[42:43], v115 offset0:50 offset1:51
	ds_read2_b32 v[44:45], v115 offset0:56 offset1:57
	ds_read2_b32 v[46:47], v115 offset0:58 offset1:59
	s_waitcnt lgkmcnt(0)
	v_mfma_f32_32x32x16_bf16 v[32:47], v[188:191], v[48:51], v[32:47]
	ds_read_b64_tr_b16 v[72:73], v231
	ds_read_b64_tr_b16 v[74:75], v231 offset:512
	ds_read_b64_tr_b16 v[76:77], v231 offset:2048
	ds_read_b64_tr_b16 v[78:79], v231 offset:2560
	ds_read_b64_tr_b16 v[220:221], v231 offset:1024
	ds_read_b64_tr_b16 v[222:223], v231 offset:1536
	ds_read_b64_tr_b16 v[224:225], v231 offset:3072
	ds_read_b64_tr_b16 v[226:227], v231 offset:3584
	v_mfma_f32_32x32x16_bf16 v[32:47], v[192:195], v[52:55], v[32:47]
	v_mfma_f32_32x32x16_bf16 v[32:47], v[196:199], v[56:59], v[32:47]
	v_mfma_f32_32x32x16_bf16 v[32:47], v[200:203], v[60:63], v[32:47]
	s_nop 11
	v_exp_f32_e32 v32, v32
	v_exp_f32_e32 v33, v33
	v_exp_f32_e32 v34, v34
	v_exp_f32_e32 v35, v35
	v_exp_f32_e32 v36, v36
	v_exp_f32_e32 v37, v37
	v_exp_f32_e32 v38, v38
	v_exp_f32_e32 v39, v39
	v_exp_f32_e32 v40, v40
	v_exp_f32_e32 v41, v41
	v_exp_f32_e32 v42, v42
	v_exp_f32_e32 v43, v43
	v_exp_f32_e32 v44, v44
	v_exp_f32_e32 v45, v45
	v_exp_f32_e32 v46, v46
	v_exp_f32_e32 v47, v47
	s_add_i32 s90, s76, -512
	v_lshlrev_b32_e32 v84, 4, v107
	v_add_u32_e32 v84, s90, v84
	v_add_u32_e32 v85, 0, v84
	v_add_u32_e32 v86, 16, v84
	v_add_u32_e32 v87, 32, v84
	v_add_u32_e32 v88, 48, v84
	v_cmp_gt_u32_e64 s[30:31], s98, v85
	v_cmp_gt_u32_e64 s[36:37], s98, v86
	v_cmp_gt_u32_e64 s[78:79], s98, v87
	v_cmp_gt_u32_e64 s[50:51], s98, v88
	v_cndmask_b32_e64 v32, 0, v32, s[30:31]
	v_add_u32_e32 v85, 128, v84
	v_cmp_gt_u32_e64 s[30:31], s98, v85
	v_cndmask_b32_e64 v33, 0, v33, s[36:37]
	v_add_u32_e32 v86, 144, v84
	v_cmp_gt_u32_e64 s[36:37], s98, v86
	v_cndmask_b32_e64 v34, 0, v34, s[78:79]
	v_add_u32_e32 v87, 160, v84
	v_cmp_gt_u32_e64 s[78:79], s98, v87
	v_cndmask_b32_e64 v35, 0, v35, s[50:51]
	v_add_u32_e32 v88, 176, v84
	v_cmp_gt_u32_e64 s[50:51], s98, v88
	v_cndmask_b32_e64 v36, 0, v36, s[30:31]
	v_add_u32_e32 v85, 256, v84
	v_cmp_gt_u32_e64 s[30:31], s98, v85
	v_cndmask_b32_e64 v37, 0, v37, s[36:37]
	v_add_u32_e32 v86, 272, v84
	v_cmp_gt_u32_e64 s[36:37], s98, v86
	v_cndmask_b32_e64 v38, 0, v38, s[78:79]
	v_add_u32_e32 v87, 288, v84
	v_cmp_gt_u32_e64 s[78:79], s98, v87
	v_cndmask_b32_e64 v39, 0, v39, s[50:51]
	v_add_u32_e32 v88, 304, v84
	v_cmp_gt_u32_e64 s[50:51], s98, v88
	v_cndmask_b32_e64 v40, 0, v40, s[30:31]
	v_add_u32_e32 v85, 384, v84
	v_cmp_gt_u32_e64 s[30:31], s98, v85
	v_cndmask_b32_e64 v41, 0, v41, s[36:37]
	v_add_u32_e32 v86, 400, v84
	v_cmp_gt_u32_e64 s[36:37], s98, v86
	v_cndmask_b32_e64 v42, 0, v42, s[78:79]
	v_add_u32_e32 v87, 416, v84
	v_cmp_gt_u32_e64 s[78:79], s98, v87
	v_cndmask_b32_e64 v43, 0, v43, s[50:51]
	v_add_u32_e32 v88, 432, v84
	v_cmp_gt_u32_e64 s[50:51], s98, v88
	v_nop
	v_cndmask_b32_e64 v44, 0, v44, s[30:31]
	v_cndmask_b32_e64 v45, 0, v45, s[36:37]
	v_cndmask_b32_e64 v46, 0, v46, s[78:79]
	v_cndmask_b32_e64 v47, 0, v47, s[50:51]
	v_cvt_pk_bf16_f32 v64, v32, v33
	v_cvt_pk_bf16_f32 v65, v34, v35
	v_cvt_pk_bf16_f32 v66, v36, v37
	v_cvt_pk_bf16_f32 v67, v38, v39
	v_cvt_pk_bf16_f32 v68, v40, v41
	v_cvt_pk_bf16_f32 v69, v42, v43
	v_cvt_pk_bf16_f32 v70, v44, v45
	v_cvt_pk_bf16_f32 v71, v46, v47
	v_pk_add_f32 v[232:233], v[232:233], v[32:33]
	v_pk_add_f32 v[232:233], v[232:233], v[34:35]
	v_pk_add_f32 v[232:233], v[232:233], v[36:37]
	v_pk_add_f32 v[232:233], v[232:233], v[38:39]
	v_pk_add_f32 v[232:233], v[232:233], v[40:41]
	v_pk_add_f32 v[232:233], v[232:233], v[42:43]
	v_pk_add_f32 v[232:233], v[232:233], v[44:45]
	v_pk_add_f32 v[232:233], v[232:233], v[46:47]
	s_waitcnt lgkmcnt(0)
	v_mfma_f32_32x32x16_bf16 v[0:15], v[64:67], v[72:75], v[0:15]
	v_mfma_f32_32x32x16_bf16 v[16:31], v[64:67], v[76:79], v[16:31]
	v_mfma_f32_32x32x16_bf16 v[0:15], v[68:71], v[220:223], v[0:15]
	v_mfma_f32_32x32x16_bf16 v[16:31], v[68:71], v[224:227], v[16:31]
	s_add_i32 s90, s76, 1024
	v_add_u32_e32 v80, s90, v243
	v_add_u32_e32 v83, s90, v244
	v_add_u32_e32 v99, s90, v245
	v_add_u32_e32 v253, s90, v246
	v_add_u32_e32 v254, s90, v148
	v_add_u32_e32 v255, s90, v151
	v_med3_i32 v80, v80, 0, s99
	v_med3_i32 v83, v83, 0, s99
	v_med3_i32 v99, v99, 0, s99
	v_med3_i32 v253, v253, 0, s99
	v_med3_i32 v254, v254, 0, s99
	v_med3_i32 v255, v255, 0, s99
	v_mad_u32_u24 v80, v80, s100, v252
	v_mad_u32_u24 v83, v83, s100, v252
	v_mad_u32_u24 v99, v99, s100, v252
	v_mad_u32_u24 v253, v253, s100, v252
	v_mad_u32_u24 v254, v254, s100, v153
	v_mad_u32_u24 v255, v255, s100, v153
	global_load_dwordx4 v[188:191], v80, s[82:83]
	global_load_dwordx4 v[192:195], v83, s[82:83]
	global_load_dwordx4 v[196:199], v99, s[82:83]
	global_load_dwordx4 v[200:203], v253, s[82:83]
	global_load_dwordx4 v[204:207], v254, s[82:83] offset:768
	global_load_dwordx4 v[208:211], v255, s[82:83] offset:768
	global_load_dwordx4 v[212:215], v254, s[82:83] offset:832
	global_load_dwordx4 v[216:219], v255, s[82:83] offset:832
	s_waitcnt vmcnt(16)
	ds_write_b128 v247, v[116:119]
	ds_write_b128 v247, v[120:123] offset:1024
	ds_write_b128 v247, v[124:127] offset:2048
	ds_write_b128 v247, v[128:131] offset:3072
	ds_read_b128 v[116:119], v248
	ds_read_b128 v[120:123], v249
	ds_read_b128 v[124:127], v250
	ds_read_b128 v[128:131], v251
	ds_write_b128 v112, v[132:135]
	ds_write_b128 v112, v[136:139] offset:1024
	ds_write_b128 v112, v[140:143] offset:2048
	ds_write_b128 v112, v[144:147] offset:3072
	ds_read2_b32 v[32:33], v115 offset0:64 offset1:65
	ds_read2_b32 v[34:35], v115 offset0:66 offset1:67
	ds_read2_b32 v[36:37], v115 offset0:72 offset1:73
	ds_read2_b32 v[38:39], v115 offset0:74 offset1:75
	ds_read2_b32 v[40:41], v115 offset0:80 offset1:81
	ds_read2_b32 v[42:43], v115 offset0:82 offset1:83
	ds_read2_b32 v[44:45], v115 offset0:88 offset1:89
	ds_read2_b32 v[46:47], v115 offset0:90 offset1:91
	s_waitcnt lgkmcnt(0)
	v_mfma_f32_32x32x16_bf16 v[32:47], v[116:119], v[48:51], v[32:47]
	ds_read_b64_tr_b16 v[72:73], v231
	ds_read_b64_tr_b16 v[74:75], v231 offset:512
	ds_read_b64_tr_b16 v[76:77], v231 offset:2048
	ds_read_b64_tr_b16 v[78:79], v231 offset:2560
	ds_read_b64_tr_b16 v[220:221], v231 offset:1024
	ds_read_b64_tr_b16 v[222:223], v231 offset:1536
	ds_read_b64_tr_b16 v[224:225], v231 offset:3072
	ds_read_b64_tr_b16 v[226:227], v231 offset:3584
	v_mfma_f32_32x32x16_bf16 v[32:47], v[120:123], v[52:55], v[32:47]
	v_mfma_f32_32x32x16_bf16 v[32:47], v[124:127], v[56:59], v[32:47]
	v_mfma_f32_32x32x16_bf16 v[32:47], v[128:131], v[60:63], v[32:47]
	s_nop 11
	v_exp_f32_e32 v32, v32
	v_exp_f32_e32 v33, v33
	v_exp_f32_e32 v34, v34
	v_exp_f32_e32 v35, v35
	v_exp_f32_e32 v36, v36
	v_exp_f32_e32 v37, v37
	v_exp_f32_e32 v38, v38
	v_exp_f32_e32 v39, v39
	v_exp_f32_e32 v40, v40
	v_exp_f32_e32 v41, v41
	v_exp_f32_e32 v42, v42
	v_exp_f32_e32 v43, v43
	v_exp_f32_e32 v44, v44
	v_exp_f32_e32 v45, v45
	v_exp_f32_e32 v46, v46
	v_exp_f32_e32 v47, v47
	s_add_i32 s90, s76, 0
	v_lshlrev_b32_e32 v84, 4, v107
	v_add_u32_e32 v84, s90, v84
	v_add_u32_e32 v85, 0, v84
	v_add_u32_e32 v86, 16, v84
	v_add_u32_e32 v87, 32, v84
	v_add_u32_e32 v88, 48, v84
	v_cmp_gt_u32_e64 s[30:31], s98, v85
	v_cmp_gt_u32_e64 s[36:37], s98, v86
	v_cmp_gt_u32_e64 s[78:79], s98, v87
	v_cmp_gt_u32_e64 s[50:51], s98, v88
	v_cndmask_b32_e64 v32, 0, v32, s[30:31]
	v_add_u32_e32 v85, 128, v84
	v_cmp_gt_u32_e64 s[30:31], s98, v85
	v_cndmask_b32_e64 v33, 0, v33, s[36:37]
	v_add_u32_e32 v86, 144, v84
	v_cmp_gt_u32_e64 s[36:37], s98, v86
	v_cndmask_b32_e64 v34, 0, v34, s[78:79]
	v_add_u32_e32 v87, 160, v84
	v_cmp_gt_u32_e64 s[78:79], s98, v87
	v_cndmask_b32_e64 v35, 0, v35, s[50:51]
	v_add_u32_e32 v88, 176, v84
	v_cmp_gt_u32_e64 s[50:51], s98, v88
	v_cndmask_b32_e64 v36, 0, v36, s[30:31]
	v_add_u32_e32 v85, 256, v84
	v_cmp_gt_u32_e64 s[30:31], s98, v85
	v_cndmask_b32_e64 v37, 0, v37, s[36:37]
	v_add_u32_e32 v86, 272, v84
	v_cmp_gt_u32_e64 s[36:37], s98, v86
	v_cndmask_b32_e64 v38, 0, v38, s[78:79]
	v_add_u32_e32 v87, 288, v84
	v_cmp_gt_u32_e64 s[78:79], s98, v87
	v_cndmask_b32_e64 v39, 0, v39, s[50:51]
	v_add_u32_e32 v88, 304, v84
	v_cmp_gt_u32_e64 s[50:51], s98, v88
	v_cndmask_b32_e64 v40, 0, v40, s[30:31]
	v_add_u32_e32 v85, 384, v84
	v_cmp_gt_u32_e64 s[30:31], s98, v85
	v_cndmask_b32_e64 v41, 0, v41, s[36:37]
	v_add_u32_e32 v86, 400, v84
	v_cmp_gt_u32_e64 s[36:37], s98, v86
	v_cndmask_b32_e64 v42, 0, v42, s[78:79]
	v_add_u32_e32 v87, 416, v84
	v_cmp_gt_u32_e64 s[78:79], s98, v87
	v_cndmask_b32_e64 v43, 0, v43, s[50:51]
	v_add_u32_e32 v88, 432, v84
	v_cmp_gt_u32_e64 s[50:51], s98, v88
	v_nop
	v_cndmask_b32_e64 v44, 0, v44, s[30:31]
	v_cndmask_b32_e64 v45, 0, v45, s[36:37]
	v_cndmask_b32_e64 v46, 0, v46, s[78:79]
	v_cndmask_b32_e64 v47, 0, v47, s[50:51]
	v_cvt_pk_bf16_f32 v64, v32, v33
	v_cvt_pk_bf16_f32 v65, v34, v35
	v_cvt_pk_bf16_f32 v66, v36, v37
	v_cvt_pk_bf16_f32 v67, v38, v39
	v_cvt_pk_bf16_f32 v68, v40, v41
	v_cvt_pk_bf16_f32 v69, v42, v43
	v_cvt_pk_bf16_f32 v70, v44, v45
	v_cvt_pk_bf16_f32 v71, v46, v47
	v_pk_add_f32 v[232:233], v[232:233], v[32:33]
	v_pk_add_f32 v[232:233], v[232:233], v[34:35]
	v_pk_add_f32 v[232:233], v[232:233], v[36:37]
	v_pk_add_f32 v[232:233], v[232:233], v[38:39]
	v_pk_add_f32 v[232:233], v[232:233], v[40:41]
	v_pk_add_f32 v[232:233], v[232:233], v[42:43]
	v_pk_add_f32 v[232:233], v[232:233], v[44:45]
	v_pk_add_f32 v[232:233], v[232:233], v[46:47]
	s_waitcnt lgkmcnt(0)
	v_mfma_f32_32x32x16_bf16 v[0:15], v[64:67], v[72:75], v[0:15]
	v_mfma_f32_32x32x16_bf16 v[16:31], v[64:67], v[76:79], v[16:31]
	v_mfma_f32_32x32x16_bf16 v[0:15], v[68:71], v[220:223], v[0:15]
	v_mfma_f32_32x32x16_bf16 v[16:31], v[68:71], v[224:227], v[16:31]
	s_waitcnt vmcnt(8)
	ds_write_b128 v247, v[156:159]
	ds_write_b128 v247, v[160:163] offset:1024
	ds_write_b128 v247, v[164:167] offset:2048
	ds_write_b128 v247, v[168:171] offset:3072
	ds_read_b128 v[156:159], v248
	ds_read_b128 v[160:163], v249
	ds_read_b128 v[164:167], v250
	ds_read_b128 v[168:171], v251
	ds_write_b128 v112, v[172:175]
	ds_write_b128 v112, v[176:179] offset:1024
	ds_write_b128 v112, v[180:183] offset:2048
	ds_write_b128 v112, v[184:187] offset:3072
	ds_read2_b32 v[32:33], v115 offset0:96 offset1:97
	ds_read2_b32 v[34:35], v115 offset0:98 offset1:99
	ds_read2_b32 v[36:37], v115 offset0:104 offset1:105
	ds_read2_b32 v[38:39], v115 offset0:106 offset1:107
	ds_read2_b32 v[40:41], v115 offset0:112 offset1:113
	ds_read2_b32 v[42:43], v115 offset0:114 offset1:115
	ds_read2_b32 v[44:45], v115 offset0:120 offset1:121
	ds_read2_b32 v[46:47], v115 offset0:122 offset1:123
	s_waitcnt lgkmcnt(0)
	v_mfma_f32_32x32x16_bf16 v[32:47], v[156:159], v[48:51], v[32:47]
	ds_read_b64_tr_b16 v[72:73], v231
	ds_read_b64_tr_b16 v[74:75], v231 offset:512
	ds_read_b64_tr_b16 v[76:77], v231 offset:2048
	ds_read_b64_tr_b16 v[78:79], v231 offset:2560
	ds_read_b64_tr_b16 v[220:221], v231 offset:1024
	ds_read_b64_tr_b16 v[222:223], v231 offset:1536
	ds_read_b64_tr_b16 v[224:225], v231 offset:3072
	ds_read_b64_tr_b16 v[226:227], v231 offset:3584
	v_mfma_f32_32x32x16_bf16 v[32:47], v[160:163], v[52:55], v[32:47]
	v_mfma_f32_32x32x16_bf16 v[32:47], v[164:167], v[56:59], v[32:47]
	v_mfma_f32_32x32x16_bf16 v[32:47], v[168:171], v[60:63], v[32:47]
	s_nop 11
	v_exp_f32_e32 v32, v32
	v_exp_f32_e32 v33, v33
	v_exp_f32_e32 v34, v34
	v_exp_f32_e32 v35, v35
	v_exp_f32_e32 v36, v36
	v_exp_f32_e32 v37, v37
	v_exp_f32_e32 v38, v38
	v_exp_f32_e32 v39, v39
	v_exp_f32_e32 v40, v40
	v_exp_f32_e32 v41, v41
	v_exp_f32_e32 v42, v42
	v_exp_f32_e32 v43, v43
	v_exp_f32_e32 v44, v44
	v_exp_f32_e32 v45, v45
	v_exp_f32_e32 v46, v46
	v_exp_f32_e32 v47, v47
	s_add_i32 s90, s76, 512
	v_lshlrev_b32_e32 v84, 4, v107
	v_add_u32_e32 v84, s90, v84
	v_add_u32_e32 v85, 0, v84
	v_add_u32_e32 v86, 16, v84
	v_add_u32_e32 v87, 32, v84
	v_add_u32_e32 v88, 48, v84
	v_cmp_gt_u32_e64 s[30:31], s98, v85
	v_cmp_gt_u32_e64 s[36:37], s98, v86
	v_cmp_gt_u32_e64 s[78:79], s98, v87
	v_cmp_gt_u32_e64 s[50:51], s98, v88
	v_cndmask_b32_e64 v32, 0, v32, s[30:31]
	v_add_u32_e32 v85, 128, v84
	v_cmp_gt_u32_e64 s[30:31], s98, v85
	v_cndmask_b32_e64 v33, 0, v33, s[36:37]
	v_add_u32_e32 v86, 144, v84
	v_cmp_gt_u32_e64 s[36:37], s98, v86
	v_cndmask_b32_e64 v34, 0, v34, s[78:79]
	v_add_u32_e32 v87, 160, v84
	v_cmp_gt_u32_e64 s[78:79], s98, v87
	v_cndmask_b32_e64 v35, 0, v35, s[50:51]
	v_add_u32_e32 v88, 176, v84
	v_cmp_gt_u32_e64 s[50:51], s98, v88
	v_cndmask_b32_e64 v36, 0, v36, s[30:31]
	v_add_u32_e32 v85, 256, v84
	v_cmp_gt_u32_e64 s[30:31], s98, v85
	v_cndmask_b32_e64 v37, 0, v37, s[36:37]
	v_add_u32_e32 v86, 272, v84
	v_cmp_gt_u32_e64 s[36:37], s98, v86
	v_cndmask_b32_e64 v38, 0, v38, s[78:79]
	v_add_u32_e32 v87, 288, v84
	v_cmp_gt_u32_e64 s[78:79], s98, v87
	v_cndmask_b32_e64 v39, 0, v39, s[50:51]
	v_add_u32_e32 v88, 304, v84
	v_cmp_gt_u32_e64 s[50:51], s98, v88
	v_cndmask_b32_e64 v40, 0, v40, s[30:31]
	v_add_u32_e32 v85, 384, v84
	v_cmp_gt_u32_e64 s[30:31], s98, v85
	v_cndmask_b32_e64 v41, 0, v41, s[36:37]
	v_add_u32_e32 v86, 400, v84
	v_cmp_gt_u32_e64 s[36:37], s98, v86
	v_cndmask_b32_e64 v42, 0, v42, s[78:79]
	v_add_u32_e32 v87, 416, v84
	v_cmp_gt_u32_e64 s[78:79], s98, v87
	v_cndmask_b32_e64 v43, 0, v43, s[50:51]
	v_add_u32_e32 v88, 432, v84
	v_cmp_gt_u32_e64 s[50:51], s98, v88
	v_nop
	v_cndmask_b32_e64 v44, 0, v44, s[30:31]
	v_cndmask_b32_e64 v45, 0, v45, s[36:37]
	v_cndmask_b32_e64 v46, 0, v46, s[78:79]
	v_cndmask_b32_e64 v47, 0, v47, s[50:51]
	v_cvt_pk_bf16_f32 v64, v32, v33
	v_cvt_pk_bf16_f32 v65, v34, v35
	v_cvt_pk_bf16_f32 v66, v36, v37
	v_cvt_pk_bf16_f32 v67, v38, v39
	v_cvt_pk_bf16_f32 v68, v40, v41
	v_cvt_pk_bf16_f32 v69, v42, v43
	v_cvt_pk_bf16_f32 v70, v44, v45
	v_cvt_pk_bf16_f32 v71, v46, v47
	v_pk_add_f32 v[232:233], v[232:233], v[32:33]
	v_pk_add_f32 v[232:233], v[232:233], v[34:35]
	v_pk_add_f32 v[232:233], v[232:233], v[36:37]
	v_pk_add_f32 v[232:233], v[232:233], v[38:39]
	v_pk_add_f32 v[232:233], v[232:233], v[40:41]
	v_pk_add_f32 v[232:233], v[232:233], v[42:43]
	v_pk_add_f32 v[232:233], v[232:233], v[44:45]
	v_pk_add_f32 v[232:233], v[232:233], v[46:47]
	s_waitcnt lgkmcnt(0)
	v_mfma_f32_32x32x16_bf16 v[0:15], v[64:67], v[72:75], v[0:15]
	v_mfma_f32_32x32x16_bf16 v[16:31], v[64:67], v[76:79], v[16:31]
	v_mfma_f32_32x32x16_bf16 v[0:15], v[68:71], v[220:223], v[0:15]
	v_mfma_f32_32x32x16_bf16 v[16:31], v[68:71], v[224:227], v[16:31]
	s_waitcnt vmcnt(0)
	ds_write_b128 v247, v[188:191]
	ds_write_b128 v247, v[192:195] offset:1024
	ds_write_b128 v247, v[196:199] offset:2048
	ds_write_b128 v247, v[200:203] offset:3072
	ds_read_b128 v[188:191], v248
	ds_read_b128 v[192:195], v249
	ds_read_b128 v[196:199], v250
	ds_read_b128 v[200:203], v251
	ds_write_b128 v112, v[204:207]
	ds_write_b128 v112, v[208:211] offset:1024
	ds_write_b128 v112, v[212:215] offset:2048
	ds_write_b128 v112, v[216:219] offset:3072
	ds_read2_b32 v[32:33], v115 offset0:128 offset1:129
	ds_read2_b32 v[34:35], v115 offset0:130 offset1:131
	ds_read2_b32 v[36:37], v115 offset0:136 offset1:137
	ds_read2_b32 v[38:39], v115 offset0:138 offset1:139
	ds_read2_b32 v[40:41], v115 offset0:144 offset1:145
	ds_read2_b32 v[42:43], v115 offset0:146 offset1:147
	ds_read2_b32 v[44:45], v115 offset0:152 offset1:153
	ds_read2_b32 v[46:47], v115 offset0:154 offset1:155
	s_waitcnt lgkmcnt(0)
; #define LAS __attribute__((address_space(3)))
; __device__ __forceinline__ void dil_unit(LAS unsigned char* lds, bf16_t* proj, int seq, int hd, int T0, int rho) {
;     ...
;     if (bound) DIL_LOOP(true); else DIL_LOOP(false);
;     ...
;     LAS bf16_t* stg = (LAS bf16_t*)wbuf;
;     l += __shfl_xor(l, 32);
	v_mfma_f32_32x32x16_bf16 v[32:47], v[188:191], v[48:51], v[32:47]
	ds_read_b64_tr_b16 v[72:73], v231
	ds_read_b64_tr_b16 v[74:75], v231 offset:512
	ds_read_b64_tr_b16 v[76:77], v231 offset:2048
	ds_read_b64_tr_b16 v[78:79], v231 offset:2560
	ds_read_b64_tr_b16 v[220:221], v231 offset:1024
	ds_read_b64_tr_b16 v[222:223], v231 offset:1536
	ds_read_b64_tr_b16 v[224:225], v231 offset:3072
	ds_read_b64_tr_b16 v[226:227], v231 offset:3584
	v_mfma_f32_32x32x16_bf16 v[32:47], v[192:195], v[52:55], v[32:47]
	v_mfma_f32_32x32x16_bf16 v[32:47], v[196:199], v[56:59], v[32:47]
	v_mfma_f32_32x32x16_bf16 v[32:47], v[200:203], v[60:63], v[32:47]
	s_nop 11
	v_exp_f32_e32 v32, v32
	v_exp_f32_e32 v33, v33
	v_exp_f32_e32 v34, v34
	v_exp_f32_e32 v35, v35
	v_exp_f32_e32 v36, v36
	v_exp_f32_e32 v37, v37
	v_exp_f32_e32 v38, v38
	v_exp_f32_e32 v39, v39
	v_exp_f32_e32 v40, v40
	v_exp_f32_e32 v41, v41
	v_exp_f32_e32 v42, v42
	v_exp_f32_e32 v43, v43
	v_exp_f32_e32 v44, v44
	v_exp_f32_e32 v45, v45
	v_exp_f32_e32 v46, v46
	v_exp_f32_e32 v47, v47
	s_add_i32 s90, s76, 1024
	v_lshlrev_b32_e32 v84, 4, v107
	v_add_u32_e32 v84, s90, v84
	v_add_u32_e32 v85, 0, v84
	v_add_u32_e32 v86, 16, v84
	v_add_u32_e32 v87, 32, v84
	v_add_u32_e32 v88, 48, v84
	v_cmp_gt_u32_e64 s[30:31], s98, v85
	v_cmp_gt_u32_e64 s[36:37], s98, v86
	v_cmp_gt_u32_e64 s[78:79], s98, v87
	v_cmp_gt_u32_e64 s[50:51], s98, v88
	v_cndmask_b32_e64 v32, 0, v32, s[30:31]
	v_add_u32_e32 v85, 128, v84
	v_cmp_gt_u32_e64 s[30:31], s98, v85
	v_cndmask_b32_e64 v33, 0, v33, s[36:37]
	v_add_u32_e32 v86, 144, v84
	v_cmp_gt_u32_e64 s[36:37], s98, v86
	v_cndmask_b32_e64 v34, 0, v34, s[78:79]
	v_add_u32_e32 v87, 160, v84
	v_cmp_gt_u32_e64 s[78:79], s98, v87
	v_cndmask_b32_e64 v35, 0, v35, s[50:51]
	v_add_u32_e32 v88, 176, v84
	v_cmp_gt_u32_e64 s[50:51], s98, v88
	v_cndmask_b32_e64 v36, 0, v36, s[30:31]
	v_add_u32_e32 v85, 256, v84
	v_cmp_gt_u32_e64 s[30:31], s98, v85
	v_cndmask_b32_e64 v37, 0, v37, s[36:37]
	v_add_u32_e32 v86, 272, v84
	v_cmp_gt_u32_e64 s[36:37], s98, v86
	v_cndmask_b32_e64 v38, 0, v38, s[78:79]
	v_add_u32_e32 v87, 288, v84
	v_cmp_gt_u32_e64 s[78:79], s98, v87
	v_cndmask_b32_e64 v39, 0, v39, s[50:51]
	v_add_u32_e32 v88, 304, v84
	v_cmp_gt_u32_e64 s[50:51], s98, v88
	v_cndmask_b32_e64 v40, 0, v40, s[30:31]
	v_add_u32_e32 v85, 384, v84
	v_cmp_gt_u32_e64 s[30:31], s98, v85
	v_cndmask_b32_e64 v41, 0, v41, s[36:37]
	v_add_u32_e32 v86, 400, v84
	v_cmp_gt_u32_e64 s[36:37], s98, v86
	v_cndmask_b32_e64 v42, 0, v42, s[78:79]
	v_add_u32_e32 v87, 416, v84
	v_cmp_gt_u32_e64 s[78:79], s98, v87
	v_cndmask_b32_e64 v43, 0, v43, s[50:51]
	v_add_u32_e32 v88, 432, v84
	v_cmp_gt_u32_e64 s[50:51], s98, v88
	v_nop
	v_cndmask_b32_e64 v44, 0, v44, s[30:31]
	v_cndmask_b32_e64 v45, 0, v45, s[36:37]
	v_cndmask_b32_e64 v46, 0, v46, s[78:79]
	v_cndmask_b32_e64 v47, 0, v47, s[50:51]
	v_cvt_pk_bf16_f32 v64, v32, v33
	v_cvt_pk_bf16_f32 v65, v34, v35
	v_cvt_pk_bf16_f32 v66, v36, v37
	v_cvt_pk_bf16_f32 v67, v38, v39
	v_cvt_pk_bf16_f32 v68, v40, v41
	v_cvt_pk_bf16_f32 v69, v42, v43
	v_cvt_pk_bf16_f32 v70, v44, v45
	v_cvt_pk_bf16_f32 v71, v46, v47
	v_pk_add_f32 v[232:233], v[232:233], v[32:33]
	v_pk_add_f32 v[232:233], v[232:233], v[34:35]
	v_pk_add_f32 v[232:233], v[232:233], v[36:37]
	v_pk_add_f32 v[232:233], v[232:233], v[38:39]
	v_pk_add_f32 v[232:233], v[232:233], v[40:41]
	v_pk_add_f32 v[232:233], v[232:233], v[42:43]
	v_pk_add_f32 v[232:233], v[232:233], v[44:45]
	v_pk_add_f32 v[232:233], v[232:233], v[46:47]
	s_waitcnt lgkmcnt(0)
	v_mfma_f32_32x32x16_bf16 v[0:15], v[64:67], v[72:75], v[0:15]
	v_mfma_f32_32x32x16_bf16 v[16:31], v[64:67], v[76:79], v[16:31]
	v_mfma_f32_32x32x16_bf16 v[0:15], v[68:71], v[220:223], v[0:15]
	v_mfma_f32_32x32x16_bf16 v[16:31], v[68:71], v[224:227], v[16:31]
	v_add_f32_e32 v113, v232, v233
	v_or_b32_e32 v114, 1, v107
	v_or_b32_e32 v97, 2, v107
	v_or_b32_e32 v96, 3, v107
	v_or_b32_e32 v95, 8, v107
	v_or_b32_e32 v94, 9, v107
	v_or_b32_e32 v93, 10, v107
	v_or_b32_e32 v92, 11, v107
	v_or_b32_e32 v91, 16, v107
	v_or_b32_e32 v90, 17, v107
	v_or_b32_e32 v89, 18, v107
	v_or_b32_e32 v88, 19, v107
	v_or_b32_e32 v87, 24, v107
	v_or_b32_e32 v86, 25, v107
	v_or_b32_e32 v85, 26, v107
	v_or_b32_e32 v84, 27, v107
	s_nop 11
	s_branch .LBB0_553

; #define LAS __attribute__((address_space(3)))
; #define GAS __attribute__((address_space(1)))
; __device__ __forceinline__ void dil_unit(LAS unsigned char* lds, bf16_t* proj, int seq, int hd, int T0, int rho) {
;     ...
;     const int tid = tid_, lane = tid & 63, r32 = lane & 31, hi = lane >> 5, wid = __builtin_amdgcn_readfirstlane(tid >> 6);
;     bf16_t* base = proj + (size_t)seq * SEQ * NIN;
;     LAS unsigned char* wbuf = lds + wid * 4096;
;     const LAS unsigned char* vp = wbuf + ((lane >> 4) & 1) * 32 + (lane & 3) * 8 + (4 * hi + ((lane & 15) >> 2)) * 64;
;     const int P0 = T0 + rho;
;     bf16x8 qr[4];
; #pragma unroll
;     for (int ks = 0; ks < 4; ++ks) qr[ks] = *(const GAS bf16x8*)(base + (size_t)(P0 + 16 * r32) * NIN + PC_LQ + hd * 64 + 16 * ks + 8 * hi);
;     f32x16 o0 = {}, o1 = {}; float l = 0.f;
;     const bool bound = (T0 < 1024) || (T0 >= 15360);
.LBB0_1270:
	s_movk_i32 s100, 0x1800
	s_add_i32 s101, s8, 0x15c00
	s_lshl_b32 s90, s54, 1
	s_add_u32 s82, s52, s90
	s_addc_u32 s83, s53, 0
	s_add_u32 s82, s82, 0x1200
	s_addc_u32 s83, s83, 0
	s_sub_i32 s90, s67, 64
	s_mul_i32 s90, s90, 0x1800
	s_add_u32 s84, s82, s90
	s_addc_u32 s85, s83, 0
	s_sub_i32 s90, s67, 256
	s_mul_i32 s90, s90, 0x1800
	s_add_u32 s86, s82, s90
	s_addc_u32 s87, s83, 0
	s_sub_i32 s90, s67, 1024
	s_mul_i32 s90, s90, 0x1800
	s_add_u32 s88, s82, s90
	s_addc_u32 s89, s83, 0
	v_lshlrev_b32_e32 v153, 1, v98
	v_mad_u32_u24 v80, v105, s100, v82
	v_mad_u32_u24 v100, v110, s100, v153
	v_add_u32_e32 v149, 0x18000, v100
	v_lshlrev_b32_e32 v83, 2, v105
	v_mad_u32_u24 v83, v83, s100, v82
	v_lshlrev_b32_e32 v101, 2, v110
	v_mad_u32_u24 v101, v101, s100, v153
	v_add_u32_e32 v150, 0x60000, v101
	v_lshlrev_b32_e32 v99, 4, v105
	v_mad_u32_u24 v99, v99, s100, v82
	v_lshlrev_b32_e32 v148, 4, v110
	v_mad_u32_u24 v148, v148, s100, v153
	v_add_u32_e32 v151, 0x180000, v148
	v_lshrrev_b32_e32 v249, 3, v103
	v_and_b32_e32 v250, 7, v103
	v_lshlrev_b32_e32 v250, 4, v250
	v_add_u32_e32 v235, 0, v249
	v_add_u32_e32 v236, 8, v249
	v_add_u32_e32 v237, 16, v249
	v_add_u32_e32 v238, 24, v249
	v_add_u32_e32 v239, 0, v249
	v_lshlrev_b32_e32 v239, 2, v239
	v_add_u32_e32 v240, 8, v249
	v_lshlrev_b32_e32 v240, 2, v240
	v_add_u32_e32 v241, 16, v249
	v_lshlrev_b32_e32 v241, 2, v241
	v_add_u32_e32 v242, 24, v249
	v_lshlrev_b32_e32 v242, 2, v242
	v_add_u32_e32 v243, 0, v249
	v_lshlrev_b32_e32 v243, 4, v243
	v_add_u32_e32 v244, 8, v249
	v_lshlrev_b32_e32 v244, 4, v244
	v_add_u32_e32 v245, 16, v249
	v_lshlrev_b32_e32 v245, 4, v245
	v_add_u32_e32 v246, 24, v249
	v_lshlrev_b32_e32 v246, 4, v246
	v_mov_b32_e32 v252, v250
	v_mov_b32_e32 v100, v110
	v_add_u32_e32 v149, 16, v100
	v_lshlrev_b32_e32 v101, 2, v110
	v_add_u32_e32 v150, 64, v101
	v_lshlrev_b32_e32 v148, 4, v110
	v_add_u32_e32 v151, 256, v148
	s_mov_b32 s98, 0x4000
	s_mov_b32 s99, 0x3fff
	v_and_b32_e32 v247, 7, v249
	v_lshlrev_b32_e32 v247, 4, v247
	v_xor_b32_e32 v247, v247, v112
	v_and_b32_e32 v153, 7, v105
	v_or_b32_e32 v248, 0, v106
	v_xor_b32_e32 v248, v248, v153
	v_lshlrev_b32_e32 v248, 4, v248
	v_lshl_add_u32 v248, v105, 7, v248
	v_add_u32_e32 v248, s69, v248
	v_or_b32_e32 v249, 2, v106
	v_xor_b32_e32 v249, v249, v153
	v_lshlrev_b32_e32 v249, 4, v249
	v_lshl_add_u32 v249, v105, 7, v249
	v_add_u32_e32 v249, s69, v249
	v_or_b32_e32 v250, 4, v106
	v_xor_b32_e32 v250, v250, v153
	v_lshlrev_b32_e32 v250, 4, v250
	v_lshl_add_u32 v250, v105, 7, v250
	v_add_u32_e32 v250, s69, v250
	v_or_b32_e32 v251, 6, v106
	v_xor_b32_e32 v251, v251, v153
	v_lshlrev_b32_e32 v251, 4, v251
	v_lshl_add_u32 v251, v105, 7, v251
	v_add_u32_e32 v251, s69, v251
	v_lshlrev_b32_e32 v153, 1, v98
	v_mul_u32_u24_e32 v228, 17, v105
	v_sub_u32_e32 v228, v107, v228
	s_mul_i32 s90, s54, 153
	s_lshr_b32 s90, s90, 1
	s_add_i32 s90, s90, 34876
	v_lshl_add_u32 v228, v228, 2, s90
	v_lshlrev_b32_e32 v229, 2, v105
	v_sub_u32_e32 v229, v107, v229
	s_add_i32 s90, s101, 5104
	v_lshl_add_u32 v229, v229, 2, s90
	v_sub_u32_e32 v230, v107, v105
	s_add_i32 s90, s101, 6364
	v_lshl_add_u32 v230, v230, 2, s90
	v_add_u32_e32 v231, v109, v108
	v_mov_b64_e32 v[232:233], 0
	v_mov_b64_e32 v[0:1], 0
	v_mov_b64_e32 v[2:3], 0
	v_mov_b64_e32 v[4:5], 0
	v_mov_b64_e32 v[6:7], 0
	v_mov_b64_e32 v[8:9], 0
	v_mov_b64_e32 v[10:11], 0
	v_mov_b64_e32 v[12:13], 0
	v_mov_b64_e32 v[14:15], 0
	v_mov_b64_e32 v[16:17], 0
	v_mov_b64_e32 v[18:19], 0
	v_mov_b64_e32 v[20:21], 0
	v_mov_b64_e32 v[22:23], 0
	v_mov_b64_e32 v[24:25], 0
	v_mov_b64_e32 v[26:27], 0
	v_mov_b64_e32 v[28:29], 0
	v_mov_b64_e32 v[30:31], 0
	s_add_i32 s90, s67, -64
	v_add_u32_e32 v80, s90, v235
	v_add_u32_e32 v83, s90, v236
	v_add_u32_e32 v99, s90, v237
	v_add_u32_e32 v253, s90, v238
	v_add_u32_e32 v254, s90, v100
	v_add_u32_e32 v255, s90, v149
	v_med3_i32 v80, v80, 0, s99
	v_med3_i32 v83, v83, 0, s99
	v_med3_i32 v99, v99, 0, s99
	v_med3_i32 v253, v253, 0, s99
	v_med3_i32 v254, v254, 0, s99
	v_med3_i32 v255, v255, 0, s99
	v_mad_u32_u24 v80, v80, s100, v252
	v_mad_u32_u24 v83, v83, s100, v252
	v_mad_u32_u24 v99, v99, s100, v252
	v_mad_u32_u24 v253, v253, s100, v252
	v_mad_u32_u24 v254, v254, s100, v153
	v_mad_u32_u24 v255, v255, s100, v153
	global_load_dwordx4 v[116:119], v80, s[82:83]
	global_load_dwordx4 v[120:123], v83, s[82:83]
	global_load_dwordx4 v[124:127], v99, s[82:83]
	global_load_dwordx4 v[128:131], v253, s[82:83]
	global_load_dwordx4 v[132:135], v254, s[82:83] offset:768
	global_load_dwordx4 v[136:139], v255, s[82:83] offset:768
	global_load_dwordx4 v[140:143], v254, s[82:83] offset:832
	global_load_dwordx4 v[144:147], v255, s[82:83] offset:832
	s_add_i32 s90, s67, -32
	v_add_u32_e32 v80, s90, v235
	v_add_u32_e32 v83, s90, v236
	v_add_u32_e32 v99, s90, v237
	v_add_u32_e32 v253, s90, v238
	v_add_u32_e32 v254, s90, v100
	v_add_u32_e32 v255, s90, v149
	v_med3_i32 v80, v80, 0, s99
	v_med3_i32 v83, v83, 0, s99
	v_med3_i32 v99, v99, 0, s99
	v_med3_i32 v253, v253, 0, s99
	v_med3_i32 v254, v254, 0, s99
	v_med3_i32 v255, v255, 0, s99
	v_mad_u32_u24 v80, v80, s100, v252
	v_mad_u32_u24 v83, v83, s100, v252
	v_mad_u32_u24 v99, v99, s100, v252
	v_mad_u32_u24 v253, v253, s100, v252
	v_mad_u32_u24 v254, v254, s100, v153
	v_mad_u32_u24 v255, v255, s100, v153
	global_load_dwordx4 v[156:159], v80, s[82:83]
	global_load_dwordx4 v[160:163], v83, s[82:83]
	global_load_dwordx4 v[164:167], v99, s[82:83]
	global_load_dwordx4 v[168:171], v253, s[82:83]
	global_load_dwordx4 v[172:175], v254, s[82:83] offset:768
	global_load_dwordx4 v[176:179], v255, s[82:83] offset:768
	global_load_dwordx4 v[180:183], v254, s[82:83] offset:832
	global_load_dwordx4 v[184:187], v255, s[82:83] offset:832
	s_add_i32 s90, s67, 0
	v_add_u32_e32 v80, s90, v235
	v_add_u32_e32 v83, s90, v236
	v_add_u32_e32 v99, s90, v237
	v_add_u32_e32 v253, s90, v238
	v_add_u32_e32 v254, s90, v100
	v_add_u32_e32 v255, s90, v149
	v_med3_i32 v80, v80, 0, s99
	v_med3_i32 v83, v83, 0, s99
	v_med3_i32 v99, v99, 0, s99
	v_med3_i32 v253, v253, 0, s99
	v_med3_i32 v254, v254, 0, s99
	v_med3_i32 v255, v255, 0, s99
	v_mad_u32_u24 v80, v80, s100, v252
	v_mad_u32_u24 v83, v83, s100, v252
	v_mad_u32_u24 v99, v99, s100, v252
	v_mad_u32_u24 v253, v253, s100, v252
	v_mad_u32_u24 v254, v254, s100, v153
	v_mad_u32_u24 v255, v255, s100, v153
	global_load_dwordx4 v[188:191], v80, s[82:83]
	global_load_dwordx4 v[192:195], v83, s[82:83]
	global_load_dwordx4 v[196:199], v99, s[82:83]
	global_load_dwordx4 v[200:203], v253, s[82:83]
	global_load_dwordx4 v[204:207], v254, s[82:83] offset:768
	global_load_dwordx4 v[208:211], v255, s[82:83] offset:768
	global_load_dwordx4 v[212:215], v254, s[82:83] offset:832
	global_load_dwordx4 v[216:219], v255, s[82:83] offset:832
	s_waitcnt vmcnt(16)
	ds_write_b128 v247, v[116:119]
	ds_write_b128 v247, v[120:123] offset:1024
	ds_write_b128 v247, v[124:127] offset:2048
	ds_write_b128 v247, v[128:131] offset:3072
	ds_read_b128 v[116:119], v248
	ds_read_b128 v[120:123], v249
	ds_read_b128 v[124:127], v250
	ds_read_b128 v[128:131], v251
	ds_write_b128 v112, v[132:135]
	ds_write_b128 v112, v[136:139] offset:1024
	ds_write_b128 v112, v[140:143] offset:2048
	ds_write_b128 v112, v[144:147] offset:3072
	v_mov_b32_e32 v115, v228
	ds_read2_b32 v[32:33], v115 offset0:0 offset1:1
	ds_read2_b32 v[34:35], v115 offset0:2 offset1:3
	ds_read2_b32 v[36:37], v115 offset0:8 offset1:9
	ds_read2_b32 v[38:39], v115 offset0:10 offset1:11
	ds_read2_b32 v[40:41], v115 offset0:17 offset1:18
	ds_read2_b32 v[42:43], v115 offset0:19 offset1:20
	ds_read2_b32 v[44:45], v115 offset0:25 offset1:26
	ds_read2_b32 v[46:47], v115 offset0:27 offset1:28
	s_waitcnt lgkmcnt(0)
	v_mfma_f32_32x32x16_bf16 v[32:47], v[116:119], v[48:51], v[32:47]
	ds_read_b64_tr_b16 v[72:73], v231
	ds_read_b64_tr_b16 v[74:75], v231 offset:512
	ds_read_b64_tr_b16 v[76:77], v231 offset:2048
	ds_read_b64_tr_b16 v[78:79], v231 offset:2560
	ds_read_b64_tr_b16 v[220:221], v231 offset:1024
	ds_read_b64_tr_b16 v[222:223], v231 offset:1536
	ds_read_b64_tr_b16 v[224:225], v231 offset:3072
	ds_read_b64_tr_b16 v[226:227], v231 offset:3584
	v_mfma_f32_32x32x16_bf16 v[32:47], v[120:123], v[52:55], v[32:47]
	v_mfma_f32_32x32x16_bf16 v[32:47], v[124:127], v[56:59], v[32:47]
	v_mfma_f32_32x32x16_bf16 v[32:47], v[128:131], v[60:63], v[32:47]
	s_nop 11
	v_exp_f32_e32 v32, v32
	v_exp_f32_e32 v33, v33
	v_exp_f32_e32 v34, v34
	v_exp_f32_e32 v35, v35
	v_exp_f32_e32 v36, v36
	v_exp_f32_e32 v37, v37
	v_exp_f32_e32 v38, v38
	v_exp_f32_e32 v39, v39
	v_exp_f32_e32 v40, v40
	v_exp_f32_e32 v41, v41
	v_exp_f32_e32 v42, v42
	v_exp_f32_e32 v43, v43
	v_exp_f32_e32 v44, v44
	v_exp_f32_e32 v45, v45
	v_exp_f32_e32 v46, v46
	v_exp_f32_e32 v47, v47
	s_add_i32 s90, s67, -64
	v_add_u32_e32 v84, s90, v107
	v_add_u32_e32 v85, 0, v84
	v_add_u32_e32 v86, 1, v84
	v_add_u32_e32 v87, 2, v84
	v_add_u32_e32 v88, 3, v84
	v_cmp_gt_u32_e64 s[30:31], s98, v85
	v_cmp_gt_u32_e64 s[36:37], s98, v86
	v_cmp_gt_u32_e64 s[78:79], s98, v87
	v_cmp_gt_u32_e64 s[50:51], s98, v88
	v_cndmask_b32_e64 v32, 0, v32, s[30:31]
	v_add_u32_e32 v85, 8, v84
	v_cmp_gt_u32_e64 s[30:31], s98, v85
	v_cndmask_b32_e64 v33, 0, v33, s[36:37]
	v_add_u32_e32 v86, 9, v84
	v_cmp_gt_u32_e64 s[36:37], s98, v86
	v_cndmask_b32_e64 v34, 0, v34, s[78:79]
	v_add_u32_e32 v87, 10, v84
	v_cmp_gt_u32_e64 s[78:79], s98, v87
	v_cndmask_b32_e64 v35, 0, v35, s[50:51]
	v_add_u32_e32 v88, 11, v84
	v_cmp_gt_u32_e64 s[50:51], s98, v88
	v_cndmask_b32_e64 v36, 0, v36, s[30:31]
	v_add_u32_e32 v85, 16, v84
	v_cmp_gt_u32_e64 s[30:31], s98, v85
	v_cndmask_b32_e64 v37, 0, v37, s[36:37]
	v_add_u32_e32 v86, 17, v84
	v_cmp_gt_u32_e64 s[36:37], s98, v86
	v_cndmask_b32_e64 v38, 0, v38, s[78:79]
	v_add_u32_e32 v87, 18, v84
	v_cmp_gt_u32_e64 s[78:79], s98, v87
	v_cndmask_b32_e64 v39, 0, v39, s[50:51]
	v_add_u32_e32 v88, 19, v84
	v_cmp_gt_u32_e64 s[50:51], s98, v88
	v_cndmask_b32_e64 v40, 0, v40, s[30:31]
	v_add_u32_e32 v85, 24, v84
	v_cmp_gt_u32_e64 s[30:31], s98, v85
	v_cndmask_b32_e64 v41, 0, v41, s[36:37]
	v_add_u32_e32 v86, 25, v84
	v_cmp_gt_u32_e64 s[36:37], s98, v86
	v_cndmask_b32_e64 v42, 0, v42, s[78:79]
	v_add_u32_e32 v87, 26, v84
	v_cmp_gt_u32_e64 s[78:79], s98, v87
	v_cndmask_b32_e64 v43, 0, v43, s[50:51]
	v_add_u32_e32 v88, 27, v84
	v_cmp_gt_u32_e64 s[50:51], s98, v88
	v_nop
	v_cndmask_b32_e64 v44, 0, v44, s[30:31]
	v_cndmask_b32_e64 v45, 0, v45, s[36:37]
	v_cndmask_b32_e64 v46, 0, v46, s[78:79]
	v_cndmask_b32_e64 v47, 0, v47, s[50:51]
	v_cvt_pk_bf16_f32 v64, v32, v33
	v_cvt_pk_bf16_f32 v65, v34, v35
	v_cvt_pk_bf16_f32 v66, v36, v37
	v_cvt_pk_bf16_f32 v67, v38, v39
	v_cvt_pk_bf16_f32 v68, v40, v41
	v_cvt_pk_bf16_f32 v69, v42, v43
	v_cvt_pk_bf16_f32 v70, v44, v45
	v_cvt_pk_bf16_f32 v71, v46, v47
	v_pk_add_f32 v[232:233], v[232:233], v[32:33]
	v_pk_add_f32 v[232:233], v[232:233], v[34:35]
	v_pk_add_f32 v[232:233], v[232:233], v[36:37]
	v_pk_add_f32 v[232:233], v[232:233], v[38:39]
	v_pk_add_f32 v[232:233], v[232:233], v[40:41]
	v_pk_add_f32 v[232:233], v[232:233], v[42:43]
	v_pk_add_f32 v[232:233], v[232:233], v[44:45]
	v_pk_add_f32 v[232:233], v[232:233], v[46:47]
	s_waitcnt lgkmcnt(0)
	v_mfma_f32_32x32x16_bf16 v[0:15], v[64:67], v[72:75], v[0:15]
	v_mfma_f32_32x32x16_bf16 v[16:31], v[64:67], v[76:79], v[16:31]
	v_mfma_f32_32x32x16_bf16 v[0:15], v[68:71], v[220:223], v[0:15]
	v_mfma_f32_32x32x16_bf16 v[16:31], v[68:71], v[224:227], v[16:31]
	s_add_i32 s90, s67, 32
	v_add_u32_e32 v80, s90, v235
	v_add_u32_e32 v83, s90, v236
	v_add_u32_e32 v99, s90, v237
	v_add_u32_e32 v253, s90, v238
	v_add_u32_e32 v254, s90, v100
	v_add_u32_e32 v255, s90, v149
	v_med3_i32 v80, v80, 0, s99
	v_med3_i32 v83, v83, 0, s99
	v_med3_i32 v99, v99, 0, s99
	v_med3_i32 v253, v253, 0, s99
	v_med3_i32 v254, v254, 0, s99
	v_med3_i32 v255, v255, 0, s99
	v_mad_u32_u24 v80, v80, s100, v252
	v_mad_u32_u24 v83, v83, s100, v252
	v_mad_u32_u24 v99, v99, s100, v252
	v_mad_u32_u24 v253, v253, s100, v252
	v_mad_u32_u24 v254, v254, s100, v153
	v_mad_u32_u24 v255, v255, s100, v153
	global_load_dwordx4 v[116:119], v80, s[82:83]
	global_load_dwordx4 v[120:123], v83, s[82:83]
	global_load_dwordx4 v[124:127], v99, s[82:83]
	global_load_dwordx4 v[128:131], v253, s[82:83]
	global_load_dwordx4 v[132:135], v254, s[82:83] offset:768
	global_load_dwordx4 v[136:139], v255, s[82:83] offset:768
	global_load_dwordx4 v[140:143], v254, s[82:83] offset:832
	global_load_dwordx4 v[144:147], v255, s[82:83] offset:832
	s_waitcnt vmcnt(16)
	ds_write_b128 v247, v[156:159]
	ds_write_b128 v247, v[160:163] offset:1024
	ds_write_b128 v247, v[164:167] offset:2048
	ds_write_b128 v247, v[168:171] offset:3072
	ds_read_b128 v[156:159], v248
	ds_read_b128 v[160:163], v249
	ds_read_b128 v[164:167], v250
	ds_read_b128 v[168:171], v251
	ds_write_b128 v112, v[172:175]
	ds_write_b128 v112, v[176:179] offset:1024
	ds_write_b128 v112, v[180:183] offset:2048
	ds_write_b128 v112, v[184:187] offset:3072
	ds_read2_b32 v[32:33], v115 offset0:34 offset1:35
	ds_read2_b32 v[34:35], v115 offset0:36 offset1:37
	ds_read2_b32 v[36:37], v115 offset0:42 offset1:43
	ds_read2_b32 v[38:39], v115 offset0:44 offset1:45
	ds_read2_b32 v[40:41], v115 offset0:51 offset1:52
	ds_read2_b32 v[42:43], v115 offset0:53 offset1:54
	ds_read2_b32 v[44:45], v115 offset0:59 offset1:60
	ds_read2_b32 v[46:47], v115 offset0:61 offset1:62
	s_waitcnt lgkmcnt(0)
	v_mfma_f32_32x32x16_bf16 v[32:47], v[156:159], v[48:51], v[32:47]
	ds_read_b64_tr_b16 v[72:73], v231
	ds_read_b64_tr_b16 v[74:75], v231 offset:512
	ds_read_b64_tr_b16 v[76:77], v231 offset:2048
	ds_read_b64_tr_b16 v[78:79], v231 offset:2560
	ds_read_b64_tr_b16 v[220:221], v231 offset:1024
	ds_read_b64_tr_b16 v[222:223], v231 offset:1536
	ds_read_b64_tr_b16 v[224:225], v231 offset:3072
	ds_read_b64_tr_b16 v[226:227], v231 offset:3584
	v_mfma_f32_32x32x16_bf16 v[32:47], v[160:163], v[52:55], v[32:47]
	v_mfma_f32_32x32x16_bf16 v[32:47], v[164:167], v[56:59], v[32:47]
	v_mfma_f32_32x32x16_bf16 v[32:47], v[168:171], v[60:63], v[32:47]
	s_nop 11
	v_exp_f32_e32 v32, v32
	v_exp_f32_e32 v33, v33
	v_exp_f32_e32 v34, v34
	v_exp_f32_e32 v35, v35
	v_exp_f32_e32 v36, v36
	v_exp_f32_e32 v37, v37
	v_exp_f32_e32 v38, v38
	v_exp_f32_e32 v39, v39
	v_exp_f32_e32 v40, v40
	v_exp_f32_e32 v41, v41
	v_exp_f32_e32 v42, v42
	v_exp_f32_e32 v43, v43
	v_exp_f32_e32 v44, v44
	v_exp_f32_e32 v45, v45
	v_exp_f32_e32 v46, v46
	v_exp_f32_e32 v47, v47
	s_add_i32 s90, s67, -32
	v_add_u32_e32 v84, s90, v107
	v_add_u32_e32 v85, 0, v84
	v_add_u32_e32 v86, 1, v84
	v_add_u32_e32 v87, 2, v84
	v_add_u32_e32 v88, 3, v84
	v_cmp_gt_u32_e64 s[30:31], s98, v85
	v_cmp_gt_u32_e64 s[36:37], s98, v86
	v_cmp_gt_u32_e64 s[78:79], s98, v87
	v_cmp_gt_u32_e64 s[50:51], s98, v88
	v_cndmask_b32_e64 v32, 0, v32, s[30:31]
	v_add_u32_e32 v85, 8, v84
	v_cmp_gt_u32_e64 s[30:31], s98, v85
	v_cndmask_b32_e64 v33, 0, v33, s[36:37]
	v_add_u32_e32 v86, 9, v84
	v_cmp_gt_u32_e64 s[36:37], s98, v86
	v_cndmask_b32_e64 v34, 0, v34, s[78:79]
	v_add_u32_e32 v87, 10, v84
	v_cmp_gt_u32_e64 s[78:79], s98, v87
	v_cndmask_b32_e64 v35, 0, v35, s[50:51]
	v_add_u32_e32 v88, 11, v84
	v_cmp_gt_u32_e64 s[50:51], s98, v88
	v_cndmask_b32_e64 v36, 0, v36, s[30:31]
	v_add_u32_e32 v85, 16, v84
	v_cmp_gt_u32_e64 s[30:31], s98, v85
	v_cndmask_b32_e64 v37, 0, v37, s[36:37]
	v_add_u32_e32 v86, 17, v84
	v_cmp_gt_u32_e64 s[36:37], s98, v86
	v_cndmask_b32_e64 v38, 0, v38, s[78:79]
	v_add_u32_e32 v87, 18, v84
	v_cmp_gt_u32_e64 s[78:79], s98, v87
	v_cndmask_b32_e64 v39, 0, v39, s[50:51]
	v_add_u32_e32 v88, 19, v84
	v_cmp_gt_u32_e64 s[50:51], s98, v88
	v_cndmask_b32_e64 v40, 0, v40, s[30:31]
	v_add_u32_e32 v85, 24, v84
	v_cmp_gt_u32_e64 s[30:31], s98, v85
	v_cndmask_b32_e64 v41, 0, v41, s[36:37]
	v_add_u32_e32 v86, 25, v84
	v_cmp_gt_u32_e64 s[36:37], s98, v86
	v_cndmask_b32_e64 v42, 0, v42, s[78:79]
	v_add_u32_e32 v87, 26, v84
	v_cmp_gt_u32_e64 s[78:79], s98, v87
	v_cndmask_b32_e64 v43, 0, v43, s[50:51]
	v_add_u32_e32 v88, 27, v84
	v_cmp_gt_u32_e64 s[50:51], s98, v88
	v_nop
	v_cndmask_b32_e64 v44, 0, v44, s[30:31]
	v_cndmask_b32_e64 v45, 0, v45, s[36:37]
	v_cndmask_b32_e64 v46, 0, v46, s[78:79]
	v_cndmask_b32_e64 v47, 0, v47, s[50:51]
	v_cvt_pk_bf16_f32 v64, v32, v33
	v_cvt_pk_bf16_f32 v65, v34, v35
	v_cvt_pk_bf16_f32 v66, v36, v37
	v_cvt_pk_bf16_f32 v67, v38, v39
	v_cvt_pk_bf16_f32 v68, v40, v41
	v_cvt_pk_bf16_f32 v69, v42, v43
	v_cvt_pk_bf16_f32 v70, v44, v45
	v_cvt_pk_bf16_f32 v71, v46, v47
	v_pk_add_f32 v[232:233], v[232:233], v[32:33]
	v_pk_add_f32 v[232:233], v[232:233], v[34:35]
	v_pk_add_f32 v[232:233], v[232:233], v[36:37]
	v_pk_add_f32 v[232:233], v[232:233], v[38:39]
	v_pk_add_f32 v[232:233], v[232:233], v[40:41]
	v_pk_add_f32 v[232:233], v[232:233], v[42:43]
	v_pk_add_f32 v[232:233], v[232:233], v[44:45]
	v_pk_add_f32 v[232:233], v[232:233], v[46:47]
	s_waitcnt lgkmcnt(0)
	v_mfma_f32_32x32x16_bf16 v[0:15], v[64:67], v[72:75], v[0:15]
	v_mfma_f32_32x32x16_bf16 v[16:31], v[64:67], v[76:79], v[16:31]
	v_mfma_f32_32x32x16_bf16 v[0:15], v[68:71], v[220:223], v[0:15]
	v_mfma_f32_32x32x16_bf16 v[16:31], v[68:71], v[224:227], v[16:31]
	s_add_i32 s90, s67, 64
	v_add_u32_e32 v80, s90, v235
	v_add_u32_e32 v83, s90, v236
	v_add_u32_e32 v99, s90, v237
	v_add_u32_e32 v253, s90, v238
	v_add_u32_e32 v254, s90, v100
	v_add_u32_e32 v255, s90, v149
	v_med3_i32 v80, v80, 0, s99
	v_med3_i32 v83, v83, 0, s99
	v_med3_i32 v99, v99, 0, s99
	v_med3_i32 v253, v253, 0, s99
	v_med3_i32 v254, v254, 0, s99
	v_med3_i32 v255, v255, 0, s99
	v_mad_u32_u24 v80, v80, s100, v252
	v_mad_u32_u24 v83, v83, s100, v252
	v_mad_u32_u24 v99, v99, s100, v252
	v_mad_u32_u24 v253, v253, s100, v252
	v_mad_u32_u24 v254, v254, s100, v153
	v_mad_u32_u24 v255, v255, s100, v153
	global_load_dwordx4 v[156:159], v80, s[82:83]
	global_load_dwordx4 v[160:163], v83, s[82:83]
	global_load_dwordx4 v[164:167], v99, s[82:83]
	global_load_dwordx4 v[168:171], v253, s[82:83]
	global_load_dwordx4 v[172:175], v254, s[82:83] offset:768
	global_load_dwordx4 v[176:179], v255, s[82:83] offset:768
	global_load_dwordx4 v[180:183], v254, s[82:83] offset:832
	global_load_dwordx4 v[184:187], v255, s[82:83] offset:832
	s_waitcnt vmcnt(16)
	ds_write_b128 v247, v[188:191]
	ds_write_b128 v247, v[192:195] offset:1024
	ds_write_b128 v247, v[196:199] offset:2048
	ds_write_b128 v247, v[200:203] offset:3072
	ds_read_b128 v[188:191], v248
	ds_read_b128 v[192:195], v249
	ds_read_b128 v[196:199], v250
	ds_read_b128 v[200:203], v251
	ds_write_b128 v112, v[204:207]
	ds_write_b128 v112, v[208:211] offset:1024
	ds_write_b128 v112, v[212:215] offset:2048
	ds_write_b128 v112, v[216:219] offset:3072
	ds_read2_b32 v[32:33], v115 offset0:68 offset1:69
	ds_read2_b32 v[34:35], v115 offset0:70 offset1:71
	ds_read2_b32 v[36:37], v115 offset0:76 offset1:77
	ds_read2_b32 v[38:39], v115 offset0:78 offset1:79
	ds_read2_b32 v[40:41], v115 offset0:85 offset1:86
	ds_read2_b32 v[42:43], v115 offset0:87 offset1:88
	ds_read2_b32 v[44:45], v115 offset0:93 offset1:94
	ds_read2_b32 v[46:47], v115 offset0:95 offset1:96
	s_waitcnt lgkmcnt(0)
	v_mfma_f32_32x32x16_bf16 v[32:47], v[188:191], v[48:51], v[32:47]
	ds_read_b64_tr_b16 v[72:73], v231
	ds_read_b64_tr_b16 v[74:75], v231 offset:512
	ds_read_b64_tr_b16 v[76:77], v231 offset:2048
	ds_read_b64_tr_b16 v[78:79], v231 offset:2560
	ds_read_b64_tr_b16 v[220:221], v231 offset:1024
	ds_read_b64_tr_b16 v[222:223], v231 offset:1536
	ds_read_b64_tr_b16 v[224:225], v231 offset:3072
	ds_read_b64_tr_b16 v[226:227], v231 offset:3584
	v_mfma_f32_32x32x16_bf16 v[32:47], v[192:195], v[52:55], v[32:47]
	v_mfma_f32_32x32x16_bf16 v[32:47], v[196:199], v[56:59], v[32:47]
	v_mfma_f32_32x32x16_bf16 v[32:47], v[200:203], v[60:63], v[32:47]
	s_nop 11
	v_exp_f32_e32 v32, v32
	v_exp_f32_e32 v33, v33
	v_exp_f32_e32 v34, v34
	v_exp_f32_e32 v35, v35
	v_exp_f32_e32 v36, v36
	v_exp_f32_e32 v37, v37
	v_exp_f32_e32 v38, v38
	v_exp_f32_e32 v39, v39
	v_exp_f32_e32 v40, v40
	v_exp_f32_e32 v41, v41
	v_exp_f32_e32 v42, v42
	v_exp_f32_e32 v43, v43
	v_exp_f32_e32 v44, v44
	v_exp_f32_e32 v45, v45
	v_exp_f32_e32 v46, v46
	v_exp_f32_e32 v47, v47
	s_add_i32 s90, s67, 0
	v_add_u32_e32 v84, s90, v107
	v_add_u32_e32 v85, 0, v84
	v_add_u32_e32 v86, 1, v84
	v_add_u32_e32 v87, 2, v84
	v_add_u32_e32 v88, 3, v84
	v_cmp_gt_u32_e64 s[30:31], s98, v85
	v_cmp_gt_u32_e64 s[36:37], s98, v86
	v_cmp_gt_u32_e64 s[78:79], s98, v87
	v_cmp_gt_u32_e64 s[50:51], s98, v88
	v_cndmask_b32_e64 v32, 0, v32, s[30:31]
	v_add_u32_e32 v85, 8, v84
	v_cmp_gt_u32_e64 s[30:31], s98, v85
	v_cndmask_b32_e64 v33, 0, v33, s[36:37]
	v_add_u32_e32 v86, 9, v84
	v_cmp_gt_u32_e64 s[36:37], s98, v86
	v_cndmask_b32_e64 v34, 0, v34, s[78:79]
	v_add_u32_e32 v87, 10, v84
	v_cmp_gt_u32_e64 s[78:79], s98, v87
	v_cndmask_b32_e64 v35, 0, v35, s[50:51]
	v_add_u32_e32 v88, 11, v84
	v_cmp_gt_u32_e64 s[50:51], s98, v88
	v_cndmask_b32_e64 v36, 0, v36, s[30:31]
	v_add_u32_e32 v85, 16, v84
	v_cmp_gt_u32_e64 s[30:31], s98, v85
	v_cndmask_b32_e64 v37, 0, v37, s[36:37]
	v_add_u32_e32 v86, 17, v84
	v_cmp_gt_u32_e64 s[36:37], s98, v86
	v_cndmask_b32_e64 v38, 0, v38, s[78:79]
	v_add_u32_e32 v87, 18, v84
	v_cmp_gt_u32_e64 s[78:79], s98, v87
	v_cndmask_b32_e64 v39, 0, v39, s[50:51]
	v_add_u32_e32 v88, 19, v84
	v_cmp_gt_u32_e64 s[50:51], s98, v88
	v_cndmask_b32_e64 v40, 0, v40, s[30:31]
	v_add_u32_e32 v85, 24, v84
	v_cmp_gt_u32_e64 s[30:31], s98, v85
	v_cndmask_b32_e64 v41, 0, v41, s[36:37]
	v_add_u32_e32 v86, 25, v84
	v_cmp_gt_u32_e64 s[36:37], s98, v86
	v_cndmask_b32_e64 v42, 0, v42, s[78:79]
	v_add_u32_e32 v87, 26, v84
	v_cmp_gt_u32_e64 s[78:79], s98, v87
	v_cndmask_b32_e64 v43, 0, v43, s[50:51]
	v_add_u32_e32 v88, 27, v84
	v_cmp_gt_u32_e64 s[50:51], s98, v88
	v_nop
	v_cndmask_b32_e64 v44, 0, v44, s[30:31]
	v_cndmask_b32_e64 v45, 0, v45, s[36:37]
	v_cndmask_b32_e64 v46, 0, v46, s[78:79]
	v_cndmask_b32_e64 v47, 0, v47, s[50:51]
	v_cvt_pk_bf16_f32 v64, v32, v33
	v_cvt_pk_bf16_f32 v65, v34, v35
	v_cvt_pk_bf16_f32 v66, v36, v37
	v_cvt_pk_bf16_f32 v67, v38, v39
	v_cvt_pk_bf16_f32 v68, v40, v41
	v_cvt_pk_bf16_f32 v69, v42, v43
	v_cvt_pk_bf16_f32 v70, v44, v45
	v_cvt_pk_bf16_f32 v71, v46, v47
	v_pk_add_f32 v[232:233], v[232:233], v[32:33]
	v_pk_add_f32 v[232:233], v[232:233], v[34:35]
	v_pk_add_f32 v[232:233], v[232:233], v[36:37]
	v_pk_add_f32 v[232:233], v[232:233], v[38:39]
	v_pk_add_f32 v[232:233], v[232:233], v[40:41]
	v_pk_add_f32 v[232:233], v[232:233], v[42:43]
	v_pk_add_f32 v[232:233], v[232:233], v[44:45]
	v_pk_add_f32 v[232:233], v[232:233], v[46:47]
	s_waitcnt lgkmcnt(0)
	v_mfma_f32_32x32x16_bf16 v[0:15], v[64:67], v[72:75], v[0:15]
	v_mfma_f32_32x32x16_bf16 v[16:31], v[64:67], v[76:79], v[16:31]
	v_mfma_f32_32x32x16_bf16 v[0:15], v[68:71], v[220:223], v[0:15]
	v_mfma_f32_32x32x16_bf16 v[16:31], v[68:71], v[224:227], v[16:31]
	s_add_i32 s90, s67, 96
	v_add_u32_e32 v80, s90, v235
	v_add_u32_e32 v83, s90, v236
	v_add_u32_e32 v99, s90, v237
	v_add_u32_e32 v253, s90, v238
	v_add_u32_e32 v254, s90, v100
	v_add_u32_e32 v255, s90, v149
	v_med3_i32 v80, v80, 0, s99
	v_med3_i32 v83, v83, 0, s99
	v_med3_i32 v99, v99, 0, s99
	v_med3_i32 v253, v253, 0, s99
	v_med3_i32 v254, v254, 0, s99
	v_med3_i32 v255, v255, 0, s99
	v_mad_u32_u24 v80, v80, s100, v252
	v_mad_u32_u24 v83, v83, s100, v252
	v_mad_u32_u24 v99, v99, s100, v252
	v_mad_u32_u24 v253, v253, s100, v252
	v_mad_u32_u24 v254, v254, s100, v153
	v_mad_u32_u24 v255, v255, s100, v153
	global_load_dwordx4 v[188:191], v80, s[82:83]
	global_load_dwordx4 v[192:195], v83, s[82:83]
	global_load_dwordx4 v[196:199], v99, s[82:83]
	global_load_dwordx4 v[200:203], v253, s[82:83]
	global_load_dwordx4 v[204:207], v254, s[82:83] offset:768
	global_load_dwordx4 v[208:211], v255, s[82:83] offset:768
	global_load_dwordx4 v[212:215], v254, s[82:83] offset:832
	global_load_dwordx4 v[216:219], v255, s[82:83] offset:832
	s_waitcnt vmcnt(16)
	ds_write_b128 v247, v[116:119]
	ds_write_b128 v247, v[120:123] offset:1024
	ds_write_b128 v247, v[124:127] offset:2048
	ds_write_b128 v247, v[128:131] offset:3072
	ds_read_b128 v[116:119], v248
	ds_read_b128 v[120:123], v249
	ds_read_b128 v[124:127], v250
	ds_read_b128 v[128:131], v251
	ds_write_b128 v112, v[132:135]
	ds_write_b128 v112, v[136:139] offset:1024
	ds_write_b128 v112, v[140:143] offset:2048
	ds_write_b128 v112, v[144:147] offset:3072
	ds_read2_b32 v[32:33], v115 offset0:102 offset1:103
	ds_read2_b32 v[34:35], v115 offset0:104 offset1:105
	ds_read2_b32 v[36:37], v115 offset0:110 offset1:111
	ds_read2_b32 v[38:39], v115 offset0:112 offset1:113
	ds_read2_b32 v[40:41], v115 offset0:119 offset1:120
	ds_read2_b32 v[42:43], v115 offset0:121 offset1:122
	ds_read2_b32 v[44:45], v115 offset0:127 offset1:128
	ds_read2_b32 v[46:47], v115 offset0:129 offset1:130
	s_waitcnt lgkmcnt(0)
	v_mfma_f32_32x32x16_bf16 v[32:47], v[116:119], v[48:51], v[32:47]
	ds_read_b64_tr_b16 v[72:73], v231
	ds_read_b64_tr_b16 v[74:75], v231 offset:512
	ds_read_b64_tr_b16 v[76:77], v231 offset:2048
	ds_read_b64_tr_b16 v[78:79], v231 offset:2560
	ds_read_b64_tr_b16 v[220:221], v231 offset:1024
	ds_read_b64_tr_b16 v[222:223], v231 offset:1536
	ds_read_b64_tr_b16 v[224:225], v231 offset:3072
	ds_read_b64_tr_b16 v[226:227], v231 offset:3584
	v_mfma_f32_32x32x16_bf16 v[32:47], v[120:123], v[52:55], v[32:47]
	v_mfma_f32_32x32x16_bf16 v[32:47], v[124:127], v[56:59], v[32:47]
	v_mfma_f32_32x32x16_bf16 v[32:47], v[128:131], v[60:63], v[32:47]
	s_nop 11
	v_exp_f32_e32 v32, v32
	v_exp_f32_e32 v33, v33
	v_exp_f32_e32 v34, v34
	v_exp_f32_e32 v35, v35
	v_exp_f32_e32 v36, v36
	v_exp_f32_e32 v37, v37
	v_exp_f32_e32 v38, v38
	v_exp_f32_e32 v39, v39
	v_exp_f32_e32 v40, v40
	v_exp_f32_e32 v41, v41
	v_exp_f32_e32 v42, v42
	v_exp_f32_e32 v43, v43
	v_exp_f32_e32 v44, v44
	v_exp_f32_e32 v45, v45
	v_exp_f32_e32 v46, v46
	v_exp_f32_e32 v47, v47
	s_add_i32 s90, s67, 32
	v_add_u32_e32 v84, s90, v107
	v_add_u32_e32 v85, 0, v84
	v_add_u32_e32 v86, 1, v84
	v_add_u32_e32 v87, 2, v84
	v_add_u32_e32 v88, 3, v84
	v_cmp_gt_u32_e64 s[30:31], s98, v85
	v_cmp_gt_u32_e64 s[36:37], s98, v86
	v_cmp_gt_u32_e64 s[78:79], s98, v87
	v_cmp_gt_u32_e64 s[50:51], s98, v88
	v_cndmask_b32_e64 v32, 0, v32, s[30:31]
	v_add_u32_e32 v85, 8, v84
	v_cmp_gt_u32_e64 s[30:31], s98, v85
	v_cndmask_b32_e64 v33, 0, v33, s[36:37]
	v_add_u32_e32 v86, 9, v84
	v_cmp_gt_u32_e64 s[36:37], s98, v86
	v_cndmask_b32_e64 v34, 0, v34, s[78:79]
	v_add_u32_e32 v87, 10, v84
	v_cmp_gt_u32_e64 s[78:79], s98, v87
	v_cndmask_b32_e64 v35, 0, v35, s[50:51]
	v_add_u32_e32 v88, 11, v84
	v_cmp_gt_u32_e64 s[50:51], s98, v88
	v_cndmask_b32_e64 v36, 0, v36, s[30:31]
	v_add_u32_e32 v85, 16, v84
	v_cmp_gt_u32_e64 s[30:31], s98, v85
	v_cndmask_b32_e64 v37, 0, v37, s[36:37]
	v_add_u32_e32 v86, 17, v84
	v_cmp_gt_u32_e64 s[36:37], s98, v86
	v_cndmask_b32_e64 v38, 0, v38, s[78:79]
	v_add_u32_e32 v87, 18, v84
	v_cmp_gt_u32_e64 s[78:79], s98, v87
	v_cndmask_b32_e64 v39, 0, v39, s[50:51]
	v_add_u32_e32 v88, 19, v84
	v_cmp_gt_u32_e64 s[50:51], s98, v88
	v_cndmask_b32_e64 v40, 0, v40, s[30:31]
	v_add_u32_e32 v85, 24, v84
	v_cmp_gt_u32_e64 s[30:31], s98, v85
	v_cndmask_b32_e64 v41, 0, v41, s[36:37]
	v_add_u32_e32 v86, 25, v84
	v_cmp_gt_u32_e64 s[36:37], s98, v86
	v_cndmask_b32_e64 v42, 0, v42, s[78:79]
	v_add_u32_e32 v87, 26, v84
	v_cmp_gt_u32_e64 s[78:79], s98, v87
	v_cndmask_b32_e64 v43, 0, v43, s[50:51]
	v_add_u32_e32 v88, 27, v84
	v_cmp_gt_u32_e64 s[50:51], s98, v88
	v_nop
	v_cndmask_b32_e64 v44, 0, v44, s[30:31]
	v_cndmask_b32_e64 v45, 0, v45, s[36:37]
	v_cndmask_b32_e64 v46, 0, v46, s[78:79]
	v_cndmask_b32_e64 v47, 0, v47, s[50:51]
	v_cvt_pk_bf16_f32 v64, v32, v33
	v_cvt_pk_bf16_f32 v65, v34, v35
	v_cvt_pk_bf16_f32 v66, v36, v37
	v_cvt_pk_bf16_f32 v67, v38, v39
	v_cvt_pk_bf16_f32 v68, v40, v41
	v_cvt_pk_bf16_f32 v69, v42, v43
	v_cvt_pk_bf16_f32 v70, v44, v45
	v_cvt_pk_bf16_f32 v71, v46, v47
	v_pk_add_f32 v[232:233], v[232:233], v[32:33]
	v_pk_add_f32 v[232:233], v[232:233], v[34:35]
	v_pk_add_f32 v[232:233], v[232:233], v[36:37]
	v_pk_add_f32 v[232:233], v[232:233], v[38:39]
	v_pk_add_f32 v[232:233], v[232:233], v[40:41]
	v_pk_add_f32 v[232:233], v[232:233], v[42:43]
	v_pk_add_f32 v[232:233], v[232:233], v[44:45]
	v_pk_add_f32 v[232:233], v[232:233], v[46:47]
	s_waitcnt lgkmcnt(0)
	v_mfma_f32_32x32x16_bf16 v[0:15], v[64:67], v[72:75], v[0:15]
	v_mfma_f32_32x32x16_bf16 v[16:31], v[64:67], v[76:79], v[16:31]
	v_mfma_f32_32x32x16_bf16 v[0:15], v[68:71], v[220:223], v[0:15]
	v_mfma_f32_32x32x16_bf16 v[16:31], v[68:71], v[224:227], v[16:31]
	s_add_i32 s90, s67, 128
	v_add_u32_e32 v80, s90, v235
	v_add_u32_e32 v83, s90, v236
	v_add_u32_e32 v99, s90, v237
	v_add_u32_e32 v253, s90, v238
	v_add_u32_e32 v254, s90, v100
	v_add_u32_e32 v255, s90, v149
	v_med3_i32 v80, v80, 0, s99
	v_med3_i32 v83, v83, 0, s99
	v_med3_i32 v99, v99, 0, s99
	v_med3_i32 v253, v253, 0, s99
	v_med3_i32 v254, v254, 0, s99
	v_med3_i32 v255, v255, 0, s99
	v_mad_u32_u24 v80, v80, s100, v252
	v_mad_u32_u24 v83, v83, s100, v252
	v_mad_u32_u24 v99, v99, s100, v252
	v_mad_u32_u24 v253, v253, s100, v252
	v_mad_u32_u24 v254, v254, s100, v153
	v_mad_u32_u24 v255, v255, s100, v153
	global_load_dwordx4 v[116:119], v80, s[82:83]
	global_load_dwordx4 v[120:123], v83, s[82:83]
	global_load_dwordx4 v[124:127], v99, s[82:83]
	global_load_dwordx4 v[128:131], v253, s[82:83]
	global_load_dwordx4 v[132:135], v254, s[82:83] offset:768
	global_load_dwordx4 v[136:139], v255, s[82:83] offset:768
	global_load_dwordx4 v[140:143], v254, s[82:83] offset:832
	global_load_dwordx4 v[144:147], v255, s[82:83] offset:832
	s_waitcnt vmcnt(16)
	ds_write_b128 v247, v[156:159]
	ds_write_b128 v247, v[160:163] offset:1024
	ds_write_b128 v247, v[164:167] offset:2048
	ds_write_b128 v247, v[168:171] offset:3072
	ds_read_b128 v[156:159], v248
	ds_read_b128 v[160:163], v249
	ds_read_b128 v[164:167], v250
	ds_read_b128 v[168:171], v251
	ds_write_b128 v112, v[172:175]
	ds_write_b128 v112, v[176:179] offset:1024
	ds_write_b128 v112, v[180:183] offset:2048
	ds_write_b128 v112, v[184:187] offset:3072
	ds_read2_b32 v[32:33], v115 offset0:136 offset1:137
	ds_read2_b32 v[34:35], v115 offset0:138 offset1:139
	ds_read2_b32 v[36:37], v115 offset0:144 offset1:145
	ds_read2_b32 v[38:39], v115 offset0:146 offset1:147
	ds_read2_b32 v[40:41], v115 offset0:153 offset1:154
	ds_read2_b32 v[42:43], v115 offset0:155 offset1:156
	ds_read2_b32 v[44:45], v115 offset0:161 offset1:162
	ds_read2_b32 v[46:47], v115 offset0:163 offset1:164
	s_waitcnt lgkmcnt(0)
	v_mfma_f32_32x32x16_bf16 v[32:47], v[156:159], v[48:51], v[32:47]
	ds_read_b64_tr_b16 v[72:73], v231
	ds_read_b64_tr_b16 v[74:75], v231 offset:512
	ds_read_b64_tr_b16 v[76:77], v231 offset:2048
	ds_read_b64_tr_b16 v[78:79], v231 offset:2560
	ds_read_b64_tr_b16 v[220:221], v231 offset:1024
	ds_read_b64_tr_b16 v[222:223], v231 offset:1536
	ds_read_b64_tr_b16 v[224:225], v231 offset:3072
	ds_read_b64_tr_b16 v[226:227], v231 offset:3584
	v_mfma_f32_32x32x16_bf16 v[32:47], v[160:163], v[52:55], v[32:47]
	v_mfma_f32_32x32x16_bf16 v[32:47], v[164:167], v[56:59], v[32:47]
	v_mfma_f32_32x32x16_bf16 v[32:47], v[168:171], v[60:63], v[32:47]
	s_nop 11
	v_exp_f32_e32 v32, v32
	v_exp_f32_e32 v33, v33
	v_exp_f32_e32 v34, v34
	v_exp_f32_e32 v35, v35
	v_exp_f32_e32 v36, v36
	v_exp_f32_e32 v37, v37
	v_exp_f32_e32 v38, v38
	v_exp_f32_e32 v39, v39
	v_exp_f32_e32 v40, v40
	v_exp_f32_e32 v41, v41
	v_exp_f32_e32 v42, v42
	v_exp_f32_e32 v43, v43
	v_exp_f32_e32 v44, v44
	v_exp_f32_e32 v45, v45
	v_exp_f32_e32 v46, v46
	v_exp_f32_e32 v47, v47
	s_add_i32 s90, s67, 64
	v_add_u32_e32 v84, s90, v107
	v_add_u32_e32 v85, 0, v84
	v_add_u32_e32 v86, 1, v84
	v_add_u32_e32 v87, 2, v84
	v_add_u32_e32 v88, 3, v84
	v_cmp_gt_u32_e64 s[30:31], s98, v85
	v_cmp_gt_u32_e64 s[36:37], s98, v86
	v_cmp_gt_u32_e64 s[78:79], s98, v87
	v_cmp_gt_u32_e64 s[50:51], s98, v88
	v_cndmask_b32_e64 v32, 0, v32, s[30:31]
	v_add_u32_e32 v85, 8, v84
	v_cmp_gt_u32_e64 s[30:31], s98, v85
	v_cndmask_b32_e64 v33, 0, v33, s[36:37]
	v_add_u32_e32 v86, 9, v84
	v_cmp_gt_u32_e64 s[36:37], s98, v86
	v_cndmask_b32_e64 v34, 0, v34, s[78:79]
	v_add_u32_e32 v87, 10, v84
	v_cmp_gt_u32_e64 s[78:79], s98, v87
	v_cndmask_b32_e64 v35, 0, v35, s[50:51]
	v_add_u32_e32 v88, 11, v84
	v_cmp_gt_u32_e64 s[50:51], s98, v88
	v_cndmask_b32_e64 v36, 0, v36, s[30:31]
	v_add_u32_e32 v85, 16, v84
	v_cmp_gt_u32_e64 s[30:31], s98, v85
	v_cndmask_b32_e64 v37, 0, v37, s[36:37]
	v_add_u32_e32 v86, 17, v84
	v_cmp_gt_u32_e64 s[36:37], s98, v86
	v_cndmask_b32_e64 v38, 0, v38, s[78:79]
	v_add_u32_e32 v87, 18, v84
	v_cmp_gt_u32_e64 s[78:79], s98, v87
	v_cndmask_b32_e64 v39, 0, v39, s[50:51]
	v_add_u32_e32 v88, 19, v84
	v_cmp_gt_u32_e64 s[50:51], s98, v88
	v_cndmask_b32_e64 v40, 0, v40, s[30:31]
	v_add_u32_e32 v85, 24, v84
	v_cmp_gt_u32_e64 s[30:31], s98, v85
	v_cndmask_b32_e64 v41, 0, v41, s[36:37]
	v_add_u32_e32 v86, 25, v84
	v_cmp_gt_u32_e64 s[36:37], s98, v86
	v_cndmask_b32_e64 v42, 0, v42, s[78:79]
	v_add_u32_e32 v87, 26, v84
	v_cmp_gt_u32_e64 s[78:79], s98, v87
	v_cndmask_b32_e64 v43, 0, v43, s[50:51]
	v_add_u32_e32 v88, 27, v84
	v_cmp_gt_u32_e64 s[50:51], s98, v88
	v_nop
	v_cndmask_b32_e64 v44, 0, v44, s[30:31]
	v_cndmask_b32_e64 v45, 0, v45, s[36:37]
	v_cndmask_b32_e64 v46, 0, v46, s[78:79]
	v_cndmask_b32_e64 v47, 0, v47, s[50:51]
	v_cvt_pk_bf16_f32 v64, v32, v33
	v_cvt_pk_bf16_f32 v65, v34, v35
	v_cvt_pk_bf16_f32 v66, v36, v37
	v_cvt_pk_bf16_f32 v67, v38, v39
	v_cvt_pk_bf16_f32 v68, v40, v41
	v_cvt_pk_bf16_f32 v69, v42, v43
	v_cvt_pk_bf16_f32 v70, v44, v45
	v_cvt_pk_bf16_f32 v71, v46, v47
	v_pk_add_f32 v[232:233], v[232:233], v[32:33]
	v_pk_add_f32 v[232:233], v[232:233], v[34:35]
	v_pk_add_f32 v[232:233], v[232:233], v[36:37]
	v_pk_add_f32 v[232:233], v[232:233], v[38:39]
	v_pk_add_f32 v[232:233], v[232:233], v[40:41]
	v_pk_add_f32 v[232:233], v[232:233], v[42:43]
	v_pk_add_f32 v[232:233], v[232:233], v[44:45]
	v_pk_add_f32 v[232:233], v[232:233], v[46:47]
	s_waitcnt lgkmcnt(0)
	v_mfma_f32_32x32x16_bf16 v[0:15], v[64:67], v[72:75], v[0:15]
	v_mfma_f32_32x32x16_bf16 v[16:31], v[64:67], v[76:79], v[16:31]
	v_mfma_f32_32x32x16_bf16 v[0:15], v[68:71], v[220:223], v[0:15]
	v_mfma_f32_32x32x16_bf16 v[16:31], v[68:71], v[224:227], v[16:31]
	s_add_i32 s90, s67, 160
	v_add_u32_e32 v80, s90, v235
	v_add_u32_e32 v83, s90, v236
	v_add_u32_e32 v99, s90, v237
	v_add_u32_e32 v253, s90, v238
	v_add_u32_e32 v254, s90, v100
	v_add_u32_e32 v255, s90, v149
	v_med3_i32 v80, v80, 0, s99
	v_med3_i32 v83, v83, 0, s99
	v_med3_i32 v99, v99, 0, s99
	v_med3_i32 v253, v253, 0, s99
	v_med3_i32 v254, v254, 0, s99
	v_med3_i32 v255, v255, 0, s99
	v_mad_u32_u24 v80, v80, s100, v252
	v_mad_u32_u24 v83, v83, s100, v252
	v_mad_u32_u24 v99, v99, s100, v252
	v_mad_u32_u24 v253, v253, s100, v252
	v_mad_u32_u24 v254, v254, s100, v153
	v_mad_u32_u24 v255, v255, s100, v153
	global_load_dwordx4 v[156:159], v80, s[82:83]
	global_load_dwordx4 v[160:163], v83, s[82:83]
	global_load_dwordx4 v[164:167], v99, s[82:83]
	global_load_dwordx4 v[168:171], v253, s[82:83]
	global_load_dwordx4 v[172:175], v254, s[82:83] offset:768
	global_load_dwordx4 v[176:179], v255, s[82:83] offset:768
	global_load_dwordx4 v[180:183], v254, s[82:83] offset:832
	global_load_dwordx4 v[184:187], v255, s[82:83] offset:832
	s_waitcnt vmcnt(16)
	ds_write_b128 v247, v[188:191]
	ds_write_b128 v247, v[192:195] offset:1024
	ds_write_b128 v247, v[196:199] offset:2048
	ds_write_b128 v247, v[200:203] offset:3072
	ds_read_b128 v[188:191], v248
	ds_read_b128 v[192:195], v249
	ds_read_b128 v[196:199], v250
	ds_read_b128 v[200:203], v251
	ds_write_b128 v112, v[204:207]
	ds_write_b128 v112, v[208:211] offset:1024
	ds_write_b128 v112, v[212:215] offset:2048
	ds_write_b128 v112, v[216:219] offset:3072
	ds_read2_b32 v[32:33], v115 offset0:170 offset1:171
	ds_read2_b32 v[34:35], v115 offset0:172 offset1:173
	ds_read2_b32 v[36:37], v115 offset0:178 offset1:179
	ds_read2_b32 v[38:39], v115 offset0:180 offset1:181
	ds_read2_b32 v[40:41], v115 offset0:187 offset1:188
	ds_read2_b32 v[42:43], v115 offset0:189 offset1:190
	ds_read2_b32 v[44:45], v115 offset0:195 offset1:196
	ds_read2_b32 v[46:47], v115 offset0:197 offset1:198
	s_waitcnt lgkmcnt(0)
	v_mfma_f32_32x32x16_bf16 v[32:47], v[188:191], v[48:51], v[32:47]
	ds_read_b64_tr_b16 v[72:73], v231
	ds_read_b64_tr_b16 v[74:75], v231 offset:512
	ds_read_b64_tr_b16 v[76:77], v231 offset:2048
	ds_read_b64_tr_b16 v[78:79], v231 offset:2560
	ds_read_b64_tr_b16 v[220:221], v231 offset:1024
	ds_read_b64_tr_b16 v[222:223], v231 offset:1536
	ds_read_b64_tr_b16 v[224:225], v231 offset:3072
	ds_read_b64_tr_b16 v[226:227], v231 offset:3584
	v_mfma_f32_32x32x16_bf16 v[32:47], v[192:195], v[52:55], v[32:47]
	v_mfma_f32_32x32x16_bf16 v[32:47], v[196:199], v[56:59], v[32:47]
	v_mfma_f32_32x32x16_bf16 v[32:47], v[200:203], v[60:63], v[32:47]
	s_nop 11
	v_exp_f32_e32 v32, v32
	v_exp_f32_e32 v33, v33
	v_exp_f32_e32 v34, v34
	v_exp_f32_e32 v35, v35
	v_exp_f32_e32 v36, v36
	v_exp_f32_e32 v37, v37
	v_exp_f32_e32 v38, v38
	v_exp_f32_e32 v39, v39
	v_exp_f32_e32 v40, v40
	v_exp_f32_e32 v41, v41
	v_exp_f32_e32 v42, v42
	v_exp_f32_e32 v43, v43
	v_exp_f32_e32 v44, v44
	v_exp_f32_e32 v45, v45
	v_exp_f32_e32 v46, v46
	v_exp_f32_e32 v47, v47
	s_add_i32 s90, s67, 96
	v_add_u32_e32 v84, s90, v107
	v_add_u32_e32 v85, 0, v84
	v_add_u32_e32 v86, 1, v84
	v_add_u32_e32 v87, 2, v84
	v_add_u32_e32 v88, 3, v84
	v_cmp_gt_u32_e64 s[30:31], s98, v85
	v_cmp_gt_u32_e64 s[36:37], s98, v86
	v_cmp_gt_u32_e64 s[78:79], s98, v87
	v_cmp_gt_u32_e64 s[50:51], s98, v88
	v_cndmask_b32_e64 v32, 0, v32, s[30:31]
	v_add_u32_e32 v85, 8, v84
	v_cmp_gt_u32_e64 s[30:31], s98, v85
	v_cndmask_b32_e64 v33, 0, v33, s[36:37]
	v_add_u32_e32 v86, 9, v84
	v_cmp_gt_u32_e64 s[36:37], s98, v86
	v_cndmask_b32_e64 v34, 0, v34, s[78:79]
	v_add_u32_e32 v87, 10, v84
	v_cmp_gt_u32_e64 s[78:79], s98, v87
	v_cndmask_b32_e64 v35, 0, v35, s[50:51]
	v_add_u32_e32 v88, 11, v84
	v_cmp_gt_u32_e64 s[50:51], s98, v88
	v_cndmask_b32_e64 v36, 0, v36, s[30:31]
	v_add_u32_e32 v85, 16, v84
	v_cmp_gt_u32_e64 s[30:31], s98, v85
	v_cndmask_b32_e64 v37, 0, v37, s[36:37]
	v_add_u32_e32 v86, 17, v84
	v_cmp_gt_u32_e64 s[36:37], s98, v86
	v_cndmask_b32_e64 v38, 0, v38, s[78:79]
	v_add_u32_e32 v87, 18, v84
	v_cmp_gt_u32_e64 s[78:79], s98, v87
	v_cndmask_b32_e64 v39, 0, v39, s[50:51]
	v_add_u32_e32 v88, 19, v84
	v_cmp_gt_u32_e64 s[50:51], s98, v88
	v_cndmask_b32_e64 v40, 0, v40, s[30:31]
	v_add_u32_e32 v85, 24, v84
	v_cmp_gt_u32_e64 s[30:31], s98, v85
	v_cndmask_b32_e64 v41, 0, v41, s[36:37]
	v_add_u32_e32 v86, 25, v84
	v_cmp_gt_u32_e64 s[36:37], s98, v86
	v_cndmask_b32_e64 v42, 0, v42, s[78:79]
	v_add_u32_e32 v87, 26, v84
	v_cmp_gt_u32_e64 s[78:79], s98, v87
	v_cndmask_b32_e64 v43, 0, v43, s[50:51]
	v_add_u32_e32 v88, 27, v84
	v_cmp_gt_u32_e64 s[50:51], s98, v88
	v_nop
	v_cndmask_b32_e64 v44, 0, v44, s[30:31]
	v_cndmask_b32_e64 v45, 0, v45, s[36:37]
	v_cndmask_b32_e64 v46, 0, v46, s[78:79]
	v_cndmask_b32_e64 v47, 0, v47, s[50:51]
	v_cvt_pk_bf16_f32 v64, v32, v33
	v_cvt_pk_bf16_f32 v65, v34, v35
	v_cvt_pk_bf16_f32 v66, v36, v37
	v_cvt_pk_bf16_f32 v67, v38, v39
	v_cvt_pk_bf16_f32 v68, v40, v41
	v_cvt_pk_bf16_f32 v69, v42, v43
	v_cvt_pk_bf16_f32 v70, v44, v45
	v_cvt_pk_bf16_f32 v71, v46, v47
	v_pk_add_f32 v[232:233], v[232:233], v[32:33]
	v_pk_add_f32 v[232:233], v[232:233], v[34:35]
	v_pk_add_f32 v[232:233], v[232:233], v[36:37]
	v_pk_add_f32 v[232:233], v[232:233], v[38:39]
	v_pk_add_f32 v[232:233], v[232:233], v[40:41]
	v_pk_add_f32 v[232:233], v[232:233], v[42:43]
	v_pk_add_f32 v[232:233], v[232:233], v[44:45]
	v_pk_add_f32 v[232:233], v[232:233], v[46:47]
	s_waitcnt lgkmcnt(0)
	v_mfma_f32_32x32x16_bf16 v[0:15], v[64:67], v[72:75], v[0:15]
	v_mfma_f32_32x32x16_bf16 v[16:31], v[64:67], v[76:79], v[16:31]
	v_mfma_f32_32x32x16_bf16 v[0:15], v[68:71], v[220:223], v[0:15]
	v_mfma_f32_32x32x16_bf16 v[16:31], v[68:71], v[224:227], v[16:31]
	s_add_i32 s90, s67, 192
	v_add_u32_e32 v80, s90, v235
	v_add_u32_e32 v83, s90, v236
	v_add_u32_e32 v99, s90, v237
	v_add_u32_e32 v253, s90, v238
	v_add_u32_e32 v254, s90, v100
	v_add_u32_e32 v255, s90, v149
	v_med3_i32 v80, v80, 0, s99
	v_med3_i32 v83, v83, 0, s99
	v_med3_i32 v99, v99, 0, s99
	v_med3_i32 v253, v253, 0, s99
	v_med3_i32 v254, v254, 0, s99
	v_med3_i32 v255, v255, 0, s99
	v_mad_u32_u24 v80, v80, s100, v252
	v_mad_u32_u24 v83, v83, s100, v252
	v_mad_u32_u24 v99, v99, s100, v252
	v_mad_u32_u24 v253, v253, s100, v252
	v_mad_u32_u24 v254, v254, s100, v153
	v_mad_u32_u24 v255, v255, s100, v153
	global_load_dwordx4 v[188:191], v80, s[82:83]
	global_load_dwordx4 v[192:195], v83, s[82:83]
	global_load_dwordx4 v[196:199], v99, s[82:83]
	global_load_dwordx4 v[200:203], v253, s[82:83]
	global_load_dwordx4 v[204:207], v254, s[82:83] offset:768
	global_load_dwordx4 v[208:211], v255, s[82:83] offset:768
	global_load_dwordx4 v[212:215], v254, s[82:83] offset:832
	global_load_dwordx4 v[216:219], v255, s[82:83] offset:832
	s_waitcnt vmcnt(16)
	ds_write_b128 v247, v[116:119]
	ds_write_b128 v247, v[120:123] offset:1024
	ds_write_b128 v247, v[124:127] offset:2048
	ds_write_b128 v247, v[128:131] offset:3072
	ds_read_b128 v[116:119], v248
	ds_read_b128 v[120:123], v249
	ds_read_b128 v[124:127], v250
	ds_read_b128 v[128:131], v251
	ds_write_b128 v112, v[132:135]
	ds_write_b128 v112, v[136:139] offset:1024
	ds_write_b128 v112, v[140:143] offset:2048
	ds_write_b128 v112, v[144:147] offset:3072
	ds_read2_b32 v[32:33], v115 offset0:204 offset1:205
	ds_read2_b32 v[34:35], v115 offset0:206 offset1:207
	ds_read2_b32 v[36:37], v115 offset0:212 offset1:213
	ds_read2_b32 v[38:39], v115 offset0:214 offset1:215
	ds_read2_b32 v[40:41], v115 offset0:221 offset1:222
	ds_read2_b32 v[42:43], v115 offset0:223 offset1:224
	ds_read2_b32 v[44:45], v115 offset0:229 offset1:230
	ds_read2_b32 v[46:47], v115 offset0:231 offset1:232
	s_waitcnt lgkmcnt(0)
	v_mfma_f32_32x32x16_bf16 v[32:47], v[116:119], v[48:51], v[32:47]
	ds_read_b64_tr_b16 v[72:73], v231
	ds_read_b64_tr_b16 v[74:75], v231 offset:512
	ds_read_b64_tr_b16 v[76:77], v231 offset:2048
	ds_read_b64_tr_b16 v[78:79], v231 offset:2560
	ds_read_b64_tr_b16 v[220:221], v231 offset:1024
	ds_read_b64_tr_b16 v[222:223], v231 offset:1536
	ds_read_b64_tr_b16 v[224:225], v231 offset:3072
	ds_read_b64_tr_b16 v[226:227], v231 offset:3584
	v_mfma_f32_32x32x16_bf16 v[32:47], v[120:123], v[52:55], v[32:47]
	v_mfma_f32_32x32x16_bf16 v[32:47], v[124:127], v[56:59], v[32:47]
	v_mfma_f32_32x32x16_bf16 v[32:47], v[128:131], v[60:63], v[32:47]
	s_nop 11
	v_exp_f32_e32 v32, v32
	v_exp_f32_e32 v33, v33
	v_exp_f32_e32 v34, v34
	v_exp_f32_e32 v35, v35
	v_exp_f32_e32 v36, v36
	v_exp_f32_e32 v37, v37
	v_exp_f32_e32 v38, v38
	v_exp_f32_e32 v39, v39
	v_exp_f32_e32 v40, v40
	v_exp_f32_e32 v41, v41
	v_exp_f32_e32 v42, v42
	v_exp_f32_e32 v43, v43
	v_exp_f32_e32 v44, v44
	v_exp_f32_e32 v45, v45
	v_exp_f32_e32 v46, v46
	v_exp_f32_e32 v47, v47
	s_add_i32 s90, s67, 128
	v_add_u32_e32 v84, s90, v107
	v_add_u32_e32 v85, 0, v84
	v_add_u32_e32 v86, 1, v84
	v_add_u32_e32 v87, 2, v84
	v_add_u32_e32 v88, 3, v84
	v_cmp_gt_u32_e64 s[30:31], s98, v85
	v_cmp_gt_u32_e64 s[36:37], s98, v86
	v_cmp_gt_u32_e64 s[78:79], s98, v87
	v_cmp_gt_u32_e64 s[50:51], s98, v88
	v_cndmask_b32_e64 v32, 0, v32, s[30:31]
	v_add_u32_e32 v85, 8, v84
	v_cmp_gt_u32_e64 s[30:31], s98, v85
	v_cndmask_b32_e64 v33, 0, v33, s[36:37]
	v_add_u32_e32 v86, 9, v84
	v_cmp_gt_u32_e64 s[36:37], s98, v86
	v_cndmask_b32_e64 v34, 0, v34, s[78:79]
	v_add_u32_e32 v87, 10, v84
	v_cmp_gt_u32_e64 s[78:79], s98, v87
	v_cndmask_b32_e64 v35, 0, v35, s[50:51]
	v_add_u32_e32 v88, 11, v84
	v_cmp_gt_u32_e64 s[50:51], s98, v88
	v_cndmask_b32_e64 v36, 0, v36, s[30:31]
	v_add_u32_e32 v85, 16, v84
	v_cmp_gt_u32_e64 s[30:31], s98, v85
	v_cndmask_b32_e64 v37, 0, v37, s[36:37]
	v_add_u32_e32 v86, 17, v84
	v_cmp_gt_u32_e64 s[36:37], s98, v86
	v_cndmask_b32_e64 v38, 0, v38, s[78:79]
	v_add_u32_e32 v87, 18, v84
	v_cmp_gt_u32_e64 s[78:79], s98, v87
	v_cndmask_b32_e64 v39, 0, v39, s[50:51]
	v_add_u32_e32 v88, 19, v84
	v_cmp_gt_u32_e64 s[50:51], s98, v88
	v_cndmask_b32_e64 v40, 0, v40, s[30:31]
	v_add_u32_e32 v85, 24, v84
	v_cmp_gt_u32_e64 s[30:31], s98, v85
	v_cndmask_b32_e64 v41, 0, v41, s[36:37]
	v_add_u32_e32 v86, 25, v84
	v_cmp_gt_u32_e64 s[36:37], s98, v86
	v_cndmask_b32_e64 v42, 0, v42, s[78:79]
	v_add_u32_e32 v87, 26, v84
	v_cmp_gt_u32_e64 s[78:79], s98, v87
	v_cndmask_b32_e64 v43, 0, v43, s[50:51]
	v_add_u32_e32 v88, 27, v84
	v_cmp_gt_u32_e64 s[50:51], s98, v88
	v_nop
	v_cndmask_b32_e64 v44, 0, v44, s[30:31]
	v_cndmask_b32_e64 v45, 0, v45, s[36:37]
	v_cndmask_b32_e64 v46, 0, v46, s[78:79]
	v_cndmask_b32_e64 v47, 0, v47, s[50:51]
	v_cvt_pk_bf16_f32 v64, v32, v33
	v_cvt_pk_bf16_f32 v65, v34, v35
	v_cvt_pk_bf16_f32 v66, v36, v37
	v_cvt_pk_bf16_f32 v67, v38, v39
	v_cvt_pk_bf16_f32 v68, v40, v41
	v_cvt_pk_bf16_f32 v69, v42, v43
	v_cvt_pk_bf16_f32 v70, v44, v45
	v_cvt_pk_bf16_f32 v71, v46, v47
	v_pk_add_f32 v[232:233], v[232:233], v[32:33]
	v_pk_add_f32 v[232:233], v[232:233], v[34:35]
	v_pk_add_f32 v[232:233], v[232:233], v[36:37]
	v_pk_add_f32 v[232:233], v[232:233], v[38:39]
	v_pk_add_f32 v[232:233], v[232:233], v[40:41]
	v_pk_add_f32 v[232:233], v[232:233], v[42:43]
	v_pk_add_f32 v[232:233], v[232:233], v[44:45]
	v_pk_add_f32 v[232:233], v[232:233], v[46:47]
	s_waitcnt lgkmcnt(0)
	v_mfma_f32_32x32x16_bf16 v[0:15], v[64:67], v[72:75], v[0:15]
	v_mfma_f32_32x32x16_bf16 v[16:31], v[64:67], v[76:79], v[16:31]
	v_mfma_f32_32x32x16_bf16 v[0:15], v[68:71], v[220:223], v[0:15]
	v_mfma_f32_32x32x16_bf16 v[16:31], v[68:71], v[224:227], v[16:31]
	s_add_i32 s90, s67, 224
	v_add_u32_e32 v80, s90, v235
	v_add_u32_e32 v83, s90, v236
	v_add_u32_e32 v99, s90, v237
	v_add_u32_e32 v253, s90, v238
	v_add_u32_e32 v254, s90, v100
	v_add_u32_e32 v255, s90, v149
	v_med3_i32 v80, v80, 0, s99
	v_med3_i32 v83, v83, 0, s99
	v_med3_i32 v99, v99, 0, s99
	v_med3_i32 v253, v253, 0, s99
	v_med3_i32 v254, v254, 0, s99
	v_med3_i32 v255, v255, 0, s99
	v_mad_u32_u24 v80, v80, s100, v252
	v_mad_u32_u24 v83, v83, s100, v252
	v_mad_u32_u24 v99, v99, s100, v252
	v_mad_u32_u24 v253, v253, s100, v252
	v_mad_u32_u24 v254, v254, s100, v153
	v_mad_u32_u24 v255, v255, s100, v153
	global_load_dwordx4 v[116:119], v80, s[82:83]
	global_load_dwordx4 v[120:123], v83, s[82:83]
	global_load_dwordx4 v[124:127], v99, s[82:83]
	global_load_dwordx4 v[128:131], v253, s[82:83]
	global_load_dwordx4 v[132:135], v254, s[82:83] offset:768
	global_load_dwordx4 v[136:139], v255, s[82:83] offset:768
	global_load_dwordx4 v[140:143], v254, s[82:83] offset:832
	global_load_dwordx4 v[144:147], v255, s[82:83] offset:832
	s_waitcnt vmcnt(16)
	ds_write_b128 v247, v[156:159]
	ds_write_b128 v247, v[160:163] offset:1024
	ds_write_b128 v247, v[164:167] offset:2048
	ds_write_b128 v247, v[168:171] offset:3072
	ds_read_b128 v[156:159], v248
	ds_read_b128 v[160:163], v249
	ds_read_b128 v[164:167], v250
	ds_read_b128 v[168:171], v251
	ds_write_b128 v112, v[172:175]
	ds_write_b128 v112, v[176:179] offset:1024
	ds_write_b128 v112, v[180:183] offset:2048
	ds_write_b128 v112, v[184:187] offset:3072
	v_add_u32_e32 v115, 952, v115
	ds_read2_b32 v[32:33], v115 offset0:0 offset1:1
	ds_read2_b32 v[34:35], v115 offset0:2 offset1:3
	ds_read2_b32 v[36:37], v115 offset0:8 offset1:9
	ds_read2_b32 v[38:39], v115 offset0:10 offset1:11
	ds_read2_b32 v[40:41], v115 offset0:17 offset1:18
	ds_read2_b32 v[42:43], v115 offset0:19 offset1:20
	ds_read2_b32 v[44:45], v115 offset0:25 offset1:26
	ds_read2_b32 v[46:47], v115 offset0:27 offset1:28
	s_waitcnt lgkmcnt(0)
	v_mfma_f32_32x32x16_bf16 v[32:47], v[156:159], v[48:51], v[32:47]
	ds_read_b64_tr_b16 v[72:73], v231
	ds_read_b64_tr_b16 v[74:75], v231 offset:512
	ds_read_b64_tr_b16 v[76:77], v231 offset:2048
	ds_read_b64_tr_b16 v[78:79], v231 offset:2560
	ds_read_b64_tr_b16 v[220:221], v231 offset:1024
	ds_read_b64_tr_b16 v[222:223], v231 offset:1536
	ds_read_b64_tr_b16 v[224:225], v231 offset:3072
	ds_read_b64_tr_b16 v[226:227], v231 offset:3584
	v_mfma_f32_32x32x16_bf16 v[32:47], v[160:163], v[52:55], v[32:47]
	v_mfma_f32_32x32x16_bf16 v[32:47], v[164:167], v[56:59], v[32:47]
	v_mfma_f32_32x32x16_bf16 v[32:47], v[168:171], v[60:63], v[32:47]
	s_nop 11
	v_exp_f32_e32 v32, v32
	v_exp_f32_e32 v33, v33
	v_exp_f32_e32 v34, v34
	v_exp_f32_e32 v35, v35
	v_exp_f32_e32 v36, v36
	v_exp_f32_e32 v37, v37
	v_exp_f32_e32 v38, v38
	v_exp_f32_e32 v39, v39
	v_exp_f32_e32 v40, v40
	v_exp_f32_e32 v41, v41
	v_exp_f32_e32 v42, v42
	v_exp_f32_e32 v43, v43
	v_exp_f32_e32 v44, v44
	v_exp_f32_e32 v45, v45
	v_exp_f32_e32 v46, v46
	v_exp_f32_e32 v47, v47
	s_add_i32 s90, s67, 160
	v_add_u32_e32 v84, s90, v107
	v_add_u32_e32 v85, 0, v84
	v_add_u32_e32 v86, 1, v84
	v_add_u32_e32 v87, 2, v84
	v_add_u32_e32 v88, 3, v84
	v_cmp_gt_u32_e64 s[30:31], s98, v85
	v_cmp_gt_u32_e64 s[36:37], s98, v86
	v_cmp_gt_u32_e64 s[78:79], s98, v87
	v_cmp_gt_u32_e64 s[50:51], s98, v88
	v_cndmask_b32_e64 v32, 0, v32, s[30:31]
	v_add_u32_e32 v85, 8, v84
	v_cmp_gt_u32_e64 s[30:31], s98, v85
	v_cndmask_b32_e64 v33, 0, v33, s[36:37]
	v_add_u32_e32 v86, 9, v84
	v_cmp_gt_u32_e64 s[36:37], s98, v86
	v_cndmask_b32_e64 v34, 0, v34, s[78:79]
	v_add_u32_e32 v87, 10, v84
	v_cmp_gt_u32_e64 s[78:79], s98, v87
	v_cndmask_b32_e64 v35, 0, v35, s[50:51]
	v_add_u32_e32 v88, 11, v84
	v_cmp_gt_u32_e64 s[50:51], s98, v88
	v_cndmask_b32_e64 v36, 0, v36, s[30:31]
	v_add_u32_e32 v85, 16, v84
	v_cmp_gt_u32_e64 s[30:31], s98, v85
	v_cndmask_b32_e64 v37, 0, v37, s[36:37]
	v_add_u32_e32 v86, 17, v84
	v_cmp_gt_u32_e64 s[36:37], s98, v86
	v_cndmask_b32_e64 v38, 0, v38, s[78:79]
	v_add_u32_e32 v87, 18, v84
	v_cmp_gt_u32_e64 s[78:79], s98, v87
	v_cndmask_b32_e64 v39, 0, v39, s[50:51]
	v_add_u32_e32 v88, 19, v84
	v_cmp_gt_u32_e64 s[50:51], s98, v88
	v_cndmask_b32_e64 v40, 0, v40, s[30:31]
	v_add_u32_e32 v85, 24, v84
	v_cmp_gt_u32_e64 s[30:31], s98, v85
	v_cndmask_b32_e64 v41, 0, v41, s[36:37]
	v_add_u32_e32 v86, 25, v84
	v_cmp_gt_u32_e64 s[36:37], s98, v86
	v_cndmask_b32_e64 v42, 0, v42, s[78:79]
	v_add_u32_e32 v87, 26, v84
	v_cmp_gt_u32_e64 s[78:79], s98, v87
	v_cndmask_b32_e64 v43, 0, v43, s[50:51]
	v_add_u32_e32 v88, 27, v84
	v_cmp_gt_u32_e64 s[50:51], s98, v88
	v_nop
	v_cndmask_b32_e64 v44, 0, v44, s[30:31]
	v_cndmask_b32_e64 v45, 0, v45, s[36:37]
	v_cndmask_b32_e64 v46, 0, v46, s[78:79]
	v_cndmask_b32_e64 v47, 0, v47, s[50:51]
	v_cvt_pk_bf16_f32 v64, v32, v33
	v_cvt_pk_bf16_f32 v65, v34, v35
	v_cvt_pk_bf16_f32 v66, v36, v37
	v_cvt_pk_bf16_f32 v67, v38, v39
	v_cvt_pk_bf16_f32 v68, v40, v41
	v_cvt_pk_bf16_f32 v69, v42, v43
	v_cvt_pk_bf16_f32 v70, v44, v45
	v_cvt_pk_bf16_f32 v71, v46, v47
	v_pk_add_f32 v[232:233], v[232:233], v[32:33]
	v_pk_add_f32 v[232:233], v[232:233], v[34:35]
	v_pk_add_f32 v[232:233], v[232:233], v[36:37]
	v_pk_add_f32 v[232:233], v[232:233], v[38:39]
	v_pk_add_f32 v[232:233], v[232:233], v[40:41]
	v_pk_add_f32 v[232:233], v[232:233], v[42:43]
	v_pk_add_f32 v[232:233], v[232:233], v[44:45]
	v_pk_add_f32 v[232:233], v[232:233], v[46:47]
	s_waitcnt lgkmcnt(0)
	v_mfma_f32_32x32x16_bf16 v[0:15], v[64:67], v[72:75], v[0:15]
	v_mfma_f32_32x32x16_bf16 v[16:31], v[64:67], v[76:79], v[16:31]
	v_mfma_f32_32x32x16_bf16 v[0:15], v[68:71], v[220:223], v[0:15]
	v_mfma_f32_32x32x16_bf16 v[16:31], v[68:71], v[224:227], v[16:31]
	s_add_i32 s90, s67, 256
	v_add_u32_e32 v80, s90, v235
	v_add_u32_e32 v83, s90, v236
	v_add_u32_e32 v99, s90, v237
	v_add_u32_e32 v253, s90, v238
	v_add_u32_e32 v254, s90, v100
	v_add_u32_e32 v255, s90, v149
	v_med3_i32 v80, v80, 0, s99
	v_med3_i32 v83, v83, 0, s99
	v_med3_i32 v99, v99, 0, s99
	v_med3_i32 v253, v253, 0, s99
	v_med3_i32 v254, v254, 0, s99
	v_med3_i32 v255, v255, 0, s99
	v_mad_u32_u24 v80, v80, s100, v252
	v_mad_u32_u24 v83, v83, s100, v252
	v_mad_u32_u24 v99, v99, s100, v252
	v_mad_u32_u24 v253, v253, s100, v252
	v_mad_u32_u24 v254, v254, s100, v153
	v_mad_u32_u24 v255, v255, s100, v153
	global_load_dwordx4 v[156:159], v80, s[82:83]
	global_load_dwordx4 v[160:163], v83, s[82:83]
	global_load_dwordx4 v[164:167], v99, s[82:83]
	global_load_dwordx4 v[168:171], v253, s[82:83]
	global_load_dwordx4 v[172:175], v254, s[82:83] offset:768
	global_load_dwordx4 v[176:179], v255, s[82:83] offset:768
	global_load_dwordx4 v[180:183], v254, s[82:83] offset:832
	global_load_dwordx4 v[184:187], v255, s[82:83] offset:832
	s_waitcnt vmcnt(16)
	ds_write_b128 v247, v[188:191]
	ds_write_b128 v247, v[192:195] offset:1024
	ds_write_b128 v247, v[196:199] offset:2048
	ds_write_b128 v247, v[200:203] offset:3072
	ds_read_b128 v[188:191], v248
	ds_read_b128 v[192:195], v249
	ds_read_b128 v[196:199], v250
	ds_read_b128 v[200:203], v251
	ds_write_b128 v112, v[204:207]
	ds_write_b128 v112, v[208:211] offset:1024
	ds_write_b128 v112, v[212:215] offset:2048
	ds_write_b128 v112, v[216:219] offset:3072
	ds_read2_b32 v[32:33], v115 offset0:34 offset1:35
	ds_read2_b32 v[34:35], v115 offset0:36 offset1:37
	ds_read2_b32 v[36:37], v115 offset0:42 offset1:43
	ds_read2_b32 v[38:39], v115 offset0:44 offset1:45
	ds_read2_b32 v[40:41], v115 offset0:51 offset1:52
	ds_read2_b32 v[42:43], v115 offset0:53 offset1:54
	ds_read2_b32 v[44:45], v115 offset0:59 offset1:60
	ds_read2_b32 v[46:47], v115 offset0:61 offset1:62
	s_waitcnt lgkmcnt(0)
	v_mfma_f32_32x32x16_bf16 v[32:47], v[188:191], v[48:51], v[32:47]
	ds_read_b64_tr_b16 v[72:73], v231
	ds_read_b64_tr_b16 v[74:75], v231 offset:512
	ds_read_b64_tr_b16 v[76:77], v231 offset:2048
	ds_read_b64_tr_b16 v[78:79], v231 offset:2560
	ds_read_b64_tr_b16 v[220:221], v231 offset:1024
	ds_read_b64_tr_b16 v[222:223], v231 offset:1536
	ds_read_b64_tr_b16 v[224:225], v231 offset:3072
	ds_read_b64_tr_b16 v[226:227], v231 offset:3584
	v_mfma_f32_32x32x16_bf16 v[32:47], v[192:195], v[52:55], v[32:47]
	v_mfma_f32_32x32x16_bf16 v[32:47], v[196:199], v[56:59], v[32:47]
	v_mfma_f32_32x32x16_bf16 v[32:47], v[200:203], v[60:63], v[32:47]
	s_nop 11
	v_exp_f32_e32 v32, v32
	v_exp_f32_e32 v33, v33
	v_exp_f32_e32 v34, v34
	v_exp_f32_e32 v35, v35
	v_exp_f32_e32 v36, v36
	v_exp_f32_e32 v37, v37
	v_exp_f32_e32 v38, v38
	v_exp_f32_e32 v39, v39
	v_exp_f32_e32 v40, v40
	v_exp_f32_e32 v41, v41
	v_exp_f32_e32 v42, v42
	v_exp_f32_e32 v43, v43
	v_exp_f32_e32 v44, v44
	v_exp_f32_e32 v45, v45
	v_exp_f32_e32 v46, v46
	v_exp_f32_e32 v47, v47
	s_add_i32 s90, s67, 192
	v_add_u32_e32 v84, s90, v107
	v_add_u32_e32 v85, 0, v84
	v_add_u32_e32 v86, 1, v84
	v_add_u32_e32 v87, 2, v84
	v_add_u32_e32 v88, 3, v84
	v_cmp_gt_u32_e64 s[30:31], s98, v85
	v_cmp_gt_u32_e64 s[36:37], s98, v86
	v_cmp_gt_u32_e64 s[78:79], s98, v87
	v_cmp_gt_u32_e64 s[50:51], s98, v88
	v_cndmask_b32_e64 v32, 0, v32, s[30:31]
	v_add_u32_e32 v85, 8, v84
	v_cmp_gt_u32_e64 s[30:31], s98, v85
	v_cndmask_b32_e64 v33, 0, v33, s[36:37]
	v_add_u32_e32 v86, 9, v84
	v_cmp_gt_u32_e64 s[36:37], s98, v86
	v_cndmask_b32_e64 v34, 0, v34, s[78:79]
	v_add_u32_e32 v87, 10, v84
	v_cmp_gt_u32_e64 s[78:79], s98, v87
	v_cndmask_b32_e64 v35, 0, v35, s[50:51]
	v_add_u32_e32 v88, 11, v84
	v_cmp_gt_u32_e64 s[50:51], s98, v88
	v_cndmask_b32_e64 v36, 0, v36, s[30:31]
	v_add_u32_e32 v85, 16, v84
	v_cmp_gt_u32_e64 s[30:31], s98, v85
	v_cndmask_b32_e64 v37, 0, v37, s[36:37]
	v_add_u32_e32 v86, 17, v84
	v_cmp_gt_u32_e64 s[36:37], s98, v86
	v_cndmask_b32_e64 v38, 0, v38, s[78:79]
	v_add_u32_e32 v87, 18, v84
	v_cmp_gt_u32_e64 s[78:79], s98, v87
	v_cndmask_b32_e64 v39, 0, v39, s[50:51]
	v_add_u32_e32 v88, 19, v84
	v_cmp_gt_u32_e64 s[50:51], s98, v88
	v_cndmask_b32_e64 v40, 0, v40, s[30:31]
	v_add_u32_e32 v85, 24, v84
	v_cmp_gt_u32_e64 s[30:31], s98, v85
	v_cndmask_b32_e64 v41, 0, v41, s[36:37]
	v_add_u32_e32 v86, 25, v84
	v_cmp_gt_u32_e64 s[36:37], s98, v86
	v_cndmask_b32_e64 v42, 0, v42, s[78:79]
	v_add_u32_e32 v87, 26, v84
	v_cmp_gt_u32_e64 s[78:79], s98, v87
	v_cndmask_b32_e64 v43, 0, v43, s[50:51]
	v_add_u32_e32 v88, 27, v84
	v_cmp_gt_u32_e64 s[50:51], s98, v88
	v_nop
	v_cndmask_b32_e64 v44, 0, v44, s[30:31]
	v_cndmask_b32_e64 v45, 0, v45, s[36:37]
	v_cndmask_b32_e64 v46, 0, v46, s[78:79]
	v_cndmask_b32_e64 v47, 0, v47, s[50:51]
	v_cvt_pk_bf16_f32 v64, v32, v33
	v_cvt_pk_bf16_f32 v65, v34, v35
	v_cvt_pk_bf16_f32 v66, v36, v37
	v_cvt_pk_bf16_f32 v67, v38, v39
	v_cvt_pk_bf16_f32 v68, v40, v41
	v_cvt_pk_bf16_f32 v69, v42, v43
	v_cvt_pk_bf16_f32 v70, v44, v45
	v_cvt_pk_bf16_f32 v71, v46, v47
	v_pk_add_f32 v[232:233], v[232:233], v[32:33]
	v_pk_add_f32 v[232:233], v[232:233], v[34:35]
	v_pk_add_f32 v[232:233], v[232:233], v[36:37]
	v_pk_add_f32 v[232:233], v[232:233], v[38:39]
	v_pk_add_f32 v[232:233], v[232:233], v[40:41]
	v_pk_add_f32 v[232:233], v[232:233], v[42:43]
	v_pk_add_f32 v[232:233], v[232:233], v[44:45]
	v_pk_add_f32 v[232:233], v[232:233], v[46:47]
	s_waitcnt lgkmcnt(0)
	v_mfma_f32_32x32x16_bf16 v[0:15], v[64:67], v[72:75], v[0:15]
	v_mfma_f32_32x32x16_bf16 v[16:31], v[64:67], v[76:79], v[16:31]
	v_mfma_f32_32x32x16_bf16 v[0:15], v[68:71], v[220:223], v[0:15]
	v_mfma_f32_32x32x16_bf16 v[16:31], v[68:71], v[224:227], v[16:31]
	s_add_i32 s90, s67, 288
	v_add_u32_e32 v80, s90, v235
	v_add_u32_e32 v83, s90, v236
	v_add_u32_e32 v99, s90, v237
	v_add_u32_e32 v253, s90, v238
	v_add_u32_e32 v254, s90, v100
	v_add_u32_e32 v255, s90, v149
	v_med3_i32 v80, v80, 0, s99
	v_med3_i32 v83, v83, 0, s99
	v_med3_i32 v99, v99, 0, s99
	v_med3_i32 v253, v253, 0, s99
	v_med3_i32 v254, v254, 0, s99
	v_med3_i32 v255, v255, 0, s99
	v_mad_u32_u24 v80, v80, s100, v252
	v_mad_u32_u24 v83, v83, s100, v252
	v_mad_u32_u24 v99, v99, s100, v252
	v_mad_u32_u24 v253, v253, s100, v252
	v_mad_u32_u24 v254, v254, s100, v153
	v_mad_u32_u24 v255, v255, s100, v153
	global_load_dwordx4 v[188:191], v80, s[82:83]
	global_load_dwordx4 v[192:195], v83, s[82:83]
	global_load_dwordx4 v[196:199], v99, s[82:83]
	global_load_dwordx4 v[200:203], v253, s[82:83]
	global_load_dwordx4 v[204:207], v254, s[82:83] offset:768
	global_load_dwordx4 v[208:211], v255, s[82:83] offset:768
	global_load_dwordx4 v[212:215], v254, s[82:83] offset:832
	global_load_dwordx4 v[216:219], v255, s[82:83] offset:832
	s_waitcnt vmcnt(16)
	ds_write_b128 v247, v[116:119]
	ds_write_b128 v247, v[120:123] offset:1024
	ds_write_b128 v247, v[124:127] offset:2048
	ds_write_b128 v247, v[128:131] offset:3072
	ds_read_b128 v[116:119], v248
	ds_read_b128 v[120:123], v249
	ds_read_b128 v[124:127], v250
	ds_read_b128 v[128:131], v251
	ds_write_b128 v112, v[132:135]
	ds_write_b128 v112, v[136:139] offset:1024
	ds_write_b128 v112, v[140:143] offset:2048
	ds_write_b128 v112, v[144:147] offset:3072
	ds_read2_b32 v[32:33], v115 offset0:68 offset1:69
	ds_read2_b32 v[34:35], v115 offset0:70 offset1:71
	ds_read2_b32 v[36:37], v115 offset0:76 offset1:77
	ds_read2_b32 v[38:39], v115 offset0:78 offset1:79
	ds_read2_b32 v[40:41], v115 offset0:85 offset1:86
	ds_read2_b32 v[42:43], v115 offset0:87 offset1:88
	ds_read2_b32 v[44:45], v115 offset0:93 offset1:94
	ds_read2_b32 v[46:47], v115 offset0:95 offset1:96
	s_waitcnt lgkmcnt(0)
	v_mfma_f32_32x32x16_bf16 v[32:47], v[116:119], v[48:51], v[32:47]
	ds_read_b64_tr_b16 v[72:73], v231
	ds_read_b64_tr_b16 v[74:75], v231 offset:512
	ds_read_b64_tr_b16 v[76:77], v231 offset:2048
	ds_read_b64_tr_b16 v[78:79], v231 offset:2560
	ds_read_b64_tr_b16 v[220:221], v231 offset:1024
	ds_read_b64_tr_b16 v[222:223], v231 offset:1536
	ds_read_b64_tr_b16 v[224:225], v231 offset:3072
	ds_read_b64_tr_b16 v[226:227], v231 offset:3584
	v_mfma_f32_32x32x16_bf16 v[32:47], v[120:123], v[52:55], v[32:47]
	v_mfma_f32_32x32x16_bf16 v[32:47], v[124:127], v[56:59], v[32:47]
	v_mfma_f32_32x32x16_bf16 v[32:47], v[128:131], v[60:63], v[32:47]
	s_nop 11
	v_exp_f32_e32 v32, v32
	v_exp_f32_e32 v33, v33
	v_exp_f32_e32 v34, v34
	v_exp_f32_e32 v35, v35
	v_exp_f32_e32 v36, v36
	v_exp_f32_e32 v37, v37
	v_exp_f32_e32 v38, v38
	v_exp_f32_e32 v39, v39
	v_exp_f32_e32 v40, v40
	v_exp_f32_e32 v41, v41
	v_exp_f32_e32 v42, v42
	v_exp_f32_e32 v43, v43
	v_exp_f32_e32 v44, v44
	v_exp_f32_e32 v45, v45
	v_exp_f32_e32 v46, v46
	v_exp_f32_e32 v47, v47
	s_add_i32 s90, s67, 224
	v_add_u32_e32 v84, s90, v107
	v_add_u32_e32 v85, 0, v84
	v_add_u32_e32 v86, 1, v84
	v_add_u32_e32 v87, 2, v84
	v_add_u32_e32 v88, 3, v84
	v_cmp_gt_u32_e64 s[30:31], s98, v85
	v_cmp_gt_u32_e64 s[36:37], s98, v86
	v_cmp_gt_u32_e64 s[78:79], s98, v87
	v_cmp_gt_u32_e64 s[50:51], s98, v88
	v_cndmask_b32_e64 v32, 0, v32, s[30:31]
	v_add_u32_e32 v85, 8, v84
	v_cmp_gt_u32_e64 s[30:31], s98, v85
	v_cndmask_b32_e64 v33, 0, v33, s[36:37]
	v_add_u32_e32 v86, 9, v84
	v_cmp_gt_u32_e64 s[36:37], s98, v86
	v_cndmask_b32_e64 v34, 0, v34, s[78:79]
	v_add_u32_e32 v87, 10, v84
	v_cmp_gt_u32_e64 s[78:79], s98, v87
	v_cndmask_b32_e64 v35, 0, v35, s[50:51]
	v_add_u32_e32 v88, 11, v84
	v_cmp_gt_u32_e64 s[50:51], s98, v88
	v_cndmask_b32_e64 v36, 0, v36, s[30:31]
	v_add_u32_e32 v85, 16, v84
	v_cmp_gt_u32_e64 s[30:31], s98, v85
	v_cndmask_b32_e64 v37, 0, v37, s[36:37]
	v_add_u32_e32 v86, 17, v84
	v_cmp_gt_u32_e64 s[36:37], s98, v86
	v_cndmask_b32_e64 v38, 0, v38, s[78:79]
	v_add_u32_e32 v87, 18, v84
	v_cmp_gt_u32_e64 s[78:79], s98, v87
	v_cndmask_b32_e64 v39, 0, v39, s[50:51]
	v_add_u32_e32 v88, 19, v84
	v_cmp_gt_u32_e64 s[50:51], s98, v88
	v_cndmask_b32_e64 v40, 0, v40, s[30:31]
	v_add_u32_e32 v85, 24, v84
	v_cmp_gt_u32_e64 s[30:31], s98, v85
	v_cndmask_b32_e64 v41, 0, v41, s[36:37]
	v_add_u32_e32 v86, 25, v84
	v_cmp_gt_u32_e64 s[36:37], s98, v86
	v_cndmask_b32_e64 v42, 0, v42, s[78:79]
	v_add_u32_e32 v87, 26, v84
	v_cmp_gt_u32_e64 s[78:79], s98, v87
	v_cndmask_b32_e64 v43, 0, v43, s[50:51]
	v_add_u32_e32 v88, 27, v84
	v_cmp_gt_u32_e64 s[50:51], s98, v88
	v_nop
	v_cndmask_b32_e64 v44, 0, v44, s[30:31]
	v_cndmask_b32_e64 v45, 0, v45, s[36:37]
	v_cndmask_b32_e64 v46, 0, v46, s[78:79]
	v_cndmask_b32_e64 v47, 0, v47, s[50:51]
	v_cvt_pk_bf16_f32 v64, v32, v33
	v_cvt_pk_bf16_f32 v65, v34, v35
	v_cvt_pk_bf16_f32 v66, v36, v37
	v_cvt_pk_bf16_f32 v67, v38, v39
	v_cvt_pk_bf16_f32 v68, v40, v41
	v_cvt_pk_bf16_f32 v69, v42, v43
	v_cvt_pk_bf16_f32 v70, v44, v45
	v_cvt_pk_bf16_f32 v71, v46, v47
	v_pk_add_f32 v[232:233], v[232:233], v[32:33]
	v_pk_add_f32 v[232:233], v[232:233], v[34:35]
	v_pk_add_f32 v[232:233], v[232:233], v[36:37]
	v_pk_add_f32 v[232:233], v[232:233], v[38:39]
	v_pk_add_f32 v[232:233], v[232:233], v[40:41]
	v_pk_add_f32 v[232:233], v[232:233], v[42:43]
	v_pk_add_f32 v[232:233], v[232:233], v[44:45]
	v_pk_add_f32 v[232:233], v[232:233], v[46:47]
	s_waitcnt lgkmcnt(0)
	v_mfma_f32_32x32x16_bf16 v[0:15], v[64:67], v[72:75], v[0:15]
	v_mfma_f32_32x32x16_bf16 v[16:31], v[64:67], v[76:79], v[16:31]
	v_mfma_f32_32x32x16_bf16 v[0:15], v[68:71], v[220:223], v[0:15]
	v_mfma_f32_32x32x16_bf16 v[16:31], v[68:71], v[224:227], v[16:31]
	s_add_i32 s90, s67, 320
	v_add_u32_e32 v80, s90, v235
	v_add_u32_e32 v83, s90, v236
	v_add_u32_e32 v99, s90, v237
	v_add_u32_e32 v253, s90, v238
	v_add_u32_e32 v254, s90, v100
	v_add_u32_e32 v255, s90, v149
	v_med3_i32 v80, v80, 0, s99
	v_med3_i32 v83, v83, 0, s99
	v_med3_i32 v99, v99, 0, s99
	v_med3_i32 v253, v253, 0, s99
	v_med3_i32 v254, v254, 0, s99
	v_med3_i32 v255, v255, 0, s99
	v_mad_u32_u24 v80, v80, s100, v252
	v_mad_u32_u24 v83, v83, s100, v252
	v_mad_u32_u24 v99, v99, s100, v252
	v_mad_u32_u24 v253, v253, s100, v252
	v_mad_u32_u24 v254, v254, s100, v153
	v_mad_u32_u24 v255, v255, s100, v153
	global_load_dwordx4 v[116:119], v80, s[82:83]
	global_load_dwordx4 v[120:123], v83, s[82:83]
	global_load_dwordx4 v[124:127], v99, s[82:83]
	global_load_dwordx4 v[128:131], v253, s[82:83]
	global_load_dwordx4 v[132:135], v254, s[82:83] offset:768
	global_load_dwordx4 v[136:139], v255, s[82:83] offset:768
	global_load_dwordx4 v[140:143], v254, s[82:83] offset:832
	global_load_dwordx4 v[144:147], v255, s[82:83] offset:832
	s_waitcnt vmcnt(16)
	ds_write_b128 v247, v[156:159]
	ds_write_b128 v247, v[160:163] offset:1024
	ds_write_b128 v247, v[164:167] offset:2048
	ds_write_b128 v247, v[168:171] offset:3072
	ds_read_b128 v[156:159], v248
	ds_read_b128 v[160:163], v249
	ds_read_b128 v[164:167], v250
	ds_read_b128 v[168:171], v251
	ds_write_b128 v112, v[172:175]
	ds_write_b128 v112, v[176:179] offset:1024
	ds_write_b128 v112, v[180:183] offset:2048
	ds_write_b128 v112, v[184:187] offset:3072
	ds_read2_b32 v[32:33], v115 offset0:102 offset1:103
	ds_read2_b32 v[34:35], v115 offset0:104 offset1:105
	ds_read2_b32 v[36:37], v115 offset0:110 offset1:111
	ds_read2_b32 v[38:39], v115 offset0:112 offset1:113
	ds_read2_b32 v[40:41], v115 offset0:119 offset1:120
	ds_read2_b32 v[42:43], v115 offset0:121 offset1:122
	ds_read2_b32 v[44:45], v115 offset0:127 offset1:128
	ds_read2_b32 v[46:47], v115 offset0:129 offset1:130
	s_waitcnt lgkmcnt(0)
	v_mfma_f32_32x32x16_bf16 v[32:47], v[156:159], v[48:51], v[32:47]
	ds_read_b64_tr_b16 v[72:73], v231
	ds_read_b64_tr_b16 v[74:75], v231 offset:512
	ds_read_b64_tr_b16 v[76:77], v231 offset:2048
	ds_read_b64_tr_b16 v[78:79], v231 offset:2560
	ds_read_b64_tr_b16 v[220:221], v231 offset:1024
	ds_read_b64_tr_b16 v[222:223], v231 offset:1536
	ds_read_b64_tr_b16 v[224:225], v231 offset:3072
	ds_read_b64_tr_b16 v[226:227], v231 offset:3584
	v_mfma_f32_32x32x16_bf16 v[32:47], v[160:163], v[52:55], v[32:47]
	v_mfma_f32_32x32x16_bf16 v[32:47], v[164:167], v[56:59], v[32:47]
	v_mfma_f32_32x32x16_bf16 v[32:47], v[168:171], v[60:63], v[32:47]
	s_nop 11
	v_exp_f32_e32 v32, v32
	v_exp_f32_e32 v33, v33
	v_exp_f32_e32 v34, v34
	v_exp_f32_e32 v35, v35
	v_exp_f32_e32 v36, v36
	v_exp_f32_e32 v37, v37
	v_exp_f32_e32 v38, v38
	v_exp_f32_e32 v39, v39
	v_exp_f32_e32 v40, v40
	v_exp_f32_e32 v41, v41
	v_exp_f32_e32 v42, v42
	v_exp_f32_e32 v43, v43
	v_exp_f32_e32 v44, v44
	v_exp_f32_e32 v45, v45
	v_exp_f32_e32 v46, v46
	v_exp_f32_e32 v47, v47
	s_add_i32 s90, s67, 256
	v_add_u32_e32 v84, s90, v107
	v_add_u32_e32 v85, 0, v84
	v_add_u32_e32 v86, 1, v84
	v_add_u32_e32 v87, 2, v84
	v_add_u32_e32 v88, 3, v84
	v_cmp_gt_u32_e64 s[30:31], s98, v85
	v_cmp_gt_u32_e64 s[36:37], s98, v86
	v_cmp_gt_u32_e64 s[78:79], s98, v87
	v_cmp_gt_u32_e64 s[50:51], s98, v88
	v_cndmask_b32_e64 v32, 0, v32, s[30:31]
	v_add_u32_e32 v85, 8, v84
	v_cmp_gt_u32_e64 s[30:31], s98, v85
	v_cndmask_b32_e64 v33, 0, v33, s[36:37]
	v_add_u32_e32 v86, 9, v84
	v_cmp_gt_u32_e64 s[36:37], s98, v86
	v_cndmask_b32_e64 v34, 0, v34, s[78:79]
	v_add_u32_e32 v87, 10, v84
	v_cmp_gt_u32_e64 s[78:79], s98, v87
	v_cndmask_b32_e64 v35, 0, v35, s[50:51]
	v_add_u32_e32 v88, 11, v84
	v_cmp_gt_u32_e64 s[50:51], s98, v88
	v_cndmask_b32_e64 v36, 0, v36, s[30:31]
	v_add_u32_e32 v85, 16, v84
	v_cmp_gt_u32_e64 s[30:31], s98, v85
	v_cndmask_b32_e64 v37, 0, v37, s[36:37]
	v_add_u32_e32 v86, 17, v84
	v_cmp_gt_u32_e64 s[36:37], s98, v86
	v_cndmask_b32_e64 v38, 0, v38, s[78:79]
	v_add_u32_e32 v87, 18, v84
	v_cmp_gt_u32_e64 s[78:79], s98, v87
	v_cndmask_b32_e64 v39, 0, v39, s[50:51]
	v_add_u32_e32 v88, 19, v84
	v_cmp_gt_u32_e64 s[50:51], s98, v88
	v_cndmask_b32_e64 v40, 0, v40, s[30:31]
	v_add_u32_e32 v85, 24, v84
	v_cmp_gt_u32_e64 s[30:31], s98, v85
	v_cndmask_b32_e64 v41, 0, v41, s[36:37]
	v_add_u32_e32 v86, 25, v84
	v_cmp_gt_u32_e64 s[36:37], s98, v86
	v_cndmask_b32_e64 v42, 0, v42, s[78:79]
	v_add_u32_e32 v87, 26, v84
	v_cmp_gt_u32_e64 s[78:79], s98, v87
	v_cndmask_b32_e64 v43, 0, v43, s[50:51]
	v_add_u32_e32 v88, 27, v84
	v_cmp_gt_u32_e64 s[50:51], s98, v88
	v_nop
	v_cndmask_b32_e64 v44, 0, v44, s[30:31]
	v_cndmask_b32_e64 v45, 0, v45, s[36:37]
	v_cndmask_b32_e64 v46, 0, v46, s[78:79]
	v_cndmask_b32_e64 v47, 0, v47, s[50:51]
	v_cvt_pk_bf16_f32 v64, v32, v33
	v_cvt_pk_bf16_f32 v65, v34, v35
	v_cvt_pk_bf16_f32 v66, v36, v37
	v_cvt_pk_bf16_f32 v67, v38, v39
	v_cvt_pk_bf16_f32 v68, v40, v41
	v_cvt_pk_bf16_f32 v69, v42, v43
	v_cvt_pk_bf16_f32 v70, v44, v45
	v_cvt_pk_bf16_f32 v71, v46, v47
	v_pk_add_f32 v[232:233], v[232:233], v[32:33]
	v_pk_add_f32 v[232:233], v[232:233], v[34:35]
	v_pk_add_f32 v[232:233], v[232:233], v[36:37]
	v_pk_add_f32 v[232:233], v[232:233], v[38:39]
	v_pk_add_f32 v[232:233], v[232:233], v[40:41]
	v_pk_add_f32 v[232:233], v[232:233], v[42:43]
	v_pk_add_f32 v[232:233], v[232:233], v[44:45]
	v_pk_add_f32 v[232:233], v[232:233], v[46:47]
	s_waitcnt lgkmcnt(0)
	v_mfma_f32_32x32x16_bf16 v[0:15], v[64:67], v[72:75], v[0:15]
	v_mfma_f32_32x32x16_bf16 v[16:31], v[64:67], v[76:79], v[16:31]
	v_mfma_f32_32x32x16_bf16 v[0:15], v[68:71], v[220:223], v[0:15]
	v_mfma_f32_32x32x16_bf16 v[16:31], v[68:71], v[224:227], v[16:31]
	s_add_i32 s90, s67, 352
	v_add_u32_e32 v80, s90, v235
	v_add_u32_e32 v83, s90, v236
	v_add_u32_e32 v99, s90, v237
	v_add_u32_e32 v253, s90, v238
	v_add_u32_e32 v254, s90, v100
	v_add_u32_e32 v255, s90, v149
	v_med3_i32 v80, v80, 0, s99
	v_med3_i32 v83, v83, 0, s99
	v_med3_i32 v99, v99, 0, s99
	v_med3_i32 v253, v253, 0, s99
	v_med3_i32 v254, v254, 0, s99
	v_med3_i32 v255, v255, 0, s99
	v_mad_u32_u24 v80, v80, s100, v252
	v_mad_u32_u24 v83, v83, s100, v252
	v_mad_u32_u24 v99, v99, s100, v252
	v_mad_u32_u24 v253, v253, s100, v252
	v_mad_u32_u24 v254, v254, s100, v153
	v_mad_u32_u24 v255, v255, s100, v153
	global_load_dwordx4 v[156:159], v80, s[82:83]
	global_load_dwordx4 v[160:163], v83, s[82:83]
	global_load_dwordx4 v[164:167], v99, s[82:83]
	global_load_dwordx4 v[168:171], v253, s[82:83]
	global_load_dwordx4 v[172:175], v254, s[82:83] offset:768
	global_load_dwordx4 v[176:179], v255, s[82:83] offset:768
	global_load_dwordx4 v[180:183], v254, s[82:83] offset:832
	global_load_dwordx4 v[184:187], v255, s[82:83] offset:832
	s_waitcnt vmcnt(16)
	ds_write_b128 v247, v[188:191]
	ds_write_b128 v247, v[192:195] offset:1024
	ds_write_b128 v247, v[196:199] offset:2048
	ds_write_b128 v247, v[200:203] offset:3072
	ds_read_b128 v[188:191], v248
	ds_read_b128 v[192:195], v249
	ds_read_b128 v[196:199], v250
	ds_read_b128 v[200:203], v251
	ds_write_b128 v112, v[204:207]
	ds_write_b128 v112, v[208:211] offset:1024
	ds_write_b128 v112, v[212:215] offset:2048
	ds_write_b128 v112, v[216:219] offset:3072
	ds_read2_b32 v[32:33], v115 offset0:136 offset1:137
	ds_read2_b32 v[34:35], v115 offset0:138 offset1:139
	ds_read2_b32 v[36:37], v115 offset0:144 offset1:145
	ds_read2_b32 v[38:39], v115 offset0:146 offset1:147
	ds_read2_b32 v[40:41], v115 offset0:153 offset1:154
	ds_read2_b32 v[42:43], v115 offset0:155 offset1:156
	ds_read2_b32 v[44:45], v115 offset0:161 offset1:162
	ds_read2_b32 v[46:47], v115 offset0:163 offset1:164
	s_waitcnt lgkmcnt(0)
	v_mfma_f32_32x32x16_bf16 v[32:47], v[188:191], v[48:51], v[32:47]
	ds_read_b64_tr_b16 v[72:73], v231
	ds_read_b64_tr_b16 v[74:75], v231 offset:512
	ds_read_b64_tr_b16 v[76:77], v231 offset:2048
	ds_read_b64_tr_b16 v[78:79], v231 offset:2560
	ds_read_b64_tr_b16 v[220:221], v231 offset:1024
	ds_read_b64_tr_b16 v[222:223], v231 offset:1536
	ds_read_b64_tr_b16 v[224:225], v231 offset:3072
	ds_read_b64_tr_b16 v[226:227], v231 offset:3584
	v_mfma_f32_32x32x16_bf16 v[32:47], v[192:195], v[52:55], v[32:47]
	v_mfma_f32_32x32x16_bf16 v[32:47], v[196:199], v[56:59], v[32:47]
	v_mfma_f32_32x32x16_bf16 v[32:47], v[200:203], v[60:63], v[32:47]
	s_nop 11
	v_exp_f32_e32 v32, v32
	v_exp_f32_e32 v33, v33
	v_exp_f32_e32 v34, v34
	v_exp_f32_e32 v35, v35
	v_exp_f32_e32 v36, v36
	v_exp_f32_e32 v37, v37
	v_exp_f32_e32 v38, v38
	v_exp_f32_e32 v39, v39
	v_exp_f32_e32 v40, v40
	v_exp_f32_e32 v41, v41
	v_exp_f32_e32 v42, v42
	v_exp_f32_e32 v43, v43
	v_exp_f32_e32 v44, v44
	v_exp_f32_e32 v45, v45
	v_exp_f32_e32 v46, v46
	v_exp_f32_e32 v47, v47
	s_add_i32 s90, s67, 288
	v_add_u32_e32 v84, s90, v107
	v_add_u32_e32 v85, 0, v84
	v_add_u32_e32 v86, 1, v84
	v_add_u32_e32 v87, 2, v84
	v_add_u32_e32 v88, 3, v84
	v_cmp_gt_u32_e64 s[30:31], s98, v85
	v_cmp_gt_u32_e64 s[36:37], s98, v86
	v_cmp_gt_u32_e64 s[78:79], s98, v87
	v_cmp_gt_u32_e64 s[50:51], s98, v88
	v_cndmask_b32_e64 v32, 0, v32, s[30:31]
	v_add_u32_e32 v85, 8, v84
	v_cmp_gt_u32_e64 s[30:31], s98, v85
	v_cndmask_b32_e64 v33, 0, v33, s[36:37]
	v_add_u32_e32 v86, 9, v84
	v_cmp_gt_u32_e64 s[36:37], s98, v86
	v_cndmask_b32_e64 v34, 0, v34, s[78:79]
	v_add_u32_e32 v87, 10, v84
	v_cmp_gt_u32_e64 s[78:79], s98, v87
	v_cndmask_b32_e64 v35, 0, v35, s[50:51]
	v_add_u32_e32 v88, 11, v84
	v_cmp_gt_u32_e64 s[50:51], s98, v88
	v_cndmask_b32_e64 v36, 0, v36, s[30:31]
	v_add_u32_e32 v85, 16, v84
	v_cmp_gt_u32_e64 s[30:31], s98, v85
	v_cndmask_b32_e64 v37, 0, v37, s[36:37]
	v_add_u32_e32 v86, 17, v84
	v_cmp_gt_u32_e64 s[36:37], s98, v86
	v_cndmask_b32_e64 v38, 0, v38, s[78:79]
	v_add_u32_e32 v87, 18, v84
	v_cmp_gt_u32_e64 s[78:79], s98, v87
	v_cndmask_b32_e64 v39, 0, v39, s[50:51]
	v_add_u32_e32 v88, 19, v84
	v_cmp_gt_u32_e64 s[50:51], s98, v88
	v_cndmask_b32_e64 v40, 0, v40, s[30:31]
	v_add_u32_e32 v85, 24, v84
	v_cmp_gt_u32_e64 s[30:31], s98, v85
	v_cndmask_b32_e64 v41, 0, v41, s[36:37]
	v_add_u32_e32 v86, 25, v84
	v_cmp_gt_u32_e64 s[36:37], s98, v86
	v_cndmask_b32_e64 v42, 0, v42, s[78:79]
	v_add_u32_e32 v87, 26, v84
	v_cmp_gt_u32_e64 s[78:79], s98, v87
	v_cndmask_b32_e64 v43, 0, v43, s[50:51]
	v_add_u32_e32 v88, 27, v84
	v_cmp_gt_u32_e64 s[50:51], s98, v88
	v_nop
	v_cndmask_b32_e64 v44, 0, v44, s[30:31]
	v_cndmask_b32_e64 v45, 0, v45, s[36:37]
	v_cndmask_b32_e64 v46, 0, v46, s[78:79]
	v_cndmask_b32_e64 v47, 0, v47, s[50:51]
	v_cvt_pk_bf16_f32 v64, v32, v33
	v_cvt_pk_bf16_f32 v65, v34, v35
	v_cvt_pk_bf16_f32 v66, v36, v37
	v_cvt_pk_bf16_f32 v67, v38, v39
	v_cvt_pk_bf16_f32 v68, v40, v41
	v_cvt_pk_bf16_f32 v69, v42, v43
	v_cvt_pk_bf16_f32 v70, v44, v45
	v_cvt_pk_bf16_f32 v71, v46, v47
	v_pk_add_f32 v[232:233], v[232:233], v[32:33]
	v_pk_add_f32 v[232:233], v[232:233], v[34:35]
	v_pk_add_f32 v[232:233], v[232:233], v[36:37]
	v_pk_add_f32 v[232:233], v[232:233], v[38:39]
	v_pk_add_f32 v[232:233], v[232:233], v[40:41]
	v_pk_add_f32 v[232:233], v[232:233], v[42:43]
	v_pk_add_f32 v[232:233], v[232:233], v[44:45]
	v_pk_add_f32 v[232:233], v[232:233], v[46:47]
	s_waitcnt lgkmcnt(0)
	v_mfma_f32_32x32x16_bf16 v[0:15], v[64:67], v[72:75], v[0:15]
	v_mfma_f32_32x32x16_bf16 v[16:31], v[64:67], v[76:79], v[16:31]
	v_mfma_f32_32x32x16_bf16 v[0:15], v[68:71], v[220:223], v[0:15]
	v_mfma_f32_32x32x16_bf16 v[16:31], v[68:71], v[224:227], v[16:31]
	s_add_i32 s90, s67, 384
	v_add_u32_e32 v80, s90, v235
	v_add_u32_e32 v83, s90, v236
	v_add_u32_e32 v99, s90, v237
	v_add_u32_e32 v253, s90, v238
	v_add_u32_e32 v254, s90, v100
	v_add_u32_e32 v255, s90, v149
	v_med3_i32 v80, v80, 0, s99
	v_med3_i32 v83, v83, 0, s99
	v_med3_i32 v99, v99, 0, s99
	v_med3_i32 v253, v253, 0, s99
	v_med3_i32 v254, v254, 0, s99
	v_med3_i32 v255, v255, 0, s99
	v_mad_u32_u24 v80, v80, s100, v252
	v_mad_u32_u24 v83, v83, s100, v252
	v_mad_u32_u24 v99, v99, s100, v252
	v_mad_u32_u24 v253, v253, s100, v252
	v_mad_u32_u24 v254, v254, s100, v153
	v_mad_u32_u24 v255, v255, s100, v153
	global_load_dwordx4 v[188:191], v80, s[82:83]
	global_load_dwordx4 v[192:195], v83, s[82:83]
	global_load_dwordx4 v[196:199], v99, s[82:83]
	global_load_dwordx4 v[200:203], v253, s[82:83]
	global_load_dwordx4 v[204:207], v254, s[82:83] offset:768
	global_load_dwordx4 v[208:211], v255, s[82:83] offset:768
	global_load_dwordx4 v[212:215], v254, s[82:83] offset:832
	global_load_dwordx4 v[216:219], v255, s[82:83] offset:832
	s_waitcnt vmcnt(16)
	ds_write_b128 v247, v[116:119]
	ds_write_b128 v247, v[120:123] offset:1024
	ds_write_b128 v247, v[124:127] offset:2048
	ds_write_b128 v247, v[128:131] offset:3072
	ds_read_b128 v[116:119], v248
	ds_read_b128 v[120:123], v249
	ds_read_b128 v[124:127], v250
	ds_read_b128 v[128:131], v251
	ds_write_b128 v112, v[132:135]
	ds_write_b128 v112, v[136:139] offset:1024
	ds_write_b128 v112, v[140:143] offset:2048
	ds_write_b128 v112, v[144:147] offset:3072
	ds_read2_b32 v[32:33], v115 offset0:170 offset1:171
	ds_read2_b32 v[34:35], v115 offset0:172 offset1:173
	ds_read2_b32 v[36:37], v115 offset0:178 offset1:179
	ds_read2_b32 v[38:39], v115 offset0:180 offset1:181
	ds_read2_b32 v[40:41], v115 offset0:187 offset1:188
	ds_read2_b32 v[42:43], v115 offset0:189 offset1:190
	ds_read2_b32 v[44:45], v115 offset0:195 offset1:196
	ds_read2_b32 v[46:47], v115 offset0:197 offset1:198
	s_waitcnt lgkmcnt(0)
	v_mfma_f32_32x32x16_bf16 v[32:47], v[116:119], v[48:51], v[32:47]
	ds_read_b64_tr_b16 v[72:73], v231
	ds_read_b64_tr_b16 v[74:75], v231 offset:512
	ds_read_b64_tr_b16 v[76:77], v231 offset:2048
	ds_read_b64_tr_b16 v[78:79], v231 offset:2560
	ds_read_b64_tr_b16 v[220:221], v231 offset:1024
	ds_read_b64_tr_b16 v[222:223], v231 offset:1536
	ds_read_b64_tr_b16 v[224:225], v231 offset:3072
	ds_read_b64_tr_b16 v[226:227], v231 offset:3584
	v_mfma_f32_32x32x16_bf16 v[32:47], v[120:123], v[52:55], v[32:47]
	v_mfma_f32_32x32x16_bf16 v[32:47], v[124:127], v[56:59], v[32:47]
	v_mfma_f32_32x32x16_bf16 v[32:47], v[128:131], v[60:63], v[32:47]
	s_nop 11
	v_exp_f32_e32 v32, v32
	v_exp_f32_e32 v33, v33
	v_exp_f32_e32 v34, v34
	v_exp_f32_e32 v35, v35
	v_exp_f32_e32 v36, v36
	v_exp_f32_e32 v37, v37
	v_exp_f32_e32 v38, v38
	v_exp_f32_e32 v39, v39
	v_exp_f32_e32 v40, v40
	v_exp_f32_e32 v41, v41
	v_exp_f32_e32 v42, v42
	v_exp_f32_e32 v43, v43
	v_exp_f32_e32 v44, v44
	v_exp_f32_e32 v45, v45
	v_exp_f32_e32 v46, v46
	v_exp_f32_e32 v47, v47
	s_add_i32 s90, s67, 320
	v_add_u32_e32 v84, s90, v107
	v_add_u32_e32 v85, 0, v84
	v_add_u32_e32 v86, 1, v84
	v_add_u32_e32 v87, 2, v84
	v_add_u32_e32 v88, 3, v84
	v_cmp_gt_u32_e64 s[30:31], s98, v85
	v_cmp_gt_u32_e64 s[36:37], s98, v86
	v_cmp_gt_u32_e64 s[78:79], s98, v87
	v_cmp_gt_u32_e64 s[50:51], s98, v88
	v_cndmask_b32_e64 v32, 0, v32, s[30:31]
	v_add_u32_e32 v85, 8, v84
	v_cmp_gt_u32_e64 s[30:31], s98, v85
	v_cndmask_b32_e64 v33, 0, v33, s[36:37]
	v_add_u32_e32 v86, 9, v84
	v_cmp_gt_u32_e64 s[36:37], s98, v86
	v_cndmask_b32_e64 v34, 0, v34, s[78:79]
	v_add_u32_e32 v87, 10, v84
	v_cmp_gt_u32_e64 s[78:79], s98, v87
	v_cndmask_b32_e64 v35, 0, v35, s[50:51]
	v_add_u32_e32 v88, 11, v84
	v_cmp_gt_u32_e64 s[50:51], s98, v88
	v_cndmask_b32_e64 v36, 0, v36, s[30:31]
	v_add_u32_e32 v85, 16, v84
	v_cmp_gt_u32_e64 s[30:31], s98, v85
	v_cndmask_b32_e64 v37, 0, v37, s[36:37]
	v_add_u32_e32 v86, 17, v84
	v_cmp_gt_u32_e64 s[36:37], s98, v86
	v_cndmask_b32_e64 v38, 0, v38, s[78:79]
	v_add_u32_e32 v87, 18, v84
	v_cmp_gt_u32_e64 s[78:79], s98, v87
	v_cndmask_b32_e64 v39, 0, v39, s[50:51]
	v_add_u32_e32 v88, 19, v84
	v_cmp_gt_u32_e64 s[50:51], s98, v88
	v_cndmask_b32_e64 v40, 0, v40, s[30:31]
	v_add_u32_e32 v85, 24, v84
	v_cmp_gt_u32_e64 s[30:31], s98, v85
	v_cndmask_b32_e64 v41, 0, v41, s[36:37]
	v_add_u32_e32 v86, 25, v84
	v_cmp_gt_u32_e64 s[36:37], s98, v86
	v_cndmask_b32_e64 v42, 0, v42, s[78:79]
	v_add_u32_e32 v87, 26, v84
	v_cmp_gt_u32_e64 s[78:79], s98, v87
	v_cndmask_b32_e64 v43, 0, v43, s[50:51]
	v_add_u32_e32 v88, 27, v84
	v_cmp_gt_u32_e64 s[50:51], s98, v88
	v_nop
	v_cndmask_b32_e64 v44, 0, v44, s[30:31]
	v_cndmask_b32_e64 v45, 0, v45, s[36:37]
	v_cndmask_b32_e64 v46, 0, v46, s[78:79]
	v_cndmask_b32_e64 v47, 0, v47, s[50:51]
	v_cvt_pk_bf16_f32 v64, v32, v33
	v_cvt_pk_bf16_f32 v65, v34, v35
	v_cvt_pk_bf16_f32 v66, v36, v37
	v_cvt_pk_bf16_f32 v67, v38, v39
	v_cvt_pk_bf16_f32 v68, v40, v41
	v_cvt_pk_bf16_f32 v69, v42, v43
	v_cvt_pk_bf16_f32 v70, v44, v45
	v_cvt_pk_bf16_f32 v71, v46, v47
	v_pk_add_f32 v[232:233], v[232:233], v[32:33]
	v_pk_add_f32 v[232:233], v[232:233], v[34:35]
	v_pk_add_f32 v[232:233], v[232:233], v[36:37]
	v_pk_add_f32 v[232:233], v[232:233], v[38:39]
	v_pk_add_f32 v[232:233], v[232:233], v[40:41]
	v_pk_add_f32 v[232:233], v[232:233], v[42:43]
	v_pk_add_f32 v[232:233], v[232:233], v[44:45]
	v_pk_add_f32 v[232:233], v[232:233], v[46:47]
	s_waitcnt lgkmcnt(0)
	v_mfma_f32_32x32x16_bf16 v[0:15], v[64:67], v[72:75], v[0:15]
	v_mfma_f32_32x32x16_bf16 v[16:31], v[64:67], v[76:79], v[16:31]
	v_mfma_f32_32x32x16_bf16 v[0:15], v[68:71], v[220:223], v[0:15]
	v_mfma_f32_32x32x16_bf16 v[16:31], v[68:71], v[224:227], v[16:31]
	s_add_i32 s90, s67, 416
	v_add_u32_e32 v80, s90, v235
	v_add_u32_e32 v83, s90, v236
	v_add_u32_e32 v99, s90, v237
	v_add_u32_e32 v253, s90, v238
	v_add_u32_e32 v254, s90, v100
	v_add_u32_e32 v255, s90, v149
	v_med3_i32 v80, v80, 0, s99
	v_med3_i32 v83, v83, 0, s99
	v_med3_i32 v99, v99, 0, s99
	v_med3_i32 v253, v253, 0, s99
	v_med3_i32 v254, v254, 0, s99
	v_med3_i32 v255, v255, 0, s99
	v_mad_u32_u24 v80, v80, s100, v252
	v_mad_u32_u24 v83, v83, s100, v252
	v_mad_u32_u24 v99, v99, s100, v252
	v_mad_u32_u24 v253, v253, s100, v252
	v_mad_u32_u24 v254, v254, s100, v153
	v_mad_u32_u24 v255, v255, s100, v153
	global_load_dwordx4 v[116:119], v80, s[82:83]
	global_load_dwordx4 v[120:123], v83, s[82:83]
	global_load_dwordx4 v[124:127], v99, s[82:83]
	global_load_dwordx4 v[128:131], v253, s[82:83]
	global_load_dwordx4 v[132:135], v254, s[82:83] offset:768
	global_load_dwordx4 v[136:139], v255, s[82:83] offset:768
	global_load_dwordx4 v[140:143], v254, s[82:83] offset:832
	global_load_dwordx4 v[144:147], v255, s[82:83] offset:832
	s_waitcnt vmcnt(16)
	ds_write_b128 v247, v[156:159]
	ds_write_b128 v247, v[160:163] offset:1024
	ds_write_b128 v247, v[164:167] offset:2048
	ds_write_b128 v247, v[168:171] offset:3072
	ds_read_b128 v[156:159], v248
	ds_read_b128 v[160:163], v249
	ds_read_b128 v[164:167], v250
	ds_read_b128 v[168:171], v251
	ds_write_b128 v112, v[172:175]
	ds_write_b128 v112, v[176:179] offset:1024
	ds_write_b128 v112, v[180:183] offset:2048
	ds_write_b128 v112, v[184:187] offset:3072
	ds_read2_b32 v[32:33], v115 offset0:204 offset1:205
	ds_read2_b32 v[34:35], v115 offset0:206 offset1:207
	ds_read2_b32 v[36:37], v115 offset0:212 offset1:213
	ds_read2_b32 v[38:39], v115 offset0:214 offset1:215
	ds_read2_b32 v[40:41], v115 offset0:221 offset1:222
	ds_read2_b32 v[42:43], v115 offset0:223 offset1:224
	ds_read2_b32 v[44:45], v115 offset0:229 offset1:230
	ds_read2_b32 v[46:47], v115 offset0:231 offset1:232
	s_waitcnt lgkmcnt(0)
	v_mfma_f32_32x32x16_bf16 v[32:47], v[156:159], v[48:51], v[32:47]
	ds_read_b64_tr_b16 v[72:73], v231
	ds_read_b64_tr_b16 v[74:75], v231 offset:512
	ds_read_b64_tr_b16 v[76:77], v231 offset:2048
	ds_read_b64_tr_b16 v[78:79], v231 offset:2560
	ds_read_b64_tr_b16 v[220:221], v231 offset:1024
	ds_read_b64_tr_b16 v[222:223], v231 offset:1536
	ds_read_b64_tr_b16 v[224:225], v231 offset:3072
	ds_read_b64_tr_b16 v[226:227], v231 offset:3584
	v_mfma_f32_32x32x16_bf16 v[32:47], v[160:163], v[52:55], v[32:47]
	v_mfma_f32_32x32x16_bf16 v[32:47], v[164:167], v[56:59], v[32:47]
	v_mfma_f32_32x32x16_bf16 v[32:47], v[168:171], v[60:63], v[32:47]
	s_nop 11
	v_exp_f32_e32 v32, v32
	v_exp_f32_e32 v33, v33
	v_exp_f32_e32 v34, v34
	v_exp_f32_e32 v35, v35
	v_exp_f32_e32 v36, v36
	v_exp_f32_e32 v37, v37
	v_exp_f32_e32 v38, v38
	v_exp_f32_e32 v39, v39
	v_exp_f32_e32 v40, v40
	v_exp_f32_e32 v41, v41
	v_exp_f32_e32 v42, v42
	v_exp_f32_e32 v43, v43
	v_exp_f32_e32 v44, v44
	v_exp_f32_e32 v45, v45
	v_exp_f32_e32 v46, v46
	v_exp_f32_e32 v47, v47
	s_add_i32 s90, s67, 352
	v_add_u32_e32 v84, s90, v107
	v_add_u32_e32 v85, 0, v84
	v_add_u32_e32 v86, 1, v84
	v_add_u32_e32 v87, 2, v84
	v_add_u32_e32 v88, 3, v84
	v_cmp_gt_u32_e64 s[30:31], s98, v85
	v_cmp_gt_u32_e64 s[36:37], s98, v86
	v_cmp_gt_u32_e64 s[78:79], s98, v87
	v_cmp_gt_u32_e64 s[50:51], s98, v88
	v_cndmask_b32_e64 v32, 0, v32, s[30:31]
	v_add_u32_e32 v85, 8, v84
	v_cmp_gt_u32_e64 s[30:31], s98, v85
	v_cndmask_b32_e64 v33, 0, v33, s[36:37]
	v_add_u32_e32 v86, 9, v84
	v_cmp_gt_u32_e64 s[36:37], s98, v86
	v_cndmask_b32_e64 v34, 0, v34, s[78:79]
	v_add_u32_e32 v87, 10, v84
	v_cmp_gt_u32_e64 s[78:79], s98, v87
	v_cndmask_b32_e64 v35, 0, v35, s[50:51]
	v_add_u32_e32 v88, 11, v84
	v_cmp_gt_u32_e64 s[50:51], s98, v88
	v_cndmask_b32_e64 v36, 0, v36, s[30:31]
	v_add_u32_e32 v85, 16, v84
	v_cmp_gt_u32_e64 s[30:31], s98, v85
	v_cndmask_b32_e64 v37, 0, v37, s[36:37]
	v_add_u32_e32 v86, 17, v84
	v_cmp_gt_u32_e64 s[36:37], s98, v86
	v_cndmask_b32_e64 v38, 0, v38, s[78:79]
	v_add_u32_e32 v87, 18, v84
	v_cmp_gt_u32_e64 s[78:79], s98, v87
	v_cndmask_b32_e64 v39, 0, v39, s[50:51]
	v_add_u32_e32 v88, 19, v84
	v_cmp_gt_u32_e64 s[50:51], s98, v88
	v_cndmask_b32_e64 v40, 0, v40, s[30:31]
	v_add_u32_e32 v85, 24, v84
	v_cmp_gt_u32_e64 s[30:31], s98, v85
	v_cndmask_b32_e64 v41, 0, v41, s[36:37]
	v_add_u32_e32 v86, 25, v84
	v_cmp_gt_u32_e64 s[36:37], s98, v86
	v_cndmask_b32_e64 v42, 0, v42, s[78:79]
	v_add_u32_e32 v87, 26, v84
	v_cmp_gt_u32_e64 s[78:79], s98, v87
	v_cndmask_b32_e64 v43, 0, v43, s[50:51]
	v_add_u32_e32 v88, 27, v84
	v_cmp_gt_u32_e64 s[50:51], s98, v88
	v_nop
	v_cndmask_b32_e64 v44, 0, v44, s[30:31]
	v_cndmask_b32_e64 v45, 0, v45, s[36:37]
	v_cndmask_b32_e64 v46, 0, v46, s[78:79]
	v_cndmask_b32_e64 v47, 0, v47, s[50:51]
	v_cvt_pk_bf16_f32 v64, v32, v33
	v_cvt_pk_bf16_f32 v65, v34, v35
	v_cvt_pk_bf16_f32 v66, v36, v37
	v_cvt_pk_bf16_f32 v67, v38, v39
	v_cvt_pk_bf16_f32 v68, v40, v41
	v_cvt_pk_bf16_f32 v69, v42, v43
	v_cvt_pk_bf16_f32 v70, v44, v45
	v_cvt_pk_bf16_f32 v71, v46, v47
	v_pk_add_f32 v[232:233], v[232:233], v[32:33]
	v_pk_add_f32 v[232:233], v[232:233], v[34:35]
	v_pk_add_f32 v[232:233], v[232:233], v[36:37]
	v_pk_add_f32 v[232:233], v[232:233], v[38:39]
	v_pk_add_f32 v[232:233], v[232:233], v[40:41]
	v_pk_add_f32 v[232:233], v[232:233], v[42:43]
	v_pk_add_f32 v[232:233], v[232:233], v[44:45]
	v_pk_add_f32 v[232:233], v[232:233], v[46:47]
	s_waitcnt lgkmcnt(0)
	v_mfma_f32_32x32x16_bf16 v[0:15], v[64:67], v[72:75], v[0:15]
	v_mfma_f32_32x32x16_bf16 v[16:31], v[64:67], v[76:79], v[16:31]
	v_mfma_f32_32x32x16_bf16 v[0:15], v[68:71], v[220:223], v[0:15]
	v_mfma_f32_32x32x16_bf16 v[16:31], v[68:71], v[224:227], v[16:31]
	s_add_i32 s90, s67, 448
	v_add_u32_e32 v80, s90, v235
	v_add_u32_e32 v83, s90, v236
	v_add_u32_e32 v99, s90, v237
	v_add_u32_e32 v253, s90, v238
	v_add_u32_e32 v254, s90, v100
	v_add_u32_e32 v255, s90, v149
	v_med3_i32 v80, v80, 0, s99
	v_med3_i32 v83, v83, 0, s99
	v_med3_i32 v99, v99, 0, s99
	v_med3_i32 v253, v253, 0, s99
	v_med3_i32 v254, v254, 0, s99
	v_med3_i32 v255, v255, 0, s99
	v_mad_u32_u24 v80, v80, s100, v252
	v_mad_u32_u24 v83, v83, s100, v252
	v_mad_u32_u24 v99, v99, s100, v252
	v_mad_u32_u24 v253, v253, s100, v252
	v_mad_u32_u24 v254, v254, s100, v153
	v_mad_u32_u24 v255, v255, s100, v153
	global_load_dwordx4 v[156:159], v80, s[82:83]
	global_load_dwordx4 v[160:163], v83, s[82:83]
	global_load_dwordx4 v[164:167], v99, s[82:83]
	global_load_dwordx4 v[168:171], v253, s[82:83]
	global_load_dwordx4 v[172:175], v254, s[82:83] offset:768
	global_load_dwordx4 v[176:179], v255, s[82:83] offset:768
	global_load_dwordx4 v[180:183], v254, s[82:83] offset:832
	global_load_dwordx4 v[184:187], v255, s[82:83] offset:832
	s_waitcnt vmcnt(16)
	ds_write_b128 v247, v[188:191]
	ds_write_b128 v247, v[192:195] offset:1024
	ds_write_b128 v247, v[196:199] offset:2048
	ds_write_b128 v247, v[200:203] offset:3072
	ds_read_b128 v[188:191], v248
	ds_read_b128 v[192:195], v249
	ds_read_b128 v[196:199], v250
	ds_read_b128 v[200:203], v251
	ds_write_b128 v112, v[204:207]
	ds_write_b128 v112, v[208:211] offset:1024
	ds_write_b128 v112, v[212:215] offset:2048
	ds_write_b128 v112, v[216:219] offset:3072
	v_add_u32_e32 v115, 952, v115
	ds_read2_b32 v[32:33], v115 offset0:0 offset1:1
	ds_read2_b32 v[34:35], v115 offset0:2 offset1:3
	ds_read2_b32 v[36:37], v115 offset0:8 offset1:9
	ds_read2_b32 v[38:39], v115 offset0:10 offset1:11
	ds_read2_b32 v[40:41], v115 offset0:17 offset1:18
	ds_read2_b32 v[42:43], v115 offset0:19 offset1:20
	ds_read2_b32 v[44:45], v115 offset0:25 offset1:26
	ds_read2_b32 v[46:47], v115 offset0:27 offset1:28
	s_waitcnt lgkmcnt(0)
	v_mfma_f32_32x32x16_bf16 v[32:47], v[188:191], v[48:51], v[32:47]
	ds_read_b64_tr_b16 v[72:73], v231
	ds_read_b64_tr_b16 v[74:75], v231 offset:512
	ds_read_b64_tr_b16 v[76:77], v231 offset:2048
	ds_read_b64_tr_b16 v[78:79], v231 offset:2560
	ds_read_b64_tr_b16 v[220:221], v231 offset:1024
	ds_read_b64_tr_b16 v[222:223], v231 offset:1536
	ds_read_b64_tr_b16 v[224:225], v231 offset:3072
	ds_read_b64_tr_b16 v[226:227], v231 offset:3584
	v_mfma_f32_32x32x16_bf16 v[32:47], v[192:195], v[52:55], v[32:47]
	v_mfma_f32_32x32x16_bf16 v[32:47], v[196:199], v[56:59], v[32:47]
	v_mfma_f32_32x32x16_bf16 v[32:47], v[200:203], v[60:63], v[32:47]
	s_nop 11
	v_exp_f32_e32 v32, v32
	v_exp_f32_e32 v33, v33
	v_exp_f32_e32 v34, v34
	v_exp_f32_e32 v35, v35
	v_exp_f32_e32 v36, v36
	v_exp_f32_e32 v37, v37
	v_exp_f32_e32 v38, v38
	v_exp_f32_e32 v39, v39
	v_exp_f32_e32 v40, v40
	v_exp_f32_e32 v41, v41
	v_exp_f32_e32 v42, v42
	v_exp_f32_e32 v43, v43
	v_exp_f32_e32 v44, v44
	v_exp_f32_e32 v45, v45
	v_exp_f32_e32 v46, v46
	v_exp_f32_e32 v47, v47
	s_add_i32 s90, s67, 384
	v_add_u32_e32 v84, s90, v107
	v_add_u32_e32 v85, 0, v84
	v_add_u32_e32 v86, 1, v84
	v_add_u32_e32 v87, 2, v84
	v_add_u32_e32 v88, 3, v84
	v_cmp_gt_u32_e64 s[30:31], s98, v85
	v_cmp_gt_u32_e64 s[36:37], s98, v86
	v_cmp_gt_u32_e64 s[78:79], s98, v87
	v_cmp_gt_u32_e64 s[50:51], s98, v88
	v_cndmask_b32_e64 v32, 0, v32, s[30:31]
	v_add_u32_e32 v85, 8, v84
	v_cmp_gt_u32_e64 s[30:31], s98, v85
	v_cndmask_b32_e64 v33, 0, v33, s[36:37]
	v_add_u32_e32 v86, 9, v84
	v_cmp_gt_u32_e64 s[36:37], s98, v86
	v_cndmask_b32_e64 v34, 0, v34, s[78:79]
	v_add_u32_e32 v87, 10, v84
	v_cmp_gt_u32_e64 s[78:79], s98, v87
	v_cndmask_b32_e64 v35, 0, v35, s[50:51]
	v_add_u32_e32 v88, 11, v84
	v_cmp_gt_u32_e64 s[50:51], s98, v88
	v_cndmask_b32_e64 v36, 0, v36, s[30:31]
	v_add_u32_e32 v85, 16, v84
	v_cmp_gt_u32_e64 s[30:31], s98, v85
	v_cndmask_b32_e64 v37, 0, v37, s[36:37]
	v_add_u32_e32 v86, 17, v84
	v_cmp_gt_u32_e64 s[36:37], s98, v86
	v_cndmask_b32_e64 v38, 0, v38, s[78:79]
	v_add_u32_e32 v87, 18, v84
	v_cmp_gt_u32_e64 s[78:79], s98, v87
	v_cndmask_b32_e64 v39, 0, v39, s[50:51]
	v_add_u32_e32 v88, 19, v84
	v_cmp_gt_u32_e64 s[50:51], s98, v88
	v_cndmask_b32_e64 v40, 0, v40, s[30:31]
	v_add_u32_e32 v85, 24, v84
	v_cmp_gt_u32_e64 s[30:31], s98, v85
	v_cndmask_b32_e64 v41, 0, v41, s[36:37]
	v_add_u32_e32 v86, 25, v84
	v_cmp_gt_u32_e64 s[36:37], s98, v86
	v_cndmask_b32_e64 v42, 0, v42, s[78:79]
	v_add_u32_e32 v87, 26, v84
	v_cmp_gt_u32_e64 s[78:79], s98, v87
	v_cndmask_b32_e64 v43, 0, v43, s[50:51]
	v_add_u32_e32 v88, 27, v84
	v_cmp_gt_u32_e64 s[50:51], s98, v88
	v_nop
	v_cndmask_b32_e64 v44, 0, v44, s[30:31]
	v_cndmask_b32_e64 v45, 0, v45, s[36:37]
	v_cndmask_b32_e64 v46, 0, v46, s[78:79]
	v_cndmask_b32_e64 v47, 0, v47, s[50:51]
	v_cvt_pk_bf16_f32 v64, v32, v33
	v_cvt_pk_bf16_f32 v65, v34, v35
	v_cvt_pk_bf16_f32 v66, v36, v37
	v_cvt_pk_bf16_f32 v67, v38, v39
	v_cvt_pk_bf16_f32 v68, v40, v41
	v_cvt_pk_bf16_f32 v69, v42, v43
	v_cvt_pk_bf16_f32 v70, v44, v45
	v_cvt_pk_bf16_f32 v71, v46, v47
	v_pk_add_f32 v[232:233], v[232:233], v[32:33]
	v_pk_add_f32 v[232:233], v[232:233], v[34:35]
	v_pk_add_f32 v[232:233], v[232:233], v[36:37]
	v_pk_add_f32 v[232:233], v[232:233], v[38:39]
	v_pk_add_f32 v[232:233], v[232:233], v[40:41]
	v_pk_add_f32 v[232:233], v[232:233], v[42:43]
	v_pk_add_f32 v[232:233], v[232:233], v[44:45]
	v_pk_add_f32 v[232:233], v[232:233], v[46:47]
	s_waitcnt lgkmcnt(0)
	v_mfma_f32_32x32x16_bf16 v[0:15], v[64:67], v[72:75], v[0:15]
	v_mfma_f32_32x32x16_bf16 v[16:31], v[64:67], v[76:79], v[16:31]
	v_mfma_f32_32x32x16_bf16 v[0:15], v[68:71], v[220:223], v[0:15]
	v_mfma_f32_32x32x16_bf16 v[16:31], v[68:71], v[224:227], v[16:31]
	s_add_i32 s90, s67, 480
	v_add_u32_e32 v80, s90, v235
	v_add_u32_e32 v83, s90, v236
	v_add_u32_e32 v99, s90, v237
	v_add_u32_e32 v253, s90, v238
	v_add_u32_e32 v254, s90, v100
	v_add_u32_e32 v255, s90, v149
	v_med3_i32 v80, v80, 0, s99
	v_med3_i32 v83, v83, 0, s99
	v_med3_i32 v99, v99, 0, s99
	v_med3_i32 v253, v253, 0, s99
	v_med3_i32 v254, v254, 0, s99
	v_med3_i32 v255, v255, 0, s99
	v_mad_u32_u24 v80, v80, s100, v252
	v_mad_u32_u24 v83, v83, s100, v252
	v_mad_u32_u24 v99, v99, s100, v252
	v_mad_u32_u24 v253, v253, s100, v252
	v_mad_u32_u24 v254, v254, s100, v153
	v_mad_u32_u24 v255, v255, s100, v153
	global_load_dwordx4 v[188:191], v80, s[82:83]
	global_load_dwordx4 v[192:195], v83, s[82:83]
	global_load_dwordx4 v[196:199], v99, s[82:83]
	global_load_dwordx4 v[200:203], v253, s[82:83]
	global_load_dwordx4 v[204:207], v254, s[82:83] offset:768
	global_load_dwordx4 v[208:211], v255, s[82:83] offset:768
	global_load_dwordx4 v[212:215], v254, s[82:83] offset:832
	global_load_dwordx4 v[216:219], v255, s[82:83] offset:832
	s_waitcnt vmcnt(16)
	ds_write_b128 v247, v[116:119]
	ds_write_b128 v247, v[120:123] offset:1024
	ds_write_b128 v247, v[124:127] offset:2048
	ds_write_b128 v247, v[128:131] offset:3072
	ds_read_b128 v[116:119], v248
	ds_read_b128 v[120:123], v249
	ds_read_b128 v[124:127], v250
	ds_read_b128 v[128:131], v251
	ds_write_b128 v112, v[132:135]
	ds_write_b128 v112, v[136:139] offset:1024
	ds_write_b128 v112, v[140:143] offset:2048
	ds_write_b128 v112, v[144:147] offset:3072
	ds_read2_b32 v[32:33], v115 offset0:34 offset1:35
	ds_read2_b32 v[34:35], v115 offset0:36 offset1:37
	ds_read2_b32 v[36:37], v115 offset0:42 offset1:43
	ds_read2_b32 v[38:39], v115 offset0:44 offset1:45
	ds_read2_b32 v[40:41], v115 offset0:51 offset1:52
	ds_read2_b32 v[42:43], v115 offset0:53 offset1:54
	ds_read2_b32 v[44:45], v115 offset0:59 offset1:60
	ds_read2_b32 v[46:47], v115 offset0:61 offset1:62
	s_waitcnt lgkmcnt(0)
	v_mfma_f32_32x32x16_bf16 v[32:47], v[116:119], v[48:51], v[32:47]
	ds_read_b64_tr_b16 v[72:73], v231
	ds_read_b64_tr_b16 v[74:75], v231 offset:512
	ds_read_b64_tr_b16 v[76:77], v231 offset:2048
	ds_read_b64_tr_b16 v[78:79], v231 offset:2560
	ds_read_b64_tr_b16 v[220:221], v231 offset:1024
	ds_read_b64_tr_b16 v[222:223], v231 offset:1536
	ds_read_b64_tr_b16 v[224:225], v231 offset:3072
	ds_read_b64_tr_b16 v[226:227], v231 offset:3584
	v_mfma_f32_32x32x16_bf16 v[32:47], v[120:123], v[52:55], v[32:47]
	v_mfma_f32_32x32x16_bf16 v[32:47], v[124:127], v[56:59], v[32:47]
	v_mfma_f32_32x32x16_bf16 v[32:47], v[128:131], v[60:63], v[32:47]
	s_nop 11
	v_exp_f32_e32 v32, v32
	v_exp_f32_e32 v33, v33
	v_exp_f32_e32 v34, v34
	v_exp_f32_e32 v35, v35
	v_exp_f32_e32 v36, v36
	v_exp_f32_e32 v37, v37
	v_exp_f32_e32 v38, v38
	v_exp_f32_e32 v39, v39
	v_exp_f32_e32 v40, v40
	v_exp_f32_e32 v41, v41
	v_exp_f32_e32 v42, v42
	v_exp_f32_e32 v43, v43
	v_exp_f32_e32 v44, v44
	v_exp_f32_e32 v45, v45
	v_exp_f32_e32 v46, v46
	v_exp_f32_e32 v47, v47
	s_add_i32 s90, s67, 416
	v_add_u32_e32 v84, s90, v107
	v_add_u32_e32 v85, 0, v84
	v_add_u32_e32 v86, 1, v84
	v_add_u32_e32 v87, 2, v84
	v_add_u32_e32 v88, 3, v84
	v_cmp_gt_u32_e64 s[30:31], s98, v85
	v_cmp_gt_u32_e64 s[36:37], s98, v86
	v_cmp_gt_u32_e64 s[78:79], s98, v87
	v_cmp_gt_u32_e64 s[50:51], s98, v88
	v_cndmask_b32_e64 v32, 0, v32, s[30:31]
	v_add_u32_e32 v85, 8, v84
	v_cmp_gt_u32_e64 s[30:31], s98, v85
	v_cndmask_b32_e64 v33, 0, v33, s[36:37]
	v_add_u32_e32 v86, 9, v84
	v_cmp_gt_u32_e64 s[36:37], s98, v86
	v_cndmask_b32_e64 v34, 0, v34, s[78:79]
	v_add_u32_e32 v87, 10, v84
	v_cmp_gt_u32_e64 s[78:79], s98, v87
	v_cndmask_b32_e64 v35, 0, v35, s[50:51]
	v_add_u32_e32 v88, 11, v84
	v_cmp_gt_u32_e64 s[50:51], s98, v88
	v_cndmask_b32_e64 v36, 0, v36, s[30:31]
	v_add_u32_e32 v85, 16, v84
	v_cmp_gt_u32_e64 s[30:31], s98, v85
	v_cndmask_b32_e64 v37, 0, v37, s[36:37]
	v_add_u32_e32 v86, 17, v84
	v_cmp_gt_u32_e64 s[36:37], s98, v86
	v_cndmask_b32_e64 v38, 0, v38, s[78:79]
	v_add_u32_e32 v87, 18, v84
	v_cmp_gt_u32_e64 s[78:79], s98, v87
	v_cndmask_b32_e64 v39, 0, v39, s[50:51]
	v_add_u32_e32 v88, 19, v84
	v_cmp_gt_u32_e64 s[50:51], s98, v88
	v_cndmask_b32_e64 v40, 0, v40, s[30:31]
	v_add_u32_e32 v85, 24, v84
	v_cmp_gt_u32_e64 s[30:31], s98, v85
	v_cndmask_b32_e64 v41, 0, v41, s[36:37]
	v_add_u32_e32 v86, 25, v84
	v_cmp_gt_u32_e64 s[36:37], s98, v86
	v_cndmask_b32_e64 v42, 0, v42, s[78:79]
	v_add_u32_e32 v87, 26, v84
	v_cmp_gt_u32_e64 s[78:79], s98, v87
	v_cndmask_b32_e64 v43, 0, v43, s[50:51]
	v_add_u32_e32 v88, 27, v84
	v_cmp_gt_u32_e64 s[50:51], s98, v88
	v_nop
	v_cndmask_b32_e64 v44, 0, v44, s[30:31]
	v_cndmask_b32_e64 v45, 0, v45, s[36:37]
	v_cndmask_b32_e64 v46, 0, v46, s[78:79]
	v_cndmask_b32_e64 v47, 0, v47, s[50:51]
	v_cvt_pk_bf16_f32 v64, v32, v33
	v_cvt_pk_bf16_f32 v65, v34, v35
	v_cvt_pk_bf16_f32 v66, v36, v37
	v_cvt_pk_bf16_f32 v67, v38, v39
	v_cvt_pk_bf16_f32 v68, v40, v41
	v_cvt_pk_bf16_f32 v69, v42, v43
	v_cvt_pk_bf16_f32 v70, v44, v45
	v_cvt_pk_bf16_f32 v71, v46, v47
	v_pk_add_f32 v[232:233], v[232:233], v[32:33]
	v_pk_add_f32 v[232:233], v[232:233], v[34:35]
	v_pk_add_f32 v[232:233], v[232:233], v[36:37]
	v_pk_add_f32 v[232:233], v[232:233], v[38:39]
	v_pk_add_f32 v[232:233], v[232:233], v[40:41]
	v_pk_add_f32 v[232:233], v[232:233], v[42:43]
	v_pk_add_f32 v[232:233], v[232:233], v[44:45]
	v_pk_add_f32 v[232:233], v[232:233], v[46:47]
	s_waitcnt lgkmcnt(0)
	v_mfma_f32_32x32x16_bf16 v[0:15], v[64:67], v[72:75], v[0:15]
	v_mfma_f32_32x32x16_bf16 v[16:31], v[64:67], v[76:79], v[16:31]
	v_mfma_f32_32x32x16_bf16 v[0:15], v[68:71], v[220:223], v[0:15]
	v_mfma_f32_32x32x16_bf16 v[16:31], v[68:71], v[224:227], v[16:31]
	s_add_i32 s90, s67, 512
	v_add_u32_e32 v80, s90, v235
	v_add_u32_e32 v83, s90, v236
	v_add_u32_e32 v99, s90, v237
	v_add_u32_e32 v253, s90, v238
	v_add_u32_e32 v254, s90, v100
	v_add_u32_e32 v255, s90, v149
	v_med3_i32 v80, v80, 0, s99
	v_med3_i32 v83, v83, 0, s99
	v_med3_i32 v99, v99, 0, s99
	v_med3_i32 v253, v253, 0, s99
	v_med3_i32 v254, v254, 0, s99
	v_med3_i32 v255, v255, 0, s99
	v_mad_u32_u24 v80, v80, s100, v252
	v_mad_u32_u24 v83, v83, s100, v252
	v_mad_u32_u24 v99, v99, s100, v252
	v_mad_u32_u24 v253, v253, s100, v252
	v_mad_u32_u24 v254, v254, s100, v153
	v_mad_u32_u24 v255, v255, s100, v153
	global_load_dwordx4 v[116:119], v80, s[82:83]
	global_load_dwordx4 v[120:123], v83, s[82:83]
	global_load_dwordx4 v[124:127], v99, s[82:83]
	global_load_dwordx4 v[128:131], v253, s[82:83]
	global_load_dwordx4 v[132:135], v254, s[82:83] offset:768
	global_load_dwordx4 v[136:139], v255, s[82:83] offset:768
	global_load_dwordx4 v[140:143], v254, s[82:83] offset:832
	global_load_dwordx4 v[144:147], v255, s[82:83] offset:832
	s_waitcnt vmcnt(16)
	ds_write_b128 v247, v[156:159]
	ds_write_b128 v247, v[160:163] offset:1024
	ds_write_b128 v247, v[164:167] offset:2048
	ds_write_b128 v247, v[168:171] offset:3072
	ds_read_b128 v[156:159], v248
	ds_read_b128 v[160:163], v249
	ds_read_b128 v[164:167], v250
	ds_read_b128 v[168:171], v251
	ds_write_b128 v112, v[172:175]
	ds_write_b128 v112, v[176:179] offset:1024
	ds_write_b128 v112, v[180:183] offset:2048
	ds_write_b128 v112, v[184:187] offset:3072
	ds_read2_b32 v[32:33], v115 offset0:68 offset1:69
	ds_read2_b32 v[34:35], v115 offset0:70 offset1:71
	ds_read2_b32 v[36:37], v115 offset0:76 offset1:77
	ds_read2_b32 v[38:39], v115 offset0:78 offset1:79
	ds_read2_b32 v[40:41], v115 offset0:85 offset1:86
	ds_read2_b32 v[42:43], v115 offset0:87 offset1:88
	ds_read2_b32 v[44:45], v115 offset0:93 offset1:94
	ds_read2_b32 v[46:47], v115 offset0:95 offset1:96
	s_waitcnt lgkmcnt(0)
	v_mfma_f32_32x32x16_bf16 v[32:47], v[156:159], v[48:51], v[32:47]
	ds_read_b64_tr_b16 v[72:73], v231
	ds_read_b64_tr_b16 v[74:75], v231 offset:512
	ds_read_b64_tr_b16 v[76:77], v231 offset:2048
	ds_read_b64_tr_b16 v[78:79], v231 offset:2560
	ds_read_b64_tr_b16 v[220:221], v231 offset:1024
	ds_read_b64_tr_b16 v[222:223], v231 offset:1536
	ds_read_b64_tr_b16 v[224:225], v231 offset:3072
	ds_read_b64_tr_b16 v[226:227], v231 offset:3584
	v_mfma_f32_32x32x16_bf16 v[32:47], v[160:163], v[52:55], v[32:47]
	v_mfma_f32_32x32x16_bf16 v[32:47], v[164:167], v[56:59], v[32:47]
	v_mfma_f32_32x32x16_bf16 v[32:47], v[168:171], v[60:63], v[32:47]
	s_nop 11
	v_exp_f32_e32 v32, v32
	v_exp_f32_e32 v33, v33
	v_exp_f32_e32 v34, v34
	v_exp_f32_e32 v35, v35
	v_exp_f32_e32 v36, v36
	v_exp_f32_e32 v37, v37
	v_exp_f32_e32 v38, v38
	v_exp_f32_e32 v39, v39
	v_exp_f32_e32 v40, v40
	v_exp_f32_e32 v41, v41
	v_exp_f32_e32 v42, v42
	v_exp_f32_e32 v43, v43
	v_exp_f32_e32 v44, v44
	v_exp_f32_e32 v45, v45
	v_exp_f32_e32 v46, v46
	v_exp_f32_e32 v47, v47
	s_add_i32 s90, s67, 448
	v_add_u32_e32 v84, s90, v107
	v_add_u32_e32 v85, 0, v84
	v_add_u32_e32 v86, 1, v84
	v_add_u32_e32 v87, 2, v84
	v_add_u32_e32 v88, 3, v84
	v_cmp_gt_u32_e64 s[30:31], s98, v85
	v_cmp_gt_u32_e64 s[36:37], s98, v86
	v_cmp_gt_u32_e64 s[78:79], s98, v87
	v_cmp_gt_u32_e64 s[50:51], s98, v88
	v_cndmask_b32_e64 v32, 0, v32, s[30:31]
	v_add_u32_e32 v85, 8, v84
	v_cmp_gt_u32_e64 s[30:31], s98, v85
	v_cndmask_b32_e64 v33, 0, v33, s[36:37]
	v_add_u32_e32 v86, 9, v84
	v_cmp_gt_u32_e64 s[36:37], s98, v86
	v_cndmask_b32_e64 v34, 0, v34, s[78:79]
	v_add_u32_e32 v87, 10, v84
	v_cmp_gt_u32_e64 s[78:79], s98, v87
	v_cndmask_b32_e64 v35, 0, v35, s[50:51]
	v_add_u32_e32 v88, 11, v84
	v_cmp_gt_u32_e64 s[50:51], s98, v88
	v_cndmask_b32_e64 v36, 0, v36, s[30:31]
	v_add_u32_e32 v85, 16, v84
	v_cmp_gt_u32_e64 s[30:31], s98, v85
	v_cndmask_b32_e64 v37, 0, v37, s[36:37]
	v_add_u32_e32 v86, 17, v84
	v_cmp_gt_u32_e64 s[36:37], s98, v86
	v_cndmask_b32_e64 v38, 0, v38, s[78:79]
	v_add_u32_e32 v87, 18, v84
	v_cmp_gt_u32_e64 s[78:79], s98, v87
	v_cndmask_b32_e64 v39, 0, v39, s[50:51]
	v_add_u32_e32 v88, 19, v84
	v_cmp_gt_u32_e64 s[50:51], s98, v88
	v_cndmask_b32_e64 v40, 0, v40, s[30:31]
	v_add_u32_e32 v85, 24, v84
	v_cmp_gt_u32_e64 s[30:31], s98, v85
	v_cndmask_b32_e64 v41, 0, v41, s[36:37]
	v_add_u32_e32 v86, 25, v84
	v_cmp_gt_u32_e64 s[36:37], s98, v86
	v_cndmask_b32_e64 v42, 0, v42, s[78:79]
	v_add_u32_e32 v87, 26, v84
	v_cmp_gt_u32_e64 s[78:79], s98, v87
	v_cndmask_b32_e64 v43, 0, v43, s[50:51]
	v_add_u32_e32 v88, 27, v84
	v_cmp_gt_u32_e64 s[50:51], s98, v88
	v_nop
	v_cndmask_b32_e64 v44, 0, v44, s[30:31]
	v_cndmask_b32_e64 v45, 0, v45, s[36:37]
	v_cndmask_b32_e64 v46, 0, v46, s[78:79]
	v_cndmask_b32_e64 v47, 0, v47, s[50:51]
	v_cvt_pk_bf16_f32 v64, v32, v33
	v_cvt_pk_bf16_f32 v65, v34, v35
	v_cvt_pk_bf16_f32 v66, v36, v37
	v_cvt_pk_bf16_f32 v67, v38, v39
	v_cvt_pk_bf16_f32 v68, v40, v41
	v_cvt_pk_bf16_f32 v69, v42, v43
	v_cvt_pk_bf16_f32 v70, v44, v45
	v_cvt_pk_bf16_f32 v71, v46, v47
	v_pk_add_f32 v[232:233], v[232:233], v[32:33]
	v_pk_add_f32 v[232:233], v[232:233], v[34:35]
	v_pk_add_f32 v[232:233], v[232:233], v[36:37]
	v_pk_add_f32 v[232:233], v[232:233], v[38:39]
	v_pk_add_f32 v[232:233], v[232:233], v[40:41]
	v_pk_add_f32 v[232:233], v[232:233], v[42:43]
	v_pk_add_f32 v[232:233], v[232:233], v[44:45]
	v_pk_add_f32 v[232:233], v[232:233], v[46:47]
	s_waitcnt lgkmcnt(0)
	v_mfma_f32_32x32x16_bf16 v[0:15], v[64:67], v[72:75], v[0:15]
	v_mfma_f32_32x32x16_bf16 v[16:31], v[64:67], v[76:79], v[16:31]
	v_mfma_f32_32x32x16_bf16 v[0:15], v[68:71], v[220:223], v[0:15]
	v_mfma_f32_32x32x16_bf16 v[16:31], v[68:71], v[224:227], v[16:31]
	s_add_i32 s90, s67, 544
	v_add_u32_e32 v80, s90, v235
	v_add_u32_e32 v83, s90, v236
	v_add_u32_e32 v99, s90, v237
	v_add_u32_e32 v253, s90, v238
	v_add_u32_e32 v254, s90, v100
	v_add_u32_e32 v255, s90, v149
	v_med3_i32 v80, v80, 0, s99
	v_med3_i32 v83, v83, 0, s99
	v_med3_i32 v99, v99, 0, s99
	v_med3_i32 v253, v253, 0, s99
	v_med3_i32 v254, v254, 0, s99
	v_med3_i32 v255, v255, 0, s99
	v_mad_u32_u24 v80, v80, s100, v252
	v_mad_u32_u24 v83, v83, s100, v252
	v_mad_u32_u24 v99, v99, s100, v252
	v_mad_u32_u24 v253, v253, s100, v252
	v_mad_u32_u24 v254, v254, s100, v153
	v_mad_u32_u24 v255, v255, s100, v153
	global_load_dwordx4 v[156:159], v80, s[82:83]
	global_load_dwordx4 v[160:163], v83, s[82:83]
	global_load_dwordx4 v[164:167], v99, s[82:83]
	global_load_dwordx4 v[168:171], v253, s[82:83]
	global_load_dwordx4 v[172:175], v254, s[82:83] offset:768
	global_load_dwordx4 v[176:179], v255, s[82:83] offset:768
	global_load_dwordx4 v[180:183], v254, s[82:83] offset:832
	global_load_dwordx4 v[184:187], v255, s[82:83] offset:832
	s_waitcnt vmcnt(16)
	ds_write_b128 v247, v[188:191]
	ds_write_b128 v247, v[192:195] offset:1024
	ds_write_b128 v247, v[196:199] offset:2048
	ds_write_b128 v247, v[200:203] offset:3072
	ds_read_b128 v[188:191], v248
	ds_read_b128 v[192:195], v249
	ds_read_b128 v[196:199], v250
	ds_read_b128 v[200:203], v251
	ds_write_b128 v112, v[204:207]
	ds_write_b128 v112, v[208:211] offset:1024
	ds_write_b128 v112, v[212:215] offset:2048
	ds_write_b128 v112, v[216:219] offset:3072
	ds_read2_b32 v[32:33], v115 offset0:102 offset1:103
	ds_read2_b32 v[34:35], v115 offset0:104 offset1:105
	ds_read2_b32 v[36:37], v115 offset0:110 offset1:111
	ds_read2_b32 v[38:39], v115 offset0:112 offset1:113
	ds_read2_b32 v[40:41], v115 offset0:119 offset1:120
	ds_read2_b32 v[42:43], v115 offset0:121 offset1:122
	ds_read2_b32 v[44:45], v115 offset0:127 offset1:128
	ds_read2_b32 v[46:47], v115 offset0:129 offset1:130
	s_waitcnt lgkmcnt(0)
	v_mfma_f32_32x32x16_bf16 v[32:47], v[188:191], v[48:51], v[32:47]
	ds_read_b64_tr_b16 v[72:73], v231
	ds_read_b64_tr_b16 v[74:75], v231 offset:512
	ds_read_b64_tr_b16 v[76:77], v231 offset:2048
	ds_read_b64_tr_b16 v[78:79], v231 offset:2560
	ds_read_b64_tr_b16 v[220:221], v231 offset:1024
	ds_read_b64_tr_b16 v[222:223], v231 offset:1536
	ds_read_b64_tr_b16 v[224:225], v231 offset:3072
	ds_read_b64_tr_b16 v[226:227], v231 offset:3584
	v_mfma_f32_32x32x16_bf16 v[32:47], v[192:195], v[52:55], v[32:47]
	v_mfma_f32_32x32x16_bf16 v[32:47], v[196:199], v[56:59], v[32:47]
	v_mfma_f32_32x32x16_bf16 v[32:47], v[200:203], v[60:63], v[32:47]
	s_nop 11
	v_exp_f32_e32 v32, v32
	v_exp_f32_e32 v33, v33
	v_exp_f32_e32 v34, v34
	v_exp_f32_e32 v35, v35
	v_exp_f32_e32 v36, v36
	v_exp_f32_e32 v37, v37
	v_exp_f32_e32 v38, v38
	v_exp_f32_e32 v39, v39
	v_exp_f32_e32 v40, v40
	v_exp_f32_e32 v41, v41
	v_exp_f32_e32 v42, v42
	v_exp_f32_e32 v43, v43
	v_exp_f32_e32 v44, v44
	v_exp_f32_e32 v45, v45
	v_exp_f32_e32 v46, v46
	v_exp_f32_e32 v47, v47
	s_add_i32 s90, s67, 480
	v_add_u32_e32 v84, s90, v107
	v_add_u32_e32 v85, 0, v84
	v_add_u32_e32 v86, 1, v84
	v_add_u32_e32 v87, 2, v84
	v_add_u32_e32 v88, 3, v84
	v_cmp_gt_u32_e64 s[30:31], s98, v85
	v_cmp_gt_u32_e64 s[36:37], s98, v86
	v_cmp_gt_u32_e64 s[78:79], s98, v87
	v_cmp_gt_u32_e64 s[50:51], s98, v88
	v_cndmask_b32_e64 v32, 0, v32, s[30:31]
	v_add_u32_e32 v85, 8, v84
	v_cmp_gt_u32_e64 s[30:31], s98, v85
	v_cndmask_b32_e64 v33, 0, v33, s[36:37]
	v_add_u32_e32 v86, 9, v84
	v_cmp_gt_u32_e64 s[36:37], s98, v86
	v_cndmask_b32_e64 v34, 0, v34, s[78:79]
	v_add_u32_e32 v87, 10, v84
	v_cmp_gt_u32_e64 s[78:79], s98, v87
	v_cndmask_b32_e64 v35, 0, v35, s[50:51]
	v_add_u32_e32 v88, 11, v84
	v_cmp_gt_u32_e64 s[50:51], s98, v88
	v_cndmask_b32_e64 v36, 0, v36, s[30:31]
	v_add_u32_e32 v85, 16, v84
	v_cmp_gt_u32_e64 s[30:31], s98, v85
	v_cndmask_b32_e64 v37, 0, v37, s[36:37]
	v_add_u32_e32 v86, 17, v84
	v_cmp_gt_u32_e64 s[36:37], s98, v86
	v_cndmask_b32_e64 v38, 0, v38, s[78:79]
	v_add_u32_e32 v87, 18, v84
	v_cmp_gt_u32_e64 s[78:79], s98, v87
	v_cndmask_b32_e64 v39, 0, v39, s[50:51]
	v_add_u32_e32 v88, 19, v84
	v_cmp_gt_u32_e64 s[50:51], s98, v88
	v_cndmask_b32_e64 v40, 0, v40, s[30:31]
	v_add_u32_e32 v85, 24, v84
	v_cmp_gt_u32_e64 s[30:31], s98, v85
	v_cndmask_b32_e64 v41, 0, v41, s[36:37]
	v_add_u32_e32 v86, 25, v84
	v_cmp_gt_u32_e64 s[36:37], s98, v86
	v_cndmask_b32_e64 v42, 0, v42, s[78:79]
	v_add_u32_e32 v87, 26, v84
	v_cmp_gt_u32_e64 s[78:79], s98, v87
	v_cndmask_b32_e64 v43, 0, v43, s[50:51]
	v_add_u32_e32 v88, 27, v84
	v_cmp_gt_u32_e64 s[50:51], s98, v88
	v_nop
	v_cndmask_b32_e64 v44, 0, v44, s[30:31]
	v_cndmask_b32_e64 v45, 0, v45, s[36:37]
	v_cndmask_b32_e64 v46, 0, v46, s[78:79]
	v_cndmask_b32_e64 v47, 0, v47, s[50:51]
	v_cvt_pk_bf16_f32 v64, v32, v33
	v_cvt_pk_bf16_f32 v65, v34, v35
	v_cvt_pk_bf16_f32 v66, v36, v37
	v_cvt_pk_bf16_f32 v67, v38, v39
	v_cvt_pk_bf16_f32 v68, v40, v41
	v_cvt_pk_bf16_f32 v69, v42, v43
	v_cvt_pk_bf16_f32 v70, v44, v45
	v_cvt_pk_bf16_f32 v71, v46, v47
	v_pk_add_f32 v[232:233], v[232:233], v[32:33]
	v_pk_add_f32 v[232:233], v[232:233], v[34:35]
	v_pk_add_f32 v[232:233], v[232:233], v[36:37]
	v_pk_add_f32 v[232:233], v[232:233], v[38:39]
	v_pk_add_f32 v[232:233], v[232:233], v[40:41]
	v_pk_add_f32 v[232:233], v[232:233], v[42:43]
	v_pk_add_f32 v[232:233], v[232:233], v[44:45]
	v_pk_add_f32 v[232:233], v[232:233], v[46:47]
	s_waitcnt lgkmcnt(0)
	v_mfma_f32_32x32x16_bf16 v[0:15], v[64:67], v[72:75], v[0:15]
	v_mfma_f32_32x32x16_bf16 v[16:31], v[64:67], v[76:79], v[16:31]
	v_mfma_f32_32x32x16_bf16 v[0:15], v[68:71], v[220:223], v[0:15]
	v_mfma_f32_32x32x16_bf16 v[16:31], v[68:71], v[224:227], v[16:31]
	s_add_i32 s90, s67, -256
	v_add_u32_e32 v80, s90, v239
	v_add_u32_e32 v83, s90, v240
	v_add_u32_e32 v99, s90, v241
	v_add_u32_e32 v253, s90, v242
	v_add_u32_e32 v254, s90, v101
	v_add_u32_e32 v255, s90, v150
	v_med3_i32 v80, v80, 0, s99
	v_med3_i32 v83, v83, 0, s99
	v_med3_i32 v99, v99, 0, s99
	v_med3_i32 v253, v253, 0, s99
	v_med3_i32 v254, v254, 0, s99
	v_med3_i32 v255, v255, 0, s99
	v_mad_u32_u24 v80, v80, s100, v252
	v_mad_u32_u24 v83, v83, s100, v252
	v_mad_u32_u24 v99, v99, s100, v252
	v_mad_u32_u24 v253, v253, s100, v252
	v_mad_u32_u24 v254, v254, s100, v153
	v_mad_u32_u24 v255, v255, s100, v153
	global_load_dwordx4 v[188:191], v80, s[82:83]
	global_load_dwordx4 v[192:195], v83, s[82:83]
	global_load_dwordx4 v[196:199], v99, s[82:83]
	global_load_dwordx4 v[200:203], v253, s[82:83]
	global_load_dwordx4 v[204:207], v254, s[82:83] offset:768
	global_load_dwordx4 v[208:211], v255, s[82:83] offset:768
	global_load_dwordx4 v[212:215], v254, s[82:83] offset:832
	global_load_dwordx4 v[216:219], v255, s[82:83] offset:832
	s_waitcnt vmcnt(16)
	ds_write_b128 v247, v[116:119]
	ds_write_b128 v247, v[120:123] offset:1024
	ds_write_b128 v247, v[124:127] offset:2048
	ds_write_b128 v247, v[128:131] offset:3072
	ds_read_b128 v[116:119], v248
	ds_read_b128 v[120:123], v249
	ds_read_b128 v[124:127], v250
	ds_read_b128 v[128:131], v251
	ds_write_b128 v112, v[132:135]
	ds_write_b128 v112, v[136:139] offset:1024
	ds_write_b128 v112, v[140:143] offset:2048
	ds_write_b128 v112, v[144:147] offset:3072
	ds_read2_b32 v[32:33], v115 offset0:136 offset1:137
	ds_read2_b32 v[34:35], v115 offset0:138 offset1:139
	ds_read2_b32 v[36:37], v115 offset0:144 offset1:145
	ds_read2_b32 v[38:39], v115 offset0:146 offset1:147
	ds_read2_b32 v[40:41], v115 offset0:153 offset1:154
	ds_read2_b32 v[42:43], v115 offset0:155 offset1:156
	ds_read2_b32 v[44:45], v115 offset0:161 offset1:162
	ds_read2_b32 v[46:47], v115 offset0:163 offset1:164
	s_waitcnt lgkmcnt(0)
	v_mfma_f32_32x32x16_bf16 v[32:47], v[116:119], v[48:51], v[32:47]
	ds_read_b64_tr_b16 v[72:73], v231
	ds_read_b64_tr_b16 v[74:75], v231 offset:512
	ds_read_b64_tr_b16 v[76:77], v231 offset:2048
	ds_read_b64_tr_b16 v[78:79], v231 offset:2560
	ds_read_b64_tr_b16 v[220:221], v231 offset:1024
	ds_read_b64_tr_b16 v[222:223], v231 offset:1536
	ds_read_b64_tr_b16 v[224:225], v231 offset:3072
	ds_read_b64_tr_b16 v[226:227], v231 offset:3584
	v_mfma_f32_32x32x16_bf16 v[32:47], v[120:123], v[52:55], v[32:47]
	v_mfma_f32_32x32x16_bf16 v[32:47], v[124:127], v[56:59], v[32:47]
	v_mfma_f32_32x32x16_bf16 v[32:47], v[128:131], v[60:63], v[32:47]
	s_nop 11
	v_exp_f32_e32 v32, v32
	v_exp_f32_e32 v33, v33
	v_exp_f32_e32 v34, v34
	v_exp_f32_e32 v35, v35
	v_exp_f32_e32 v36, v36
	v_exp_f32_e32 v37, v37
	v_exp_f32_e32 v38, v38
	v_exp_f32_e32 v39, v39
	v_exp_f32_e32 v40, v40
	v_exp_f32_e32 v41, v41
	v_exp_f32_e32 v42, v42
	v_exp_f32_e32 v43, v43
	v_exp_f32_e32 v44, v44
	v_exp_f32_e32 v45, v45
	v_exp_f32_e32 v46, v46
	v_exp_f32_e32 v47, v47
	s_add_i32 s90, s67, 512
	v_add_u32_e32 v84, s90, v107
	v_add_u32_e32 v85, 0, v84
	v_add_u32_e32 v86, 1, v84
	v_add_u32_e32 v87, 2, v84
	v_add_u32_e32 v88, 3, v84
	v_cmp_gt_u32_e64 s[30:31], s98, v85
	v_cmp_gt_u32_e64 s[36:37], s98, v86
	v_cmp_gt_u32_e64 s[78:79], s98, v87
	v_cmp_gt_u32_e64 s[50:51], s98, v88
	v_cndmask_b32_e64 v32, 0, v32, s[30:31]
	v_add_u32_e32 v85, 8, v84
	v_cmp_gt_u32_e64 s[30:31], s98, v85
	v_cndmask_b32_e64 v33, 0, v33, s[36:37]
	v_add_u32_e32 v86, 9, v84
	v_cmp_gt_u32_e64 s[36:37], s98, v86
	v_cndmask_b32_e64 v34, 0, v34, s[78:79]
	v_add_u32_e32 v87, 10, v84
	v_cmp_gt_u32_e64 s[78:79], s98, v87
	v_cndmask_b32_e64 v35, 0, v35, s[50:51]
	v_add_u32_e32 v88, 11, v84
	v_cmp_gt_u32_e64 s[50:51], s98, v88
	v_cndmask_b32_e64 v36, 0, v36, s[30:31]
	v_add_u32_e32 v85, 16, v84
	v_cmp_gt_u32_e64 s[30:31], s98, v85
	v_cndmask_b32_e64 v37, 0, v37, s[36:37]
	v_add_u32_e32 v86, 17, v84
	v_cmp_gt_u32_e64 s[36:37], s98, v86
	v_cndmask_b32_e64 v38, 0, v38, s[78:79]
	v_add_u32_e32 v87, 18, v84
	v_cmp_gt_u32_e64 s[78:79], s98, v87
	v_cndmask_b32_e64 v39, 0, v39, s[50:51]
	v_add_u32_e32 v88, 19, v84
	v_cmp_gt_u32_e64 s[50:51], s98, v88
	v_cndmask_b32_e64 v40, 0, v40, s[30:31]
	v_add_u32_e32 v85, 24, v84
	v_cmp_gt_u32_e64 s[30:31], s98, v85
	v_cndmask_b32_e64 v41, 0, v41, s[36:37]
	v_add_u32_e32 v86, 25, v84
	v_cmp_gt_u32_e64 s[36:37], s98, v86
	v_cndmask_b32_e64 v42, 0, v42, s[78:79]
	v_add_u32_e32 v87, 26, v84
	v_cmp_gt_u32_e64 s[78:79], s98, v87
	v_cndmask_b32_e64 v43, 0, v43, s[50:51]
	v_add_u32_e32 v88, 27, v84
	v_cmp_gt_u32_e64 s[50:51], s98, v88
	v_nop
	v_cndmask_b32_e64 v44, 0, v44, s[30:31]
	v_cndmask_b32_e64 v45, 0, v45, s[36:37]
	v_cndmask_b32_e64 v46, 0, v46, s[78:79]
	v_cndmask_b32_e64 v47, 0, v47, s[50:51]
	v_cvt_pk_bf16_f32 v64, v32, v33
	v_cvt_pk_bf16_f32 v65, v34, v35
	v_cvt_pk_bf16_f32 v66, v36, v37
	v_cvt_pk_bf16_f32 v67, v38, v39
	v_cvt_pk_bf16_f32 v68, v40, v41
	v_cvt_pk_bf16_f32 v69, v42, v43
	v_cvt_pk_bf16_f32 v70, v44, v45
	v_cvt_pk_bf16_f32 v71, v46, v47
	v_pk_add_f32 v[232:233], v[232:233], v[32:33]
	v_pk_add_f32 v[232:233], v[232:233], v[34:35]
	v_pk_add_f32 v[232:233], v[232:233], v[36:37]
	v_pk_add_f32 v[232:233], v[232:233], v[38:39]
	v_pk_add_f32 v[232:233], v[232:233], v[40:41]
	v_pk_add_f32 v[232:233], v[232:233], v[42:43]
	v_pk_add_f32 v[232:233], v[232:233], v[44:45]
	v_pk_add_f32 v[232:233], v[232:233], v[46:47]
	s_waitcnt lgkmcnt(0)
	v_mfma_f32_32x32x16_bf16 v[0:15], v[64:67], v[72:75], v[0:15]
	v_mfma_f32_32x32x16_bf16 v[16:31], v[64:67], v[76:79], v[16:31]
	v_mfma_f32_32x32x16_bf16 v[0:15], v[68:71], v[220:223], v[0:15]
	v_mfma_f32_32x32x16_bf16 v[16:31], v[68:71], v[224:227], v[16:31]
	s_add_i32 s90, s67, -128
	v_add_u32_e32 v80, s90, v239
	v_add_u32_e32 v83, s90, v240
	v_add_u32_e32 v99, s90, v241
	v_add_u32_e32 v253, s90, v242
	v_add_u32_e32 v254, s90, v101
	v_add_u32_e32 v255, s90, v150
	v_med3_i32 v80, v80, 0, s99
	v_med3_i32 v83, v83, 0, s99
	v_med3_i32 v99, v99, 0, s99
	v_med3_i32 v253, v253, 0, s99
	v_med3_i32 v254, v254, 0, s99
	v_med3_i32 v255, v255, 0, s99
	v_mad_u32_u24 v80, v80, s100, v252
	v_mad_u32_u24 v83, v83, s100, v252
	v_mad_u32_u24 v99, v99, s100, v252
	v_mad_u32_u24 v253, v253, s100, v252
	v_mad_u32_u24 v254, v254, s100, v153
	v_mad_u32_u24 v255, v255, s100, v153
	global_load_dwordx4 v[116:119], v80, s[82:83]
	global_load_dwordx4 v[120:123], v83, s[82:83]
	global_load_dwordx4 v[124:127], v99, s[82:83]
	global_load_dwordx4 v[128:131], v253, s[82:83]
	global_load_dwordx4 v[132:135], v254, s[82:83] offset:768
	global_load_dwordx4 v[136:139], v255, s[82:83] offset:768
	global_load_dwordx4 v[140:143], v254, s[82:83] offset:832
	global_load_dwordx4 v[144:147], v255, s[82:83] offset:832
	s_waitcnt vmcnt(16)
	ds_write_b128 v247, v[156:159]
	ds_write_b128 v247, v[160:163] offset:1024
	ds_write_b128 v247, v[164:167] offset:2048
	ds_write_b128 v247, v[168:171] offset:3072
	ds_read_b128 v[156:159], v248
	ds_read_b128 v[160:163], v249
	ds_read_b128 v[164:167], v250
	ds_read_b128 v[168:171], v251
	ds_write_b128 v112, v[172:175]
	ds_write_b128 v112, v[176:179] offset:1024
	ds_write_b128 v112, v[180:183] offset:2048
	ds_write_b128 v112, v[184:187] offset:3072
	ds_read2_b32 v[32:33], v115 offset0:170 offset1:171
	ds_read2_b32 v[34:35], v115 offset0:172 offset1:173
	ds_read2_b32 v[36:37], v115 offset0:178 offset1:179
	ds_read2_b32 v[38:39], v115 offset0:180 offset1:181
	ds_read2_b32 v[40:41], v115 offset0:187 offset1:188
	ds_read2_b32 v[42:43], v115 offset0:189 offset1:190
	ds_read2_b32 v[44:45], v115 offset0:195 offset1:196
	ds_read2_b32 v[46:47], v115 offset0:197 offset1:198
	s_waitcnt lgkmcnt(0)
	v_mfma_f32_32x32x16_bf16 v[32:47], v[156:159], v[48:51], v[32:47]
	ds_read_b64_tr_b16 v[72:73], v231
	ds_read_b64_tr_b16 v[74:75], v231 offset:512
	ds_read_b64_tr_b16 v[76:77], v231 offset:2048
	ds_read_b64_tr_b16 v[78:79], v231 offset:2560
	ds_read_b64_tr_b16 v[220:221], v231 offset:1024
	ds_read_b64_tr_b16 v[222:223], v231 offset:1536
	ds_read_b64_tr_b16 v[224:225], v231 offset:3072
	ds_read_b64_tr_b16 v[226:227], v231 offset:3584
	v_mfma_f32_32x32x16_bf16 v[32:47], v[160:163], v[52:55], v[32:47]
	v_mfma_f32_32x32x16_bf16 v[32:47], v[164:167], v[56:59], v[32:47]
	v_mfma_f32_32x32x16_bf16 v[32:47], v[168:171], v[60:63], v[32:47]
	s_nop 11
	v_exp_f32_e32 v32, v32
	v_exp_f32_e32 v33, v33
	v_exp_f32_e32 v34, v34
	v_exp_f32_e32 v35, v35
	v_exp_f32_e32 v36, v36
	v_exp_f32_e32 v37, v37
	v_exp_f32_e32 v38, v38
	v_exp_f32_e32 v39, v39
	v_exp_f32_e32 v40, v40
	v_exp_f32_e32 v41, v41
	v_exp_f32_e32 v42, v42
	v_exp_f32_e32 v43, v43
	v_exp_f32_e32 v44, v44
	v_exp_f32_e32 v45, v45
	v_exp_f32_e32 v46, v46
	v_exp_f32_e32 v47, v47
	s_add_i32 s90, s67, 544
	v_add_u32_e32 v84, s90, v107
	v_add_u32_e32 v85, 0, v84
	v_add_u32_e32 v86, 1, v84
	v_add_u32_e32 v87, 2, v84
	v_add_u32_e32 v88, 3, v84
	v_cmp_gt_u32_e64 s[30:31], s98, v85
	v_cmp_gt_u32_e64 s[36:37], s98, v86
	v_cmp_gt_u32_e64 s[78:79], s98, v87
	v_cmp_gt_u32_e64 s[50:51], s98, v88
	v_cndmask_b32_e64 v32, 0, v32, s[30:31]
	v_add_u32_e32 v85, 8, v84
	v_cmp_gt_u32_e64 s[30:31], s98, v85
	v_cndmask_b32_e64 v33, 0, v33, s[36:37]
	v_add_u32_e32 v86, 9, v84
	v_cmp_gt_u32_e64 s[36:37], s98, v86
	v_cndmask_b32_e64 v34, 0, v34, s[78:79]
	v_add_u32_e32 v87, 10, v84
	v_cmp_gt_u32_e64 s[78:79], s98, v87
	v_cndmask_b32_e64 v35, 0, v35, s[50:51]
	v_add_u32_e32 v88, 11, v84
	v_cmp_gt_u32_e64 s[50:51], s98, v88
	v_cndmask_b32_e64 v36, 0, v36, s[30:31]
	v_add_u32_e32 v85, 16, v84
	v_cmp_gt_u32_e64 s[30:31], s98, v85
	v_cndmask_b32_e64 v37, 0, v37, s[36:37]
	v_add_u32_e32 v86, 17, v84
	v_cmp_gt_u32_e64 s[36:37], s98, v86
	v_cndmask_b32_e64 v38, 0, v38, s[78:79]
	v_add_u32_e32 v87, 18, v84
	v_cmp_gt_u32_e64 s[78:79], s98, v87
	v_cndmask_b32_e64 v39, 0, v39, s[50:51]
	v_add_u32_e32 v88, 19, v84
	v_cmp_gt_u32_e64 s[50:51], s98, v88
	v_cndmask_b32_e64 v40, 0, v40, s[30:31]
	v_add_u32_e32 v85, 24, v84
	v_cmp_gt_u32_e64 s[30:31], s98, v85
	v_cndmask_b32_e64 v41, 0, v41, s[36:37]
	v_add_u32_e32 v86, 25, v84
	v_cmp_gt_u32_e64 s[36:37], s98, v86
	v_cndmask_b32_e64 v42, 0, v42, s[78:79]
	v_add_u32_e32 v87, 26, v84
	v_cmp_gt_u32_e64 s[78:79], s98, v87
	v_cndmask_b32_e64 v43, 0, v43, s[50:51]
	v_add_u32_e32 v88, 27, v84
	v_cmp_gt_u32_e64 s[50:51], s98, v88
	v_nop
	v_cndmask_b32_e64 v44, 0, v44, s[30:31]
	v_cndmask_b32_e64 v45, 0, v45, s[36:37]
	v_cndmask_b32_e64 v46, 0, v46, s[78:79]
	v_cndmask_b32_e64 v47, 0, v47, s[50:51]
	v_cvt_pk_bf16_f32 v64, v32, v33
	v_cvt_pk_bf16_f32 v65, v34, v35
	v_cvt_pk_bf16_f32 v66, v36, v37
	v_cvt_pk_bf16_f32 v67, v38, v39
	v_cvt_pk_bf16_f32 v68, v40, v41
	v_cvt_pk_bf16_f32 v69, v42, v43
	v_cvt_pk_bf16_f32 v70, v44, v45
	v_cvt_pk_bf16_f32 v71, v46, v47
	v_pk_add_f32 v[232:233], v[232:233], v[32:33]
	v_pk_add_f32 v[232:233], v[232:233], v[34:35]
	v_pk_add_f32 v[232:233], v[232:233], v[36:37]
	v_pk_add_f32 v[232:233], v[232:233], v[38:39]
	v_pk_add_f32 v[232:233], v[232:233], v[40:41]
	v_pk_add_f32 v[232:233], v[232:233], v[42:43]
	v_pk_add_f32 v[232:233], v[232:233], v[44:45]
	v_pk_add_f32 v[232:233], v[232:233], v[46:47]
	s_waitcnt lgkmcnt(0)
	v_mfma_f32_32x32x16_bf16 v[0:15], v[64:67], v[72:75], v[0:15]
	v_mfma_f32_32x32x16_bf16 v[16:31], v[64:67], v[76:79], v[16:31]
	v_mfma_f32_32x32x16_bf16 v[0:15], v[68:71], v[220:223], v[0:15]
	v_mfma_f32_32x32x16_bf16 v[16:31], v[68:71], v[224:227], v[16:31]
	s_add_i32 s90, s67, 0
	v_add_u32_e32 v80, s90, v239
	v_add_u32_e32 v83, s90, v240
	v_add_u32_e32 v99, s90, v241
	v_add_u32_e32 v253, s90, v242
	v_add_u32_e32 v254, s90, v101
	v_add_u32_e32 v255, s90, v150
	v_med3_i32 v80, v80, 0, s99
	v_med3_i32 v83, v83, 0, s99
	v_med3_i32 v99, v99, 0, s99
	v_med3_i32 v253, v253, 0, s99
	v_med3_i32 v254, v254, 0, s99
	v_med3_i32 v255, v255, 0, s99
	v_mad_u32_u24 v80, v80, s100, v252
	v_mad_u32_u24 v83, v83, s100, v252
	v_mad_u32_u24 v99, v99, s100, v252
	v_mad_u32_u24 v253, v253, s100, v252
	v_mad_u32_u24 v254, v254, s100, v153
	v_mad_u32_u24 v255, v255, s100, v153
	global_load_dwordx4 v[156:159], v80, s[82:83]
	global_load_dwordx4 v[160:163], v83, s[82:83]
	global_load_dwordx4 v[164:167], v99, s[82:83]
	global_load_dwordx4 v[168:171], v253, s[82:83]
	global_load_dwordx4 v[172:175], v254, s[82:83] offset:768
	global_load_dwordx4 v[176:179], v255, s[82:83] offset:768
	global_load_dwordx4 v[180:183], v254, s[82:83] offset:832
	global_load_dwordx4 v[184:187], v255, s[82:83] offset:832
	s_waitcnt vmcnt(16)
	ds_write_b128 v247, v[188:191]
	ds_write_b128 v247, v[192:195] offset:1024
	ds_write_b128 v247, v[196:199] offset:2048
	ds_write_b128 v247, v[200:203] offset:3072
	ds_read_b128 v[188:191], v248
	ds_read_b128 v[192:195], v249
	ds_read_b128 v[196:199], v250
	ds_read_b128 v[200:203], v251
	ds_write_b128 v112, v[204:207]
	ds_write_b128 v112, v[208:211] offset:1024
	ds_write_b128 v112, v[212:215] offset:2048
	ds_write_b128 v112, v[216:219] offset:3072
	v_mov_b32_e32 v115, v229
	ds_read2_b32 v[32:33], v115 offset0:0 offset1:1
	ds_read2_b32 v[34:35], v115 offset0:2 offset1:3
	ds_read2_b32 v[36:37], v115 offset0:8 offset1:9
	ds_read2_b32 v[38:39], v115 offset0:10 offset1:11
	ds_read2_b32 v[40:41], v115 offset0:16 offset1:17
	ds_read2_b32 v[42:43], v115 offset0:18 offset1:19
	ds_read2_b32 v[44:45], v115 offset0:24 offset1:25
	ds_read2_b32 v[46:47], v115 offset0:26 offset1:27
	s_waitcnt lgkmcnt(0)
	v_mfma_f32_32x32x16_bf16 v[32:47], v[188:191], v[48:51], v[32:47]
	ds_read_b64_tr_b16 v[72:73], v231
	ds_read_b64_tr_b16 v[74:75], v231 offset:512
	ds_read_b64_tr_b16 v[76:77], v231 offset:2048
	ds_read_b64_tr_b16 v[78:79], v231 offset:2560
	ds_read_b64_tr_b16 v[220:221], v231 offset:1024
	ds_read_b64_tr_b16 v[222:223], v231 offset:1536
	ds_read_b64_tr_b16 v[224:225], v231 offset:3072
	ds_read_b64_tr_b16 v[226:227], v231 offset:3584
	v_mfma_f32_32x32x16_bf16 v[32:47], v[192:195], v[52:55], v[32:47]
	v_mfma_f32_32x32x16_bf16 v[32:47], v[196:199], v[56:59], v[32:47]
	v_mfma_f32_32x32x16_bf16 v[32:47], v[200:203], v[60:63], v[32:47]
	s_nop 11
	v_exp_f32_e32 v32, v32
	v_exp_f32_e32 v33, v33
	v_exp_f32_e32 v34, v34
	v_exp_f32_e32 v35, v35
	v_exp_f32_e32 v36, v36
	v_exp_f32_e32 v37, v37
	v_exp_f32_e32 v38, v38
	v_exp_f32_e32 v39, v39
	v_exp_f32_e32 v40, v40
	v_exp_f32_e32 v41, v41
	v_exp_f32_e32 v42, v42
	v_exp_f32_e32 v43, v43
	v_exp_f32_e32 v44, v44
	v_exp_f32_e32 v45, v45
	v_exp_f32_e32 v46, v46
	v_exp_f32_e32 v47, v47
	s_add_i32 s90, s67, -256
	v_lshlrev_b32_e32 v84, 2, v107
	v_add_u32_e32 v84, s90, v84
	v_add_u32_e32 v85, 0, v84
	v_add_u32_e32 v86, 4, v84
	v_add_u32_e32 v87, 8, v84
	v_add_u32_e32 v88, 12, v84
	v_cmp_gt_u32_e64 s[30:31], s98, v85
	v_cmp_gt_u32_e64 s[36:37], s98, v86
	v_cmp_gt_u32_e64 s[78:79], s98, v87
	v_cmp_gt_u32_e64 s[50:51], s98, v88
	v_cndmask_b32_e64 v32, 0, v32, s[30:31]
	v_add_u32_e32 v85, 32, v84
	v_cmp_gt_u32_e64 s[30:31], s98, v85
	v_cndmask_b32_e64 v33, 0, v33, s[36:37]
	v_add_u32_e32 v86, 36, v84
	v_cmp_gt_u32_e64 s[36:37], s98, v86
	v_cndmask_b32_e64 v34, 0, v34, s[78:79]
	v_add_u32_e32 v87, 40, v84
	v_cmp_gt_u32_e64 s[78:79], s98, v87
	v_cndmask_b32_e64 v35, 0, v35, s[50:51]
	v_add_u32_e32 v88, 44, v84
	v_cmp_gt_u32_e64 s[50:51], s98, v88
	v_cndmask_b32_e64 v36, 0, v36, s[30:31]
	v_add_u32_e32 v85, 64, v84
	v_cmp_gt_u32_e64 s[30:31], s98, v85
	v_cndmask_b32_e64 v37, 0, v37, s[36:37]
	v_add_u32_e32 v86, 68, v84
	v_cmp_gt_u32_e64 s[36:37], s98, v86
	v_cndmask_b32_e64 v38, 0, v38, s[78:79]
	v_add_u32_e32 v87, 72, v84
	v_cmp_gt_u32_e64 s[78:79], s98, v87
	v_cndmask_b32_e64 v39, 0, v39, s[50:51]
	v_add_u32_e32 v88, 76, v84
	v_cmp_gt_u32_e64 s[50:51], s98, v88
	v_cndmask_b32_e64 v40, 0, v40, s[30:31]
	v_add_u32_e32 v85, 96, v84
	v_cmp_gt_u32_e64 s[30:31], s98, v85
	v_cndmask_b32_e64 v41, 0, v41, s[36:37]
	v_add_u32_e32 v86, 100, v84
	v_cmp_gt_u32_e64 s[36:37], s98, v86
	v_cndmask_b32_e64 v42, 0, v42, s[78:79]
	v_add_u32_e32 v87, 104, v84
	v_cmp_gt_u32_e64 s[78:79], s98, v87
	v_cndmask_b32_e64 v43, 0, v43, s[50:51]
	v_add_u32_e32 v88, 108, v84
	v_cmp_gt_u32_e64 s[50:51], s98, v88
	v_nop
	v_cndmask_b32_e64 v44, 0, v44, s[30:31]
	v_cndmask_b32_e64 v45, 0, v45, s[36:37]
	v_cndmask_b32_e64 v46, 0, v46, s[78:79]
	v_cndmask_b32_e64 v47, 0, v47, s[50:51]
	v_cvt_pk_bf16_f32 v64, v32, v33
	v_cvt_pk_bf16_f32 v65, v34, v35
	v_cvt_pk_bf16_f32 v66, v36, v37
	v_cvt_pk_bf16_f32 v67, v38, v39
	v_cvt_pk_bf16_f32 v68, v40, v41
	v_cvt_pk_bf16_f32 v69, v42, v43
	v_cvt_pk_bf16_f32 v70, v44, v45
	v_cvt_pk_bf16_f32 v71, v46, v47
	v_pk_add_f32 v[232:233], v[232:233], v[32:33]
	v_pk_add_f32 v[232:233], v[232:233], v[34:35]
	v_pk_add_f32 v[232:233], v[232:233], v[36:37]
	v_pk_add_f32 v[232:233], v[232:233], v[38:39]
	v_pk_add_f32 v[232:233], v[232:233], v[40:41]
	v_pk_add_f32 v[232:233], v[232:233], v[42:43]
	v_pk_add_f32 v[232:233], v[232:233], v[44:45]
	v_pk_add_f32 v[232:233], v[232:233], v[46:47]
	s_waitcnt lgkmcnt(0)
	v_mfma_f32_32x32x16_bf16 v[0:15], v[64:67], v[72:75], v[0:15]
	v_mfma_f32_32x32x16_bf16 v[16:31], v[64:67], v[76:79], v[16:31]
	v_mfma_f32_32x32x16_bf16 v[0:15], v[68:71], v[220:223], v[0:15]
	v_mfma_f32_32x32x16_bf16 v[16:31], v[68:71], v[224:227], v[16:31]
	s_add_i32 s90, s67, 128
	v_add_u32_e32 v80, s90, v239
	v_add_u32_e32 v83, s90, v240
	v_add_u32_e32 v99, s90, v241
	v_add_u32_e32 v253, s90, v242
	v_add_u32_e32 v254, s90, v101
	v_add_u32_e32 v255, s90, v150
	v_med3_i32 v80, v80, 0, s99
	v_med3_i32 v83, v83, 0, s99
	v_med3_i32 v99, v99, 0, s99
	v_med3_i32 v253, v253, 0, s99
	v_med3_i32 v254, v254, 0, s99
	v_med3_i32 v255, v255, 0, s99
	v_mad_u32_u24 v80, v80, s100, v252
	v_mad_u32_u24 v83, v83, s100, v252
	v_mad_u32_u24 v99, v99, s100, v252
	v_mad_u32_u24 v253, v253, s100, v252
	v_mad_u32_u24 v254, v254, s100, v153
	v_mad_u32_u24 v255, v255, s100, v153
	global_load_dwordx4 v[188:191], v80, s[82:83]
	global_load_dwordx4 v[192:195], v83, s[82:83]
	global_load_dwordx4 v[196:199], v99, s[82:83]
	global_load_dwordx4 v[200:203], v253, s[82:83]
	global_load_dwordx4 v[204:207], v254, s[82:83] offset:768
	global_load_dwordx4 v[208:211], v255, s[82:83] offset:768
	global_load_dwordx4 v[212:215], v254, s[82:83] offset:832
	global_load_dwordx4 v[216:219], v255, s[82:83] offset:832
	s_waitcnt vmcnt(16)
	ds_write_b128 v247, v[116:119]
	ds_write_b128 v247, v[120:123] offset:1024
	ds_write_b128 v247, v[124:127] offset:2048
	ds_write_b128 v247, v[128:131] offset:3072
	ds_read_b128 v[116:119], v248
	ds_read_b128 v[120:123], v249
	ds_read_b128 v[124:127], v250
	ds_read_b128 v[128:131], v251
	ds_write_b128 v112, v[132:135]
	ds_write_b128 v112, v[136:139] offset:1024
	ds_write_b128 v112, v[140:143] offset:2048
	ds_write_b128 v112, v[144:147] offset:3072
	ds_read2_b32 v[32:33], v115 offset0:32 offset1:33
	ds_read2_b32 v[34:35], v115 offset0:34 offset1:35
	ds_read2_b32 v[36:37], v115 offset0:40 offset1:41
	ds_read2_b32 v[38:39], v115 offset0:42 offset1:43
	ds_read2_b32 v[40:41], v115 offset0:48 offset1:49
	ds_read2_b32 v[42:43], v115 offset0:50 offset1:51
	ds_read2_b32 v[44:45], v115 offset0:56 offset1:57
	ds_read2_b32 v[46:47], v115 offset0:58 offset1:59
	s_waitcnt lgkmcnt(0)
	v_mfma_f32_32x32x16_bf16 v[32:47], v[116:119], v[48:51], v[32:47]
	ds_read_b64_tr_b16 v[72:73], v231
	ds_read_b64_tr_b16 v[74:75], v231 offset:512
	ds_read_b64_tr_b16 v[76:77], v231 offset:2048
	ds_read_b64_tr_b16 v[78:79], v231 offset:2560
	ds_read_b64_tr_b16 v[220:221], v231 offset:1024
	ds_read_b64_tr_b16 v[222:223], v231 offset:1536
	ds_read_b64_tr_b16 v[224:225], v231 offset:3072
	ds_read_b64_tr_b16 v[226:227], v231 offset:3584
	v_mfma_f32_32x32x16_bf16 v[32:47], v[120:123], v[52:55], v[32:47]
	v_mfma_f32_32x32x16_bf16 v[32:47], v[124:127], v[56:59], v[32:47]
	v_mfma_f32_32x32x16_bf16 v[32:47], v[128:131], v[60:63], v[32:47]
	s_nop 11
	v_exp_f32_e32 v32, v32
	v_exp_f32_e32 v33, v33
	v_exp_f32_e32 v34, v34
	v_exp_f32_e32 v35, v35
	v_exp_f32_e32 v36, v36
	v_exp_f32_e32 v37, v37
	v_exp_f32_e32 v38, v38
	v_exp_f32_e32 v39, v39
	v_exp_f32_e32 v40, v40
	v_exp_f32_e32 v41, v41
	v_exp_f32_e32 v42, v42
	v_exp_f32_e32 v43, v43
	v_exp_f32_e32 v44, v44
	v_exp_f32_e32 v45, v45
	v_exp_f32_e32 v46, v46
	v_exp_f32_e32 v47, v47
	s_add_i32 s90, s67, -128
	v_lshlrev_b32_e32 v84, 2, v107
	v_add_u32_e32 v84, s90, v84
	v_add_u32_e32 v85, 0, v84
	v_add_u32_e32 v86, 4, v84
	v_add_u32_e32 v87, 8, v84
	v_add_u32_e32 v88, 12, v84
	v_cmp_gt_u32_e64 s[30:31], s98, v85
	v_cmp_gt_u32_e64 s[36:37], s98, v86
	v_cmp_gt_u32_e64 s[78:79], s98, v87
	v_cmp_gt_u32_e64 s[50:51], s98, v88
	v_cndmask_b32_e64 v32, 0, v32, s[30:31]
	v_add_u32_e32 v85, 32, v84
	v_cmp_gt_u32_e64 s[30:31], s98, v85
	v_cndmask_b32_e64 v33, 0, v33, s[36:37]
	v_add_u32_e32 v86, 36, v84
	v_cmp_gt_u32_e64 s[36:37], s98, v86
	v_cndmask_b32_e64 v34, 0, v34, s[78:79]
	v_add_u32_e32 v87, 40, v84
	v_cmp_gt_u32_e64 s[78:79], s98, v87
	v_cndmask_b32_e64 v35, 0, v35, s[50:51]
	v_add_u32_e32 v88, 44, v84
	v_cmp_gt_u32_e64 s[50:51], s98, v88
	v_cndmask_b32_e64 v36, 0, v36, s[30:31]
	v_add_u32_e32 v85, 64, v84
	v_cmp_gt_u32_e64 s[30:31], s98, v85
	v_cndmask_b32_e64 v37, 0, v37, s[36:37]
	v_add_u32_e32 v86, 68, v84
	v_cmp_gt_u32_e64 s[36:37], s98, v86
	v_cndmask_b32_e64 v38, 0, v38, s[78:79]
	v_add_u32_e32 v87, 72, v84
	v_cmp_gt_u32_e64 s[78:79], s98, v87
	v_cndmask_b32_e64 v39, 0, v39, s[50:51]
	v_add_u32_e32 v88, 76, v84
	v_cmp_gt_u32_e64 s[50:51], s98, v88
	v_cndmask_b32_e64 v40, 0, v40, s[30:31]
	v_add_u32_e32 v85, 96, v84
	v_cmp_gt_u32_e64 s[30:31], s98, v85
	v_cndmask_b32_e64 v41, 0, v41, s[36:37]
	v_add_u32_e32 v86, 100, v84
	v_cmp_gt_u32_e64 s[36:37], s98, v86
	v_cndmask_b32_e64 v42, 0, v42, s[78:79]
	v_add_u32_e32 v87, 104, v84
	v_cmp_gt_u32_e64 s[78:79], s98, v87
	v_cndmask_b32_e64 v43, 0, v43, s[50:51]
	v_add_u32_e32 v88, 108, v84
	v_cmp_gt_u32_e64 s[50:51], s98, v88
	v_nop
	v_cndmask_b32_e64 v44, 0, v44, s[30:31]
	v_cndmask_b32_e64 v45, 0, v45, s[36:37]
	v_cndmask_b32_e64 v46, 0, v46, s[78:79]
	v_cndmask_b32_e64 v47, 0, v47, s[50:51]
	v_cvt_pk_bf16_f32 v64, v32, v33
	v_cvt_pk_bf16_f32 v65, v34, v35
	v_cvt_pk_bf16_f32 v66, v36, v37
	v_cvt_pk_bf16_f32 v67, v38, v39
	v_cvt_pk_bf16_f32 v68, v40, v41
	v_cvt_pk_bf16_f32 v69, v42, v43
	v_cvt_pk_bf16_f32 v70, v44, v45
	v_cvt_pk_bf16_f32 v71, v46, v47
	v_pk_add_f32 v[232:233], v[232:233], v[32:33]
	v_pk_add_f32 v[232:233], v[232:233], v[34:35]
	v_pk_add_f32 v[232:233], v[232:233], v[36:37]
	v_pk_add_f32 v[232:233], v[232:233], v[38:39]
	v_pk_add_f32 v[232:233], v[232:233], v[40:41]
	v_pk_add_f32 v[232:233], v[232:233], v[42:43]
	v_pk_add_f32 v[232:233], v[232:233], v[44:45]
	v_pk_add_f32 v[232:233], v[232:233], v[46:47]
	s_waitcnt lgkmcnt(0)
	v_mfma_f32_32x32x16_bf16 v[0:15], v[64:67], v[72:75], v[0:15]
	v_mfma_f32_32x32x16_bf16 v[16:31], v[64:67], v[76:79], v[16:31]
	v_mfma_f32_32x32x16_bf16 v[0:15], v[68:71], v[220:223], v[0:15]
	v_mfma_f32_32x32x16_bf16 v[16:31], v[68:71], v[224:227], v[16:31]
	s_add_i32 s90, s67, 256
	v_add_u32_e32 v80, s90, v239
	v_add_u32_e32 v83, s90, v240
	v_add_u32_e32 v99, s90, v241
	v_add_u32_e32 v253, s90, v242
	v_add_u32_e32 v254, s90, v101
	v_add_u32_e32 v255, s90, v150
	v_med3_i32 v80, v80, 0, s99
	v_med3_i32 v83, v83, 0, s99
	v_med3_i32 v99, v99, 0, s99
	v_med3_i32 v253, v253, 0, s99
	v_med3_i32 v254, v254, 0, s99
	v_med3_i32 v255, v255, 0, s99
	v_mad_u32_u24 v80, v80, s100, v252
	v_mad_u32_u24 v83, v83, s100, v252
	v_mad_u32_u24 v99, v99, s100, v252
	v_mad_u32_u24 v253, v253, s100, v252
	v_mad_u32_u24 v254, v254, s100, v153
	v_mad_u32_u24 v255, v255, s100, v153
	global_load_dwordx4 v[116:119], v80, s[82:83]
	global_load_dwordx4 v[120:123], v83, s[82:83]
	global_load_dwordx4 v[124:127], v99, s[82:83]
	global_load_dwordx4 v[128:131], v253, s[82:83]
	global_load_dwordx4 v[132:135], v254, s[82:83] offset:768
	global_load_dwordx4 v[136:139], v255, s[82:83] offset:768
	global_load_dwordx4 v[140:143], v254, s[82:83] offset:832
	global_load_dwordx4 v[144:147], v255, s[82:83] offset:832
	s_waitcnt vmcnt(16)
	ds_write_b128 v247, v[156:159]
	ds_write_b128 v247, v[160:163] offset:1024
	ds_write_b128 v247, v[164:167] offset:2048
	ds_write_b128 v247, v[168:171] offset:3072
	ds_read_b128 v[156:159], v248
	ds_read_b128 v[160:163], v249
	ds_read_b128 v[164:167], v250
	ds_read_b128 v[168:171], v251
	ds_write_b128 v112, v[172:175]
	ds_write_b128 v112, v[176:179] offset:1024
	ds_write_b128 v112, v[180:183] offset:2048
	ds_write_b128 v112, v[184:187] offset:3072
	ds_read2_b32 v[32:33], v115 offset0:64 offset1:65
	ds_read2_b32 v[34:35], v115 offset0:66 offset1:67
	ds_read2_b32 v[36:37], v115 offset0:72 offset1:73
	ds_read2_b32 v[38:39], v115 offset0:74 offset1:75
	ds_read2_b32 v[40:41], v115 offset0:80 offset1:81
	ds_read2_b32 v[42:43], v115 offset0:82 offset1:83
	ds_read2_b32 v[44:45], v115 offset0:88 offset1:89
	ds_read2_b32 v[46:47], v115 offset0:90 offset1:91
	s_waitcnt lgkmcnt(0)
	v_mfma_f32_32x32x16_bf16 v[32:47], v[156:159], v[48:51], v[32:47]
	ds_read_b64_tr_b16 v[72:73], v231
	ds_read_b64_tr_b16 v[74:75], v231 offset:512
	ds_read_b64_tr_b16 v[76:77], v231 offset:2048
	ds_read_b64_tr_b16 v[78:79], v231 offset:2560
	ds_read_b64_tr_b16 v[220:221], v231 offset:1024
	ds_read_b64_tr_b16 v[222:223], v231 offset:1536
	ds_read_b64_tr_b16 v[224:225], v231 offset:3072
	ds_read_b64_tr_b16 v[226:227], v231 offset:3584
	v_mfma_f32_32x32x16_bf16 v[32:47], v[160:163], v[52:55], v[32:47]
	v_mfma_f32_32x32x16_bf16 v[32:47], v[164:167], v[56:59], v[32:47]
	v_mfma_f32_32x32x16_bf16 v[32:47], v[168:171], v[60:63], v[32:47]
	s_nop 11
	v_exp_f32_e32 v32, v32
	v_exp_f32_e32 v33, v33
	v_exp_f32_e32 v34, v34
	v_exp_f32_e32 v35, v35
	v_exp_f32_e32 v36, v36
	v_exp_f32_e32 v37, v37
	v_exp_f32_e32 v38, v38
	v_exp_f32_e32 v39, v39
	v_exp_f32_e32 v40, v40
	v_exp_f32_e32 v41, v41
	v_exp_f32_e32 v42, v42
	v_exp_f32_e32 v43, v43
	v_exp_f32_e32 v44, v44
	v_exp_f32_e32 v45, v45
	v_exp_f32_e32 v46, v46
	v_exp_f32_e32 v47, v47
	s_add_i32 s90, s67, 0
	v_lshlrev_b32_e32 v84, 2, v107
	v_add_u32_e32 v84, s90, v84
	v_add_u32_e32 v85, 0, v84
	v_add_u32_e32 v86, 4, v84
	v_add_u32_e32 v87, 8, v84
	v_add_u32_e32 v88, 12, v84
	v_cmp_gt_u32_e64 s[30:31], s98, v85
	v_cmp_gt_u32_e64 s[36:37], s98, v86
	v_cmp_gt_u32_e64 s[78:79], s98, v87
	v_cmp_gt_u32_e64 s[50:51], s98, v88
	v_cndmask_b32_e64 v32, 0, v32, s[30:31]
	v_add_u32_e32 v85, 32, v84
	v_cmp_gt_u32_e64 s[30:31], s98, v85
	v_cndmask_b32_e64 v33, 0, v33, s[36:37]
	v_add_u32_e32 v86, 36, v84
	v_cmp_gt_u32_e64 s[36:37], s98, v86
	v_cndmask_b32_e64 v34, 0, v34, s[78:79]
	v_add_u32_e32 v87, 40, v84
	v_cmp_gt_u32_e64 s[78:79], s98, v87
	v_cndmask_b32_e64 v35, 0, v35, s[50:51]
	v_add_u32_e32 v88, 44, v84
	v_cmp_gt_u32_e64 s[50:51], s98, v88
	v_cndmask_b32_e64 v36, 0, v36, s[30:31]
	v_add_u32_e32 v85, 64, v84
	v_cmp_gt_u32_e64 s[30:31], s98, v85
	v_cndmask_b32_e64 v37, 0, v37, s[36:37]
	v_add_u32_e32 v86, 68, v84
	v_cmp_gt_u32_e64 s[36:37], s98, v86
	v_cndmask_b32_e64 v38, 0, v38, s[78:79]
	v_add_u32_e32 v87, 72, v84
	v_cmp_gt_u32_e64 s[78:79], s98, v87
	v_cndmask_b32_e64 v39, 0, v39, s[50:51]
	v_add_u32_e32 v88, 76, v84
	v_cmp_gt_u32_e64 s[50:51], s98, v88
	v_cndmask_b32_e64 v40, 0, v40, s[30:31]
	v_add_u32_e32 v85, 96, v84
	v_cmp_gt_u32_e64 s[30:31], s98, v85
	v_cndmask_b32_e64 v41, 0, v41, s[36:37]
	v_add_u32_e32 v86, 100, v84
	v_cmp_gt_u32_e64 s[36:37], s98, v86
	v_cndmask_b32_e64 v42, 0, v42, s[78:79]
	v_add_u32_e32 v87, 104, v84
	v_cmp_gt_u32_e64 s[78:79], s98, v87
	v_cndmask_b32_e64 v43, 0, v43, s[50:51]
	v_add_u32_e32 v88, 108, v84
	v_cmp_gt_u32_e64 s[50:51], s98, v88
	v_nop
	v_cndmask_b32_e64 v44, 0, v44, s[30:31]
	v_cndmask_b32_e64 v45, 0, v45, s[36:37]
	v_cndmask_b32_e64 v46, 0, v46, s[78:79]
	v_cndmask_b32_e64 v47, 0, v47, s[50:51]
	v_cvt_pk_bf16_f32 v64, v32, v33
	v_cvt_pk_bf16_f32 v65, v34, v35
	v_cvt_pk_bf16_f32 v66, v36, v37
	v_cvt_pk_bf16_f32 v67, v38, v39
	v_cvt_pk_bf16_f32 v68, v40, v41
	v_cvt_pk_bf16_f32 v69, v42, v43
	v_cvt_pk_bf16_f32 v70, v44, v45
	v_cvt_pk_bf16_f32 v71, v46, v47
	v_pk_add_f32 v[232:233], v[232:233], v[32:33]
	v_pk_add_f32 v[232:233], v[232:233], v[34:35]
	v_pk_add_f32 v[232:233], v[232:233], v[36:37]
	v_pk_add_f32 v[232:233], v[232:233], v[38:39]
	v_pk_add_f32 v[232:233], v[232:233], v[40:41]
	v_pk_add_f32 v[232:233], v[232:233], v[42:43]
	v_pk_add_f32 v[232:233], v[232:233], v[44:45]
	v_pk_add_f32 v[232:233], v[232:233], v[46:47]
	s_waitcnt lgkmcnt(0)
	v_mfma_f32_32x32x16_bf16 v[0:15], v[64:67], v[72:75], v[0:15]
	v_mfma_f32_32x32x16_bf16 v[16:31], v[64:67], v[76:79], v[16:31]
	v_mfma_f32_32x32x16_bf16 v[0:15], v[68:71], v[220:223], v[0:15]
	v_mfma_f32_32x32x16_bf16 v[16:31], v[68:71], v[224:227], v[16:31]
	s_add_i32 s90, s67, 384
	v_add_u32_e32 v80, s90, v239
	v_add_u32_e32 v83, s90, v240
	v_add_u32_e32 v99, s90, v241
	v_add_u32_e32 v253, s90, v242
	v_add_u32_e32 v254, s90, v101
	v_add_u32_e32 v255, s90, v150
	v_med3_i32 v80, v80, 0, s99
	v_med3_i32 v83, v83, 0, s99
	v_med3_i32 v99, v99, 0, s99
	v_med3_i32 v253, v253, 0, s99
	v_med3_i32 v254, v254, 0, s99
	v_med3_i32 v255, v255, 0, s99
	v_mad_u32_u24 v80, v80, s100, v252
	v_mad_u32_u24 v83, v83, s100, v252
	v_mad_u32_u24 v99, v99, s100, v252
	v_mad_u32_u24 v253, v253, s100, v252
	v_mad_u32_u24 v254, v254, s100, v153
	v_mad_u32_u24 v255, v255, s100, v153
	global_load_dwordx4 v[156:159], v80, s[82:83]
	global_load_dwordx4 v[160:163], v83, s[82:83]
	global_load_dwordx4 v[164:167], v99, s[82:83]
	global_load_dwordx4 v[168:171], v253, s[82:83]
	global_load_dwordx4 v[172:175], v254, s[82:83] offset:768
	global_load_dwordx4 v[176:179], v255, s[82:83] offset:768
	global_load_dwordx4 v[180:183], v254, s[82:83] offset:832
	global_load_dwordx4 v[184:187], v255, s[82:83] offset:832
	s_waitcnt vmcnt(16)
	ds_write_b128 v247, v[188:191]
	ds_write_b128 v247, v[192:195] offset:1024
	ds_write_b128 v247, v[196:199] offset:2048
	ds_write_b128 v247, v[200:203] offset:3072
	ds_read_b128 v[188:191], v248
	ds_read_b128 v[192:195], v249
	ds_read_b128 v[196:199], v250
	ds_read_b128 v[200:203], v251
	ds_write_b128 v112, v[204:207]
	ds_write_b128 v112, v[208:211] offset:1024
	ds_write_b128 v112, v[212:215] offset:2048
	ds_write_b128 v112, v[216:219] offset:3072
	ds_read2_b32 v[32:33], v115 offset0:96 offset1:97
	ds_read2_b32 v[34:35], v115 offset0:98 offset1:99
	ds_read2_b32 v[36:37], v115 offset0:104 offset1:105
	ds_read2_b32 v[38:39], v115 offset0:106 offset1:107
	ds_read2_b32 v[40:41], v115 offset0:112 offset1:113
	ds_read2_b32 v[42:43], v115 offset0:114 offset1:115
	ds_read2_b32 v[44:45], v115 offset0:120 offset1:121
	ds_read2_b32 v[46:47], v115 offset0:122 offset1:123
	s_waitcnt lgkmcnt(0)
	v_mfma_f32_32x32x16_bf16 v[32:47], v[188:191], v[48:51], v[32:47]
	ds_read_b64_tr_b16 v[72:73], v231
	ds_read_b64_tr_b16 v[74:75], v231 offset:512
	ds_read_b64_tr_b16 v[76:77], v231 offset:2048
	ds_read_b64_tr_b16 v[78:79], v231 offset:2560
	ds_read_b64_tr_b16 v[220:221], v231 offset:1024
	ds_read_b64_tr_b16 v[222:223], v231 offset:1536
	ds_read_b64_tr_b16 v[224:225], v231 offset:3072
	ds_read_b64_tr_b16 v[226:227], v231 offset:3584
	v_mfma_f32_32x32x16_bf16 v[32:47], v[192:195], v[52:55], v[32:47]
	v_mfma_f32_32x32x16_bf16 v[32:47], v[196:199], v[56:59], v[32:47]
	v_mfma_f32_32x32x16_bf16 v[32:47], v[200:203], v[60:63], v[32:47]
	s_nop 11
	v_exp_f32_e32 v32, v32
	v_exp_f32_e32 v33, v33
	v_exp_f32_e32 v34, v34
	v_exp_f32_e32 v35, v35
	v_exp_f32_e32 v36, v36
	v_exp_f32_e32 v37, v37
	v_exp_f32_e32 v38, v38
	v_exp_f32_e32 v39, v39
	v_exp_f32_e32 v40, v40
	v_exp_f32_e32 v41, v41
	v_exp_f32_e32 v42, v42
	v_exp_f32_e32 v43, v43
	v_exp_f32_e32 v44, v44
	v_exp_f32_e32 v45, v45
	v_exp_f32_e32 v46, v46
	v_exp_f32_e32 v47, v47
	s_add_i32 s90, s67, 128
	v_lshlrev_b32_e32 v84, 2, v107
	v_add_u32_e32 v84, s90, v84
	v_add_u32_e32 v85, 0, v84
	v_add_u32_e32 v86, 4, v84
	v_add_u32_e32 v87, 8, v84
	v_add_u32_e32 v88, 12, v84
	v_cmp_gt_u32_e64 s[30:31], s98, v85
	v_cmp_gt_u32_e64 s[36:37], s98, v86
	v_cmp_gt_u32_e64 s[78:79], s98, v87
	v_cmp_gt_u32_e64 s[50:51], s98, v88
	v_cndmask_b32_e64 v32, 0, v32, s[30:31]
	v_add_u32_e32 v85, 32, v84
	v_cmp_gt_u32_e64 s[30:31], s98, v85
	v_cndmask_b32_e64 v33, 0, v33, s[36:37]
	v_add_u32_e32 v86, 36, v84
	v_cmp_gt_u32_e64 s[36:37], s98, v86
	v_cndmask_b32_e64 v34, 0, v34, s[78:79]
	v_add_u32_e32 v87, 40, v84
	v_cmp_gt_u32_e64 s[78:79], s98, v87
	v_cndmask_b32_e64 v35, 0, v35, s[50:51]
	v_add_u32_e32 v88, 44, v84
	v_cmp_gt_u32_e64 s[50:51], s98, v88
	v_cndmask_b32_e64 v36, 0, v36, s[30:31]
	v_add_u32_e32 v85, 64, v84
	v_cmp_gt_u32_e64 s[30:31], s98, v85
	v_cndmask_b32_e64 v37, 0, v37, s[36:37]
	v_add_u32_e32 v86, 68, v84
	v_cmp_gt_u32_e64 s[36:37], s98, v86
	v_cndmask_b32_e64 v38, 0, v38, s[78:79]
	v_add_u32_e32 v87, 72, v84
	v_cmp_gt_u32_e64 s[78:79], s98, v87
	v_cndmask_b32_e64 v39, 0, v39, s[50:51]
	v_add_u32_e32 v88, 76, v84
	v_cmp_gt_u32_e64 s[50:51], s98, v88
	v_cndmask_b32_e64 v40, 0, v40, s[30:31]
	v_add_u32_e32 v85, 96, v84
	v_cmp_gt_u32_e64 s[30:31], s98, v85
	v_cndmask_b32_e64 v41, 0, v41, s[36:37]
	v_add_u32_e32 v86, 100, v84
	v_cmp_gt_u32_e64 s[36:37], s98, v86
	v_cndmask_b32_e64 v42, 0, v42, s[78:79]
	v_add_u32_e32 v87, 104, v84
	v_cmp_gt_u32_e64 s[78:79], s98, v87
	v_cndmask_b32_e64 v43, 0, v43, s[50:51]
	v_add_u32_e32 v88, 108, v84
	v_cmp_gt_u32_e64 s[50:51], s98, v88
	v_nop
	v_cndmask_b32_e64 v44, 0, v44, s[30:31]
	v_cndmask_b32_e64 v45, 0, v45, s[36:37]
	v_cndmask_b32_e64 v46, 0, v46, s[78:79]
	v_cndmask_b32_e64 v47, 0, v47, s[50:51]
	v_cvt_pk_bf16_f32 v64, v32, v33
	v_cvt_pk_bf16_f32 v65, v34, v35
	v_cvt_pk_bf16_f32 v66, v36, v37
	v_cvt_pk_bf16_f32 v67, v38, v39
	v_cvt_pk_bf16_f32 v68, v40, v41
	v_cvt_pk_bf16_f32 v69, v42, v43
	v_cvt_pk_bf16_f32 v70, v44, v45
	v_cvt_pk_bf16_f32 v71, v46, v47
	v_pk_add_f32 v[232:233], v[232:233], v[32:33]
	v_pk_add_f32 v[232:233], v[232:233], v[34:35]
	v_pk_add_f32 v[232:233], v[232:233], v[36:37]
	v_pk_add_f32 v[232:233], v[232:233], v[38:39]
	v_pk_add_f32 v[232:233], v[232:233], v[40:41]
	v_pk_add_f32 v[232:233], v[232:233], v[42:43]
	v_pk_add_f32 v[232:233], v[232:233], v[44:45]
	v_pk_add_f32 v[232:233], v[232:233], v[46:47]
	s_waitcnt lgkmcnt(0)
	v_mfma_f32_32x32x16_bf16 v[0:15], v[64:67], v[72:75], v[0:15]
	v_mfma_f32_32x32x16_bf16 v[16:31], v[64:67], v[76:79], v[16:31]
	v_mfma_f32_32x32x16_bf16 v[0:15], v[68:71], v[220:223], v[0:15]
	v_mfma_f32_32x32x16_bf16 v[16:31], v[68:71], v[224:227], v[16:31]
	s_add_i32 s90, s67, 512
	v_add_u32_e32 v80, s90, v239
	v_add_u32_e32 v83, s90, v240
	v_add_u32_e32 v99, s90, v241
	v_add_u32_e32 v253, s90, v242
	v_add_u32_e32 v254, s90, v101
	v_add_u32_e32 v255, s90, v150
	v_med3_i32 v80, v80, 0, s99
	v_med3_i32 v83, v83, 0, s99
	v_med3_i32 v99, v99, 0, s99
	v_med3_i32 v253, v253, 0, s99
	v_med3_i32 v254, v254, 0, s99
	v_med3_i32 v255, v255, 0, s99
	v_mad_u32_u24 v80, v80, s100, v252
	v_mad_u32_u24 v83, v83, s100, v252
	v_mad_u32_u24 v99, v99, s100, v252
	v_mad_u32_u24 v253, v253, s100, v252
	v_mad_u32_u24 v254, v254, s100, v153
	v_mad_u32_u24 v255, v255, s100, v153
	global_load_dwordx4 v[188:191], v80, s[82:83]
	global_load_dwordx4 v[192:195], v83, s[82:83]
	global_load_dwordx4 v[196:199], v99, s[82:83]
	global_load_dwordx4 v[200:203], v253, s[82:83]
	global_load_dwordx4 v[204:207], v254, s[82:83] offset:768
	global_load_dwordx4 v[208:211], v255, s[82:83] offset:768
	global_load_dwordx4 v[212:215], v254, s[82:83] offset:832
	global_load_dwordx4 v[216:219], v255, s[82:83] offset:832
	s_waitcnt vmcnt(16)
	ds_write_b128 v247, v[116:119]
	ds_write_b128 v247, v[120:123] offset:1024
	ds_write_b128 v247, v[124:127] offset:2048
	ds_write_b128 v247, v[128:131] offset:3072
	ds_read_b128 v[116:119], v248
	ds_read_b128 v[120:123], v249
	ds_read_b128 v[124:127], v250
	ds_read_b128 v[128:131], v251
	ds_write_b128 v112, v[132:135]
	ds_write_b128 v112, v[136:139] offset:1024
	ds_write_b128 v112, v[140:143] offset:2048
	ds_write_b128 v112, v[144:147] offset:3072
	ds_read2_b32 v[32:33], v115 offset0:128 offset1:129
	ds_read2_b32 v[34:35], v115 offset0:130 offset1:131
	ds_read2_b32 v[36:37], v115 offset0:136 offset1:137
	ds_read2_b32 v[38:39], v115 offset0:138 offset1:139
	ds_read2_b32 v[40:41], v115 offset0:144 offset1:145
	ds_read2_b32 v[42:43], v115 offset0:146 offset1:147
	ds_read2_b32 v[44:45], v115 offset0:152 offset1:153
	ds_read2_b32 v[46:47], v115 offset0:154 offset1:155
	s_waitcnt lgkmcnt(0)
	v_mfma_f32_32x32x16_bf16 v[32:47], v[116:119], v[48:51], v[32:47]
	ds_read_b64_tr_b16 v[72:73], v231
	ds_read_b64_tr_b16 v[74:75], v231 offset:512
	ds_read_b64_tr_b16 v[76:77], v231 offset:2048
	ds_read_b64_tr_b16 v[78:79], v231 offset:2560
	ds_read_b64_tr_b16 v[220:221], v231 offset:1024
	ds_read_b64_tr_b16 v[222:223], v231 offset:1536
	ds_read_b64_tr_b16 v[224:225], v231 offset:3072
	ds_read_b64_tr_b16 v[226:227], v231 offset:3584
	v_mfma_f32_32x32x16_bf16 v[32:47], v[120:123], v[52:55], v[32:47]
	v_mfma_f32_32x32x16_bf16 v[32:47], v[124:127], v[56:59], v[32:47]
	v_mfma_f32_32x32x16_bf16 v[32:47], v[128:131], v[60:63], v[32:47]
	s_nop 11
	v_exp_f32_e32 v32, v32
	v_exp_f32_e32 v33, v33
	v_exp_f32_e32 v34, v34
	v_exp_f32_e32 v35, v35
	v_exp_f32_e32 v36, v36
	v_exp_f32_e32 v37, v37
	v_exp_f32_e32 v38, v38
	v_exp_f32_e32 v39, v39
	v_exp_f32_e32 v40, v40
	v_exp_f32_e32 v41, v41
	v_exp_f32_e32 v42, v42
	v_exp_f32_e32 v43, v43
	v_exp_f32_e32 v44, v44
	v_exp_f32_e32 v45, v45
	v_exp_f32_e32 v46, v46
	v_exp_f32_e32 v47, v47
	s_add_i32 s90, s67, 256
	v_lshlrev_b32_e32 v84, 2, v107
	v_add_u32_e32 v84, s90, v84
	v_add_u32_e32 v85, 0, v84
	v_add_u32_e32 v86, 4, v84
	v_add_u32_e32 v87, 8, v84
	v_add_u32_e32 v88, 12, v84
	v_cmp_gt_u32_e64 s[30:31], s98, v85
	v_cmp_gt_u32_e64 s[36:37], s98, v86
	v_cmp_gt_u32_e64 s[78:79], s98, v87
	v_cmp_gt_u32_e64 s[50:51], s98, v88
	v_cndmask_b32_e64 v32, 0, v32, s[30:31]
	v_add_u32_e32 v85, 32, v84
	v_cmp_gt_u32_e64 s[30:31], s98, v85
	v_cndmask_b32_e64 v33, 0, v33, s[36:37]
	v_add_u32_e32 v86, 36, v84
	v_cmp_gt_u32_e64 s[36:37], s98, v86
	v_cndmask_b32_e64 v34, 0, v34, s[78:79]
	v_add_u32_e32 v87, 40, v84
	v_cmp_gt_u32_e64 s[78:79], s98, v87
	v_cndmask_b32_e64 v35, 0, v35, s[50:51]
	v_add_u32_e32 v88, 44, v84
	v_cmp_gt_u32_e64 s[50:51], s98, v88
	v_cndmask_b32_e64 v36, 0, v36, s[30:31]
	v_add_u32_e32 v85, 64, v84
	v_cmp_gt_u32_e64 s[30:31], s98, v85
	v_cndmask_b32_e64 v37, 0, v37, s[36:37]
	v_add_u32_e32 v86, 68, v84
	v_cmp_gt_u32_e64 s[36:37], s98, v86
	v_cndmask_b32_e64 v38, 0, v38, s[78:79]
	v_add_u32_e32 v87, 72, v84
	v_cmp_gt_u32_e64 s[78:79], s98, v87
	v_cndmask_b32_e64 v39, 0, v39, s[50:51]
	v_add_u32_e32 v88, 76, v84
	v_cmp_gt_u32_e64 s[50:51], s98, v88
	v_cndmask_b32_e64 v40, 0, v40, s[30:31]
	v_add_u32_e32 v85, 96, v84
	v_cmp_gt_u32_e64 s[30:31], s98, v85
	v_cndmask_b32_e64 v41, 0, v41, s[36:37]
	v_add_u32_e32 v86, 100, v84
	v_cmp_gt_u32_e64 s[36:37], s98, v86
	v_cndmask_b32_e64 v42, 0, v42, s[78:79]
	v_add_u32_e32 v87, 104, v84
	v_cmp_gt_u32_e64 s[78:79], s98, v87
	v_cndmask_b32_e64 v43, 0, v43, s[50:51]
	v_add_u32_e32 v88, 108, v84
	v_cmp_gt_u32_e64 s[50:51], s98, v88
	v_nop
	v_cndmask_b32_e64 v44, 0, v44, s[30:31]
	v_cndmask_b32_e64 v45, 0, v45, s[36:37]
	v_cndmask_b32_e64 v46, 0, v46, s[78:79]
	v_cndmask_b32_e64 v47, 0, v47, s[50:51]
	v_cvt_pk_bf16_f32 v64, v32, v33
	v_cvt_pk_bf16_f32 v65, v34, v35
	v_cvt_pk_bf16_f32 v66, v36, v37
	v_cvt_pk_bf16_f32 v67, v38, v39
	v_cvt_pk_bf16_f32 v68, v40, v41
	v_cvt_pk_bf16_f32 v69, v42, v43
	v_cvt_pk_bf16_f32 v70, v44, v45
	v_cvt_pk_bf16_f32 v71, v46, v47
	v_pk_add_f32 v[232:233], v[232:233], v[32:33]
	v_pk_add_f32 v[232:233], v[232:233], v[34:35]
	v_pk_add_f32 v[232:233], v[232:233], v[36:37]
	v_pk_add_f32 v[232:233], v[232:233], v[38:39]
	v_pk_add_f32 v[232:233], v[232:233], v[40:41]
	v_pk_add_f32 v[232:233], v[232:233], v[42:43]
	v_pk_add_f32 v[232:233], v[232:233], v[44:45]
	v_pk_add_f32 v[232:233], v[232:233], v[46:47]
	s_waitcnt lgkmcnt(0)
	v_mfma_f32_32x32x16_bf16 v[0:15], v[64:67], v[72:75], v[0:15]
	v_mfma_f32_32x32x16_bf16 v[16:31], v[64:67], v[76:79], v[16:31]
	v_mfma_f32_32x32x16_bf16 v[0:15], v[68:71], v[220:223], v[0:15]
	v_mfma_f32_32x32x16_bf16 v[16:31], v[68:71], v[224:227], v[16:31]
	s_add_i32 s90, s67, 640
	v_add_u32_e32 v80, s90, v239
	v_add_u32_e32 v83, s90, v240
	v_add_u32_e32 v99, s90, v241
	v_add_u32_e32 v253, s90, v242
	v_add_u32_e32 v254, s90, v101
	v_add_u32_e32 v255, s90, v150
	v_med3_i32 v80, v80, 0, s99
	v_med3_i32 v83, v83, 0, s99
	v_med3_i32 v99, v99, 0, s99
	v_med3_i32 v253, v253, 0, s99
	v_med3_i32 v254, v254, 0, s99
	v_med3_i32 v255, v255, 0, s99
	v_mad_u32_u24 v80, v80, s100, v252
	v_mad_u32_u24 v83, v83, s100, v252
	v_mad_u32_u24 v99, v99, s100, v252
	v_mad_u32_u24 v253, v253, s100, v252
	v_mad_u32_u24 v254, v254, s100, v153
	v_mad_u32_u24 v255, v255, s100, v153
	global_load_dwordx4 v[116:119], v80, s[82:83]
	global_load_dwordx4 v[120:123], v83, s[82:83]
	global_load_dwordx4 v[124:127], v99, s[82:83]
	global_load_dwordx4 v[128:131], v253, s[82:83]
	global_load_dwordx4 v[132:135], v254, s[82:83] offset:768
	global_load_dwordx4 v[136:139], v255, s[82:83] offset:768
	global_load_dwordx4 v[140:143], v254, s[82:83] offset:832
	global_load_dwordx4 v[144:147], v255, s[82:83] offset:832
	s_waitcnt vmcnt(16)
	ds_write_b128 v247, v[156:159]
	ds_write_b128 v247, v[160:163] offset:1024
	ds_write_b128 v247, v[164:167] offset:2048
	ds_write_b128 v247, v[168:171] offset:3072
	ds_read_b128 v[156:159], v248
	ds_read_b128 v[160:163], v249
	ds_read_b128 v[164:167], v250
	ds_read_b128 v[168:171], v251
	ds_write_b128 v112, v[172:175]
	ds_write_b128 v112, v[176:179] offset:1024
	ds_write_b128 v112, v[180:183] offset:2048
	ds_write_b128 v112, v[184:187] offset:3072
	ds_read2_b32 v[32:33], v115 offset0:160 offset1:161
	ds_read2_b32 v[34:35], v115 offset0:162 offset1:163
	ds_read2_b32 v[36:37], v115 offset0:168 offset1:169
	ds_read2_b32 v[38:39], v115 offset0:170 offset1:171
	ds_read2_b32 v[40:41], v115 offset0:176 offset1:177
	ds_read2_b32 v[42:43], v115 offset0:178 offset1:179
	ds_read2_b32 v[44:45], v115 offset0:184 offset1:185
	ds_read2_b32 v[46:47], v115 offset0:186 offset1:187
	s_waitcnt lgkmcnt(0)
	v_mfma_f32_32x32x16_bf16 v[32:47], v[156:159], v[48:51], v[32:47]
	ds_read_b64_tr_b16 v[72:73], v231
	ds_read_b64_tr_b16 v[74:75], v231 offset:512
	ds_read_b64_tr_b16 v[76:77], v231 offset:2048
	ds_read_b64_tr_b16 v[78:79], v231 offset:2560
	ds_read_b64_tr_b16 v[220:221], v231 offset:1024
	ds_read_b64_tr_b16 v[222:223], v231 offset:1536
	ds_read_b64_tr_b16 v[224:225], v231 offset:3072
	ds_read_b64_tr_b16 v[226:227], v231 offset:3584
	v_mfma_f32_32x32x16_bf16 v[32:47], v[160:163], v[52:55], v[32:47]
	v_mfma_f32_32x32x16_bf16 v[32:47], v[164:167], v[56:59], v[32:47]
	v_mfma_f32_32x32x16_bf16 v[32:47], v[168:171], v[60:63], v[32:47]
	s_nop 11
	v_exp_f32_e32 v32, v32
	v_exp_f32_e32 v33, v33
	v_exp_f32_e32 v34, v34
	v_exp_f32_e32 v35, v35
	v_exp_f32_e32 v36, v36
	v_exp_f32_e32 v37, v37
	v_exp_f32_e32 v38, v38
	v_exp_f32_e32 v39, v39
	v_exp_f32_e32 v40, v40
	v_exp_f32_e32 v41, v41
	v_exp_f32_e32 v42, v42
	v_exp_f32_e32 v43, v43
	v_exp_f32_e32 v44, v44
	v_exp_f32_e32 v45, v45
	v_exp_f32_e32 v46, v46
	v_exp_f32_e32 v47, v47
	s_add_i32 s90, s67, 384
	v_lshlrev_b32_e32 v84, 2, v107
	v_add_u32_e32 v84, s90, v84
	v_add_u32_e32 v85, 0, v84
	v_add_u32_e32 v86, 4, v84
	v_add_u32_e32 v87, 8, v84
	v_add_u32_e32 v88, 12, v84
	v_cmp_gt_u32_e64 s[30:31], s98, v85
	v_cmp_gt_u32_e64 s[36:37], s98, v86
	v_cmp_gt_u32_e64 s[78:79], s98, v87
	v_cmp_gt_u32_e64 s[50:51], s98, v88
	v_cndmask_b32_e64 v32, 0, v32, s[30:31]
	v_add_u32_e32 v85, 32, v84
	v_cmp_gt_u32_e64 s[30:31], s98, v85
	v_cndmask_b32_e64 v33, 0, v33, s[36:37]
	v_add_u32_e32 v86, 36, v84
	v_cmp_gt_u32_e64 s[36:37], s98, v86
	v_cndmask_b32_e64 v34, 0, v34, s[78:79]
	v_add_u32_e32 v87, 40, v84
	v_cmp_gt_u32_e64 s[78:79], s98, v87
	v_cndmask_b32_e64 v35, 0, v35, s[50:51]
	v_add_u32_e32 v88, 44, v84
	v_cmp_gt_u32_e64 s[50:51], s98, v88
	v_cndmask_b32_e64 v36, 0, v36, s[30:31]
	v_add_u32_e32 v85, 64, v84
	v_cmp_gt_u32_e64 s[30:31], s98, v85
	v_cndmask_b32_e64 v37, 0, v37, s[36:37]
	v_add_u32_e32 v86, 68, v84
	v_cmp_gt_u32_e64 s[36:37], s98, v86
	v_cndmask_b32_e64 v38, 0, v38, s[78:79]
	v_add_u32_e32 v87, 72, v84
	v_cmp_gt_u32_e64 s[78:79], s98, v87
	v_cndmask_b32_e64 v39, 0, v39, s[50:51]
	v_add_u32_e32 v88, 76, v84
	v_cmp_gt_u32_e64 s[50:51], s98, v88
	v_cndmask_b32_e64 v40, 0, v40, s[30:31]
	v_add_u32_e32 v85, 96, v84
	v_cmp_gt_u32_e64 s[30:31], s98, v85
	v_cndmask_b32_e64 v41, 0, v41, s[36:37]
	v_add_u32_e32 v86, 100, v84
	v_cmp_gt_u32_e64 s[36:37], s98, v86
	v_cndmask_b32_e64 v42, 0, v42, s[78:79]
	v_add_u32_e32 v87, 104, v84
	v_cmp_gt_u32_e64 s[78:79], s98, v87
	v_cndmask_b32_e64 v43, 0, v43, s[50:51]
	v_add_u32_e32 v88, 108, v84
	v_cmp_gt_u32_e64 s[50:51], s98, v88
	v_nop
	v_cndmask_b32_e64 v44, 0, v44, s[30:31]
	v_cndmask_b32_e64 v45, 0, v45, s[36:37]
	v_cndmask_b32_e64 v46, 0, v46, s[78:79]
	v_cndmask_b32_e64 v47, 0, v47, s[50:51]
	v_cvt_pk_bf16_f32 v64, v32, v33
	v_cvt_pk_bf16_f32 v65, v34, v35
	v_cvt_pk_bf16_f32 v66, v36, v37
	v_cvt_pk_bf16_f32 v67, v38, v39
	v_cvt_pk_bf16_f32 v68, v40, v41
	v_cvt_pk_bf16_f32 v69, v42, v43
	v_cvt_pk_bf16_f32 v70, v44, v45
	v_cvt_pk_bf16_f32 v71, v46, v47
	v_pk_add_f32 v[232:233], v[232:233], v[32:33]
	v_pk_add_f32 v[232:233], v[232:233], v[34:35]
	v_pk_add_f32 v[232:233], v[232:233], v[36:37]
	v_pk_add_f32 v[232:233], v[232:233], v[38:39]
	v_pk_add_f32 v[232:233], v[232:233], v[40:41]
	v_pk_add_f32 v[232:233], v[232:233], v[42:43]
	v_pk_add_f32 v[232:233], v[232:233], v[44:45]
	v_pk_add_f32 v[232:233], v[232:233], v[46:47]
	s_waitcnt lgkmcnt(0)
	v_mfma_f32_32x32x16_bf16 v[0:15], v[64:67], v[72:75], v[0:15]
	v_mfma_f32_32x32x16_bf16 v[16:31], v[64:67], v[76:79], v[16:31]
	v_mfma_f32_32x32x16_bf16 v[0:15], v[68:71], v[220:223], v[0:15]
	v_mfma_f32_32x32x16_bf16 v[16:31], v[68:71], v[224:227], v[16:31]
	s_add_i32 s90, s67, -1024
	v_add_u32_e32 v80, s90, v243
	v_add_u32_e32 v83, s90, v244
	v_add_u32_e32 v99, s90, v245
	v_add_u32_e32 v253, s90, v246
	v_add_u32_e32 v254, s90, v148
	v_add_u32_e32 v255, s90, v151
	v_med3_i32 v80, v80, 0, s99
	v_med3_i32 v83, v83, 0, s99
	v_med3_i32 v99, v99, 0, s99
	v_med3_i32 v253, v253, 0, s99
	v_med3_i32 v254, v254, 0, s99
	v_med3_i32 v255, v255, 0, s99
	v_mad_u32_u24 v80, v80, s100, v252
	v_mad_u32_u24 v83, v83, s100, v252
	v_mad_u32_u24 v99, v99, s100, v252
	v_mad_u32_u24 v253, v253, s100, v252
	v_mad_u32_u24 v254, v254, s100, v153
	v_mad_u32_u24 v255, v255, s100, v153
	global_load_dwordx4 v[156:159], v80, s[82:83]
	global_load_dwordx4 v[160:163], v83, s[82:83]
	global_load_dwordx4 v[164:167], v99, s[82:83]
	global_load_dwordx4 v[168:171], v253, s[82:83]
	global_load_dwordx4 v[172:175], v254, s[82:83] offset:768
	global_load_dwordx4 v[176:179], v255, s[82:83] offset:768
	global_load_dwordx4 v[180:183], v254, s[82:83] offset:832
	global_load_dwordx4 v[184:187], v255, s[82:83] offset:832
	s_waitcnt vmcnt(16)
	ds_write_b128 v247, v[188:191]
	ds_write_b128 v247, v[192:195] offset:1024
	ds_write_b128 v247, v[196:199] offset:2048
	ds_write_b128 v247, v[200:203] offset:3072
	ds_read_b128 v[188:191], v248
	ds_read_b128 v[192:195], v249
	ds_read_b128 v[196:199], v250
	ds_read_b128 v[200:203], v251
	ds_write_b128 v112, v[204:207]
	ds_write_b128 v112, v[208:211] offset:1024
	ds_write_b128 v112, v[212:215] offset:2048
	ds_write_b128 v112, v[216:219] offset:3072
	ds_read2_b32 v[32:33], v115 offset0:192 offset1:193
	ds_read2_b32 v[34:35], v115 offset0:194 offset1:195
	ds_read2_b32 v[36:37], v115 offset0:200 offset1:201
	ds_read2_b32 v[38:39], v115 offset0:202 offset1:203
	ds_read2_b32 v[40:41], v115 offset0:208 offset1:209
	ds_read2_b32 v[42:43], v115 offset0:210 offset1:211
	ds_read2_b32 v[44:45], v115 offset0:216 offset1:217
	ds_read2_b32 v[46:47], v115 offset0:218 offset1:219
	s_waitcnt lgkmcnt(0)
	v_mfma_f32_32x32x16_bf16 v[32:47], v[188:191], v[48:51], v[32:47]
	ds_read_b64_tr_b16 v[72:73], v231
	ds_read_b64_tr_b16 v[74:75], v231 offset:512
	ds_read_b64_tr_b16 v[76:77], v231 offset:2048
	ds_read_b64_tr_b16 v[78:79], v231 offset:2560
	ds_read_b64_tr_b16 v[220:221], v231 offset:1024
	ds_read_b64_tr_b16 v[222:223], v231 offset:1536
	ds_read_b64_tr_b16 v[224:225], v231 offset:3072
	ds_read_b64_tr_b16 v[226:227], v231 offset:3584
	v_mfma_f32_32x32x16_bf16 v[32:47], v[192:195], v[52:55], v[32:47]
	v_mfma_f32_32x32x16_bf16 v[32:47], v[196:199], v[56:59], v[32:47]
	v_mfma_f32_32x32x16_bf16 v[32:47], v[200:203], v[60:63], v[32:47]
	s_nop 11
	v_exp_f32_e32 v32, v32
	v_exp_f32_e32 v33, v33
	v_exp_f32_e32 v34, v34
	v_exp_f32_e32 v35, v35
	v_exp_f32_e32 v36, v36
	v_exp_f32_e32 v37, v37
	v_exp_f32_e32 v38, v38
	v_exp_f32_e32 v39, v39
	v_exp_f32_e32 v40, v40
	v_exp_f32_e32 v41, v41
	v_exp_f32_e32 v42, v42
	v_exp_f32_e32 v43, v43
	v_exp_f32_e32 v44, v44
	v_exp_f32_e32 v45, v45
	v_exp_f32_e32 v46, v46
	v_exp_f32_e32 v47, v47
	s_add_i32 s90, s67, 512
	v_lshlrev_b32_e32 v84, 2, v107
	v_add_u32_e32 v84, s90, v84
	v_add_u32_e32 v85, 0, v84
	v_add_u32_e32 v86, 4, v84
	v_add_u32_e32 v87, 8, v84
	v_add_u32_e32 v88, 12, v84
	v_cmp_gt_u32_e64 s[30:31], s98, v85
	v_cmp_gt_u32_e64 s[36:37], s98, v86
	v_cmp_gt_u32_e64 s[78:79], s98, v87
	v_cmp_gt_u32_e64 s[50:51], s98, v88
	v_cndmask_b32_e64 v32, 0, v32, s[30:31]
	v_add_u32_e32 v85, 32, v84
	v_cmp_gt_u32_e64 s[30:31], s98, v85
	v_cndmask_b32_e64 v33, 0, v33, s[36:37]
	v_add_u32_e32 v86, 36, v84
	v_cmp_gt_u32_e64 s[36:37], s98, v86
	v_cndmask_b32_e64 v34, 0, v34, s[78:79]
	v_add_u32_e32 v87, 40, v84
	v_cmp_gt_u32_e64 s[78:79], s98, v87
	v_cndmask_b32_e64 v35, 0, v35, s[50:51]
	v_add_u32_e32 v88, 44, v84
	v_cmp_gt_u32_e64 s[50:51], s98, v88
	v_cndmask_b32_e64 v36, 0, v36, s[30:31]
	v_add_u32_e32 v85, 64, v84
	v_cmp_gt_u32_e64 s[30:31], s98, v85
	v_cndmask_b32_e64 v37, 0, v37, s[36:37]
	v_add_u32_e32 v86, 68, v84
	v_cmp_gt_u32_e64 s[36:37], s98, v86
	v_cndmask_b32_e64 v38, 0, v38, s[78:79]
	v_add_u32_e32 v87, 72, v84
	v_cmp_gt_u32_e64 s[78:79], s98, v87
	v_cndmask_b32_e64 v39, 0, v39, s[50:51]
	v_add_u32_e32 v88, 76, v84
	v_cmp_gt_u32_e64 s[50:51], s98, v88
	v_cndmask_b32_e64 v40, 0, v40, s[30:31]
	v_add_u32_e32 v85, 96, v84
	v_cmp_gt_u32_e64 s[30:31], s98, v85
	v_cndmask_b32_e64 v41, 0, v41, s[36:37]
	v_add_u32_e32 v86, 100, v84
	v_cmp_gt_u32_e64 s[36:37], s98, v86
	v_cndmask_b32_e64 v42, 0, v42, s[78:79]
	v_add_u32_e32 v87, 104, v84
	v_cmp_gt_u32_e64 s[78:79], s98, v87
	v_cndmask_b32_e64 v43, 0, v43, s[50:51]
	v_add_u32_e32 v88, 108, v84
	v_cmp_gt_u32_e64 s[50:51], s98, v88
	v_nop
	v_cndmask_b32_e64 v44, 0, v44, s[30:31]
	v_cndmask_b32_e64 v45, 0, v45, s[36:37]
	v_cndmask_b32_e64 v46, 0, v46, s[78:79]
	v_cndmask_b32_e64 v47, 0, v47, s[50:51]
	v_cvt_pk_bf16_f32 v64, v32, v33
	v_cvt_pk_bf16_f32 v65, v34, v35
	v_cvt_pk_bf16_f32 v66, v36, v37
	v_cvt_pk_bf16_f32 v67, v38, v39
	v_cvt_pk_bf16_f32 v68, v40, v41
	v_cvt_pk_bf16_f32 v69, v42, v43
	v_cvt_pk_bf16_f32 v70, v44, v45
	v_cvt_pk_bf16_f32 v71, v46, v47
	v_pk_add_f32 v[232:233], v[232:233], v[32:33]
	v_pk_add_f32 v[232:233], v[232:233], v[34:35]
	v_pk_add_f32 v[232:233], v[232:233], v[36:37]
	v_pk_add_f32 v[232:233], v[232:233], v[38:39]
	v_pk_add_f32 v[232:233], v[232:233], v[40:41]
	v_pk_add_f32 v[232:233], v[232:233], v[42:43]
	v_pk_add_f32 v[232:233], v[232:233], v[44:45]
	v_pk_add_f32 v[232:233], v[232:233], v[46:47]
	s_waitcnt lgkmcnt(0)
	v_mfma_f32_32x32x16_bf16 v[0:15], v[64:67], v[72:75], v[0:15]
	v_mfma_f32_32x32x16_bf16 v[16:31], v[64:67], v[76:79], v[16:31]
	v_mfma_f32_32x32x16_bf16 v[0:15], v[68:71], v[220:223], v[0:15]
	v_mfma_f32_32x32x16_bf16 v[16:31], v[68:71], v[224:227], v[16:31]
	s_add_i32 s90, s67, -512
	v_add_u32_e32 v80, s90, v243
	v_add_u32_e32 v83, s90, v244
	v_add_u32_e32 v99, s90, v245
	v_add_u32_e32 v253, s90, v246
	v_add_u32_e32 v254, s90, v148
	v_add_u32_e32 v255, s90, v151
	v_med3_i32 v80, v80, 0, s99
	v_med3_i32 v83, v83, 0, s99
	v_med3_i32 v99, v99, 0, s99
	v_med3_i32 v253, v253, 0, s99
	v_med3_i32 v254, v254, 0, s99
	v_med3_i32 v255, v255, 0, s99
	v_mad_u32_u24 v80, v80, s100, v252
	v_mad_u32_u24 v83, v83, s100, v252
	v_mad_u32_u24 v99, v99, s100, v252
	v_mad_u32_u24 v253, v253, s100, v252
	v_mad_u32_u24 v254, v254, s100, v153
	v_mad_u32_u24 v255, v255, s100, v153
	global_load_dwordx4 v[188:191], v80, s[82:83]
	global_load_dwordx4 v[192:195], v83, s[82:83]
	global_load_dwordx4 v[196:199], v99, s[82:83]
	global_load_dwordx4 v[200:203], v253, s[82:83]
	global_load_dwordx4 v[204:207], v254, s[82:83] offset:768
	global_load_dwordx4 v[208:211], v255, s[82:83] offset:768
	global_load_dwordx4 v[212:215], v254, s[82:83] offset:832
	global_load_dwordx4 v[216:219], v255, s[82:83] offset:832
	s_waitcnt vmcnt(16)
	ds_write_b128 v247, v[116:119]
	ds_write_b128 v247, v[120:123] offset:1024
	ds_write_b128 v247, v[124:127] offset:2048
	ds_write_b128 v247, v[128:131] offset:3072
	ds_read_b128 v[116:119], v248
	ds_read_b128 v[120:123], v249
	ds_read_b128 v[124:127], v250
	ds_read_b128 v[128:131], v251
	ds_write_b128 v112, v[132:135]
	ds_write_b128 v112, v[136:139] offset:1024
	ds_write_b128 v112, v[140:143] offset:2048
	ds_write_b128 v112, v[144:147] offset:3072
	ds_read2_b32 v[32:33], v115 offset0:224 offset1:225
	ds_read2_b32 v[34:35], v115 offset0:226 offset1:227
	ds_read2_b32 v[36:37], v115 offset0:232 offset1:233
	ds_read2_b32 v[38:39], v115 offset0:234 offset1:235
	ds_read2_b32 v[40:41], v115 offset0:240 offset1:241
	ds_read2_b32 v[42:43], v115 offset0:242 offset1:243
	ds_read2_b32 v[44:45], v115 offset0:248 offset1:249
	ds_read2_b32 v[46:47], v115 offset0:250 offset1:251
	s_waitcnt lgkmcnt(0)
	v_mfma_f32_32x32x16_bf16 v[32:47], v[116:119], v[48:51], v[32:47]
	ds_read_b64_tr_b16 v[72:73], v231
	ds_read_b64_tr_b16 v[74:75], v231 offset:512
	ds_read_b64_tr_b16 v[76:77], v231 offset:2048
	ds_read_b64_tr_b16 v[78:79], v231 offset:2560
	ds_read_b64_tr_b16 v[220:221], v231 offset:1024
	ds_read_b64_tr_b16 v[222:223], v231 offset:1536
	ds_read_b64_tr_b16 v[224:225], v231 offset:3072
	ds_read_b64_tr_b16 v[226:227], v231 offset:3584
	v_mfma_f32_32x32x16_bf16 v[32:47], v[120:123], v[52:55], v[32:47]
	v_mfma_f32_32x32x16_bf16 v[32:47], v[124:127], v[56:59], v[32:47]
	v_mfma_f32_32x32x16_bf16 v[32:47], v[128:131], v[60:63], v[32:47]
	s_nop 11
	v_exp_f32_e32 v32, v32
	v_exp_f32_e32 v33, v33
	v_exp_f32_e32 v34, v34
	v_exp_f32_e32 v35, v35
	v_exp_f32_e32 v36, v36
	v_exp_f32_e32 v37, v37
	v_exp_f32_e32 v38, v38
	v_exp_f32_e32 v39, v39
	v_exp_f32_e32 v40, v40
	v_exp_f32_e32 v41, v41
	v_exp_f32_e32 v42, v42
	v_exp_f32_e32 v43, v43
	v_exp_f32_e32 v44, v44
	v_exp_f32_e32 v45, v45
	v_exp_f32_e32 v46, v46
	v_exp_f32_e32 v47, v47
	s_add_i32 s90, s67, 640
	v_lshlrev_b32_e32 v84, 2, v107
	v_add_u32_e32 v84, s90, v84
	v_add_u32_e32 v85, 0, v84
	v_add_u32_e32 v86, 4, v84
	v_add_u32_e32 v87, 8, v84
	v_add_u32_e32 v88, 12, v84
	v_cmp_gt_u32_e64 s[30:31], s98, v85
	v_cmp_gt_u32_e64 s[36:37], s98, v86
	v_cmp_gt_u32_e64 s[78:79], s98, v87
	v_cmp_gt_u32_e64 s[50:51], s98, v88
	v_cndmask_b32_e64 v32, 0, v32, s[30:31]
	v_add_u32_e32 v85, 32, v84
	v_cmp_gt_u32_e64 s[30:31], s98, v85
	v_cndmask_b32_e64 v33, 0, v33, s[36:37]
	v_add_u32_e32 v86, 36, v84
	v_cmp_gt_u32_e64 s[36:37], s98, v86
	v_cndmask_b32_e64 v34, 0, v34, s[78:79]
	v_add_u32_e32 v87, 40, v84
	v_cmp_gt_u32_e64 s[78:79], s98, v87
	v_cndmask_b32_e64 v35, 0, v35, s[50:51]
	v_add_u32_e32 v88, 44, v84
	v_cmp_gt_u32_e64 s[50:51], s98, v88
	v_cndmask_b32_e64 v36, 0, v36, s[30:31]
	v_add_u32_e32 v85, 64, v84
	v_cmp_gt_u32_e64 s[30:31], s98, v85
	v_cndmask_b32_e64 v37, 0, v37, s[36:37]
	v_add_u32_e32 v86, 68, v84
	v_cmp_gt_u32_e64 s[36:37], s98, v86
	v_cndmask_b32_e64 v38, 0, v38, s[78:79]
	v_add_u32_e32 v87, 72, v84
	v_cmp_gt_u32_e64 s[78:79], s98, v87
	v_cndmask_b32_e64 v39, 0, v39, s[50:51]
	v_add_u32_e32 v88, 76, v84
	v_cmp_gt_u32_e64 s[50:51], s98, v88
	v_cndmask_b32_e64 v40, 0, v40, s[30:31]
	v_add_u32_e32 v85, 96, v84
	v_cmp_gt_u32_e64 s[30:31], s98, v85
	v_cndmask_b32_e64 v41, 0, v41, s[36:37]
	v_add_u32_e32 v86, 100, v84
	v_cmp_gt_u32_e64 s[36:37], s98, v86
	v_cndmask_b32_e64 v42, 0, v42, s[78:79]
	v_add_u32_e32 v87, 104, v84
	v_cmp_gt_u32_e64 s[78:79], s98, v87
	v_cndmask_b32_e64 v43, 0, v43, s[50:51]
	v_add_u32_e32 v88, 108, v84
	v_cmp_gt_u32_e64 s[50:51], s98, v88
	v_nop
	v_cndmask_b32_e64 v44, 0, v44, s[30:31]
	v_cndmask_b32_e64 v45, 0, v45, s[36:37]
	v_cndmask_b32_e64 v46, 0, v46, s[78:79]
	v_cndmask_b32_e64 v47, 0, v47, s[50:51]
	v_cvt_pk_bf16_f32 v64, v32, v33
	v_cvt_pk_bf16_f32 v65, v34, v35
	v_cvt_pk_bf16_f32 v66, v36, v37
	v_cvt_pk_bf16_f32 v67, v38, v39
	v_cvt_pk_bf16_f32 v68, v40, v41
	v_cvt_pk_bf16_f32 v69, v42, v43
	v_cvt_pk_bf16_f32 v70, v44, v45
	v_cvt_pk_bf16_f32 v71, v46, v47
	v_pk_add_f32 v[232:233], v[232:233], v[32:33]
	v_pk_add_f32 v[232:233], v[232:233], v[34:35]
	v_pk_add_f32 v[232:233], v[232:233], v[36:37]
	v_pk_add_f32 v[232:233], v[232:233], v[38:39]
	v_pk_add_f32 v[232:233], v[232:233], v[40:41]
	v_pk_add_f32 v[232:233], v[232:233], v[42:43]
	v_pk_add_f32 v[232:233], v[232:233], v[44:45]
	v_pk_add_f32 v[232:233], v[232:233], v[46:47]
	s_waitcnt lgkmcnt(0)
	v_mfma_f32_32x32x16_bf16 v[0:15], v[64:67], v[72:75], v[0:15]
	v_mfma_f32_32x32x16_bf16 v[16:31], v[64:67], v[76:79], v[16:31]
	v_mfma_f32_32x32x16_bf16 v[0:15], v[68:71], v[220:223], v[0:15]
	v_mfma_f32_32x32x16_bf16 v[16:31], v[68:71], v[224:227], v[16:31]
	s_add_i32 s90, s67, 0
	v_add_u32_e32 v80, s90, v243
	v_add_u32_e32 v83, s90, v244
	v_add_u32_e32 v99, s90, v245
	v_add_u32_e32 v253, s90, v246
	v_add_u32_e32 v254, s90, v148
	v_add_u32_e32 v255, s90, v151
	v_med3_i32 v80, v80, 0, s99
	v_med3_i32 v83, v83, 0, s99
	v_med3_i32 v99, v99, 0, s99
	v_med3_i32 v253, v253, 0, s99
	v_med3_i32 v254, v254, 0, s99
	v_med3_i32 v255, v255, 0, s99
	v_mad_u32_u24 v80, v80, s100, v252
	v_mad_u32_u24 v83, v83, s100, v252
	v_mad_u32_u24 v99, v99, s100, v252
	v_mad_u32_u24 v253, v253, s100, v252
	v_mad_u32_u24 v254, v254, s100, v153
	v_mad_u32_u24 v255, v255, s100, v153
	global_load_dwordx4 v[116:119], v80, s[82:83]
	global_load_dwordx4 v[120:123], v83, s[82:83]
	global_load_dwordx4 v[124:127], v99, s[82:83]
	global_load_dwordx4 v[128:131], v253, s[82:83]
	global_load_dwordx4 v[132:135], v254, s[82:83] offset:768
	global_load_dwordx4 v[136:139], v255, s[82:83] offset:768
	global_load_dwordx4 v[140:143], v254, s[82:83] offset:832
	global_load_dwordx4 v[144:147], v255, s[82:83] offset:832
	s_waitcnt vmcnt(16)
	ds_write_b128 v247, v[156:159]
	ds_write_b128 v247, v[160:163] offset:1024
	ds_write_b128 v247, v[164:167] offset:2048
	ds_write_b128 v247, v[168:171] offset:3072
	ds_read_b128 v[156:159], v248
	ds_read_b128 v[160:163], v249
	ds_read_b128 v[164:167], v250
	ds_read_b128 v[168:171], v251
	ds_write_b128 v112, v[172:175]
	ds_write_b128 v112, v[176:179] offset:1024
	ds_write_b128 v112, v[180:183] offset:2048
	ds_write_b128 v112, v[184:187] offset:3072
	v_mov_b32_e32 v115, v230
	ds_read2_b32 v[32:33], v115 offset0:0 offset1:1
	ds_read2_b32 v[34:35], v115 offset0:2 offset1:3
	ds_read2_b32 v[36:37], v115 offset0:8 offset1:9
	ds_read2_b32 v[38:39], v115 offset0:10 offset1:11
	ds_read2_b32 v[40:41], v115 offset0:16 offset1:17
	ds_read2_b32 v[42:43], v115 offset0:18 offset1:19
	ds_read2_b32 v[44:45], v115 offset0:24 offset1:25
	ds_read2_b32 v[46:47], v115 offset0:26 offset1:27
	s_waitcnt lgkmcnt(0)
	v_mfma_f32_32x32x16_bf16 v[32:47], v[156:159], v[48:51], v[32:47]
	ds_read_b64_tr_b16 v[72:73], v231
	ds_read_b64_tr_b16 v[74:75], v231 offset:512
	ds_read_b64_tr_b16 v[76:77], v231 offset:2048
	ds_read_b64_tr_b16 v[78:79], v231 offset:2560
	ds_read_b64_tr_b16 v[220:221], v231 offset:1024
	ds_read_b64_tr_b16 v[222:223], v231 offset:1536
	ds_read_b64_tr_b16 v[224:225], v231 offset:3072
	ds_read_b64_tr_b16 v[226:227], v231 offset:3584
	v_mfma_f32_32x32x16_bf16 v[32:47], v[160:163], v[52:55], v[32:47]
	v_mfma_f32_32x32x16_bf16 v[32:47], v[164:167], v[56:59], v[32:47]
	v_mfma_f32_32x32x16_bf16 v[32:47], v[168:171], v[60:63], v[32:47]
	s_nop 11
	v_exp_f32_e32 v32, v32
	v_exp_f32_e32 v33, v33
	v_exp_f32_e32 v34, v34
	v_exp_f32_e32 v35, v35
	v_exp_f32_e32 v36, v36
	v_exp_f32_e32 v37, v37
	v_exp_f32_e32 v38, v38
	v_exp_f32_e32 v39, v39
	v_exp_f32_e32 v40, v40
	v_exp_f32_e32 v41, v41
	v_exp_f32_e32 v42, v42
	v_exp_f32_e32 v43, v43
	v_exp_f32_e32 v44, v44
	v_exp_f32_e32 v45, v45
	v_exp_f32_e32 v46, v46
	v_exp_f32_e32 v47, v47
	s_add_i32 s90, s67, -1024
	v_lshlrev_b32_e32 v84, 4, v107
	v_add_u32_e32 v84, s90, v84
	v_add_u32_e32 v85, 0, v84
	v_add_u32_e32 v86, 16, v84
	v_add_u32_e32 v87, 32, v84
	v_add_u32_e32 v88, 48, v84
	v_cmp_gt_u32_e64 s[30:31], s98, v85
	v_cmp_gt_u32_e64 s[36:37], s98, v86
	v_cmp_gt_u32_e64 s[78:79], s98, v87
	v_cmp_gt_u32_e64 s[50:51], s98, v88
	v_cndmask_b32_e64 v32, 0, v32, s[30:31]
	v_add_u32_e32 v85, 128, v84
	v_cmp_gt_u32_e64 s[30:31], s98, v85
	v_cndmask_b32_e64 v33, 0, v33, s[36:37]
	v_add_u32_e32 v86, 144, v84
	v_cmp_gt_u32_e64 s[36:37], s98, v86
	v_cndmask_b32_e64 v34, 0, v34, s[78:79]
	v_add_u32_e32 v87, 160, v84
	v_cmp_gt_u32_e64 s[78:79], s98, v87
	v_cndmask_b32_e64 v35, 0, v35, s[50:51]
	v_add_u32_e32 v88, 176, v84
	v_cmp_gt_u32_e64 s[50:51], s98, v88
	v_cndmask_b32_e64 v36, 0, v36, s[30:31]
	v_add_u32_e32 v85, 256, v84
	v_cmp_gt_u32_e64 s[30:31], s98, v85
	v_cndmask_b32_e64 v37, 0, v37, s[36:37]
	v_add_u32_e32 v86, 272, v84
	v_cmp_gt_u32_e64 s[36:37], s98, v86
	v_cndmask_b32_e64 v38, 0, v38, s[78:79]
	v_add_u32_e32 v87, 288, v84
	v_cmp_gt_u32_e64 s[78:79], s98, v87
	v_cndmask_b32_e64 v39, 0, v39, s[50:51]
	v_add_u32_e32 v88, 304, v84
	v_cmp_gt_u32_e64 s[50:51], s98, v88
	v_cndmask_b32_e64 v40, 0, v40, s[30:31]
	v_add_u32_e32 v85, 384, v84
	v_cmp_gt_u32_e64 s[30:31], s98, v85
	v_cndmask_b32_e64 v41, 0, v41, s[36:37]
	v_add_u32_e32 v86, 400, v84
	v_cmp_gt_u32_e64 s[36:37], s98, v86
	v_cndmask_b32_e64 v42, 0, v42, s[78:79]
	v_add_u32_e32 v87, 416, v84
	v_cmp_gt_u32_e64 s[78:79], s98, v87
	v_cndmask_b32_e64 v43, 0, v43, s[50:51]
	v_add_u32_e32 v88, 432, v84
	v_cmp_gt_u32_e64 s[50:51], s98, v88
	v_nop
	v_cndmask_b32_e64 v44, 0, v44, s[30:31]
	v_cndmask_b32_e64 v45, 0, v45, s[36:37]
	v_cndmask_b32_e64 v46, 0, v46, s[78:79]
	v_cndmask_b32_e64 v47, 0, v47, s[50:51]
	v_cvt_pk_bf16_f32 v64, v32, v33
	v_cvt_pk_bf16_f32 v65, v34, v35
	v_cvt_pk_bf16_f32 v66, v36, v37
	v_cvt_pk_bf16_f32 v67, v38, v39
	v_cvt_pk_bf16_f32 v68, v40, v41
	v_cvt_pk_bf16_f32 v69, v42, v43
	v_cvt_pk_bf16_f32 v70, v44, v45
	v_cvt_pk_bf16_f32 v71, v46, v47
	v_pk_add_f32 v[232:233], v[232:233], v[32:33]
	v_pk_add_f32 v[232:233], v[232:233], v[34:35]
	v_pk_add_f32 v[232:233], v[232:233], v[36:37]
	v_pk_add_f32 v[232:233], v[232:233], v[38:39]
	v_pk_add_f32 v[232:233], v[232:233], v[40:41]
	v_pk_add_f32 v[232:233], v[232:233], v[42:43]
	v_pk_add_f32 v[232:233], v[232:233], v[44:45]
	v_pk_add_f32 v[232:233], v[232:233], v[46:47]
	s_waitcnt lgkmcnt(0)
	v_mfma_f32_32x32x16_bf16 v[0:15], v[64:67], v[72:75], v[0:15]
	v_mfma_f32_32x32x16_bf16 v[16:31], v[64:67], v[76:79], v[16:31]
	v_mfma_f32_32x32x16_bf16 v[0:15], v[68:71], v[220:223], v[0:15]
	v_mfma_f32_32x32x16_bf16 v[16:31], v[68:71], v[224:227], v[16:31]
	s_add_i32 s90, s67, 512
	v_add_u32_e32 v80, s90, v243
	v_add_u32_e32 v83, s90, v244
	v_add_u32_e32 v99, s90, v245
	v_add_u32_e32 v253, s90, v246
	v_add_u32_e32 v254, s90, v148
	v_add_u32_e32 v255, s90, v151
	v_med3_i32 v80, v80, 0, s99
	v_med3_i32 v83, v83, 0, s99
	v_med3_i32 v99, v99, 0, s99
	v_med3_i32 v253, v253, 0, s99
	v_med3_i32 v254, v254, 0, s99
	v_med3_i32 v255, v255, 0, s99
	v_mad_u32_u24 v80, v80, s100, v252
	v_mad_u32_u24 v83, v83, s100, v252
	v_mad_u32_u24 v99, v99, s100, v252
	v_mad_u32_u24 v253, v253, s100, v252
	v_mad_u32_u24 v254, v254, s100, v153
	v_mad_u32_u24 v255, v255, s100, v153
	global_load_dwordx4 v[156:159], v80, s[82:83]
	global_load_dwordx4 v[160:163], v83, s[82:83]
	global_load_dwordx4 v[164:167], v99, s[82:83]
	global_load_dwordx4 v[168:171], v253, s[82:83]
	global_load_dwordx4 v[172:175], v254, s[82:83] offset:768
	global_load_dwordx4 v[176:179], v255, s[82:83] offset:768
	global_load_dwordx4 v[180:183], v254, s[82:83] offset:832
	global_load_dwordx4 v[184:187], v255, s[82:83] offset:832
	s_waitcnt vmcnt(16)
	ds_write_b128 v247, v[188:191]
	ds_write_b128 v247, v[192:195] offset:1024
	ds_write_b128 v247, v[196:199] offset:2048
	ds_write_b128 v247, v[200:203] offset:3072
	ds_read_b128 v[188:191], v248
	ds_read_b128 v[192:195], v249
	ds_read_b128 v[196:199], v250
	ds_read_b128 v[200:203], v251
	ds_write_b128 v112, v[204:207]
	ds_write_b128 v112, v[208:211] offset:1024
	ds_write_b128 v112, v[212:215] offset:2048
	ds_write_b128 v112, v[216:219] offset:3072
	ds_read2_b32 v[32:33], v115 offset0:32 offset1:33
	ds_read2_b32 v[34:35], v115 offset0:34 offset1:35
	ds_read2_b32 v[36:37], v115 offset0:40 offset1:41
	ds_read2_b32 v[38:39], v115 offset0:42 offset1:43
	ds_read2_b32 v[40:41], v115 offset0:48 offset1:49
	ds_read2_b32 v[42:43], v115 offset0:50 offset1:51
	ds_read2_b32 v[44:45], v115 offset0:56 offset1:57
	ds_read2_b32 v[46:47], v115 offset0:58 offset1:59
	s_waitcnt lgkmcnt(0)
	v_mfma_f32_32x32x16_bf16 v[32:47], v[188:191], v[48:51], v[32:47]
	ds_read_b64_tr_b16 v[72:73], v231
	ds_read_b64_tr_b16 v[74:75], v231 offset:512
	ds_read_b64_tr_b16 v[76:77], v231 offset:2048
	ds_read_b64_tr_b16 v[78:79], v231 offset:2560
	ds_read_b64_tr_b16 v[220:221], v231 offset:1024
	ds_read_b64_tr_b16 v[222:223], v231 offset:1536
	ds_read_b64_tr_b16 v[224:225], v231 offset:3072
	ds_read_b64_tr_b16 v[226:227], v231 offset:3584
	v_mfma_f32_32x32x16_bf16 v[32:47], v[192:195], v[52:55], v[32:47]
	v_mfma_f32_32x32x16_bf16 v[32:47], v[196:199], v[56:59], v[32:47]
	v_mfma_f32_32x32x16_bf16 v[32:47], v[200:203], v[60:63], v[32:47]
	s_nop 11
	v_exp_f32_e32 v32, v32
	v_exp_f32_e32 v33, v33
	v_exp_f32_e32 v34, v34
	v_exp_f32_e32 v35, v35
	v_exp_f32_e32 v36, v36
	v_exp_f32_e32 v37, v37
	v_exp_f32_e32 v38, v38
	v_exp_f32_e32 v39, v39
	v_exp_f32_e32 v40, v40
	v_exp_f32_e32 v41, v41
	v_exp_f32_e32 v42, v42
	v_exp_f32_e32 v43, v43
	v_exp_f32_e32 v44, v44
	v_exp_f32_e32 v45, v45
	v_exp_f32_e32 v46, v46
	v_exp_f32_e32 v47, v47
	s_add_i32 s90, s67, -512
	v_lshlrev_b32_e32 v84, 4, v107
	v_add_u32_e32 v84, s90, v84
	v_add_u32_e32 v85, 0, v84
	v_add_u32_e32 v86, 16, v84
	v_add_u32_e32 v87, 32, v84
	v_add_u32_e32 v88, 48, v84
	v_cmp_gt_u32_e64 s[30:31], s98, v85
	v_cmp_gt_u32_e64 s[36:37], s98, v86
	v_cmp_gt_u32_e64 s[78:79], s98, v87
	v_cmp_gt_u32_e64 s[50:51], s98, v88
	v_cndmask_b32_e64 v32, 0, v32, s[30:31]
	v_add_u32_e32 v85, 128, v84
	v_cmp_gt_u32_e64 s[30:31], s98, v85
	v_cndmask_b32_e64 v33, 0, v33, s[36:37]
	v_add_u32_e32 v86, 144, v84
	v_cmp_gt_u32_e64 s[36:37], s98, v86
	v_cndmask_b32_e64 v34, 0, v34, s[78:79]
	v_add_u32_e32 v87, 160, v84
	v_cmp_gt_u32_e64 s[78:79], s98, v87
	v_cndmask_b32_e64 v35, 0, v35, s[50:51]
	v_add_u32_e32 v88, 176, v84
	v_cmp_gt_u32_e64 s[50:51], s98, v88
	v_cndmask_b32_e64 v36, 0, v36, s[30:31]
	v_add_u32_e32 v85, 256, v84
	v_cmp_gt_u32_e64 s[30:31], s98, v85
	v_cndmask_b32_e64 v37, 0, v37, s[36:37]
	v_add_u32_e32 v86, 272, v84
	v_cmp_gt_u32_e64 s[36:37], s98, v86
	v_cndmask_b32_e64 v38, 0, v38, s[78:79]
	v_add_u32_e32 v87, 288, v84
	v_cmp_gt_u32_e64 s[78:79], s98, v87
	v_cndmask_b32_e64 v39, 0, v39, s[50:51]
	v_add_u32_e32 v88, 304, v84
	v_cmp_gt_u32_e64 s[50:51], s98, v88
	v_cndmask_b32_e64 v40, 0, v40, s[30:31]
	v_add_u32_e32 v85, 384, v84
	v_cmp_gt_u32_e64 s[30:31], s98, v85
	v_cndmask_b32_e64 v41, 0, v41, s[36:37]
	v_add_u32_e32 v86, 400, v84
	v_cmp_gt_u32_e64 s[36:37], s98, v86
	v_cndmask_b32_e64 v42, 0, v42, s[78:79]
	v_add_u32_e32 v87, 416, v84
	v_cmp_gt_u32_e64 s[78:79], s98, v87
	v_cndmask_b32_e64 v43, 0, v43, s[50:51]
	v_add_u32_e32 v88, 432, v84
	v_cmp_gt_u32_e64 s[50:51], s98, v88
	v_nop
	v_cndmask_b32_e64 v44, 0, v44, s[30:31]
	v_cndmask_b32_e64 v45, 0, v45, s[36:37]
	v_cndmask_b32_e64 v46, 0, v46, s[78:79]
	v_cndmask_b32_e64 v47, 0, v47, s[50:51]
	v_cvt_pk_bf16_f32 v64, v32, v33
	v_cvt_pk_bf16_f32 v65, v34, v35
	v_cvt_pk_bf16_f32 v66, v36, v37
	v_cvt_pk_bf16_f32 v67, v38, v39
	v_cvt_pk_bf16_f32 v68, v40, v41
	v_cvt_pk_bf16_f32 v69, v42, v43
	v_cvt_pk_bf16_f32 v70, v44, v45
	v_cvt_pk_bf16_f32 v71, v46, v47
	v_pk_add_f32 v[232:233], v[232:233], v[32:33]
	v_pk_add_f32 v[232:233], v[232:233], v[34:35]
	v_pk_add_f32 v[232:233], v[232:233], v[36:37]
	v_pk_add_f32 v[232:233], v[232:233], v[38:39]
	v_pk_add_f32 v[232:233], v[232:233], v[40:41]
	v_pk_add_f32 v[232:233], v[232:233], v[42:43]
	v_pk_add_f32 v[232:233], v[232:233], v[44:45]
	v_pk_add_f32 v[232:233], v[232:233], v[46:47]
	s_waitcnt lgkmcnt(0)
	v_mfma_f32_32x32x16_bf16 v[0:15], v[64:67], v[72:75], v[0:15]
	v_mfma_f32_32x32x16_bf16 v[16:31], v[64:67], v[76:79], v[16:31]
	v_mfma_f32_32x32x16_bf16 v[0:15], v[68:71], v[220:223], v[0:15]
	v_mfma_f32_32x32x16_bf16 v[16:31], v[68:71], v[224:227], v[16:31]
	s_add_i32 s90, s67, 1024
	v_add_u32_e32 v80, s90, v243
	v_add_u32_e32 v83, s90, v244
	v_add_u32_e32 v99, s90, v245
	v_add_u32_e32 v253, s90, v246
	v_add_u32_e32 v254, s90, v148
	v_add_u32_e32 v255, s90, v151
	v_med3_i32 v80, v80, 0, s99
	v_med3_i32 v83, v83, 0, s99
	v_med3_i32 v99, v99, 0, s99
	v_med3_i32 v253, v253, 0, s99
	v_med3_i32 v254, v254, 0, s99
	v_med3_i32 v255, v255, 0, s99
	v_mad_u32_u24 v80, v80, s100, v252
	v_mad_u32_u24 v83, v83, s100, v252
	v_mad_u32_u24 v99, v99, s100, v252
	v_mad_u32_u24 v253, v253, s100, v252
	v_mad_u32_u24 v254, v254, s100, v153
	v_mad_u32_u24 v255, v255, s100, v153
	global_load_dwordx4 v[188:191], v80, s[82:83]
	global_load_dwordx4 v[192:195], v83, s[82:83]
	global_load_dwordx4 v[196:199], v99, s[82:83]
	global_load_dwordx4 v[200:203], v253, s[82:83]
	global_load_dwordx4 v[204:207], v254, s[82:83] offset:768
	global_load_dwordx4 v[208:211], v255, s[82:83] offset:768
	global_load_dwordx4 v[212:215], v254, s[82:83] offset:832
	global_load_dwordx4 v[216:219], v255, s[82:83] offset:832
	s_waitcnt vmcnt(16)
	ds_write_b128 v247, v[116:119]
	ds_write_b128 v247, v[120:123] offset:1024
	ds_write_b128 v247, v[124:127] offset:2048
	ds_write_b128 v247, v[128:131] offset:3072
	ds_read_b128 v[116:119], v248
	ds_read_b128 v[120:123], v249
	ds_read_b128 v[124:127], v250
	ds_read_b128 v[128:131], v251
	ds_write_b128 v112, v[132:135]
	ds_write_b128 v112, v[136:139] offset:1024
	ds_write_b128 v112, v[140:143] offset:2048
	ds_write_b128 v112, v[144:147] offset:3072
	ds_read2_b32 v[32:33], v115 offset0:64 offset1:65
	ds_read2_b32 v[34:35], v115 offset0:66 offset1:67
	ds_read2_b32 v[36:37], v115 offset0:72 offset1:73
	ds_read2_b32 v[38:39], v115 offset0:74 offset1:75
	ds_read2_b32 v[40:41], v115 offset0:80 offset1:81
	ds_read2_b32 v[42:43], v115 offset0:82 offset1:83
	ds_read2_b32 v[44:45], v115 offset0:88 offset1:89
	ds_read2_b32 v[46:47], v115 offset0:90 offset1:91
	s_waitcnt lgkmcnt(0)
	v_mfma_f32_32x32x16_bf16 v[32:47], v[116:119], v[48:51], v[32:47]
	ds_read_b64_tr_b16 v[72:73], v231
	ds_read_b64_tr_b16 v[74:75], v231 offset:512
	ds_read_b64_tr_b16 v[76:77], v231 offset:2048
	ds_read_b64_tr_b16 v[78:79], v231 offset:2560
	ds_read_b64_tr_b16 v[220:221], v231 offset:1024
	ds_read_b64_tr_b16 v[222:223], v231 offset:1536
	ds_read_b64_tr_b16 v[224:225], v231 offset:3072
	ds_read_b64_tr_b16 v[226:227], v231 offset:3584
	v_mfma_f32_32x32x16_bf16 v[32:47], v[120:123], v[52:55], v[32:47]
	v_mfma_f32_32x32x16_bf16 v[32:47], v[124:127], v[56:59], v[32:47]
	v_mfma_f32_32x32x16_bf16 v[32:47], v[128:131], v[60:63], v[32:47]
	s_nop 11
	v_exp_f32_e32 v32, v32
	v_exp_f32_e32 v33, v33
	v_exp_f32_e32 v34, v34
	v_exp_f32_e32 v35, v35
	v_exp_f32_e32 v36, v36
	v_exp_f32_e32 v37, v37
	v_exp_f32_e32 v38, v38
	v_exp_f32_e32 v39, v39
	v_exp_f32_e32 v40, v40
	v_exp_f32_e32 v41, v41
	v_exp_f32_e32 v42, v42
	v_exp_f32_e32 v43, v43
	v_exp_f32_e32 v44, v44
	v_exp_f32_e32 v45, v45
	v_exp_f32_e32 v46, v46
	v_exp_f32_e32 v47, v47
	s_add_i32 s90, s67, 0
	v_lshlrev_b32_e32 v84, 4, v107
	v_add_u32_e32 v84, s90, v84
	v_add_u32_e32 v85, 0, v84
	v_add_u32_e32 v86, 16, v84
	v_add_u32_e32 v87, 32, v84
	v_add_u32_e32 v88, 48, v84
	v_cmp_gt_u32_e64 s[30:31], s98, v85
	v_cmp_gt_u32_e64 s[36:37], s98, v86
	v_cmp_gt_u32_e64 s[78:79], s98, v87
	v_cmp_gt_u32_e64 s[50:51], s98, v88
	v_cndmask_b32_e64 v32, 0, v32, s[30:31]
	v_add_u32_e32 v85, 128, v84
	v_cmp_gt_u32_e64 s[30:31], s98, v85
	v_cndmask_b32_e64 v33, 0, v33, s[36:37]
	v_add_u32_e32 v86, 144, v84
	v_cmp_gt_u32_e64 s[36:37], s98, v86
	v_cndmask_b32_e64 v34, 0, v34, s[78:79]
	v_add_u32_e32 v87, 160, v84
	v_cmp_gt_u32_e64 s[78:79], s98, v87
	v_cndmask_b32_e64 v35, 0, v35, s[50:51]
	v_add_u32_e32 v88, 176, v84
	v_cmp_gt_u32_e64 s[50:51], s98, v88
	v_cndmask_b32_e64 v36, 0, v36, s[30:31]
	v_add_u32_e32 v85, 256, v84
	v_cmp_gt_u32_e64 s[30:31], s98, v85
	v_cndmask_b32_e64 v37, 0, v37, s[36:37]
	v_add_u32_e32 v86, 272, v84
	v_cmp_gt_u32_e64 s[36:37], s98, v86
	v_cndmask_b32_e64 v38, 0, v38, s[78:79]
	v_add_u32_e32 v87, 288, v84
	v_cmp_gt_u32_e64 s[78:79], s98, v87
	v_cndmask_b32_e64 v39, 0, v39, s[50:51]
	v_add_u32_e32 v88, 304, v84
	v_cmp_gt_u32_e64 s[50:51], s98, v88
	v_cndmask_b32_e64 v40, 0, v40, s[30:31]
	v_add_u32_e32 v85, 384, v84
	v_cmp_gt_u32_e64 s[30:31], s98, v85
	v_cndmask_b32_e64 v41, 0, v41, s[36:37]
	v_add_u32_e32 v86, 400, v84
	v_cmp_gt_u32_e64 s[36:37], s98, v86
	v_cndmask_b32_e64 v42, 0, v42, s[78:79]
	v_add_u32_e32 v87, 416, v84
	v_cmp_gt_u32_e64 s[78:79], s98, v87
	v_cndmask_b32_e64 v43, 0, v43, s[50:51]
	v_add_u32_e32 v88, 432, v84
	v_cmp_gt_u32_e64 s[50:51], s98, v88
	v_nop
	v_cndmask_b32_e64 v44, 0, v44, s[30:31]
	v_cndmask_b32_e64 v45, 0, v45, s[36:37]
	v_cndmask_b32_e64 v46, 0, v46, s[78:79]
	v_cndmask_b32_e64 v47, 0, v47, s[50:51]
	v_cvt_pk_bf16_f32 v64, v32, v33
	v_cvt_pk_bf16_f32 v65, v34, v35
	v_cvt_pk_bf16_f32 v66, v36, v37
	v_cvt_pk_bf16_f32 v67, v38, v39
	v_cvt_pk_bf16_f32 v68, v40, v41
	v_cvt_pk_bf16_f32 v69, v42, v43
	v_cvt_pk_bf16_f32 v70, v44, v45
	v_cvt_pk_bf16_f32 v71, v46, v47
	v_pk_add_f32 v[232:233], v[232:233], v[32:33]
	v_pk_add_f32 v[232:233], v[232:233], v[34:35]
	v_pk_add_f32 v[232:233], v[232:233], v[36:37]
	v_pk_add_f32 v[232:233], v[232:233], v[38:39]
	v_pk_add_f32 v[232:233], v[232:233], v[40:41]
	v_pk_add_f32 v[232:233], v[232:233], v[42:43]
	v_pk_add_f32 v[232:233], v[232:233], v[44:45]
	v_pk_add_f32 v[232:233], v[232:233], v[46:47]
	s_waitcnt lgkmcnt(0)
	v_mfma_f32_32x32x16_bf16 v[0:15], v[64:67], v[72:75], v[0:15]
	v_mfma_f32_32x32x16_bf16 v[16:31], v[64:67], v[76:79], v[16:31]
	v_mfma_f32_32x32x16_bf16 v[0:15], v[68:71], v[220:223], v[0:15]
	v_mfma_f32_32x32x16_bf16 v[16:31], v[68:71], v[224:227], v[16:31]
	s_waitcnt vmcnt(8)
	ds_write_b128 v247, v[156:159]
	ds_write_b128 v247, v[160:163] offset:1024
	ds_write_b128 v247, v[164:167] offset:2048
	ds_write_b128 v247, v[168:171] offset:3072
	ds_read_b128 v[156:159], v248
	ds_read_b128 v[160:163], v249
	ds_read_b128 v[164:167], v250
	ds_read_b128 v[168:171], v251
	ds_write_b128 v112, v[172:175]
	ds_write_b128 v112, v[176:179] offset:1024
	ds_write_b128 v112, v[180:183] offset:2048
	ds_write_b128 v112, v[184:187] offset:3072
	ds_read2_b32 v[32:33], v115 offset0:96 offset1:97
	ds_read2_b32 v[34:35], v115 offset0:98 offset1:99
	ds_read2_b32 v[36:37], v115 offset0:104 offset1:105
	ds_read2_b32 v[38:39], v115 offset0:106 offset1:107
	ds_read2_b32 v[40:41], v115 offset0:112 offset1:113
	ds_read2_b32 v[42:43], v115 offset0:114 offset1:115
	ds_read2_b32 v[44:45], v115 offset0:120 offset1:121
	ds_read2_b32 v[46:47], v115 offset0:122 offset1:123
	s_waitcnt lgkmcnt(0)
	v_mfma_f32_32x32x16_bf16 v[32:47], v[156:159], v[48:51], v[32:47]
	ds_read_b64_tr_b16 v[72:73], v231
	ds_read_b64_tr_b16 v[74:75], v231 offset:512
	ds_read_b64_tr_b16 v[76:77], v231 offset:2048
	ds_read_b64_tr_b16 v[78:79], v231 offset:2560
	ds_read_b64_tr_b16 v[220:221], v231 offset:1024
	ds_read_b64_tr_b16 v[222:223], v231 offset:1536
	ds_read_b64_tr_b16 v[224:225], v231 offset:3072
	ds_read_b64_tr_b16 v[226:227], v231 offset:3584
	v_mfma_f32_32x32x16_bf16 v[32:47], v[160:163], v[52:55], v[32:47]
	v_mfma_f32_32x32x16_bf16 v[32:47], v[164:167], v[56:59], v[32:47]
	v_mfma_f32_32x32x16_bf16 v[32:47], v[168:171], v[60:63], v[32:47]
	s_nop 11
	v_exp_f32_e32 v32, v32
	v_exp_f32_e32 v33, v33
	v_exp_f32_e32 v34, v34
	v_exp_f32_e32 v35, v35
	v_exp_f32_e32 v36, v36
	v_exp_f32_e32 v37, v37
	v_exp_f32_e32 v38, v38
	v_exp_f32_e32 v39, v39
	v_exp_f32_e32 v40, v40
	v_exp_f32_e32 v41, v41
	v_exp_f32_e32 v42, v42
	v_exp_f32_e32 v43, v43
	v_exp_f32_e32 v44, v44
	v_exp_f32_e32 v45, v45
	v_exp_f32_e32 v46, v46
	v_exp_f32_e32 v47, v47
	s_add_i32 s90, s67, 512
	v_lshlrev_b32_e32 v84, 4, v107
	v_add_u32_e32 v84, s90, v84
	v_add_u32_e32 v85, 0, v84
	v_add_u32_e32 v86, 16, v84
	v_add_u32_e32 v87, 32, v84
	v_add_u32_e32 v88, 48, v84
	v_cmp_gt_u32_e64 s[30:31], s98, v85
	v_cmp_gt_u32_e64 s[36:37], s98, v86
	v_cmp_gt_u32_e64 s[78:79], s98, v87
	v_cmp_gt_u32_e64 s[50:51], s98, v88
	v_cndmask_b32_e64 v32, 0, v32, s[30:31]
	v_add_u32_e32 v85, 128, v84
	v_cmp_gt_u32_e64 s[30:31], s98, v85
	v_cndmask_b32_e64 v33, 0, v33, s[36:37]
	v_add_u32_e32 v86, 144, v84
	v_cmp_gt_u32_e64 s[36:37], s98, v86
	v_cndmask_b32_e64 v34, 0, v34, s[78:79]
	v_add_u32_e32 v87, 160, v84
	v_cmp_gt_u32_e64 s[78:79], s98, v87
	v_cndmask_b32_e64 v35, 0, v35, s[50:51]
	v_add_u32_e32 v88, 176, v84
	v_cmp_gt_u32_e64 s[50:51], s98, v88
	v_cndmask_b32_e64 v36, 0, v36, s[30:31]
	v_add_u32_e32 v85, 256, v84
	v_cmp_gt_u32_e64 s[30:31], s98, v85
	v_cndmask_b32_e64 v37, 0, v37, s[36:37]
	v_add_u32_e32 v86, 272, v84
	v_cmp_gt_u32_e64 s[36:37], s98, v86
	v_cndmask_b32_e64 v38, 0, v38, s[78:79]
	v_add_u32_e32 v87, 288, v84
	v_cmp_gt_u32_e64 s[78:79], s98, v87
	v_cndmask_b32_e64 v39, 0, v39, s[50:51]
	v_add_u32_e32 v88, 304, v84
	v_cmp_gt_u32_e64 s[50:51], s98, v88
	v_cndmask_b32_e64 v40, 0, v40, s[30:31]
	v_add_u32_e32 v85, 384, v84
	v_cmp_gt_u32_e64 s[30:31], s98, v85
	v_cndmask_b32_e64 v41, 0, v41, s[36:37]
	v_add_u32_e32 v86, 400, v84
	v_cmp_gt_u32_e64 s[36:37], s98, v86
	v_cndmask_b32_e64 v42, 0, v42, s[78:79]
	v_add_u32_e32 v87, 416, v84
	v_cmp_gt_u32_e64 s[78:79], s98, v87
	v_cndmask_b32_e64 v43, 0, v43, s[50:51]
	v_add_u32_e32 v88, 432, v84
	v_cmp_gt_u32_e64 s[50:51], s98, v88
	v_nop
	v_cndmask_b32_e64 v44, 0, v44, s[30:31]
	v_cndmask_b32_e64 v45, 0, v45, s[36:37]
	v_cndmask_b32_e64 v46, 0, v46, s[78:79]
	v_cndmask_b32_e64 v47, 0, v47, s[50:51]
	v_cvt_pk_bf16_f32 v64, v32, v33
	v_cvt_pk_bf16_f32 v65, v34, v35
	v_cvt_pk_bf16_f32 v66, v36, v37
	v_cvt_pk_bf16_f32 v67, v38, v39
	v_cvt_pk_bf16_f32 v68, v40, v41
	v_cvt_pk_bf16_f32 v69, v42, v43
	v_cvt_pk_bf16_f32 v70, v44, v45
	v_cvt_pk_bf16_f32 v71, v46, v47
	v_pk_add_f32 v[232:233], v[232:233], v[32:33]
	v_pk_add_f32 v[232:233], v[232:233], v[34:35]
	v_pk_add_f32 v[232:233], v[232:233], v[36:37]
	v_pk_add_f32 v[232:233], v[232:233], v[38:39]
	v_pk_add_f32 v[232:233], v[232:233], v[40:41]
	v_pk_add_f32 v[232:233], v[232:233], v[42:43]
	v_pk_add_f32 v[232:233], v[232:233], v[44:45]
	v_pk_add_f32 v[232:233], v[232:233], v[46:47]
	s_waitcnt lgkmcnt(0)
	v_mfma_f32_32x32x16_bf16 v[0:15], v[64:67], v[72:75], v[0:15]
	v_mfma_f32_32x32x16_bf16 v[16:31], v[64:67], v[76:79], v[16:31]
	v_mfma_f32_32x32x16_bf16 v[0:15], v[68:71], v[220:223], v[0:15]
	v_mfma_f32_32x32x16_bf16 v[16:31], v[68:71], v[224:227], v[16:31]
	s_waitcnt vmcnt(0)
	ds_write_b128 v247, v[188:191]
	ds_write_b128 v247, v[192:195] offset:1024
	ds_write_b128 v247, v[196:199] offset:2048
	ds_write_b128 v247, v[200:203] offset:3072
	ds_read_b128 v[188:191], v248
	ds_read_b128 v[192:195], v249
	ds_read_b128 v[196:199], v250
	ds_read_b128 v[200:203], v251
	ds_write_b128 v112, v[204:207]
	ds_write_b128 v112, v[208:211] offset:1024
	ds_write_b128 v112, v[212:215] offset:2048
	ds_write_b128 v112, v[216:219] offset:3072
	ds_read2_b32 v[32:33], v115 offset0:128 offset1:129
	ds_read2_b32 v[34:35], v115 offset0:130 offset1:131
	ds_read2_b32 v[36:37], v115 offset0:136 offset1:137
	ds_read2_b32 v[38:39], v115 offset0:138 offset1:139
	ds_read2_b32 v[40:41], v115 offset0:144 offset1:145
	ds_read2_b32 v[42:43], v115 offset0:146 offset1:147
	ds_read2_b32 v[44:45], v115 offset0:152 offset1:153
	ds_read2_b32 v[46:47], v115 offset0:154 offset1:155
	s_waitcnt lgkmcnt(0)
; __device__ __forceinline__ int crow(int r, int hi) { return (r & 3) + 8 * (r >> 2) + 4 * hi; }
; __device__ __forceinline__ void dil_unit(LAS unsigned char* lds, bf16_t* proj, int seq, int hd, int T0, int rho) {
;     ...
;     l += __shfl_xor(l, 32);
; #pragma unroll
;     for (int rr = 0; rr < 16; ++rr) {
;         const int j = crow(rr, hi);
	v_mfma_f32_32x32x16_bf16 v[32:47], v[188:191], v[48:51], v[32:47]
	ds_read_b64_tr_b16 v[72:73], v231
	ds_read_b64_tr_b16 v[74:75], v231 offset:512
	ds_read_b64_tr_b16 v[76:77], v231 offset:2048
	ds_read_b64_tr_b16 v[78:79], v231 offset:2560
	ds_read_b64_tr_b16 v[220:221], v231 offset:1024
	ds_read_b64_tr_b16 v[222:223], v231 offset:1536
	ds_read_b64_tr_b16 v[224:225], v231 offset:3072
	ds_read_b64_tr_b16 v[226:227], v231 offset:3584
	v_mfma_f32_32x32x16_bf16 v[32:47], v[192:195], v[52:55], v[32:47]
	v_mfma_f32_32x32x16_bf16 v[32:47], v[196:199], v[56:59], v[32:47]
	v_mfma_f32_32x32x16_bf16 v[32:47], v[200:203], v[60:63], v[32:47]
	s_nop 11
	v_exp_f32_e32 v32, v32
	v_exp_f32_e32 v33, v33
	v_exp_f32_e32 v34, v34
	v_exp_f32_e32 v35, v35
	v_exp_f32_e32 v36, v36
	v_exp_f32_e32 v37, v37
	v_exp_f32_e32 v38, v38
	v_exp_f32_e32 v39, v39
	v_exp_f32_e32 v40, v40
	v_exp_f32_e32 v41, v41
	v_exp_f32_e32 v42, v42
	v_exp_f32_e32 v43, v43
	v_exp_f32_e32 v44, v44
	v_exp_f32_e32 v45, v45
	v_exp_f32_e32 v46, v46
	v_exp_f32_e32 v47, v47
	s_add_i32 s90, s67, 1024
	v_lshlrev_b32_e32 v84, 4, v107
	v_add_u32_e32 v84, s90, v84
	v_add_u32_e32 v85, 0, v84
	v_add_u32_e32 v86, 16, v84
	v_add_u32_e32 v87, 32, v84
	v_add_u32_e32 v88, 48, v84
	v_cmp_gt_u32_e64 s[30:31], s98, v85
	v_cmp_gt_u32_e64 s[36:37], s98, v86
	v_cmp_gt_u32_e64 s[78:79], s98, v87
	v_cmp_gt_u32_e64 s[50:51], s98, v88
	v_cndmask_b32_e64 v32, 0, v32, s[30:31]
	v_add_u32_e32 v85, 128, v84
	v_cmp_gt_u32_e64 s[30:31], s98, v85
	v_cndmask_b32_e64 v33, 0, v33, s[36:37]
	v_add_u32_e32 v86, 144, v84
	v_cmp_gt_u32_e64 s[36:37], s98, v86
	v_cndmask_b32_e64 v34, 0, v34, s[78:79]
	v_add_u32_e32 v87, 160, v84
	v_cmp_gt_u32_e64 s[78:79], s98, v87
	v_cndmask_b32_e64 v35, 0, v35, s[50:51]
	v_add_u32_e32 v88, 176, v84
	v_cmp_gt_u32_e64 s[50:51], s98, v88
	v_cndmask_b32_e64 v36, 0, v36, s[30:31]
	v_add_u32_e32 v85, 256, v84
	v_cmp_gt_u32_e64 s[30:31], s98, v85
	v_cndmask_b32_e64 v37, 0, v37, s[36:37]
	v_add_u32_e32 v86, 272, v84
	v_cmp_gt_u32_e64 s[36:37], s98, v86
	v_cndmask_b32_e64 v38, 0, v38, s[78:79]
	v_add_u32_e32 v87, 288, v84
	v_cmp_gt_u32_e64 s[78:79], s98, v87
	v_cndmask_b32_e64 v39, 0, v39, s[50:51]
	v_add_u32_e32 v88, 304, v84
	v_cmp_gt_u32_e64 s[50:51], s98, v88
	v_cndmask_b32_e64 v40, 0, v40, s[30:31]
	v_add_u32_e32 v85, 384, v84
	v_cmp_gt_u32_e64 s[30:31], s98, v85
	v_cndmask_b32_e64 v41, 0, v41, s[36:37]
	v_add_u32_e32 v86, 400, v84
	v_cmp_gt_u32_e64 s[36:37], s98, v86
	v_cndmask_b32_e64 v42, 0, v42, s[78:79]
	v_add_u32_e32 v87, 416, v84
	v_cmp_gt_u32_e64 s[78:79], s98, v87
	v_cndmask_b32_e64 v43, 0, v43, s[50:51]
	v_add_u32_e32 v88, 432, v84
	v_cmp_gt_u32_e64 s[50:51], s98, v88
	v_nop
	v_cndmask_b32_e64 v44, 0, v44, s[30:31]
	v_cndmask_b32_e64 v45, 0, v45, s[36:37]
	v_cndmask_b32_e64 v46, 0, v46, s[78:79]
	v_cndmask_b32_e64 v47, 0, v47, s[50:51]
	v_cvt_pk_bf16_f32 v64, v32, v33
	v_cvt_pk_bf16_f32 v65, v34, v35
	v_cvt_pk_bf16_f32 v66, v36, v37
	v_cvt_pk_bf16_f32 v67, v38, v39
	v_cvt_pk_bf16_f32 v68, v40, v41
	v_cvt_pk_bf16_f32 v69, v42, v43
	v_cvt_pk_bf16_f32 v70, v44, v45
	v_cvt_pk_bf16_f32 v71, v46, v47
	v_pk_add_f32 v[232:233], v[232:233], v[32:33]
	v_pk_add_f32 v[232:233], v[232:233], v[34:35]
	v_pk_add_f32 v[232:233], v[232:233], v[36:37]
	v_pk_add_f32 v[232:233], v[232:233], v[38:39]
	v_pk_add_f32 v[232:233], v[232:233], v[40:41]
	v_pk_add_f32 v[232:233], v[232:233], v[42:43]
	v_pk_add_f32 v[232:233], v[232:233], v[44:45]
	v_pk_add_f32 v[232:233], v[232:233], v[46:47]
	s_waitcnt lgkmcnt(0)
	v_mfma_f32_32x32x16_bf16 v[0:15], v[64:67], v[72:75], v[0:15]
	v_mfma_f32_32x32x16_bf16 v[16:31], v[64:67], v[76:79], v[16:31]
	v_mfma_f32_32x32x16_bf16 v[0:15], v[68:71], v[220:223], v[0:15]
	v_mfma_f32_32x32x16_bf16 v[16:31], v[68:71], v[224:227], v[16:31]
	v_add_f32_e32 v113, v232, v233
	v_or_b32_e32 v114, 1, v107
	v_or_b32_e32 v97, 2, v107
	v_or_b32_e32 v96, 3, v107
	v_or_b32_e32 v95, 8, v107
	v_or_b32_e32 v94, 9, v107
	v_or_b32_e32 v93, 10, v107
	v_or_b32_e32 v92, 11, v107
	v_or_b32_e32 v91, 16, v107
	v_or_b32_e32 v90, 17, v107
	v_or_b32_e32 v89, 18, v107
	v_or_b32_e32 v88, 19, v107
	v_or_b32_e32 v87, 24, v107
	v_or_b32_e32 v86, 25, v107
	v_or_b32_e32 v85, 26, v107
	v_or_b32_e32 v84, 27, v107
	s_nop 11
	s_branch .LBB0_1265
